# K-loops: MFMA order keeps the second source fragment (A rows) fixed for four consecutive MFMAs across both column halves, snake over the other fragment
# speedup vs baseline: 1.0061x; 1.0061x over previous
; #define PG8_STAGEA(bufoff, gbase) PG8_STAGE_(bufoff, gbase, voffA)
; #define PG8_STAGEB(bufoff, gbase) PG8_STAGE_(bufoff, gbase, voffB)
; #define PG8_LDA(dst, b, h) do { _Pragma("unroll") for (int m = 0; m < 4; ++m) _Pragma("unroll") for (int k = 0; k < 2; ++k) dst[m][k] = *(const LAS bf16x8*)(lds + PG8_SA(b, h) + aoff + m * 2048 + k * 1024); } while (0)
; #define PG8_LDB(dst, b, h) do { _Pragma("unroll") for (int n = 0; n < 2; ++n) _Pragma("unroll") for (int k = 0; k < 2; ++k) dst[n][k] = *(const LAS bf16x8*)(lds + PG8_SB(b, h) + boff + n * 2048 + k * 1024); } while (0)
; #define PG8_MMA(ai, bj, At, Bt_) do { __builtin_amdgcn_s_setprio(1); _Pragma("unroll") for (int m = 0; m < 4; ++m) _Pragma("unroll") for (int n = 0; n < 2; ++n) _Pragma("unroll") for (int k = 0; k < 2; ++k) \
;         acc[ai][bj][m][n] = __builtin_amdgcn_mfma_f32_16x16x32_bf16(Bt_[n][k], At[m][k], acc[ai][bj][m][n], 0, 0, 0); __builtin_amdgcn_s_setprio(0); } while (0)
; #define PG8_WAIT_V(n) asm volatile("s_waitcnt vmcnt(" #n ")" ::: "memory")
; #define PG8_WAIT_L(n) asm volatile("s_waitcnt lgkmcnt(" #n ")" ::: "memory")
; #define PG8_BAR __builtin_amdgcn_s_barrier()
; template <int EK, int SK = -1>
; __device__ __forceinline__ void gemm_phase(LAS unsigned char* lds, const bf16_t* A, const bf16_t* Bt, int nM, int N, int K, const EpiArgs& E) {
;     ...
;         const bool has_next = S.next(ui + 1, nxt);
;         const char* nA = has_next ? (const char*)A + (size_t)nxt.pm * tstep : cA; const char* nB = has_next ? (const char*)Bt + (size_t)nxt.pn * tstep : cB;
;         for (int t = 0; t < nt; t += 2) {
;             const bool last = (t == nt - 2);
;             const char* a1 = cA + (size_t)(t + 1) * kstep;
;             const char* a2 = last ? nA : cA + (size_t)(t + 2) * kstep; const char* b2 = last ? nB : cB + (size_t)(t + 2) * kstep;
;             const char* a3 = a2 + kstep; const char* b3 = b2 + kstep;
;             PG8_LDB(B0, 0, 0); PG8_LDB(B1, 0, 1); PG8_SCHED; PG8_LDA(At, 0, 0); PG8_STAGEA(PG8_SA(1, 1), a1 + hstep);
;             PG8_WAIT_V(8); PG8_WAIT_L(0); PG8_BAR; PG8_MMA(0, 0, At, B0); PG8_MMA(0, 1, At, B1); PG8_BAR; PG8_SCHED;
;             PG8_LDA(At, 0, 1); PG8_STAGEB(PG8_SB(0, 0), b2); PG8_STAGEB(PG8_SB(0, 1), b2 + hstep); PG8_STAGEA(PG8_SA(0, 0), a2);
;             PG8_WAIT_V(8); PG8_WAIT_L(0); PG8_BAR; PG8_MMA(1, 0, At, B0); PG8_MMA(1, 1, At, B1); PG8_BAR; PG8_SCHED;
.LBB0_197:
	s_add_u32 s58, s78, 0x100
	s_addc_u32 s59, s79, 0
	s_ashr_i32 s75, s74, 31
	s_lshl_b64 s[76:77], s[74:75], 19
	s_add_u32 s80, s62, s76
	s_addc_u32 s81, s63, s77
	s_and_b64 s[76:77], s[6:7], exec
	s_cselect_b32 s75, s81, s71
	s_cselect_b32 s90, s80, s70
	s_ashr_i32 s73, s72, 31
	s_lshl_b64 s[76:77], s[72:73], 19
	s_add_u32 s76, s30, s76
	s_addc_u32 s77, s31, s77
	s_and_b64 s[82:83], s[6:7], exec
	s_cselect_b32 s73, s77, s79
	s_cselect_b32 s91, s76, s78
	v_lshl_add_u64 v[146:147], s[70:71], 0, v[138:139]
	v_lshl_add_u64 v[148:149], s[70:71], 0, v[140:141]
	s_mov_b32 s92, -2
	s_mov_b64 s[78:79], 0
	v_add_u32_e32 v150, s54, v152
	ds_read_b128 v[156:159], v150
	ds_read_b128 v[160:163], v150 offset:1024
	ds_read_b128 v[164:167], v150 offset:2048
	ds_read_b128 v[168:171], v150 offset:3072
	v_add_u32_e32 v150, s55, v152
	s_add_u32 s82, s70, s78
	ds_read_b128 v[172:175], v150
	ds_read_b128 v[176:179], v150 offset:1024
	ds_read_b128 v[180:183], v150 offset:2048
	ds_read_b128 v[184:187], v150 offset:3072
	s_addc_u32 s83, s71, s79
	s_add_u32 s82, s82, 0x100
	s_addc_u32 s83, s83, 0
	s_add_u32 s93, s58, s78
	s_addc_u32 s94, s59, s79
	s_cmpk_eq_i32 s78, 0x700
	s_cselect_b32 s85, s75, s83
	s_cselect_b32 s84, s90, s82
	s_cselect_b32 s83, s73, s94
	s_cselect_b32 s82, s91, s93
	v_lshl_add_u64 v[150:151], v[146:147], 0, s[78:79]
	s_add_i32 m0, s67, 0xc000
	ds_read_b128 v[188:191], v155
	ds_read_b128 v[192:195], v155 offset:1024
	ds_read_b128 v[196:199], v155 offset:2048
	ds_read_b128 v[200:203], v155 offset:3072
	ds_read_b128 v[204:207], v155 offset:4096
	ds_read_b128 v[208:211], v155 offset:5120
	ds_read_b128 v[212:215], v155 offset:6144
	ds_read_b128 v[216:219], v155 offset:7168
	global_load_lds_dwordx4 v[150:151], off
	v_lshl_add_u64 v[150:151], v[148:149], 0, s[78:79]
	s_add_i32 m0, s67, 0xe000
	s_nop 0
	global_load_lds_dwordx4 v[150:151], off
	s_waitcnt vmcnt(8)
	s_waitcnt lgkmcnt(0)
	s_barrier
	s_waitcnt lgkmcnt(0)
	v_mfma_f32_16x16x32_bf16 v[110:113], v[156:159], v[188:191], 0
	v_mfma_f32_16x16x32_bf16 v[106:109], v[164:167], v[188:191], 0
	v_mfma_f32_16x16x32_bf16 v[78:81], v[172:175], v[188:191], 0
	v_mfma_f32_16x16x32_bf16 v[74:77], v[180:183], v[188:191], 0
	v_mfma_f32_16x16x32_bf16 v[66:69], v[180:183], v[196:199], 0
	v_mfma_f32_16x16x32_bf16 v[70:73], v[172:175], v[196:199], 0
	v_mfma_f32_16x16x32_bf16 v[98:101], v[164:167], v[196:199], 0
	v_mfma_f32_16x16x32_bf16 v[102:105], v[156:159], v[196:199], 0
	v_mfma_f32_16x16x32_bf16 v[94:97], v[156:159], v[204:207], 0
	v_mfma_f32_16x16x32_bf16 v[90:93], v[164:167], v[204:207], 0
	v_mfma_f32_16x16x32_bf16 v[62:65], v[172:175], v[204:207], 0
	v_mfma_f32_16x16x32_bf16 v[58:61], v[180:183], v[204:207], 0
	v_mfma_f32_16x16x32_bf16 v[50:53], v[180:183], v[212:215], 0
	v_mfma_f32_16x16x32_bf16 v[54:57], v[172:175], v[212:215], 0
	v_mfma_f32_16x16x32_bf16 v[82:85], v[164:167], v[212:215], 0
	v_mfma_f32_16x16x32_bf16 v[86:89], v[156:159], v[212:215], 0
	v_mfma_f32_16x16x32_bf16 v[110:113], v[160:163], v[192:195], v[110:113]
	v_mfma_f32_16x16x32_bf16 v[106:109], v[168:171], v[192:195], v[106:109]
	v_mfma_f32_16x16x32_bf16 v[78:81], v[176:179], v[192:195], v[78:81]
	v_mfma_f32_16x16x32_bf16 v[74:77], v[184:187], v[192:195], v[74:77]
	v_mfma_f32_16x16x32_bf16 v[66:69], v[184:187], v[200:203], v[66:69]
	v_mfma_f32_16x16x32_bf16 v[70:73], v[176:179], v[200:203], v[70:73]
	v_mfma_f32_16x16x32_bf16 v[98:101], v[168:171], v[200:203], v[98:101]
	v_mfma_f32_16x16x32_bf16 v[102:105], v[160:163], v[200:203], v[102:105]
	v_mfma_f32_16x16x32_bf16 v[94:97], v[160:163], v[208:211], v[94:97]
	v_mfma_f32_16x16x32_bf16 v[90:93], v[168:171], v[208:211], v[90:93]
	v_mfma_f32_16x16x32_bf16 v[62:65], v[176:179], v[208:211], v[62:65]
	v_mfma_f32_16x16x32_bf16 v[58:61], v[184:187], v[208:211], v[58:61]
	v_mfma_f32_16x16x32_bf16 v[50:53], v[184:187], v[216:219], v[50:53]
	v_mfma_f32_16x16x32_bf16 v[54:57], v[176:179], v[216:219], v[54:57]
	v_mfma_f32_16x16x32_bf16 v[82:85], v[168:171], v[216:219], v[82:85]
	v_mfma_f32_16x16x32_bf16 v[86:89], v[160:163], v[216:219], v[86:89]
	s_barrier
	s_add_i32 s93, s54, s87
	v_lshl_add_u64 v[150:151], s[82:83], 0, v[132:133]
	s_mov_b32 m0, s93
	ds_read_b128 v[188:191], v155 offset:16384
	ds_read_b128 v[192:195], v155 offset:17408
	ds_read_b128 v[196:199], v155 offset:18432
	ds_read_b128 v[200:203], v155 offset:19456
	ds_read_b128 v[204:207], v155 offset:20480
	ds_read_b128 v[208:211], v155 offset:21504
	ds_read_b128 v[212:215], v155 offset:22528
	ds_read_b128 v[216:219], v155 offset:23552
	global_load_lds_dwordx4 v[150:151], off
	s_add_i32 m0, s93, 0x2000
	s_add_u32 s94, s82, 0x40000
	v_lshl_add_u64 v[220:221], s[82:83], 0, v[136:137]
	s_addc_u32 s95, s83, 0
	s_add_i32 s93, s55, s87
	global_load_lds_dwordx4 v[220:221], off
	v_lshl_add_u64 v[222:223], s[94:95], 0, v[132:133]
	s_mov_b32 m0, s93
	v_lshl_add_u64 v[224:225], s[84:85], 0, v[134:135]
	global_load_lds_dwordx4 v[222:223], off
	v_lshl_add_u64 v[222:223], s[94:95], 0, v[136:137]
	s_add_i32 m0, s93, 0x2000
	s_nop 0
	global_load_lds_dwordx4 v[222:223], off
	v_lshl_add_u64 v[222:223], s[84:85], 0, v[130:131]
	s_mov_b32 m0, s67
	s_nop 0
	global_load_lds_dwordx4 v[222:223], off
	s_mov_b32 m0, s69
	s_nop 0
	global_load_lds_dwordx4 v[224:225], off
	s_waitcnt vmcnt(8)
	s_waitcnt lgkmcnt(0)
	s_barrier
; #define PG8_STAGEA(bufoff, gbase) PG8_STAGE_(bufoff, gbase, voffA)
; #define PG8_LDA(dst, b, h) do { _Pragma("unroll") for (int m = 0; m < 4; ++m) _Pragma("unroll") for (int k = 0; k < 2; ++k) dst[m][k] = *(const LAS bf16x8*)(lds + PG8_SA(b, h) + aoff + m * 2048 + k * 1024); } while (0)
; #define PG8_LDB(dst, b, h) do { _Pragma("unroll") for (int n = 0; n < 2; ++n) _Pragma("unroll") for (int k = 0; k < 2; ++k) dst[n][k] = *(const LAS bf16x8*)(lds + PG8_SB(b, h) + boff + n * 2048 + k * 1024); } while (0)
; #define PG8_MMA(ai, bj, At, Bt_) do { __builtin_amdgcn_s_setprio(1); _Pragma("unroll") for (int m = 0; m < 4; ++m) _Pragma("unroll") for (int n = 0; n < 2; ++n) _Pragma("unroll") for (int k = 0; k < 2; ++k) \
;         acc[ai][bj][m][n] = __builtin_amdgcn_mfma_f32_16x16x32_bf16(Bt_[n][k], At[m][k], acc[ai][bj][m][n], 0, 0, 0); __builtin_amdgcn_s_setprio(0); } while (0)
; #define PG8_WAIT_V(n) asm volatile("s_waitcnt vmcnt(" #n ")" ::: "memory")
; #define PG8_WAIT_L(n) asm volatile("s_waitcnt lgkmcnt(" #n ")" ::: "memory")
; #define PG8_BAR __builtin_amdgcn_s_barrier()
; #define PG8_SCHED __builtin_amdgcn_sched_barrier(0)
; template <int EK, int SK = -1>
; __device__ __forceinline__ void gemm_phase(LAS unsigned char* lds, const bf16_t* A, const bf16_t* Bt, int nM, int N, int K, const EpiArgs& E) {
;     ...
;             PG8_WAIT_V(8); PG8_WAIT_L(0); PG8_BAR; PG8_MMA(1, 0, At, B0); PG8_MMA(1, 1, At, B1); PG8_BAR; PG8_SCHED;
;             PG8_LDB(B0, 1, 0); PG8_LDB(B1, 1, 1); PG8_SCHED; PG8_LDA(At, 1, 0); PG8_STAGEA(PG8_SA(0, 1), a2 + hstep);
;             PG8_WAIT_V(8); PG8_WAIT_L(0); PG8_BAR; PG8_MMA(0, 0, At, B0); PG8_MMA(0, 1, At, B1); PG8_BAR; PG8_SCHED;
	s_waitcnt lgkmcnt(0)
	v_mfma_f32_16x16x32_bf16 v[46:49], v[156:159], v[188:191], 0
	v_mfma_f32_16x16x32_bf16 v[42:45], v[164:167], v[188:191], 0
	v_mfma_f32_16x16x32_bf16 v[14:17], v[172:175], v[188:191], 0
	v_mfma_f32_16x16x32_bf16 v[10:13], v[180:183], v[188:191], 0
	v_mfma_f32_16x16x32_bf16 v[2:5], v[180:183], v[196:199], 0
	v_mfma_f32_16x16x32_bf16 v[6:9], v[172:175], v[196:199], 0
	v_mfma_f32_16x16x32_bf16 v[34:37], v[164:167], v[196:199], 0
	v_mfma_f32_16x16x32_bf16 v[38:41], v[156:159], v[196:199], 0
	v_mfma_f32_16x16x32_bf16 v[30:33], v[156:159], v[204:207], 0
	v_mfma_f32_16x16x32_bf16 v[26:29], v[164:167], v[204:207], 0
	v_mfma_f32_16x16x32_bf16 v[114:117], v[172:175], v[204:207], 0
	v_mfma_f32_16x16x32_bf16 v[118:121], v[180:183], v[204:207], 0
	v_mfma_f32_16x16x32_bf16 v[126:129], v[180:183], v[212:215], 0
	v_mfma_f32_16x16x32_bf16 v[122:125], v[172:175], v[212:215], 0
	v_mfma_f32_16x16x32_bf16 v[18:21], v[164:167], v[212:215], 0
	v_mfma_f32_16x16x32_bf16 v[22:25], v[156:159], v[212:215], 0
	v_mfma_f32_16x16x32_bf16 v[46:49], v[160:163], v[192:195], v[46:49]
	v_mfma_f32_16x16x32_bf16 v[42:45], v[168:171], v[192:195], v[42:45]
	v_mfma_f32_16x16x32_bf16 v[14:17], v[176:179], v[192:195], v[14:17]
	v_mfma_f32_16x16x32_bf16 v[10:13], v[184:187], v[192:195], v[10:13]
	v_mfma_f32_16x16x32_bf16 v[2:5], v[184:187], v[200:203], v[2:5]
	v_mfma_f32_16x16x32_bf16 v[6:9], v[176:179], v[200:203], v[6:9]
	v_mfma_f32_16x16x32_bf16 v[34:37], v[168:171], v[200:203], v[34:37]
	v_mfma_f32_16x16x32_bf16 v[38:41], v[160:163], v[200:203], v[38:41]
	v_mfma_f32_16x16x32_bf16 v[30:33], v[160:163], v[208:211], v[30:33]
	v_mfma_f32_16x16x32_bf16 v[26:29], v[168:171], v[208:211], v[26:29]
	v_mfma_f32_16x16x32_bf16 v[114:117], v[176:179], v[208:211], v[114:117]
	v_mfma_f32_16x16x32_bf16 v[118:121], v[184:187], v[208:211], v[118:121]
	v_mfma_f32_16x16x32_bf16 v[126:129], v[184:187], v[216:219], v[126:129]
	v_mfma_f32_16x16x32_bf16 v[122:125], v[176:179], v[216:219], v[122:125]
	v_mfma_f32_16x16x32_bf16 v[18:21], v[168:171], v[216:219], v[18:21]
	v_mfma_f32_16x16x32_bf16 v[22:25], v[160:163], v[216:219], v[22:25]
	s_barrier
	s_add_i32 s93, 0, 0x18000
	s_add_i32 s94, 0, 0x1c000
	v_add_u32_e32 v168, s93, v152
	v_add_u32_e32 v184, s94, v152
	ds_read_b128 v[156:159], v168
	ds_read_b128 v[160:163], v168 offset:1024
	ds_read_b128 v[164:167], v168 offset:2048
	ds_read_b128 v[168:171], v168 offset:3072
	ds_read_b128 v[172:175], v184
	ds_read_b128 v[176:179], v184 offset:1024
	ds_read_b128 v[180:183], v184 offset:2048
	ds_read_b128 v[184:187], v184 offset:3072
	s_add_u32 s84, s84, 0x40000
	s_addc_u32 s85, s85, 0
	s_mov_b32 m0, s88
	v_lshl_add_u64 v[226:227], s[84:85], 0, v[130:131]
	ds_read_b128 v[188:191], v155 offset:32768
	ds_read_b128 v[192:195], v155 offset:33792
	ds_read_b128 v[196:199], v155 offset:34816
	ds_read_b128 v[200:203], v155 offset:35840
	ds_read_b128 v[204:207], v155 offset:36864
	ds_read_b128 v[208:211], v155 offset:37888
	ds_read_b128 v[212:215], v155 offset:38912
	ds_read_b128 v[216:219], v155 offset:39936
	global_load_lds_dwordx4 v[226:227], off
	v_lshl_add_u64 v[226:227], s[84:85], 0, v[134:135]
	s_mov_b32 m0, s89
	s_nop 0
	global_load_lds_dwordx4 v[226:227], off
	s_waitcnt vmcnt(8)
	s_waitcnt lgkmcnt(0)
	s_barrier
	s_waitcnt lgkmcnt(0)
	v_mfma_f32_16x16x32_bf16 v[110:113], v[156:159], v[188:191], v[110:113]
	v_mfma_f32_16x16x32_bf16 v[106:109], v[164:167], v[188:191], v[106:109]
	v_mfma_f32_16x16x32_bf16 v[78:81], v[172:175], v[188:191], v[78:81]
	v_mfma_f32_16x16x32_bf16 v[74:77], v[180:183], v[188:191], v[74:77]
	v_mfma_f32_16x16x32_bf16 v[66:69], v[180:183], v[196:199], v[66:69]
	v_mfma_f32_16x16x32_bf16 v[70:73], v[172:175], v[196:199], v[70:73]
	v_mfma_f32_16x16x32_bf16 v[98:101], v[164:167], v[196:199], v[98:101]
	v_mfma_f32_16x16x32_bf16 v[102:105], v[156:159], v[196:199], v[102:105]
	v_mfma_f32_16x16x32_bf16 v[94:97], v[156:159], v[204:207], v[94:97]
	v_mfma_f32_16x16x32_bf16 v[90:93], v[164:167], v[204:207], v[90:93]
	v_mfma_f32_16x16x32_bf16 v[62:65], v[172:175], v[204:207], v[62:65]
	v_mfma_f32_16x16x32_bf16 v[58:61], v[180:183], v[204:207], v[58:61]
	v_mfma_f32_16x16x32_bf16 v[50:53], v[180:183], v[212:215], v[50:53]
	v_mfma_f32_16x16x32_bf16 v[54:57], v[172:175], v[212:215], v[54:57]
	v_mfma_f32_16x16x32_bf16 v[82:85], v[164:167], v[212:215], v[82:85]
	v_mfma_f32_16x16x32_bf16 v[86:89], v[156:159], v[212:215], v[86:89]
	v_mfma_f32_16x16x32_bf16 v[110:113], v[160:163], v[192:195], v[110:113]
	v_mfma_f32_16x16x32_bf16 v[106:109], v[168:171], v[192:195], v[106:109]
	v_mfma_f32_16x16x32_bf16 v[78:81], v[176:179], v[192:195], v[78:81]
	v_mfma_f32_16x16x32_bf16 v[74:77], v[184:187], v[192:195], v[74:77]
	v_mfma_f32_16x16x32_bf16 v[66:69], v[184:187], v[200:203], v[66:69]
	v_mfma_f32_16x16x32_bf16 v[70:73], v[176:179], v[200:203], v[70:73]
	v_mfma_f32_16x16x32_bf16 v[98:101], v[168:171], v[200:203], v[98:101]
	v_mfma_f32_16x16x32_bf16 v[102:105], v[160:163], v[200:203], v[102:105]
	v_mfma_f32_16x16x32_bf16 v[94:97], v[160:163], v[208:211], v[94:97]
	v_mfma_f32_16x16x32_bf16 v[90:93], v[168:171], v[208:211], v[90:93]
	v_mfma_f32_16x16x32_bf16 v[62:65], v[176:179], v[208:211], v[62:65]
	v_mfma_f32_16x16x32_bf16 v[58:61], v[184:187], v[208:211], v[58:61]
	v_mfma_f32_16x16x32_bf16 v[50:53], v[184:187], v[216:219], v[50:53]
	v_mfma_f32_16x16x32_bf16 v[54:57], v[176:179], v[216:219], v[54:57]
	v_mfma_f32_16x16x32_bf16 v[82:85], v[168:171], v[216:219], v[82:85]
	v_mfma_f32_16x16x32_bf16 v[86:89], v[160:163], v[216:219], v[86:89]
	s_barrier
; #define PG8_STAGEA(bufoff, gbase) PG8_STAGE_(bufoff, gbase, voffA)
; #define PG8_STAGEB(bufoff, gbase) PG8_STAGE_(bufoff, gbase, voffB)
; #define PG8_LDA(dst, b, h) do { _Pragma("unroll") for (int m = 0; m < 4; ++m) _Pragma("unroll") for (int k = 0; k < 2; ++k) dst[m][k] = *(const LAS bf16x8*)(lds + PG8_SA(b, h) + aoff + m * 2048 + k * 1024); } while (0)
; #define PG8_LDB(dst, b, h) do { _Pragma("unroll") for (int n = 0; n < 2; ++n) _Pragma("unroll") for (int k = 0; k < 2; ++k) dst[n][k] = *(const LAS bf16x8*)(lds + PG8_SB(b, h) + boff + n * 2048 + k * 1024); } while (0)
; #define PG8_MMA(ai, bj, At, Bt_) do { __builtin_amdgcn_s_setprio(1); _Pragma("unroll") for (int m = 0; m < 4; ++m) _Pragma("unroll") for (int n = 0; n < 2; ++n) _Pragma("unroll") for (int k = 0; k < 2; ++k) \
;         acc[ai][bj][m][n] = __builtin_amdgcn_mfma_f32_16x16x32_bf16(Bt_[n][k], At[m][k], acc[ai][bj][m][n], 0, 0, 0); __builtin_amdgcn_s_setprio(0); } while (0)
; #define PG8_WAIT_V(n) asm volatile("s_waitcnt vmcnt(" #n ")" ::: "memory")
; #define PG8_WAIT_L(n) asm volatile("s_waitcnt lgkmcnt(" #n ")" ::: "memory")
; #define PG8_BAR __builtin_amdgcn_s_barrier()
; #define PG8_SCHED __builtin_amdgcn_sched_barrier(0)
; template <int EK, int SK = -1>
; __device__ __forceinline__ void gemm_phase(LAS unsigned char* lds, const bf16_t* A, const bf16_t* Bt, int nM, int N, int K, const EpiArgs& E) {
;     ...
;             PG8_LDB(B0, 0, 0); PG8_LDB(B1, 0, 1); PG8_SCHED; PG8_LDA(At, 0, 0); PG8_STAGEA(PG8_SA(1, 1), a1 + hstep);
;             PG8_WAIT_V(8); PG8_WAIT_L(0); PG8_BAR; PG8_MMA(0, 0, At, B0); PG8_MMA(0, 1, At, B1); PG8_BAR; PG8_SCHED;
;     ...
;             PG8_LDA(At, 1, 1); PG8_STAGEB(PG8_SB(1, 0), b3); PG8_STAGEB(PG8_SB(1, 1), b3 + hstep); PG8_STAGEA(PG8_SA(1, 0), a3);
;             PG8_WAIT_V(8); PG8_WAIT_L(0); PG8_BAR; PG8_MMA(1, 0, At, B0); PG8_MMA(1, 1, At, B1); PG8_BAR; PG8_SCHED;
;         }
	s_add_i32 s84, s93, s87
	v_lshl_add_u64 v[150:151], v[150:151], 0, s[10:11]
	s_mov_b32 m0, s84
	ds_read_b128 v[188:191], v155 offset:49152
	ds_read_b128 v[192:195], v155 offset:50176
	ds_read_b128 v[196:199], v155 offset:51200
	ds_read_b128 v[200:203], v155 offset:52224
	ds_read_b128 v[204:207], v155 offset:53248
	ds_read_b128 v[208:211], v155 offset:54272
	ds_read_b128 v[212:215], v155 offset:55296
	ds_read_b128 v[216:219], v155 offset:56320
	global_load_lds_dwordx4 v[150:151], off
	s_add_i32 m0, s84, 0x2000
	s_add_u32 s82, s82, 0x40080
	v_lshl_add_u64 v[150:151], v[220:221], 0, s[10:11]
	s_addc_u32 s83, s83, 0
	s_add_i32 s84, s94, s87
	global_load_lds_dwordx4 v[150:151], off
	v_lshl_add_u64 v[150:151], s[82:83], 0, v[132:133]
	s_mov_b32 m0, s84
	s_nop 0
	global_load_lds_dwordx4 v[150:151], off
	v_lshl_add_u64 v[150:151], s[82:83], 0, v[136:137]
	s_add_i32 m0, s84, 0x2000
	s_nop 0
	global_load_lds_dwordx4 v[150:151], off
	v_lshl_add_u64 v[150:151], v[222:223], 0, s[10:11]
	s_mov_b32 m0, s52
	s_nop 0
	global_load_lds_dwordx4 v[150:151], off
	v_lshl_add_u64 v[150:151], v[224:225], 0, s[10:11]
	s_mov_b32 m0, s53
	s_nop 0
	global_load_lds_dwordx4 v[150:151], off
	s_waitcnt vmcnt(8)
	s_waitcnt lgkmcnt(0)
	s_barrier
	s_waitcnt lgkmcnt(0)
	v_mfma_f32_16x16x32_bf16 v[46:49], v[156:159], v[188:191], v[46:49]
	v_mfma_f32_16x16x32_bf16 v[42:45], v[164:167], v[188:191], v[42:45]
	v_mfma_f32_16x16x32_bf16 v[14:17], v[172:175], v[188:191], v[14:17]
	v_mfma_f32_16x16x32_bf16 v[10:13], v[180:183], v[188:191], v[10:13]
	v_mfma_f32_16x16x32_bf16 v[2:5], v[180:183], v[196:199], v[2:5]
	v_mfma_f32_16x16x32_bf16 v[6:9], v[172:175], v[196:199], v[6:9]
	v_mfma_f32_16x16x32_bf16 v[34:37], v[164:167], v[196:199], v[34:37]
	v_mfma_f32_16x16x32_bf16 v[38:41], v[156:159], v[196:199], v[38:41]
	v_mfma_f32_16x16x32_bf16 v[30:33], v[156:159], v[204:207], v[30:33]
	v_mfma_f32_16x16x32_bf16 v[26:29], v[164:167], v[204:207], v[26:29]
	v_mfma_f32_16x16x32_bf16 v[114:117], v[172:175], v[204:207], v[114:117]
	v_mfma_f32_16x16x32_bf16 v[118:121], v[180:183], v[204:207], v[118:121]
	v_mfma_f32_16x16x32_bf16 v[126:129], v[180:183], v[212:215], v[126:129]
	v_mfma_f32_16x16x32_bf16 v[122:125], v[172:175], v[212:215], v[122:125]
	v_mfma_f32_16x16x32_bf16 v[18:21], v[164:167], v[212:215], v[18:21]
	v_mfma_f32_16x16x32_bf16 v[22:25], v[156:159], v[212:215], v[22:25]
	v_mfma_f32_16x16x32_bf16 v[46:49], v[160:163], v[192:195], v[46:49]
	v_mfma_f32_16x16x32_bf16 v[42:45], v[168:171], v[192:195], v[42:45]
	v_mfma_f32_16x16x32_bf16 v[14:17], v[176:179], v[192:195], v[14:17]
	v_mfma_f32_16x16x32_bf16 v[10:13], v[184:187], v[192:195], v[10:13]
	v_mfma_f32_16x16x32_bf16 v[2:5], v[184:187], v[200:203], v[2:5]
	v_mfma_f32_16x16x32_bf16 v[6:9], v[176:179], v[200:203], v[6:9]
	v_mfma_f32_16x16x32_bf16 v[34:37], v[168:171], v[200:203], v[34:37]
	v_mfma_f32_16x16x32_bf16 v[38:41], v[160:163], v[200:203], v[38:41]
	v_mfma_f32_16x16x32_bf16 v[30:33], v[160:163], v[208:211], v[30:33]
	v_mfma_f32_16x16x32_bf16 v[26:29], v[168:171], v[208:211], v[26:29]
	v_mfma_f32_16x16x32_bf16 v[114:117], v[176:179], v[208:211], v[114:117]
	v_mfma_f32_16x16x32_bf16 v[118:121], v[184:187], v[208:211], v[118:121]
	v_mfma_f32_16x16x32_bf16 v[126:129], v[184:187], v[216:219], v[126:129]
	v_mfma_f32_16x16x32_bf16 v[122:125], v[176:179], v[216:219], v[122:125]
	v_mfma_f32_16x16x32_bf16 v[18:21], v[168:171], v[216:219], v[18:21]
	v_mfma_f32_16x16x32_bf16 v[22:25], v[160:163], v[216:219], v[22:25]
	s_barrier
	s_add_i32 s92, s92, 2
	s_add_u32 s78, s78, 0x100
	s_addc_u32 s79, s79, 0
	s_cmp_gt_u32 s92, 13
	s_cbranch_scc0 .LBB0_198
	s_branch .Lmy_kexit_0
.LBB0_198:
	v_add_u32_e32 v150, s54, v152
	ds_read_b128 v[156:159], v150
	ds_read_b128 v[160:163], v150 offset:1024
	ds_read_b128 v[164:167], v150 offset:2048
	ds_read_b128 v[168:171], v150 offset:3072
	v_add_u32_e32 v150, s55, v152
	s_add_u32 s82, s70, s78
	ds_read_b128 v[172:175], v150
	ds_read_b128 v[176:179], v150 offset:1024
	ds_read_b128 v[180:183], v150 offset:2048
	ds_read_b128 v[184:187], v150 offset:3072
	s_addc_u32 s83, s71, s79
	s_add_u32 s82, s82, 0x100
	s_addc_u32 s83, s83, 0
	s_add_u32 s93, s58, s78
	s_addc_u32 s94, s59, s79
	s_cmpk_eq_i32 s78, 0x700
	s_cselect_b32 s85, s75, s83
	s_cselect_b32 s84, s90, s82
	s_cselect_b32 s83, s73, s94
	s_cselect_b32 s82, s91, s93
	v_lshl_add_u64 v[150:151], v[146:147], 0, s[78:79]
	s_add_i32 m0, s67, 0xc000
	ds_read_b128 v[188:191], v155
	ds_read_b128 v[192:195], v155 offset:1024
	ds_read_b128 v[196:199], v155 offset:2048
	ds_read_b128 v[200:203], v155 offset:3072
	ds_read_b128 v[204:207], v155 offset:4096
	ds_read_b128 v[208:211], v155 offset:5120
	ds_read_b128 v[212:215], v155 offset:6144
	ds_read_b128 v[216:219], v155 offset:7168
	global_load_lds_dwordx4 v[150:151], off
	v_lshl_add_u64 v[150:151], v[148:149], 0, s[78:79]
	s_add_i32 m0, s67, 0xe000
	s_nop 0
	global_load_lds_dwordx4 v[150:151], off
	s_waitcnt vmcnt(8)
	s_waitcnt lgkmcnt(0)
	s_barrier
; #define PG8_STAGEA(bufoff, gbase) PG8_STAGE_(bufoff, gbase, voffA)
; #define PG8_STAGEB(bufoff, gbase) PG8_STAGE_(bufoff, gbase, voffB)
; #define PG8_LDA(dst, b, h) do { _Pragma("unroll") for (int m = 0; m < 4; ++m) _Pragma("unroll") for (int k = 0; k < 2; ++k) dst[m][k] = *(const LAS bf16x8*)(lds + PG8_SA(b, h) + aoff + m * 2048 + k * 1024); } while (0)
; #define PG8_MMA(ai, bj, At, Bt_) do { __builtin_amdgcn_s_setprio(1); _Pragma("unroll") for (int m = 0; m < 4; ++m) _Pragma("unroll") for (int n = 0; n < 2; ++n) _Pragma("unroll") for (int k = 0; k < 2; ++k) \
;         acc[ai][bj][m][n] = __builtin_amdgcn_mfma_f32_16x16x32_bf16(Bt_[n][k], At[m][k], acc[ai][bj][m][n], 0, 0, 0); __builtin_amdgcn_s_setprio(0); } while (0)
; #define PG8_WAIT_V(n) asm volatile("s_waitcnt vmcnt(" #n ")" ::: "memory")
; #define PG8_WAIT_L(n) asm volatile("s_waitcnt lgkmcnt(" #n ")" ::: "memory")
; #define PG8_BAR __builtin_amdgcn_s_barrier()
; #define PG8_SCHED __builtin_amdgcn_sched_barrier(0)
; template <int EK, int SK = -1>
; __device__ __forceinline__ void gemm_phase(LAS unsigned char* lds, const bf16_t* A, const bf16_t* Bt, int nM, int N, int K, const EpiArgs& E) {
;     ...
;             PG8_WAIT_V(8); PG8_WAIT_L(0); PG8_BAR; PG8_MMA(0, 0, At, B0); PG8_MMA(0, 1, At, B1); PG8_BAR; PG8_SCHED;
;             PG8_LDA(At, 0, 1); PG8_STAGEB(PG8_SB(0, 0), b2); PG8_STAGEB(PG8_SB(0, 1), b2 + hstep); PG8_STAGEA(PG8_SA(0, 0), a2);
;             PG8_WAIT_V(8); PG8_WAIT_L(0); PG8_BAR; PG8_MMA(1, 0, At, B0); PG8_MMA(1, 1, At, B1); PG8_BAR; PG8_SCHED;
	s_waitcnt lgkmcnt(0)
	v_mfma_f32_16x16x32_bf16 v[110:113], v[156:159], v[188:191], v[110:113]
	v_mfma_f32_16x16x32_bf16 v[106:109], v[164:167], v[188:191], v[106:109]
	v_mfma_f32_16x16x32_bf16 v[78:81], v[172:175], v[188:191], v[78:81]
	v_mfma_f32_16x16x32_bf16 v[74:77], v[180:183], v[188:191], v[74:77]
	v_mfma_f32_16x16x32_bf16 v[66:69], v[180:183], v[196:199], v[66:69]
	v_mfma_f32_16x16x32_bf16 v[70:73], v[172:175], v[196:199], v[70:73]
	v_mfma_f32_16x16x32_bf16 v[98:101], v[164:167], v[196:199], v[98:101]
	v_mfma_f32_16x16x32_bf16 v[102:105], v[156:159], v[196:199], v[102:105]
	v_mfma_f32_16x16x32_bf16 v[94:97], v[156:159], v[204:207], v[94:97]
	v_mfma_f32_16x16x32_bf16 v[90:93], v[164:167], v[204:207], v[90:93]
	v_mfma_f32_16x16x32_bf16 v[62:65], v[172:175], v[204:207], v[62:65]
	v_mfma_f32_16x16x32_bf16 v[58:61], v[180:183], v[204:207], v[58:61]
	v_mfma_f32_16x16x32_bf16 v[50:53], v[180:183], v[212:215], v[50:53]
	v_mfma_f32_16x16x32_bf16 v[54:57], v[172:175], v[212:215], v[54:57]
	v_mfma_f32_16x16x32_bf16 v[82:85], v[164:167], v[212:215], v[82:85]
	v_mfma_f32_16x16x32_bf16 v[86:89], v[156:159], v[212:215], v[86:89]
	v_mfma_f32_16x16x32_bf16 v[110:113], v[160:163], v[192:195], v[110:113]
	v_mfma_f32_16x16x32_bf16 v[106:109], v[168:171], v[192:195], v[106:109]
	v_mfma_f32_16x16x32_bf16 v[78:81], v[176:179], v[192:195], v[78:81]
	v_mfma_f32_16x16x32_bf16 v[74:77], v[184:187], v[192:195], v[74:77]
	v_mfma_f32_16x16x32_bf16 v[66:69], v[184:187], v[200:203], v[66:69]
	v_mfma_f32_16x16x32_bf16 v[70:73], v[176:179], v[200:203], v[70:73]
	v_mfma_f32_16x16x32_bf16 v[98:101], v[168:171], v[200:203], v[98:101]
	v_mfma_f32_16x16x32_bf16 v[102:105], v[160:163], v[200:203], v[102:105]
	v_mfma_f32_16x16x32_bf16 v[94:97], v[160:163], v[208:211], v[94:97]
	v_mfma_f32_16x16x32_bf16 v[90:93], v[168:171], v[208:211], v[90:93]
	v_mfma_f32_16x16x32_bf16 v[62:65], v[176:179], v[208:211], v[62:65]
	v_mfma_f32_16x16x32_bf16 v[58:61], v[184:187], v[208:211], v[58:61]
	v_mfma_f32_16x16x32_bf16 v[50:53], v[184:187], v[216:219], v[50:53]
	v_mfma_f32_16x16x32_bf16 v[54:57], v[176:179], v[216:219], v[54:57]
	v_mfma_f32_16x16x32_bf16 v[82:85], v[168:171], v[216:219], v[82:85]
	v_mfma_f32_16x16x32_bf16 v[86:89], v[160:163], v[216:219], v[86:89]
	s_barrier
	s_add_i32 s93, s54, s87
	v_lshl_add_u64 v[150:151], s[82:83], 0, v[132:133]
	s_mov_b32 m0, s93
	ds_read_b128 v[188:191], v155 offset:16384
	ds_read_b128 v[192:195], v155 offset:17408
	ds_read_b128 v[196:199], v155 offset:18432
	ds_read_b128 v[200:203], v155 offset:19456
	ds_read_b128 v[204:207], v155 offset:20480
	ds_read_b128 v[208:211], v155 offset:21504
	ds_read_b128 v[212:215], v155 offset:22528
	ds_read_b128 v[216:219], v155 offset:23552
	global_load_lds_dwordx4 v[150:151], off
	s_add_i32 m0, s93, 0x2000
	s_add_u32 s94, s82, 0x40000
	v_lshl_add_u64 v[220:221], s[82:83], 0, v[136:137]
	s_addc_u32 s95, s83, 0
	s_add_i32 s93, s55, s87
	global_load_lds_dwordx4 v[220:221], off
	v_lshl_add_u64 v[222:223], s[94:95], 0, v[132:133]
	s_mov_b32 m0, s93
	v_lshl_add_u64 v[224:225], s[84:85], 0, v[134:135]
	global_load_lds_dwordx4 v[222:223], off
	v_lshl_add_u64 v[222:223], s[94:95], 0, v[136:137]
	s_add_i32 m0, s93, 0x2000
	s_nop 0
	global_load_lds_dwordx4 v[222:223], off
	v_lshl_add_u64 v[222:223], s[84:85], 0, v[130:131]
	s_mov_b32 m0, s67
	s_nop 0
	global_load_lds_dwordx4 v[222:223], off
	s_mov_b32 m0, s69
	s_nop 0
	global_load_lds_dwordx4 v[224:225], off
	s_waitcnt vmcnt(8)
	s_waitcnt lgkmcnt(0)
	s_barrier
	s_waitcnt lgkmcnt(0)
	v_mfma_f32_16x16x32_bf16 v[46:49], v[156:159], v[188:191], v[46:49]
	v_mfma_f32_16x16x32_bf16 v[42:45], v[164:167], v[188:191], v[42:45]
	v_mfma_f32_16x16x32_bf16 v[14:17], v[172:175], v[188:191], v[14:17]
	v_mfma_f32_16x16x32_bf16 v[10:13], v[180:183], v[188:191], v[10:13]
	v_mfma_f32_16x16x32_bf16 v[2:5], v[180:183], v[196:199], v[2:5]
	v_mfma_f32_16x16x32_bf16 v[6:9], v[172:175], v[196:199], v[6:9]
	v_mfma_f32_16x16x32_bf16 v[34:37], v[164:167], v[196:199], v[34:37]
	v_mfma_f32_16x16x32_bf16 v[38:41], v[156:159], v[196:199], v[38:41]
	v_mfma_f32_16x16x32_bf16 v[30:33], v[156:159], v[204:207], v[30:33]
	v_mfma_f32_16x16x32_bf16 v[26:29], v[164:167], v[204:207], v[26:29]
	v_mfma_f32_16x16x32_bf16 v[114:117], v[172:175], v[204:207], v[114:117]
	v_mfma_f32_16x16x32_bf16 v[118:121], v[180:183], v[204:207], v[118:121]
	v_mfma_f32_16x16x32_bf16 v[126:129], v[180:183], v[212:215], v[126:129]
	v_mfma_f32_16x16x32_bf16 v[122:125], v[172:175], v[212:215], v[122:125]
	v_mfma_f32_16x16x32_bf16 v[18:21], v[164:167], v[212:215], v[18:21]
	v_mfma_f32_16x16x32_bf16 v[22:25], v[156:159], v[212:215], v[22:25]
	v_mfma_f32_16x16x32_bf16 v[46:49], v[160:163], v[192:195], v[46:49]
	v_mfma_f32_16x16x32_bf16 v[42:45], v[168:171], v[192:195], v[42:45]
	v_mfma_f32_16x16x32_bf16 v[14:17], v[176:179], v[192:195], v[14:17]
	v_mfma_f32_16x16x32_bf16 v[10:13], v[184:187], v[192:195], v[10:13]
	v_mfma_f32_16x16x32_bf16 v[2:5], v[184:187], v[200:203], v[2:5]
	v_mfma_f32_16x16x32_bf16 v[6:9], v[176:179], v[200:203], v[6:9]
	v_mfma_f32_16x16x32_bf16 v[34:37], v[168:171], v[200:203], v[34:37]
	v_mfma_f32_16x16x32_bf16 v[38:41], v[160:163], v[200:203], v[38:41]
	v_mfma_f32_16x16x32_bf16 v[30:33], v[160:163], v[208:211], v[30:33]
	v_mfma_f32_16x16x32_bf16 v[26:29], v[168:171], v[208:211], v[26:29]
	v_mfma_f32_16x16x32_bf16 v[114:117], v[176:179], v[208:211], v[114:117]
	v_mfma_f32_16x16x32_bf16 v[118:121], v[184:187], v[208:211], v[118:121]
	v_mfma_f32_16x16x32_bf16 v[126:129], v[184:187], v[216:219], v[126:129]
	v_mfma_f32_16x16x32_bf16 v[122:125], v[176:179], v[216:219], v[122:125]
	v_mfma_f32_16x16x32_bf16 v[18:21], v[168:171], v[216:219], v[18:21]
	v_mfma_f32_16x16x32_bf16 v[22:25], v[160:163], v[216:219], v[22:25]
	s_barrier
; #define PG8_STAGEA(bufoff, gbase) PG8_STAGE_(bufoff, gbase, voffA)
; #define PG8_STAGEB(bufoff, gbase) PG8_STAGE_(bufoff, gbase, voffB)
; #define PG8_LDA(dst, b, h) do { _Pragma("unroll") for (int m = 0; m < 4; ++m) _Pragma("unroll") for (int k = 0; k < 2; ++k) dst[m][k] = *(const LAS bf16x8*)(lds + PG8_SA(b, h) + aoff + m * 2048 + k * 1024); } while (0)
; #define PG8_LDB(dst, b, h) do { _Pragma("unroll") for (int n = 0; n < 2; ++n) _Pragma("unroll") for (int k = 0; k < 2; ++k) dst[n][k] = *(const LAS bf16x8*)(lds + PG8_SB(b, h) + boff + n * 2048 + k * 1024); } while (0)
; #define PG8_MMA(ai, bj, At, Bt_) do { __builtin_amdgcn_s_setprio(1); _Pragma("unroll") for (int m = 0; m < 4; ++m) _Pragma("unroll") for (int n = 0; n < 2; ++n) _Pragma("unroll") for (int k = 0; k < 2; ++k) \
;         acc[ai][bj][m][n] = __builtin_amdgcn_mfma_f32_16x16x32_bf16(Bt_[n][k], At[m][k], acc[ai][bj][m][n], 0, 0, 0); __builtin_amdgcn_s_setprio(0); } while (0)
; #define PG8_WAIT_V(n) asm volatile("s_waitcnt vmcnt(" #n ")" ::: "memory")
; #define PG8_WAIT_L(n) asm volatile("s_waitcnt lgkmcnt(" #n ")" ::: "memory")
; #define PG8_BAR __builtin_amdgcn_s_barrier()
; #define PG8_SCHED __builtin_amdgcn_sched_barrier(0)
; template <int EK, int SK = -1>
; __device__ __forceinline__ void gemm_phase(LAS unsigned char* lds, const bf16_t* A, const bf16_t* Bt, int nM, int N, int K, const EpiArgs& E) {
;     ...
;             PG8_LDB(B0, 1, 0); PG8_LDB(B1, 1, 1); PG8_SCHED; PG8_LDA(At, 1, 0); PG8_STAGEA(PG8_SA(0, 1), a2 + hstep);
;             PG8_WAIT_V(8); PG8_WAIT_L(0); PG8_BAR; PG8_MMA(0, 0, At, B0); PG8_MMA(0, 1, At, B1); PG8_BAR; PG8_SCHED;
;             PG8_LDA(At, 1, 1); PG8_STAGEB(PG8_SB(1, 0), b3); PG8_STAGEB(PG8_SB(1, 1), b3 + hstep); PG8_STAGEA(PG8_SA(1, 0), a3);
;             PG8_WAIT_V(8); PG8_WAIT_L(0); PG8_BAR; PG8_MMA(1, 0, At, B0); PG8_MMA(1, 1, At, B1); PG8_BAR; PG8_SCHED;
;         }
	s_add_i32 s93, 0, 0x18000
	s_add_i32 s94, 0, 0x1c000
	v_add_u32_e32 v168, s93, v152
	v_add_u32_e32 v184, s94, v152
	ds_read_b128 v[156:159], v168
	ds_read_b128 v[160:163], v168 offset:1024
	ds_read_b128 v[164:167], v168 offset:2048
	ds_read_b128 v[168:171], v168 offset:3072
	ds_read_b128 v[172:175], v184
	ds_read_b128 v[176:179], v184 offset:1024
	ds_read_b128 v[180:183], v184 offset:2048
	ds_read_b128 v[184:187], v184 offset:3072
	s_add_u32 s84, s84, 0x40000
	s_addc_u32 s85, s85, 0
	s_mov_b32 m0, s88
	v_lshl_add_u64 v[226:227], s[84:85], 0, v[130:131]
	ds_read_b128 v[188:191], v155 offset:32768
	ds_read_b128 v[192:195], v155 offset:33792
	ds_read_b128 v[196:199], v155 offset:34816
	ds_read_b128 v[200:203], v155 offset:35840
	ds_read_b128 v[204:207], v155 offset:36864
	ds_read_b128 v[208:211], v155 offset:37888
	ds_read_b128 v[212:215], v155 offset:38912
	ds_read_b128 v[216:219], v155 offset:39936
	global_load_lds_dwordx4 v[226:227], off
	v_lshl_add_u64 v[226:227], s[84:85], 0, v[134:135]
	s_mov_b32 m0, s89
	s_nop 0
	global_load_lds_dwordx4 v[226:227], off
	s_waitcnt vmcnt(8)
	s_waitcnt lgkmcnt(0)
	s_barrier
	s_waitcnt lgkmcnt(0)
	v_mfma_f32_16x16x32_bf16 v[110:113], v[156:159], v[188:191], v[110:113]
	v_mfma_f32_16x16x32_bf16 v[106:109], v[164:167], v[188:191], v[106:109]
	v_mfma_f32_16x16x32_bf16 v[78:81], v[172:175], v[188:191], v[78:81]
	v_mfma_f32_16x16x32_bf16 v[74:77], v[180:183], v[188:191], v[74:77]
	v_mfma_f32_16x16x32_bf16 v[66:69], v[180:183], v[196:199], v[66:69]
	v_mfma_f32_16x16x32_bf16 v[70:73], v[172:175], v[196:199], v[70:73]
	v_mfma_f32_16x16x32_bf16 v[98:101], v[164:167], v[196:199], v[98:101]
	v_mfma_f32_16x16x32_bf16 v[102:105], v[156:159], v[196:199], v[102:105]
	v_mfma_f32_16x16x32_bf16 v[94:97], v[156:159], v[204:207], v[94:97]
	v_mfma_f32_16x16x32_bf16 v[90:93], v[164:167], v[204:207], v[90:93]
	v_mfma_f32_16x16x32_bf16 v[62:65], v[172:175], v[204:207], v[62:65]
	v_mfma_f32_16x16x32_bf16 v[58:61], v[180:183], v[204:207], v[58:61]
	v_mfma_f32_16x16x32_bf16 v[50:53], v[180:183], v[212:215], v[50:53]
	v_mfma_f32_16x16x32_bf16 v[54:57], v[172:175], v[212:215], v[54:57]
	v_mfma_f32_16x16x32_bf16 v[82:85], v[164:167], v[212:215], v[82:85]
	v_mfma_f32_16x16x32_bf16 v[86:89], v[156:159], v[212:215], v[86:89]
	v_mfma_f32_16x16x32_bf16 v[110:113], v[160:163], v[192:195], v[110:113]
	v_mfma_f32_16x16x32_bf16 v[106:109], v[168:171], v[192:195], v[106:109]
	v_mfma_f32_16x16x32_bf16 v[78:81], v[176:179], v[192:195], v[78:81]
	v_mfma_f32_16x16x32_bf16 v[74:77], v[184:187], v[192:195], v[74:77]
	v_mfma_f32_16x16x32_bf16 v[66:69], v[184:187], v[200:203], v[66:69]
	v_mfma_f32_16x16x32_bf16 v[70:73], v[176:179], v[200:203], v[70:73]
	v_mfma_f32_16x16x32_bf16 v[98:101], v[168:171], v[200:203], v[98:101]
	v_mfma_f32_16x16x32_bf16 v[102:105], v[160:163], v[200:203], v[102:105]
	v_mfma_f32_16x16x32_bf16 v[94:97], v[160:163], v[208:211], v[94:97]
	v_mfma_f32_16x16x32_bf16 v[90:93], v[168:171], v[208:211], v[90:93]
	v_mfma_f32_16x16x32_bf16 v[62:65], v[176:179], v[208:211], v[62:65]
	v_mfma_f32_16x16x32_bf16 v[58:61], v[184:187], v[208:211], v[58:61]
	v_mfma_f32_16x16x32_bf16 v[50:53], v[184:187], v[216:219], v[50:53]
	v_mfma_f32_16x16x32_bf16 v[54:57], v[176:179], v[216:219], v[54:57]
	v_mfma_f32_16x16x32_bf16 v[82:85], v[168:171], v[216:219], v[82:85]
	v_mfma_f32_16x16x32_bf16 v[86:89], v[160:163], v[216:219], v[86:89]
	s_barrier
	s_add_i32 s84, s93, s87
	v_lshl_add_u64 v[150:151], v[150:151], 0, s[10:11]
	s_mov_b32 m0, s84
	ds_read_b128 v[188:191], v155 offset:49152
	ds_read_b128 v[192:195], v155 offset:50176
	ds_read_b128 v[196:199], v155 offset:51200
	ds_read_b128 v[200:203], v155 offset:52224
	ds_read_b128 v[204:207], v155 offset:53248
	ds_read_b128 v[208:211], v155 offset:54272
	ds_read_b128 v[212:215], v155 offset:55296
	ds_read_b128 v[216:219], v155 offset:56320
	global_load_lds_dwordx4 v[150:151], off
	s_add_i32 m0, s84, 0x2000
	s_add_u32 s82, s82, 0x40080
	v_lshl_add_u64 v[150:151], v[220:221], 0, s[10:11]
	s_addc_u32 s83, s83, 0
	s_add_i32 s84, s94, s87
	global_load_lds_dwordx4 v[150:151], off
	v_lshl_add_u64 v[150:151], s[82:83], 0, v[132:133]
	s_mov_b32 m0, s84
	s_nop 0
	global_load_lds_dwordx4 v[150:151], off
	v_lshl_add_u64 v[150:151], s[82:83], 0, v[136:137]
	s_add_i32 m0, s84, 0x2000
	s_nop 0
	global_load_lds_dwordx4 v[150:151], off
	v_lshl_add_u64 v[150:151], v[222:223], 0, s[10:11]
	s_mov_b32 m0, s52
	s_nop 0
	global_load_lds_dwordx4 v[150:151], off
	v_lshl_add_u64 v[150:151], v[224:225], 0, s[10:11]
	s_mov_b32 m0, s53
	s_nop 0
	global_load_lds_dwordx4 v[150:151], off
	s_waitcnt vmcnt(8)
	s_waitcnt lgkmcnt(0)
	s_barrier
	s_waitcnt lgkmcnt(0)
	v_mfma_f32_16x16x32_bf16 v[46:49], v[156:159], v[188:191], v[46:49]
	v_mfma_f32_16x16x32_bf16 v[42:45], v[164:167], v[188:191], v[42:45]
	v_mfma_f32_16x16x32_bf16 v[14:17], v[172:175], v[188:191], v[14:17]
	v_mfma_f32_16x16x32_bf16 v[10:13], v[180:183], v[188:191], v[10:13]
	v_mfma_f32_16x16x32_bf16 v[2:5], v[180:183], v[196:199], v[2:5]
	v_mfma_f32_16x16x32_bf16 v[6:9], v[172:175], v[196:199], v[6:9]
	v_mfma_f32_16x16x32_bf16 v[34:37], v[164:167], v[196:199], v[34:37]
	v_mfma_f32_16x16x32_bf16 v[38:41], v[156:159], v[196:199], v[38:41]
	v_mfma_f32_16x16x32_bf16 v[30:33], v[156:159], v[204:207], v[30:33]
	v_mfma_f32_16x16x32_bf16 v[26:29], v[164:167], v[204:207], v[26:29]
	v_mfma_f32_16x16x32_bf16 v[114:117], v[172:175], v[204:207], v[114:117]
	v_mfma_f32_16x16x32_bf16 v[118:121], v[180:183], v[204:207], v[118:121]
	v_mfma_f32_16x16x32_bf16 v[126:129], v[180:183], v[212:215], v[126:129]
	v_mfma_f32_16x16x32_bf16 v[122:125], v[172:175], v[212:215], v[122:125]
	v_mfma_f32_16x16x32_bf16 v[18:21], v[164:167], v[212:215], v[18:21]
	v_mfma_f32_16x16x32_bf16 v[22:25], v[156:159], v[212:215], v[22:25]
	v_mfma_f32_16x16x32_bf16 v[46:49], v[160:163], v[192:195], v[46:49]
	v_mfma_f32_16x16x32_bf16 v[42:45], v[168:171], v[192:195], v[42:45]
	v_mfma_f32_16x16x32_bf16 v[14:17], v[176:179], v[192:195], v[14:17]
	v_mfma_f32_16x16x32_bf16 v[10:13], v[184:187], v[192:195], v[10:13]
	v_mfma_f32_16x16x32_bf16 v[2:5], v[184:187], v[200:203], v[2:5]
	v_mfma_f32_16x16x32_bf16 v[6:9], v[176:179], v[200:203], v[6:9]
	v_mfma_f32_16x16x32_bf16 v[34:37], v[168:171], v[200:203], v[34:37]
	v_mfma_f32_16x16x32_bf16 v[38:41], v[160:163], v[200:203], v[38:41]
	v_mfma_f32_16x16x32_bf16 v[30:33], v[160:163], v[208:211], v[30:33]
	v_mfma_f32_16x16x32_bf16 v[26:29], v[168:171], v[208:211], v[26:29]
	v_mfma_f32_16x16x32_bf16 v[114:117], v[176:179], v[208:211], v[114:117]
	v_mfma_f32_16x16x32_bf16 v[118:121], v[184:187], v[208:211], v[118:121]
	v_mfma_f32_16x16x32_bf16 v[126:129], v[184:187], v[216:219], v[126:129]
	v_mfma_f32_16x16x32_bf16 v[122:125], v[176:179], v[216:219], v[122:125]
	v_mfma_f32_16x16x32_bf16 v[18:21], v[168:171], v[216:219], v[18:21]
	v_mfma_f32_16x16x32_bf16 v[22:25], v[160:163], v[216:219], v[22:25]
	s_barrier
	s_add_i32 s92, s92, 2
	s_add_u32 s78, s78, 0x100
	s_addc_u32 s79, s79, 0
	s_cmp_gt_u32 s92, 13
	s_cbranch_scc0 .LBB0_198

; #define PG8_STAGEA(bufoff, gbase) PG8_STAGE_(bufoff, gbase, voffA)
; #define PG8_STAGEB(bufoff, gbase) PG8_STAGE_(bufoff, gbase, voffB)
; #define PG8_LDA(dst, b, h) do { _Pragma("unroll") for (int m = 0; m < 4; ++m) _Pragma("unroll") for (int k = 0; k < 2; ++k) dst[m][k] = *(const LAS bf16x8*)(lds + PG8_SA(b, h) + aoff + m * 2048 + k * 1024); } while (0)
; #define PG8_LDB(dst, b, h) do { _Pragma("unroll") for (int n = 0; n < 2; ++n) _Pragma("unroll") for (int k = 0; k < 2; ++k) dst[n][k] = *(const LAS bf16x8*)(lds + PG8_SB(b, h) + boff + n * 2048 + k * 1024); } while (0)
; #define PG8_MMA(ai, bj, At, Bt_) do { __builtin_amdgcn_s_setprio(1); _Pragma("unroll") for (int m = 0; m < 4; ++m) _Pragma("unroll") for (int n = 0; n < 2; ++n) _Pragma("unroll") for (int k = 0; k < 2; ++k) \
;         acc[ai][bj][m][n] = __builtin_amdgcn_mfma_f32_16x16x32_bf16(Bt_[n][k], At[m][k], acc[ai][bj][m][n], 0, 0, 0); __builtin_amdgcn_s_setprio(0); } while (0)
; #define PG8_WAIT_V(n) asm volatile("s_waitcnt vmcnt(" #n ")" ::: "memory")
; #define PG8_WAIT_L(n) asm volatile("s_waitcnt lgkmcnt(" #n ")" ::: "memory")
; #define PG8_BAR __builtin_amdgcn_s_barrier()
; template <int EK, int SK = -1>
; __device__ __forceinline__ void gemm_phase(LAS unsigned char* lds, const bf16_t* A, const bf16_t* Bt, int nM, int N, int K, const EpiArgs& E) {
;     ...
;         const bool has_next = S.next(ui + 1, nxt);
;         const char* nA = has_next ? (const char*)A + (size_t)nxt.pm * tstep : cA; const char* nB = has_next ? (const char*)Bt + (size_t)nxt.pn * tstep : cB;
;         for (int t = 0; t < nt; t += 2) {
;             const bool last = (t == nt - 2);
;             const char* a1 = cA + (size_t)(t + 1) * kstep;
;             const char* a2 = last ? nA : cA + (size_t)(t + 2) * kstep; const char* b2 = last ? nB : cB + (size_t)(t + 2) * kstep;
;             const char* a3 = a2 + kstep; const char* b3 = b2 + kstep;
;             PG8_LDB(B0, 0, 0); PG8_LDB(B1, 0, 1); PG8_SCHED; PG8_LDA(At, 0, 0); PG8_STAGEA(PG8_SA(1, 1), a1 + hstep);
;             PG8_WAIT_V(8); PG8_WAIT_L(0); PG8_BAR; PG8_MMA(0, 0, At, B0); PG8_MMA(0, 1, At, B1); PG8_BAR; PG8_SCHED;
;             PG8_LDA(At, 0, 1); PG8_STAGEB(PG8_SB(0, 0), b2); PG8_STAGEB(PG8_SB(0, 1), b2 + hstep); PG8_STAGEA(PG8_SA(0, 0), a2);
;             PG8_WAIT_V(8); PG8_WAIT_L(0); PG8_BAR; PG8_MMA(1, 0, At, B0); PG8_MMA(1, 1, At, B1); PG8_BAR; PG8_SCHED;
.LBB0_412:
	s_add_u32 s53, s80, 0x100
	s_addc_u32 s54, s81, 0
	s_ashr_i32 s75, s74, 31
	s_lshl_b64 s[56:57], s[74:75], 19
	s_add_u32 s78, s66, s56
	s_addc_u32 s79, s67, s57
	s_and_b64 s[56:57], s[8:9], exec
	s_cselect_b32 s40, s79, s19
	s_cselect_b32 s55, s78, s18
	s_ashr_i32 s73, s72, 31
	s_lshl_b64 s[56:57], s[72:73], 19
	s_add_u32 s76, s86, s56
	s_addc_u32 s77, s87, s57
	s_and_b64 s[56:57], s[8:9], exec
	s_cselect_b32 s56, s77, s81
	s_cselect_b32 s57, s76, s80
	v_lshl_add_u64 v[146:147], s[18:19], 0, v[138:139]
	v_lshl_add_u64 v[148:149], s[18:19], 0, v[140:141]
	s_mov_b32 s58, -2
	s_mov_b64 s[80:81], 0
	v_add_u32_e32 v150, s95, v152
	ds_read_b128 v[156:159], v150
	ds_read_b128 v[160:163], v150 offset:1024
	ds_read_b128 v[164:167], v150 offset:2048
	ds_read_b128 v[168:171], v150 offset:3072
	v_add_u32_e32 v150, s96, v152
	s_add_u32 s59, s18, s80
	ds_read_b128 v[172:175], v150
	ds_read_b128 v[176:179], v150 offset:1024
	ds_read_b128 v[180:183], v150 offset:2048
	ds_read_b128 v[184:187], v150 offset:3072
	s_addc_u32 s73, s19, s81
	s_add_u32 s59, s59, 0x100
	s_addc_u32 s73, s73, 0
	s_add_u32 s75, s53, s80
	s_addc_u32 s82, s54, s81
	s_cmpk_eq_i32 s80, 0x700
	s_cselect_b32 s85, s40, s73
	s_cselect_b32 s84, s55, s59
	s_cselect_b32 s83, s56, s82
	s_cselect_b32 s82, s57, s75
	v_lshl_add_u64 v[150:151], v[146:147], 0, s[80:81]
	s_add_i32 m0, s15, 0xc000
	ds_read_b128 v[188:191], v154
	ds_read_b128 v[192:195], v154 offset:1024
	ds_read_b128 v[196:199], v154 offset:2048
	ds_read_b128 v[200:203], v154 offset:3072
	ds_read_b128 v[204:207], v154 offset:4096
	ds_read_b128 v[208:211], v154 offset:5120
	ds_read_b128 v[212:215], v154 offset:6144
	ds_read_b128 v[216:219], v154 offset:7168
	global_load_lds_dwordx4 v[150:151], off
	v_lshl_add_u64 v[150:151], v[148:149], 0, s[80:81]
	s_add_i32 m0, s15, 0xe000
	s_nop 0
	global_load_lds_dwordx4 v[150:151], off
	s_waitcnt vmcnt(8)
	s_waitcnt lgkmcnt(0)
	s_barrier
	s_waitcnt lgkmcnt(0)
	v_mfma_f32_16x16x32_bf16 v[126:129], v[156:159], v[188:191], 0
	v_mfma_f32_16x16x32_bf16 v[122:125], v[164:167], v[188:191], 0
	v_mfma_f32_16x16x32_bf16 v[94:97], v[172:175], v[188:191], 0
	v_mfma_f32_16x16x32_bf16 v[90:93], v[180:183], v[188:191], 0
	v_mfma_f32_16x16x32_bf16 v[82:85], v[180:183], v[196:199], 0
	v_mfma_f32_16x16x32_bf16 v[86:89], v[172:175], v[196:199], 0
	v_mfma_f32_16x16x32_bf16 v[114:117], v[164:167], v[196:199], 0
	v_mfma_f32_16x16x32_bf16 v[118:121], v[156:159], v[196:199], 0
	v_mfma_f32_16x16x32_bf16 v[110:113], v[156:159], v[204:207], 0
	v_mfma_f32_16x16x32_bf16 v[106:109], v[164:167], v[204:207], 0
	v_mfma_f32_16x16x32_bf16 v[78:81], v[172:175], v[204:207], 0
	v_mfma_f32_16x16x32_bf16 v[74:77], v[180:183], v[204:207], 0
	v_mfma_f32_16x16x32_bf16 v[66:69], v[180:183], v[212:215], 0
	v_mfma_f32_16x16x32_bf16 v[70:73], v[172:175], v[212:215], 0
	v_mfma_f32_16x16x32_bf16 v[98:101], v[164:167], v[212:215], 0
	v_mfma_f32_16x16x32_bf16 v[102:105], v[156:159], v[212:215], 0
	v_mfma_f32_16x16x32_bf16 v[126:129], v[160:163], v[192:195], v[126:129]
	v_mfma_f32_16x16x32_bf16 v[122:125], v[168:171], v[192:195], v[122:125]
	v_mfma_f32_16x16x32_bf16 v[94:97], v[176:179], v[192:195], v[94:97]
	v_mfma_f32_16x16x32_bf16 v[90:93], v[184:187], v[192:195], v[90:93]
	v_mfma_f32_16x16x32_bf16 v[82:85], v[184:187], v[200:203], v[82:85]
	v_mfma_f32_16x16x32_bf16 v[86:89], v[176:179], v[200:203], v[86:89]
	v_mfma_f32_16x16x32_bf16 v[114:117], v[168:171], v[200:203], v[114:117]
	v_mfma_f32_16x16x32_bf16 v[118:121], v[160:163], v[200:203], v[118:121]
	v_mfma_f32_16x16x32_bf16 v[110:113], v[160:163], v[208:211], v[110:113]
	v_mfma_f32_16x16x32_bf16 v[106:109], v[168:171], v[208:211], v[106:109]
	v_mfma_f32_16x16x32_bf16 v[78:81], v[176:179], v[208:211], v[78:81]
	v_mfma_f32_16x16x32_bf16 v[74:77], v[184:187], v[208:211], v[74:77]
	v_mfma_f32_16x16x32_bf16 v[66:69], v[184:187], v[216:219], v[66:69]
	v_mfma_f32_16x16x32_bf16 v[70:73], v[176:179], v[216:219], v[70:73]
	v_mfma_f32_16x16x32_bf16 v[98:101], v[168:171], v[216:219], v[98:101]
	v_mfma_f32_16x16x32_bf16 v[102:105], v[160:163], v[216:219], v[102:105]
	s_barrier
	s_add_i32 s59, s95, s88
	v_lshl_add_u64 v[150:151], s[82:83], 0, v[132:133]
	s_mov_b32 m0, s59
	ds_read_b128 v[188:191], v154 offset:16384
	ds_read_b128 v[192:195], v154 offset:17408
	ds_read_b128 v[196:199], v154 offset:18432
	ds_read_b128 v[200:203], v154 offset:19456
	ds_read_b128 v[204:207], v154 offset:20480
	ds_read_b128 v[208:211], v154 offset:21504
	ds_read_b128 v[212:215], v154 offset:22528
	ds_read_b128 v[216:219], v154 offset:23552
	global_load_lds_dwordx4 v[150:151], off
	s_add_i32 m0, s59, 0x2000
	s_add_u32 vcc_lo, s82, 0x40000
	v_lshl_add_u64 v[220:221], s[82:83], 0, v[136:137]
	s_addc_u32 vcc_hi, s83, 0
	s_add_i32 s59, s96, s88
	global_load_lds_dwordx4 v[220:221], off
	v_lshl_add_u64 v[222:223], vcc, 0, v[132:133]
	s_mov_b32 m0, s59
	v_lshl_add_u64 v[224:225], s[84:85], 0, v[134:135]
	global_load_lds_dwordx4 v[222:223], off
	v_lshl_add_u64 v[222:223], vcc, 0, v[136:137]
	s_add_i32 m0, s59, 0x2000
	s_nop 0
	global_load_lds_dwordx4 v[222:223], off
	v_lshl_add_u64 v[222:223], s[84:85], 0, v[130:131]
	s_mov_b32 m0, s15
	s_nop 0
	global_load_lds_dwordx4 v[222:223], off
	s_mov_b32 m0, s17
	s_nop 0
	global_load_lds_dwordx4 v[224:225], off
	s_waitcnt vmcnt(8)
	s_waitcnt lgkmcnt(0)
	s_barrier
; #define PG8_STAGEA(bufoff, gbase) PG8_STAGE_(bufoff, gbase, voffA)
; #define PG8_LDA(dst, b, h) do { _Pragma("unroll") for (int m = 0; m < 4; ++m) _Pragma("unroll") for (int k = 0; k < 2; ++k) dst[m][k] = *(const LAS bf16x8*)(lds + PG8_SA(b, h) + aoff + m * 2048 + k * 1024); } while (0)
; #define PG8_LDB(dst, b, h) do { _Pragma("unroll") for (int n = 0; n < 2; ++n) _Pragma("unroll") for (int k = 0; k < 2; ++k) dst[n][k] = *(const LAS bf16x8*)(lds + PG8_SB(b, h) + boff + n * 2048 + k * 1024); } while (0)
; #define PG8_MMA(ai, bj, At, Bt_) do { __builtin_amdgcn_s_setprio(1); _Pragma("unroll") for (int m = 0; m < 4; ++m) _Pragma("unroll") for (int n = 0; n < 2; ++n) _Pragma("unroll") for (int k = 0; k < 2; ++k) \
;         acc[ai][bj][m][n] = __builtin_amdgcn_mfma_f32_16x16x32_bf16(Bt_[n][k], At[m][k], acc[ai][bj][m][n], 0, 0, 0); __builtin_amdgcn_s_setprio(0); } while (0)
; #define PG8_WAIT_V(n) asm volatile("s_waitcnt vmcnt(" #n ")" ::: "memory")
; #define PG8_WAIT_L(n) asm volatile("s_waitcnt lgkmcnt(" #n ")" ::: "memory")
; #define PG8_BAR __builtin_amdgcn_s_barrier()
; #define PG8_SCHED __builtin_amdgcn_sched_barrier(0)
; template <int EK, int SK = -1>
; __device__ __forceinline__ void gemm_phase(LAS unsigned char* lds, const bf16_t* A, const bf16_t* Bt, int nM, int N, int K, const EpiArgs& E) {
;     ...
;             PG8_WAIT_V(8); PG8_WAIT_L(0); PG8_BAR; PG8_MMA(1, 0, At, B0); PG8_MMA(1, 1, At, B1); PG8_BAR; PG8_SCHED;
;             PG8_LDB(B0, 1, 0); PG8_LDB(B1, 1, 1); PG8_SCHED; PG8_LDA(At, 1, 0); PG8_STAGEA(PG8_SA(0, 1), a2 + hstep);
;             PG8_WAIT_V(8); PG8_WAIT_L(0); PG8_BAR; PG8_MMA(0, 0, At, B0); PG8_MMA(0, 1, At, B1); PG8_BAR; PG8_SCHED;
	s_waitcnt lgkmcnt(0)
	v_mfma_f32_16x16x32_bf16 v[62:65], v[156:159], v[188:191], 0
	v_mfma_f32_16x16x32_bf16 v[58:61], v[164:167], v[188:191], 0
	v_mfma_f32_16x16x32_bf16 v[30:33], v[172:175], v[188:191], 0
	v_mfma_f32_16x16x32_bf16 v[26:29], v[180:183], v[188:191], 0
	v_mfma_f32_16x16x32_bf16 v[18:21], v[180:183], v[196:199], 0
	v_mfma_f32_16x16x32_bf16 v[22:25], v[172:175], v[196:199], 0
	v_mfma_f32_16x16x32_bf16 v[50:53], v[164:167], v[196:199], 0
	v_mfma_f32_16x16x32_bf16 v[54:57], v[156:159], v[196:199], 0
	v_mfma_f32_16x16x32_bf16 v[46:49], v[156:159], v[204:207], 0
	v_mfma_f32_16x16x32_bf16 v[42:45], v[164:167], v[204:207], 0
	v_mfma_f32_16x16x32_bf16 v[14:17], v[172:175], v[204:207], 0
	v_mfma_f32_16x16x32_bf16 v[10:13], v[180:183], v[204:207], 0
	v_mfma_f32_16x16x32_bf16 v[2:5], v[180:183], v[212:215], 0
	v_mfma_f32_16x16x32_bf16 v[6:9], v[172:175], v[212:215], 0
	v_mfma_f32_16x16x32_bf16 v[34:37], v[164:167], v[212:215], 0
	v_mfma_f32_16x16x32_bf16 v[38:41], v[156:159], v[212:215], 0
	v_mfma_f32_16x16x32_bf16 v[62:65], v[160:163], v[192:195], v[62:65]
	v_mfma_f32_16x16x32_bf16 v[58:61], v[168:171], v[192:195], v[58:61]
	v_mfma_f32_16x16x32_bf16 v[30:33], v[176:179], v[192:195], v[30:33]
	v_mfma_f32_16x16x32_bf16 v[26:29], v[184:187], v[192:195], v[26:29]
	v_mfma_f32_16x16x32_bf16 v[18:21], v[184:187], v[200:203], v[18:21]
	v_mfma_f32_16x16x32_bf16 v[22:25], v[176:179], v[200:203], v[22:25]
	v_mfma_f32_16x16x32_bf16 v[50:53], v[168:171], v[200:203], v[50:53]
	v_mfma_f32_16x16x32_bf16 v[54:57], v[160:163], v[200:203], v[54:57]
	v_mfma_f32_16x16x32_bf16 v[46:49], v[160:163], v[208:211], v[46:49]
	v_mfma_f32_16x16x32_bf16 v[42:45], v[168:171], v[208:211], v[42:45]
	v_mfma_f32_16x16x32_bf16 v[14:17], v[176:179], v[208:211], v[14:17]
	v_mfma_f32_16x16x32_bf16 v[10:13], v[184:187], v[208:211], v[10:13]
	v_mfma_f32_16x16x32_bf16 v[2:5], v[184:187], v[216:219], v[2:5]
	v_mfma_f32_16x16x32_bf16 v[6:9], v[176:179], v[216:219], v[6:9]
	v_mfma_f32_16x16x32_bf16 v[34:37], v[168:171], v[216:219], v[34:37]
	v_mfma_f32_16x16x32_bf16 v[38:41], v[160:163], v[216:219], v[38:41]
	s_barrier
	s_add_i32 s59, 0, 0x18000
	s_add_i32 s73, 0, 0x1c000
	v_add_u32_e32 v168, s59, v152
	v_add_u32_e32 v184, s73, v152
	ds_read_b128 v[156:159], v168
	ds_read_b128 v[160:163], v168 offset:1024
	ds_read_b128 v[164:167], v168 offset:2048
	ds_read_b128 v[168:171], v168 offset:3072
	ds_read_b128 v[172:175], v184
	ds_read_b128 v[176:179], v184 offset:1024
	ds_read_b128 v[180:183], v184 offset:2048
	ds_read_b128 v[184:187], v184 offset:3072
	s_add_u32 s84, s84, 0x40000
	s_addc_u32 s85, s85, 0
	s_mov_b32 m0, s89
	v_lshl_add_u64 v[226:227], s[84:85], 0, v[130:131]
	ds_read_b128 v[188:191], v154 offset:32768
	ds_read_b128 v[192:195], v154 offset:33792
	ds_read_b128 v[196:199], v154 offset:34816
	ds_read_b128 v[200:203], v154 offset:35840
	ds_read_b128 v[204:207], v154 offset:36864
	ds_read_b128 v[208:211], v154 offset:37888
	ds_read_b128 v[212:215], v154 offset:38912
	ds_read_b128 v[216:219], v154 offset:39936
	global_load_lds_dwordx4 v[226:227], off
	v_lshl_add_u64 v[226:227], s[84:85], 0, v[134:135]
	s_mov_b32 m0, s90
	s_nop 0
	global_load_lds_dwordx4 v[226:227], off
	s_waitcnt vmcnt(8)
	s_waitcnt lgkmcnt(0)
	s_barrier
	s_waitcnt lgkmcnt(0)
	v_mfma_f32_16x16x32_bf16 v[126:129], v[156:159], v[188:191], v[126:129]
	v_mfma_f32_16x16x32_bf16 v[122:125], v[164:167], v[188:191], v[122:125]
	v_mfma_f32_16x16x32_bf16 v[94:97], v[172:175], v[188:191], v[94:97]
	v_mfma_f32_16x16x32_bf16 v[90:93], v[180:183], v[188:191], v[90:93]
	v_mfma_f32_16x16x32_bf16 v[82:85], v[180:183], v[196:199], v[82:85]
	v_mfma_f32_16x16x32_bf16 v[86:89], v[172:175], v[196:199], v[86:89]
	v_mfma_f32_16x16x32_bf16 v[114:117], v[164:167], v[196:199], v[114:117]
	v_mfma_f32_16x16x32_bf16 v[118:121], v[156:159], v[196:199], v[118:121]
	v_mfma_f32_16x16x32_bf16 v[110:113], v[156:159], v[204:207], v[110:113]
	v_mfma_f32_16x16x32_bf16 v[106:109], v[164:167], v[204:207], v[106:109]
	v_mfma_f32_16x16x32_bf16 v[78:81], v[172:175], v[204:207], v[78:81]
	v_mfma_f32_16x16x32_bf16 v[74:77], v[180:183], v[204:207], v[74:77]
	v_mfma_f32_16x16x32_bf16 v[66:69], v[180:183], v[212:215], v[66:69]
	v_mfma_f32_16x16x32_bf16 v[70:73], v[172:175], v[212:215], v[70:73]
	v_mfma_f32_16x16x32_bf16 v[98:101], v[164:167], v[212:215], v[98:101]
	v_mfma_f32_16x16x32_bf16 v[102:105], v[156:159], v[212:215], v[102:105]
	v_mfma_f32_16x16x32_bf16 v[126:129], v[160:163], v[192:195], v[126:129]
	v_mfma_f32_16x16x32_bf16 v[122:125], v[168:171], v[192:195], v[122:125]
	v_mfma_f32_16x16x32_bf16 v[94:97], v[176:179], v[192:195], v[94:97]
	v_mfma_f32_16x16x32_bf16 v[90:93], v[184:187], v[192:195], v[90:93]
	v_mfma_f32_16x16x32_bf16 v[82:85], v[184:187], v[200:203], v[82:85]
	v_mfma_f32_16x16x32_bf16 v[86:89], v[176:179], v[200:203], v[86:89]
	v_mfma_f32_16x16x32_bf16 v[114:117], v[168:171], v[200:203], v[114:117]
	v_mfma_f32_16x16x32_bf16 v[118:121], v[160:163], v[200:203], v[118:121]
	v_mfma_f32_16x16x32_bf16 v[110:113], v[160:163], v[208:211], v[110:113]
	v_mfma_f32_16x16x32_bf16 v[106:109], v[168:171], v[208:211], v[106:109]
	v_mfma_f32_16x16x32_bf16 v[78:81], v[176:179], v[208:211], v[78:81]
	v_mfma_f32_16x16x32_bf16 v[74:77], v[184:187], v[208:211], v[74:77]
	v_mfma_f32_16x16x32_bf16 v[66:69], v[184:187], v[216:219], v[66:69]
	v_mfma_f32_16x16x32_bf16 v[70:73], v[176:179], v[216:219], v[70:73]
	v_mfma_f32_16x16x32_bf16 v[98:101], v[168:171], v[216:219], v[98:101]
	v_mfma_f32_16x16x32_bf16 v[102:105], v[160:163], v[216:219], v[102:105]
	s_barrier
; #define PG8_STAGEA(bufoff, gbase) PG8_STAGE_(bufoff, gbase, voffA)
; #define PG8_STAGEB(bufoff, gbase) PG8_STAGE_(bufoff, gbase, voffB)
; #define PG8_LDA(dst, b, h) do { _Pragma("unroll") for (int m = 0; m < 4; ++m) _Pragma("unroll") for (int k = 0; k < 2; ++k) dst[m][k] = *(const LAS bf16x8*)(lds + PG8_SA(b, h) + aoff + m * 2048 + k * 1024); } while (0)
; #define PG8_LDB(dst, b, h) do { _Pragma("unroll") for (int n = 0; n < 2; ++n) _Pragma("unroll") for (int k = 0; k < 2; ++k) dst[n][k] = *(const LAS bf16x8*)(lds + PG8_SB(b, h) + boff + n * 2048 + k * 1024); } while (0)
; #define PG8_MMA(ai, bj, At, Bt_) do { __builtin_amdgcn_s_setprio(1); _Pragma("unroll") for (int m = 0; m < 4; ++m) _Pragma("unroll") for (int n = 0; n < 2; ++n) _Pragma("unroll") for (int k = 0; k < 2; ++k) \
;         acc[ai][bj][m][n] = __builtin_amdgcn_mfma_f32_16x16x32_bf16(Bt_[n][k], At[m][k], acc[ai][bj][m][n], 0, 0, 0); __builtin_amdgcn_s_setprio(0); } while (0)
; #define PG8_WAIT_V(n) asm volatile("s_waitcnt vmcnt(" #n ")" ::: "memory")
; #define PG8_WAIT_L(n) asm volatile("s_waitcnt lgkmcnt(" #n ")" ::: "memory")
; #define PG8_BAR __builtin_amdgcn_s_barrier()
; #define PG8_SCHED __builtin_amdgcn_sched_barrier(0)
; template <int EK, int SK = -1>
; __device__ __forceinline__ void gemm_phase(LAS unsigned char* lds, const bf16_t* A, const bf16_t* Bt, int nM, int N, int K, const EpiArgs& E) {
;     ...
;             PG8_LDB(B0, 0, 0); PG8_LDB(B1, 0, 1); PG8_SCHED; PG8_LDA(At, 0, 0); PG8_STAGEA(PG8_SA(1, 1), a1 + hstep);
;             PG8_WAIT_V(8); PG8_WAIT_L(0); PG8_BAR; PG8_MMA(0, 0, At, B0); PG8_MMA(0, 1, At, B1); PG8_BAR; PG8_SCHED;
;     ...
;             PG8_LDA(At, 1, 1); PG8_STAGEB(PG8_SB(1, 0), b3); PG8_STAGEB(PG8_SB(1, 1), b3 + hstep); PG8_STAGEA(PG8_SA(1, 0), a3);
;             PG8_WAIT_V(8); PG8_WAIT_L(0); PG8_BAR; PG8_MMA(1, 0, At, B0); PG8_MMA(1, 1, At, B1); PG8_BAR; PG8_SCHED;
;         }
	s_add_i32 s59, s59, s88
	v_lshl_add_u64 v[150:151], v[150:151], 0, s[68:69]
	s_mov_b32 m0, s59
	ds_read_b128 v[188:191], v154 offset:49152
	ds_read_b128 v[192:195], v154 offset:50176
	ds_read_b128 v[196:199], v154 offset:51200
	ds_read_b128 v[200:203], v154 offset:52224
	ds_read_b128 v[204:207], v154 offset:53248
	ds_read_b128 v[208:211], v154 offset:54272
	ds_read_b128 v[212:215], v154 offset:55296
	ds_read_b128 v[216:219], v154 offset:56320
	global_load_lds_dwordx4 v[150:151], off
	s_add_i32 m0, s59, 0x2000
	s_add_u32 s82, s82, 0x40080
	v_lshl_add_u64 v[150:151], v[220:221], 0, s[68:69]
	s_addc_u32 s83, s83, 0
	s_add_i32 s59, s73, s88
	global_load_lds_dwordx4 v[150:151], off
	v_lshl_add_u64 v[150:151], s[82:83], 0, v[132:133]
	s_mov_b32 m0, s59
	s_nop 0
	global_load_lds_dwordx4 v[150:151], off
	v_lshl_add_u64 v[150:151], s[82:83], 0, v[136:137]
	s_add_i32 m0, s59, 0x2000
	s_nop 0
	global_load_lds_dwordx4 v[150:151], off
	v_lshl_add_u64 v[150:151], v[222:223], 0, s[68:69]
	s_mov_b32 m0, s93
	s_nop 0
	global_load_lds_dwordx4 v[150:151], off
	v_lshl_add_u64 v[150:151], v[224:225], 0, s[68:69]
	s_mov_b32 m0, s94
	s_nop 0
	global_load_lds_dwordx4 v[150:151], off
	s_waitcnt vmcnt(8)
	s_waitcnt lgkmcnt(0)
	s_barrier
	s_waitcnt lgkmcnt(0)
	v_mfma_f32_16x16x32_bf16 v[62:65], v[156:159], v[188:191], v[62:65]
	v_mfma_f32_16x16x32_bf16 v[58:61], v[164:167], v[188:191], v[58:61]
	v_mfma_f32_16x16x32_bf16 v[30:33], v[172:175], v[188:191], v[30:33]
	v_mfma_f32_16x16x32_bf16 v[26:29], v[180:183], v[188:191], v[26:29]
	v_mfma_f32_16x16x32_bf16 v[18:21], v[180:183], v[196:199], v[18:21]
	v_mfma_f32_16x16x32_bf16 v[22:25], v[172:175], v[196:199], v[22:25]
	v_mfma_f32_16x16x32_bf16 v[50:53], v[164:167], v[196:199], v[50:53]
	v_mfma_f32_16x16x32_bf16 v[54:57], v[156:159], v[196:199], v[54:57]
	v_mfma_f32_16x16x32_bf16 v[46:49], v[156:159], v[204:207], v[46:49]
	v_mfma_f32_16x16x32_bf16 v[42:45], v[164:167], v[204:207], v[42:45]
	v_mfma_f32_16x16x32_bf16 v[14:17], v[172:175], v[204:207], v[14:17]
	v_mfma_f32_16x16x32_bf16 v[10:13], v[180:183], v[204:207], v[10:13]
	v_mfma_f32_16x16x32_bf16 v[2:5], v[180:183], v[212:215], v[2:5]
	v_mfma_f32_16x16x32_bf16 v[6:9], v[172:175], v[212:215], v[6:9]
	v_mfma_f32_16x16x32_bf16 v[34:37], v[164:167], v[212:215], v[34:37]
	v_mfma_f32_16x16x32_bf16 v[38:41], v[156:159], v[212:215], v[38:41]
	v_mfma_f32_16x16x32_bf16 v[62:65], v[160:163], v[192:195], v[62:65]
	v_mfma_f32_16x16x32_bf16 v[58:61], v[168:171], v[192:195], v[58:61]
	v_mfma_f32_16x16x32_bf16 v[30:33], v[176:179], v[192:195], v[30:33]
	v_mfma_f32_16x16x32_bf16 v[26:29], v[184:187], v[192:195], v[26:29]
	v_mfma_f32_16x16x32_bf16 v[18:21], v[184:187], v[200:203], v[18:21]
	v_mfma_f32_16x16x32_bf16 v[22:25], v[176:179], v[200:203], v[22:25]
	v_mfma_f32_16x16x32_bf16 v[50:53], v[168:171], v[200:203], v[50:53]
	v_mfma_f32_16x16x32_bf16 v[54:57], v[160:163], v[200:203], v[54:57]
	v_mfma_f32_16x16x32_bf16 v[46:49], v[160:163], v[208:211], v[46:49]
	v_mfma_f32_16x16x32_bf16 v[42:45], v[168:171], v[208:211], v[42:45]
	v_mfma_f32_16x16x32_bf16 v[14:17], v[176:179], v[208:211], v[14:17]
	v_mfma_f32_16x16x32_bf16 v[10:13], v[184:187], v[208:211], v[10:13]
	v_mfma_f32_16x16x32_bf16 v[2:5], v[184:187], v[216:219], v[2:5]
	v_mfma_f32_16x16x32_bf16 v[6:9], v[176:179], v[216:219], v[6:9]
	v_mfma_f32_16x16x32_bf16 v[34:37], v[168:171], v[216:219], v[34:37]
	v_mfma_f32_16x16x32_bf16 v[38:41], v[160:163], v[216:219], v[38:41]
	s_barrier
	s_add_i32 s58, s58, 2
	s_add_u32 s80, s80, 0x100
	s_addc_u32 s81, s81, 0
	s_cmp_gt_u32 s58, 13
	s_cbranch_scc0 .LBB0_413
	s_branch .Lmy_kexit_1
.LBB0_413:
	v_add_u32_e32 v150, s95, v152
	ds_read_b128 v[156:159], v150
	ds_read_b128 v[160:163], v150 offset:1024
	ds_read_b128 v[164:167], v150 offset:2048
	ds_read_b128 v[168:171], v150 offset:3072
	v_add_u32_e32 v150, s96, v152
	s_add_u32 s59, s18, s80
	ds_read_b128 v[172:175], v150
	ds_read_b128 v[176:179], v150 offset:1024
	ds_read_b128 v[180:183], v150 offset:2048
	ds_read_b128 v[184:187], v150 offset:3072
	s_addc_u32 s73, s19, s81
	s_add_u32 s59, s59, 0x100
	s_addc_u32 s73, s73, 0
	s_add_u32 s75, s53, s80
	s_addc_u32 s82, s54, s81
	s_cmpk_eq_i32 s80, 0x700
	s_cselect_b32 s85, s40, s73
	s_cselect_b32 s84, s55, s59
	s_cselect_b32 s83, s56, s82
	s_cselect_b32 s82, s57, s75
	v_lshl_add_u64 v[150:151], v[146:147], 0, s[80:81]
	s_add_i32 m0, s15, 0xc000
	ds_read_b128 v[188:191], v154
	ds_read_b128 v[192:195], v154 offset:1024
	ds_read_b128 v[196:199], v154 offset:2048
	ds_read_b128 v[200:203], v154 offset:3072
	ds_read_b128 v[204:207], v154 offset:4096
	ds_read_b128 v[208:211], v154 offset:5120
	ds_read_b128 v[212:215], v154 offset:6144
	ds_read_b128 v[216:219], v154 offset:7168
	global_load_lds_dwordx4 v[150:151], off
	v_lshl_add_u64 v[150:151], v[148:149], 0, s[80:81]
	s_add_i32 m0, s15, 0xe000
	s_nop 0
	global_load_lds_dwordx4 v[150:151], off
	s_waitcnt vmcnt(8)
	s_waitcnt lgkmcnt(0)
	s_barrier
; #define PG8_STAGEA(bufoff, gbase) PG8_STAGE_(bufoff, gbase, voffA)
; #define PG8_STAGEB(bufoff, gbase) PG8_STAGE_(bufoff, gbase, voffB)
; #define PG8_LDA(dst, b, h) do { _Pragma("unroll") for (int m = 0; m < 4; ++m) _Pragma("unroll") for (int k = 0; k < 2; ++k) dst[m][k] = *(const LAS bf16x8*)(lds + PG8_SA(b, h) + aoff + m * 2048 + k * 1024); } while (0)
; #define PG8_MMA(ai, bj, At, Bt_) do { __builtin_amdgcn_s_setprio(1); _Pragma("unroll") for (int m = 0; m < 4; ++m) _Pragma("unroll") for (int n = 0; n < 2; ++n) _Pragma("unroll") for (int k = 0; k < 2; ++k) \
;         acc[ai][bj][m][n] = __builtin_amdgcn_mfma_f32_16x16x32_bf16(Bt_[n][k], At[m][k], acc[ai][bj][m][n], 0, 0, 0); __builtin_amdgcn_s_setprio(0); } while (0)
; #define PG8_WAIT_V(n) asm volatile("s_waitcnt vmcnt(" #n ")" ::: "memory")
; #define PG8_WAIT_L(n) asm volatile("s_waitcnt lgkmcnt(" #n ")" ::: "memory")
; #define PG8_BAR __builtin_amdgcn_s_barrier()
; #define PG8_SCHED __builtin_amdgcn_sched_barrier(0)
; template <int EK, int SK = -1>
; __device__ __forceinline__ void gemm_phase(LAS unsigned char* lds, const bf16_t* A, const bf16_t* Bt, int nM, int N, int K, const EpiArgs& E) {
;     ...
;             PG8_WAIT_V(8); PG8_WAIT_L(0); PG8_BAR; PG8_MMA(0, 0, At, B0); PG8_MMA(0, 1, At, B1); PG8_BAR; PG8_SCHED;
;             PG8_LDA(At, 0, 1); PG8_STAGEB(PG8_SB(0, 0), b2); PG8_STAGEB(PG8_SB(0, 1), b2 + hstep); PG8_STAGEA(PG8_SA(0, 0), a2);
;             PG8_WAIT_V(8); PG8_WAIT_L(0); PG8_BAR; PG8_MMA(1, 0, At, B0); PG8_MMA(1, 1, At, B1); PG8_BAR; PG8_SCHED;
	s_waitcnt lgkmcnt(0)
	v_mfma_f32_16x16x32_bf16 v[126:129], v[156:159], v[188:191], v[126:129]
	v_mfma_f32_16x16x32_bf16 v[122:125], v[164:167], v[188:191], v[122:125]
	v_mfma_f32_16x16x32_bf16 v[94:97], v[172:175], v[188:191], v[94:97]
	v_mfma_f32_16x16x32_bf16 v[90:93], v[180:183], v[188:191], v[90:93]
	v_mfma_f32_16x16x32_bf16 v[82:85], v[180:183], v[196:199], v[82:85]
	v_mfma_f32_16x16x32_bf16 v[86:89], v[172:175], v[196:199], v[86:89]
	v_mfma_f32_16x16x32_bf16 v[114:117], v[164:167], v[196:199], v[114:117]
	v_mfma_f32_16x16x32_bf16 v[118:121], v[156:159], v[196:199], v[118:121]
	v_mfma_f32_16x16x32_bf16 v[110:113], v[156:159], v[204:207], v[110:113]
	v_mfma_f32_16x16x32_bf16 v[106:109], v[164:167], v[204:207], v[106:109]
	v_mfma_f32_16x16x32_bf16 v[78:81], v[172:175], v[204:207], v[78:81]
	v_mfma_f32_16x16x32_bf16 v[74:77], v[180:183], v[204:207], v[74:77]
	v_mfma_f32_16x16x32_bf16 v[66:69], v[180:183], v[212:215], v[66:69]
	v_mfma_f32_16x16x32_bf16 v[70:73], v[172:175], v[212:215], v[70:73]
	v_mfma_f32_16x16x32_bf16 v[98:101], v[164:167], v[212:215], v[98:101]
	v_mfma_f32_16x16x32_bf16 v[102:105], v[156:159], v[212:215], v[102:105]
	v_mfma_f32_16x16x32_bf16 v[126:129], v[160:163], v[192:195], v[126:129]
	v_mfma_f32_16x16x32_bf16 v[122:125], v[168:171], v[192:195], v[122:125]
	v_mfma_f32_16x16x32_bf16 v[94:97], v[176:179], v[192:195], v[94:97]
	v_mfma_f32_16x16x32_bf16 v[90:93], v[184:187], v[192:195], v[90:93]
	v_mfma_f32_16x16x32_bf16 v[82:85], v[184:187], v[200:203], v[82:85]
	v_mfma_f32_16x16x32_bf16 v[86:89], v[176:179], v[200:203], v[86:89]
	v_mfma_f32_16x16x32_bf16 v[114:117], v[168:171], v[200:203], v[114:117]
	v_mfma_f32_16x16x32_bf16 v[118:121], v[160:163], v[200:203], v[118:121]
	v_mfma_f32_16x16x32_bf16 v[110:113], v[160:163], v[208:211], v[110:113]
	v_mfma_f32_16x16x32_bf16 v[106:109], v[168:171], v[208:211], v[106:109]
	v_mfma_f32_16x16x32_bf16 v[78:81], v[176:179], v[208:211], v[78:81]
	v_mfma_f32_16x16x32_bf16 v[74:77], v[184:187], v[208:211], v[74:77]
	v_mfma_f32_16x16x32_bf16 v[66:69], v[184:187], v[216:219], v[66:69]
	v_mfma_f32_16x16x32_bf16 v[70:73], v[176:179], v[216:219], v[70:73]
	v_mfma_f32_16x16x32_bf16 v[98:101], v[168:171], v[216:219], v[98:101]
	v_mfma_f32_16x16x32_bf16 v[102:105], v[160:163], v[216:219], v[102:105]
	s_barrier
	s_add_i32 s59, s95, s88
	v_lshl_add_u64 v[150:151], s[82:83], 0, v[132:133]
	s_mov_b32 m0, s59
	ds_read_b128 v[188:191], v154 offset:16384
	ds_read_b128 v[192:195], v154 offset:17408
	ds_read_b128 v[196:199], v154 offset:18432
	ds_read_b128 v[200:203], v154 offset:19456
	ds_read_b128 v[204:207], v154 offset:20480
	ds_read_b128 v[208:211], v154 offset:21504
	ds_read_b128 v[212:215], v154 offset:22528
	ds_read_b128 v[216:219], v154 offset:23552
	global_load_lds_dwordx4 v[150:151], off
	s_add_i32 m0, s59, 0x2000
	s_add_u32 vcc_lo, s82, 0x40000
	v_lshl_add_u64 v[220:221], s[82:83], 0, v[136:137]
	s_addc_u32 vcc_hi, s83, 0
	s_add_i32 s59, s96, s88
	global_load_lds_dwordx4 v[220:221], off
	v_lshl_add_u64 v[222:223], vcc, 0, v[132:133]
	s_mov_b32 m0, s59
	v_lshl_add_u64 v[224:225], s[84:85], 0, v[134:135]
	global_load_lds_dwordx4 v[222:223], off
	v_lshl_add_u64 v[222:223], vcc, 0, v[136:137]
	s_add_i32 m0, s59, 0x2000
	s_nop 0
	global_load_lds_dwordx4 v[222:223], off
	v_lshl_add_u64 v[222:223], s[84:85], 0, v[130:131]
	s_mov_b32 m0, s15
	s_nop 0
	global_load_lds_dwordx4 v[222:223], off
	s_mov_b32 m0, s17
	s_nop 0
	global_load_lds_dwordx4 v[224:225], off
	s_waitcnt vmcnt(8)
	s_waitcnt lgkmcnt(0)
	s_barrier
	s_waitcnt lgkmcnt(0)
	v_mfma_f32_16x16x32_bf16 v[62:65], v[156:159], v[188:191], v[62:65]
	v_mfma_f32_16x16x32_bf16 v[58:61], v[164:167], v[188:191], v[58:61]
	v_mfma_f32_16x16x32_bf16 v[30:33], v[172:175], v[188:191], v[30:33]
	v_mfma_f32_16x16x32_bf16 v[26:29], v[180:183], v[188:191], v[26:29]
	v_mfma_f32_16x16x32_bf16 v[18:21], v[180:183], v[196:199], v[18:21]
	v_mfma_f32_16x16x32_bf16 v[22:25], v[172:175], v[196:199], v[22:25]
	v_mfma_f32_16x16x32_bf16 v[50:53], v[164:167], v[196:199], v[50:53]
	v_mfma_f32_16x16x32_bf16 v[54:57], v[156:159], v[196:199], v[54:57]
	v_mfma_f32_16x16x32_bf16 v[46:49], v[156:159], v[204:207], v[46:49]
	v_mfma_f32_16x16x32_bf16 v[42:45], v[164:167], v[204:207], v[42:45]
	v_mfma_f32_16x16x32_bf16 v[14:17], v[172:175], v[204:207], v[14:17]
	v_mfma_f32_16x16x32_bf16 v[10:13], v[180:183], v[204:207], v[10:13]
	v_mfma_f32_16x16x32_bf16 v[2:5], v[180:183], v[212:215], v[2:5]
	v_mfma_f32_16x16x32_bf16 v[6:9], v[172:175], v[212:215], v[6:9]
	v_mfma_f32_16x16x32_bf16 v[34:37], v[164:167], v[212:215], v[34:37]
	v_mfma_f32_16x16x32_bf16 v[38:41], v[156:159], v[212:215], v[38:41]
	v_mfma_f32_16x16x32_bf16 v[62:65], v[160:163], v[192:195], v[62:65]
	v_mfma_f32_16x16x32_bf16 v[58:61], v[168:171], v[192:195], v[58:61]
	v_mfma_f32_16x16x32_bf16 v[30:33], v[176:179], v[192:195], v[30:33]
	v_mfma_f32_16x16x32_bf16 v[26:29], v[184:187], v[192:195], v[26:29]
	v_mfma_f32_16x16x32_bf16 v[18:21], v[184:187], v[200:203], v[18:21]
	v_mfma_f32_16x16x32_bf16 v[22:25], v[176:179], v[200:203], v[22:25]
	v_mfma_f32_16x16x32_bf16 v[50:53], v[168:171], v[200:203], v[50:53]
	v_mfma_f32_16x16x32_bf16 v[54:57], v[160:163], v[200:203], v[54:57]
	v_mfma_f32_16x16x32_bf16 v[46:49], v[160:163], v[208:211], v[46:49]
	v_mfma_f32_16x16x32_bf16 v[42:45], v[168:171], v[208:211], v[42:45]
	v_mfma_f32_16x16x32_bf16 v[14:17], v[176:179], v[208:211], v[14:17]
	v_mfma_f32_16x16x32_bf16 v[10:13], v[184:187], v[208:211], v[10:13]
	v_mfma_f32_16x16x32_bf16 v[2:5], v[184:187], v[216:219], v[2:5]
	v_mfma_f32_16x16x32_bf16 v[6:9], v[176:179], v[216:219], v[6:9]
	v_mfma_f32_16x16x32_bf16 v[34:37], v[168:171], v[216:219], v[34:37]
	v_mfma_f32_16x16x32_bf16 v[38:41], v[160:163], v[216:219], v[38:41]
	s_barrier
; #define PG8_STAGEA(bufoff, gbase) PG8_STAGE_(bufoff, gbase, voffA)
; #define PG8_STAGEB(bufoff, gbase) PG8_STAGE_(bufoff, gbase, voffB)
; #define PG8_LDA(dst, b, h) do { _Pragma("unroll") for (int m = 0; m < 4; ++m) _Pragma("unroll") for (int k = 0; k < 2; ++k) dst[m][k] = *(const LAS bf16x8*)(lds + PG8_SA(b, h) + aoff + m * 2048 + k * 1024); } while (0)
; #define PG8_LDB(dst, b, h) do { _Pragma("unroll") for (int n = 0; n < 2; ++n) _Pragma("unroll") for (int k = 0; k < 2; ++k) dst[n][k] = *(const LAS bf16x8*)(lds + PG8_SB(b, h) + boff + n * 2048 + k * 1024); } while (0)
; #define PG8_MMA(ai, bj, At, Bt_) do { __builtin_amdgcn_s_setprio(1); _Pragma("unroll") for (int m = 0; m < 4; ++m) _Pragma("unroll") for (int n = 0; n < 2; ++n) _Pragma("unroll") for (int k = 0; k < 2; ++k) \
;         acc[ai][bj][m][n] = __builtin_amdgcn_mfma_f32_16x16x32_bf16(Bt_[n][k], At[m][k], acc[ai][bj][m][n], 0, 0, 0); __builtin_amdgcn_s_setprio(0); } while (0)
; #define PG8_WAIT_V(n) asm volatile("s_waitcnt vmcnt(" #n ")" ::: "memory")
; #define PG8_WAIT_L(n) asm volatile("s_waitcnt lgkmcnt(" #n ")" ::: "memory")
; #define PG8_BAR __builtin_amdgcn_s_barrier()
; #define PG8_SCHED __builtin_amdgcn_sched_barrier(0)
; template <int EK, int SK = -1>
; __device__ __forceinline__ void gemm_phase(LAS unsigned char* lds, const bf16_t* A, const bf16_t* Bt, int nM, int N, int K, const EpiArgs& E) {
;     ...
;             PG8_LDB(B0, 1, 0); PG8_LDB(B1, 1, 1); PG8_SCHED; PG8_LDA(At, 1, 0); PG8_STAGEA(PG8_SA(0, 1), a2 + hstep);
;             PG8_WAIT_V(8); PG8_WAIT_L(0); PG8_BAR; PG8_MMA(0, 0, At, B0); PG8_MMA(0, 1, At, B1); PG8_BAR; PG8_SCHED;
;             PG8_LDA(At, 1, 1); PG8_STAGEB(PG8_SB(1, 0), b3); PG8_STAGEB(PG8_SB(1, 1), b3 + hstep); PG8_STAGEA(PG8_SA(1, 0), a3);
;             PG8_WAIT_V(8); PG8_WAIT_L(0); PG8_BAR; PG8_MMA(1, 0, At, B0); PG8_MMA(1, 1, At, B1); PG8_BAR; PG8_SCHED;
;         }
	s_add_i32 s59, 0, 0x18000
	s_add_i32 s73, 0, 0x1c000
	v_add_u32_e32 v168, s59, v152
	v_add_u32_e32 v184, s73, v152
	ds_read_b128 v[156:159], v168
	ds_read_b128 v[160:163], v168 offset:1024
	ds_read_b128 v[164:167], v168 offset:2048
	ds_read_b128 v[168:171], v168 offset:3072
	ds_read_b128 v[172:175], v184
	ds_read_b128 v[176:179], v184 offset:1024
	ds_read_b128 v[180:183], v184 offset:2048
	ds_read_b128 v[184:187], v184 offset:3072
	s_add_u32 s84, s84, 0x40000
	s_addc_u32 s85, s85, 0
	s_mov_b32 m0, s89
	v_lshl_add_u64 v[226:227], s[84:85], 0, v[130:131]
	ds_read_b128 v[188:191], v154 offset:32768
	ds_read_b128 v[192:195], v154 offset:33792
	ds_read_b128 v[196:199], v154 offset:34816
	ds_read_b128 v[200:203], v154 offset:35840
	ds_read_b128 v[204:207], v154 offset:36864
	ds_read_b128 v[208:211], v154 offset:37888
	ds_read_b128 v[212:215], v154 offset:38912
	ds_read_b128 v[216:219], v154 offset:39936
	global_load_lds_dwordx4 v[226:227], off
	v_lshl_add_u64 v[226:227], s[84:85], 0, v[134:135]
	s_mov_b32 m0, s90
	s_nop 0
	global_load_lds_dwordx4 v[226:227], off
	s_waitcnt vmcnt(8)
	s_waitcnt lgkmcnt(0)
	s_barrier
	s_waitcnt lgkmcnt(0)
	v_mfma_f32_16x16x32_bf16 v[126:129], v[156:159], v[188:191], v[126:129]
	v_mfma_f32_16x16x32_bf16 v[122:125], v[164:167], v[188:191], v[122:125]
	v_mfma_f32_16x16x32_bf16 v[94:97], v[172:175], v[188:191], v[94:97]
	v_mfma_f32_16x16x32_bf16 v[90:93], v[180:183], v[188:191], v[90:93]
	v_mfma_f32_16x16x32_bf16 v[82:85], v[180:183], v[196:199], v[82:85]
	v_mfma_f32_16x16x32_bf16 v[86:89], v[172:175], v[196:199], v[86:89]
	v_mfma_f32_16x16x32_bf16 v[114:117], v[164:167], v[196:199], v[114:117]
	v_mfma_f32_16x16x32_bf16 v[118:121], v[156:159], v[196:199], v[118:121]
	v_mfma_f32_16x16x32_bf16 v[110:113], v[156:159], v[204:207], v[110:113]
	v_mfma_f32_16x16x32_bf16 v[106:109], v[164:167], v[204:207], v[106:109]
	v_mfma_f32_16x16x32_bf16 v[78:81], v[172:175], v[204:207], v[78:81]
	v_mfma_f32_16x16x32_bf16 v[74:77], v[180:183], v[204:207], v[74:77]
	v_mfma_f32_16x16x32_bf16 v[66:69], v[180:183], v[212:215], v[66:69]
	v_mfma_f32_16x16x32_bf16 v[70:73], v[172:175], v[212:215], v[70:73]
	v_mfma_f32_16x16x32_bf16 v[98:101], v[164:167], v[212:215], v[98:101]
	v_mfma_f32_16x16x32_bf16 v[102:105], v[156:159], v[212:215], v[102:105]
	v_mfma_f32_16x16x32_bf16 v[126:129], v[160:163], v[192:195], v[126:129]
	v_mfma_f32_16x16x32_bf16 v[122:125], v[168:171], v[192:195], v[122:125]
	v_mfma_f32_16x16x32_bf16 v[94:97], v[176:179], v[192:195], v[94:97]
	v_mfma_f32_16x16x32_bf16 v[90:93], v[184:187], v[192:195], v[90:93]
	v_mfma_f32_16x16x32_bf16 v[82:85], v[184:187], v[200:203], v[82:85]
	v_mfma_f32_16x16x32_bf16 v[86:89], v[176:179], v[200:203], v[86:89]
	v_mfma_f32_16x16x32_bf16 v[114:117], v[168:171], v[200:203], v[114:117]
	v_mfma_f32_16x16x32_bf16 v[118:121], v[160:163], v[200:203], v[118:121]
	v_mfma_f32_16x16x32_bf16 v[110:113], v[160:163], v[208:211], v[110:113]
	v_mfma_f32_16x16x32_bf16 v[106:109], v[168:171], v[208:211], v[106:109]
	v_mfma_f32_16x16x32_bf16 v[78:81], v[176:179], v[208:211], v[78:81]
	v_mfma_f32_16x16x32_bf16 v[74:77], v[184:187], v[208:211], v[74:77]
	v_mfma_f32_16x16x32_bf16 v[66:69], v[184:187], v[216:219], v[66:69]
	v_mfma_f32_16x16x32_bf16 v[70:73], v[176:179], v[216:219], v[70:73]
	v_mfma_f32_16x16x32_bf16 v[98:101], v[168:171], v[216:219], v[98:101]
	v_mfma_f32_16x16x32_bf16 v[102:105], v[160:163], v[216:219], v[102:105]
	s_barrier
	s_add_i32 s59, s59, s88
	v_lshl_add_u64 v[150:151], v[150:151], 0, s[68:69]
	s_mov_b32 m0, s59
	ds_read_b128 v[188:191], v154 offset:49152
	ds_read_b128 v[192:195], v154 offset:50176
	ds_read_b128 v[196:199], v154 offset:51200
	ds_read_b128 v[200:203], v154 offset:52224
	ds_read_b128 v[204:207], v154 offset:53248
	ds_read_b128 v[208:211], v154 offset:54272
	ds_read_b128 v[212:215], v154 offset:55296
	ds_read_b128 v[216:219], v154 offset:56320
	global_load_lds_dwordx4 v[150:151], off
	s_add_i32 m0, s59, 0x2000
	s_add_u32 s82, s82, 0x40080
	v_lshl_add_u64 v[150:151], v[220:221], 0, s[68:69]
	s_addc_u32 s83, s83, 0
	s_add_i32 s59, s73, s88
	global_load_lds_dwordx4 v[150:151], off
	v_lshl_add_u64 v[150:151], s[82:83], 0, v[132:133]
	s_mov_b32 m0, s59
	s_nop 0
	global_load_lds_dwordx4 v[150:151], off
	v_lshl_add_u64 v[150:151], s[82:83], 0, v[136:137]
	s_add_i32 m0, s59, 0x2000
	s_nop 0
	global_load_lds_dwordx4 v[150:151], off
	v_lshl_add_u64 v[150:151], v[222:223], 0, s[68:69]
	s_mov_b32 m0, s93
	s_nop 0
	global_load_lds_dwordx4 v[150:151], off
	v_lshl_add_u64 v[150:151], v[224:225], 0, s[68:69]
	s_mov_b32 m0, s94
	s_nop 0
	global_load_lds_dwordx4 v[150:151], off
	s_waitcnt vmcnt(8)
	s_waitcnt lgkmcnt(0)
	s_barrier
	s_waitcnt lgkmcnt(0)
	v_mfma_f32_16x16x32_bf16 v[62:65], v[156:159], v[188:191], v[62:65]
	v_mfma_f32_16x16x32_bf16 v[58:61], v[164:167], v[188:191], v[58:61]
	v_mfma_f32_16x16x32_bf16 v[30:33], v[172:175], v[188:191], v[30:33]
	v_mfma_f32_16x16x32_bf16 v[26:29], v[180:183], v[188:191], v[26:29]
	v_mfma_f32_16x16x32_bf16 v[18:21], v[180:183], v[196:199], v[18:21]
	v_mfma_f32_16x16x32_bf16 v[22:25], v[172:175], v[196:199], v[22:25]
	v_mfma_f32_16x16x32_bf16 v[50:53], v[164:167], v[196:199], v[50:53]
	v_mfma_f32_16x16x32_bf16 v[54:57], v[156:159], v[196:199], v[54:57]
	v_mfma_f32_16x16x32_bf16 v[46:49], v[156:159], v[204:207], v[46:49]
	v_mfma_f32_16x16x32_bf16 v[42:45], v[164:167], v[204:207], v[42:45]
	v_mfma_f32_16x16x32_bf16 v[14:17], v[172:175], v[204:207], v[14:17]
	v_mfma_f32_16x16x32_bf16 v[10:13], v[180:183], v[204:207], v[10:13]
	v_mfma_f32_16x16x32_bf16 v[2:5], v[180:183], v[212:215], v[2:5]
	v_mfma_f32_16x16x32_bf16 v[6:9], v[172:175], v[212:215], v[6:9]
	v_mfma_f32_16x16x32_bf16 v[34:37], v[164:167], v[212:215], v[34:37]
	v_mfma_f32_16x16x32_bf16 v[38:41], v[156:159], v[212:215], v[38:41]
	v_mfma_f32_16x16x32_bf16 v[62:65], v[160:163], v[192:195], v[62:65]
	v_mfma_f32_16x16x32_bf16 v[58:61], v[168:171], v[192:195], v[58:61]
	v_mfma_f32_16x16x32_bf16 v[30:33], v[176:179], v[192:195], v[30:33]
	v_mfma_f32_16x16x32_bf16 v[26:29], v[184:187], v[192:195], v[26:29]
	v_mfma_f32_16x16x32_bf16 v[18:21], v[184:187], v[200:203], v[18:21]
	v_mfma_f32_16x16x32_bf16 v[22:25], v[176:179], v[200:203], v[22:25]
	v_mfma_f32_16x16x32_bf16 v[50:53], v[168:171], v[200:203], v[50:53]
	v_mfma_f32_16x16x32_bf16 v[54:57], v[160:163], v[200:203], v[54:57]
	v_mfma_f32_16x16x32_bf16 v[46:49], v[160:163], v[208:211], v[46:49]
	v_mfma_f32_16x16x32_bf16 v[42:45], v[168:171], v[208:211], v[42:45]
	v_mfma_f32_16x16x32_bf16 v[14:17], v[176:179], v[208:211], v[14:17]
	v_mfma_f32_16x16x32_bf16 v[10:13], v[184:187], v[208:211], v[10:13]
	v_mfma_f32_16x16x32_bf16 v[2:5], v[184:187], v[216:219], v[2:5]
	v_mfma_f32_16x16x32_bf16 v[6:9], v[176:179], v[216:219], v[6:9]
	v_mfma_f32_16x16x32_bf16 v[34:37], v[168:171], v[216:219], v[34:37]
	v_mfma_f32_16x16x32_bf16 v[38:41], v[160:163], v[216:219], v[38:41]
	s_barrier
	s_add_i32 s58, s58, 2
	s_add_u32 s80, s80, 0x100
	s_addc_u32 s81, s81, 0
	s_cmp_gt_u32 s58, 13
	s_cbranch_scc0 .LBB0_413

; #define PG8_STAGEA(bufoff, gbase) PG8_STAGE_(bufoff, gbase, voffA)
; #define PG8_STAGEB(bufoff, gbase) PG8_STAGE_(bufoff, gbase, voffB)
; #define PG8_LDA(dst, b, h) do { _Pragma("unroll") for (int m = 0; m < 4; ++m) _Pragma("unroll") for (int k = 0; k < 2; ++k) dst[m][k] = *(const LAS bf16x8*)(lds + PG8_SA(b, h) + aoff + m * 2048 + k * 1024); } while (0)
; #define PG8_LDB(dst, b, h) do { _Pragma("unroll") for (int n = 0; n < 2; ++n) _Pragma("unroll") for (int k = 0; k < 2; ++k) dst[n][k] = *(const LAS bf16x8*)(lds + PG8_SB(b, h) + boff + n * 2048 + k * 1024); } while (0)
; #define PG8_MMA(ai, bj, At, Bt_) do { __builtin_amdgcn_s_setprio(1); _Pragma("unroll") for (int m = 0; m < 4; ++m) _Pragma("unroll") for (int n = 0; n < 2; ++n) _Pragma("unroll") for (int k = 0; k < 2; ++k) \
;         acc[ai][bj][m][n] = __builtin_amdgcn_mfma_f32_16x16x32_bf16(Bt_[n][k], At[m][k], acc[ai][bj][m][n], 0, 0, 0); __builtin_amdgcn_s_setprio(0); } while (0)
; #define PG8_WAIT_V(n) asm volatile("s_waitcnt vmcnt(" #n ")" ::: "memory")
; #define PG8_WAIT_L(n) asm volatile("s_waitcnt lgkmcnt(" #n ")" ::: "memory")
; #define PG8_BAR __builtin_amdgcn_s_barrier()
; template <int EK, int SK = -1>
; __device__ __forceinline__ void gemm_phase(LAS unsigned char* lds, const bf16_t* A, const bf16_t* Bt, int nM, int N, int K, const EpiArgs& E) {
;     ...
;         const bool has_next = S.next(ui + 1, nxt);
;         const char* nA = has_next ? (const char*)A + (size_t)nxt.pm * tstep : cA; const char* nB = has_next ? (const char*)Bt + (size_t)nxt.pn * tstep : cB;
;         for (int t = 0; t < nt; t += 2) {
;             const bool last = (t == nt - 2);
;             const char* a1 = cA + (size_t)(t + 1) * kstep;
;             const char* a2 = last ? nA : cA + (size_t)(t + 2) * kstep; const char* b2 = last ? nB : cB + (size_t)(t + 2) * kstep;
;             const char* a3 = a2 + kstep; const char* b3 = b2 + kstep;
;             PG8_LDB(B0, 0, 0); PG8_LDB(B1, 0, 1); PG8_SCHED; PG8_LDA(At, 0, 0); PG8_STAGEA(PG8_SA(1, 1), a1 + hstep);
;             PG8_WAIT_V(8); PG8_WAIT_L(0); PG8_BAR; PG8_MMA(0, 0, At, B0); PG8_MMA(0, 1, At, B1); PG8_BAR; PG8_SCHED;
;             PG8_LDA(At, 0, 1); PG8_STAGEB(PG8_SB(0, 0), b2); PG8_STAGEB(PG8_SB(0, 1), b2 + hstep); PG8_STAGEA(PG8_SA(0, 0), a2);
;             PG8_WAIT_V(8); PG8_WAIT_L(0); PG8_BAR; PG8_MMA(1, 0, At, B0); PG8_MMA(1, 1, At, B1); PG8_BAR; PG8_SCHED;
.LBB0_537:
	s_add_u32 s54, s74, 0x100
	s_addc_u32 s55, s75, 0
	s_ashr_i32 s69, s68, 31
	s_lshl_b64 s[56:57], s[68:69], 19
	s_add_u32 s72, s62, s56
	s_addc_u32 s73, s63, s57
	s_and_b64 s[56:57], s[6:7], exec
	s_cselect_b32 s56, s73, s39
	s_cselect_b32 s57, s72, s38
	s_ashr_i32 s41, s40, 31
	s_lshl_b64 s[58:59], s[40:41], 19
	s_add_u32 s70, s81, s58
	s_addc_u32 s71, s82, s59
	s_and_b64 s[58:59], s[6:7], exec
	s_cselect_b32 s41, s71, s75
	s_cselect_b32 s58, s70, s74
	v_lshl_add_u64 v[146:147], s[38:39], 0, v[138:139]
	v_lshl_add_u64 v[148:149], s[38:39], 0, v[140:141]
	s_mov_b32 s59, -2
	s_mov_b64 s[74:75], 0
	v_add_u32_e32 v154, s88, v159
	ds_read_b128 v[150:153], v154
	ds_read_b128 v[164:167], v154 offset:1024
	ds_read_b128 v[168:171], v154 offset:2048
	ds_read_b128 v[172:175], v154 offset:3072
	v_add_u32_e32 v154, s89, v159
	s_add_u32 s69, s38, s74
	ds_read_b128 v[176:179], v154
	ds_read_b128 v[180:183], v154 offset:1024
	ds_read_b128 v[184:187], v154 offset:2048
	ds_read_b128 v[188:191], v154 offset:3072
	s_addc_u32 s76, s39, s75
	s_add_u32 s69, s69, 0x100
	s_addc_u32 s76, s76, 0
	s_add_u32 s91, s54, s74
	s_addc_u32 s77, s55, s75
	s_cmpk_eq_i32 s74, 0x700
	s_cselect_b32 s79, s56, s76
	s_cselect_b32 s78, s57, s69
	s_cselect_b32 s77, s41, s77
	s_cselect_b32 s76, s58, s91
	v_lshl_add_u64 v[154:155], v[146:147], 0, s[74:75]
	s_add_i32 m0, s15, 0xc000
	ds_read_b128 v[192:195], v162
	ds_read_b128 v[196:199], v162 offset:1024
	ds_read_b128 v[200:203], v162 offset:2048
	ds_read_b128 v[204:207], v162 offset:3072
	ds_read_b128 v[208:211], v162 offset:4096
	ds_read_b128 v[212:215], v162 offset:5120
	ds_read_b128 v[216:219], v162 offset:6144
	ds_read_b128 v[220:223], v162 offset:7168
	global_load_lds_dwordx4 v[154:155], off
	v_lshl_add_u64 v[154:155], v[148:149], 0, s[74:75]
	s_add_i32 m0, s15, 0xe000
	s_nop 0
	global_load_lds_dwordx4 v[154:155], off
	s_waitcnt vmcnt(8)
	s_waitcnt lgkmcnt(0)
	s_barrier
	s_waitcnt lgkmcnt(0)
	v_mfma_f32_16x16x32_bf16 v[110:113], v[150:153], v[192:195], 0
	v_mfma_f32_16x16x32_bf16 v[106:109], v[168:171], v[192:195], 0
	v_mfma_f32_16x16x32_bf16 v[78:81], v[176:179], v[192:195], 0
	v_mfma_f32_16x16x32_bf16 v[74:77], v[184:187], v[192:195], 0
	v_mfma_f32_16x16x32_bf16 v[66:69], v[184:187], v[200:203], 0
	v_mfma_f32_16x16x32_bf16 v[70:73], v[176:179], v[200:203], 0
	v_mfma_f32_16x16x32_bf16 v[98:101], v[168:171], v[200:203], 0
	v_mfma_f32_16x16x32_bf16 v[102:105], v[150:153], v[200:203], 0
	v_mfma_f32_16x16x32_bf16 v[94:97], v[150:153], v[208:211], 0
	v_mfma_f32_16x16x32_bf16 v[90:93], v[168:171], v[208:211], 0
	v_mfma_f32_16x16x32_bf16 v[62:65], v[176:179], v[208:211], 0
	v_mfma_f32_16x16x32_bf16 v[58:61], v[184:187], v[208:211], 0
	v_mfma_f32_16x16x32_bf16 v[50:53], v[184:187], v[216:219], 0
	v_mfma_f32_16x16x32_bf16 v[54:57], v[176:179], v[216:219], 0
	v_mfma_f32_16x16x32_bf16 v[82:85], v[168:171], v[216:219], 0
	v_mfma_f32_16x16x32_bf16 v[86:89], v[150:153], v[216:219], 0
	v_mfma_f32_16x16x32_bf16 v[110:113], v[164:167], v[196:199], v[110:113]
	v_mfma_f32_16x16x32_bf16 v[106:109], v[172:175], v[196:199], v[106:109]
	v_mfma_f32_16x16x32_bf16 v[78:81], v[180:183], v[196:199], v[78:81]
	v_mfma_f32_16x16x32_bf16 v[74:77], v[188:191], v[196:199], v[74:77]
	v_mfma_f32_16x16x32_bf16 v[66:69], v[188:191], v[204:207], v[66:69]
	v_mfma_f32_16x16x32_bf16 v[70:73], v[180:183], v[204:207], v[70:73]
	v_mfma_f32_16x16x32_bf16 v[98:101], v[172:175], v[204:207], v[98:101]
	v_mfma_f32_16x16x32_bf16 v[102:105], v[164:167], v[204:207], v[102:105]
	v_mfma_f32_16x16x32_bf16 v[94:97], v[164:167], v[212:215], v[94:97]
	v_mfma_f32_16x16x32_bf16 v[90:93], v[172:175], v[212:215], v[90:93]
	v_mfma_f32_16x16x32_bf16 v[62:65], v[180:183], v[212:215], v[62:65]
	v_mfma_f32_16x16x32_bf16 v[58:61], v[188:191], v[212:215], v[58:61]
	v_mfma_f32_16x16x32_bf16 v[50:53], v[188:191], v[220:223], v[50:53]
	v_mfma_f32_16x16x32_bf16 v[54:57], v[180:183], v[220:223], v[54:57]
	v_mfma_f32_16x16x32_bf16 v[82:85], v[172:175], v[220:223], v[82:85]
	v_mfma_f32_16x16x32_bf16 v[86:89], v[164:167], v[220:223], v[86:89]
	s_barrier
	s_add_i32 s69, s88, s83
	v_lshl_add_u64 v[154:155], s[76:77], 0, v[132:133]
	s_mov_b32 m0, s69
	ds_read_b128 v[192:195], v162 offset:16384
	ds_read_b128 v[196:199], v162 offset:17408
	ds_read_b128 v[200:203], v162 offset:18432
	ds_read_b128 v[204:207], v162 offset:19456
	ds_read_b128 v[208:211], v162 offset:20480
	ds_read_b128 v[212:215], v162 offset:21504
	ds_read_b128 v[216:219], v162 offset:22528
	ds_read_b128 v[220:223], v162 offset:23552
	global_load_lds_dwordx4 v[154:155], off
	s_add_i32 m0, s69, 0x2000
	s_add_u32 s92, s76, 0x40000
	v_lshl_add_u64 v[224:225], s[76:77], 0, v[136:137]
	s_addc_u32 s93, s77, 0
	s_add_i32 s69, s89, s83
	global_load_lds_dwordx4 v[224:225], off
	v_lshl_add_u64 v[226:227], s[92:93], 0, v[132:133]
	s_mov_b32 m0, s69
	v_lshl_add_u64 v[228:229], s[78:79], 0, v[134:135]
	global_load_lds_dwordx4 v[226:227], off
	v_lshl_add_u64 v[226:227], s[92:93], 0, v[136:137]
	s_add_i32 m0, s69, 0x2000
	s_nop 0
	global_load_lds_dwordx4 v[226:227], off
	v_lshl_add_u64 v[226:227], s[78:79], 0, v[130:131]
	s_mov_b32 m0, s15
	s_nop 0
	global_load_lds_dwordx4 v[226:227], off
	s_mov_b32 m0, s17
	s_nop 0
	global_load_lds_dwordx4 v[228:229], off
	s_waitcnt vmcnt(8)
	s_waitcnt lgkmcnt(0)
	s_barrier
; #define PG8_STAGEA(bufoff, gbase) PG8_STAGE_(bufoff, gbase, voffA)
; #define PG8_STAGEB(bufoff, gbase) PG8_STAGE_(bufoff, gbase, voffB)
; #define PG8_LDA(dst, b, h) do { _Pragma("unroll") for (int m = 0; m < 4; ++m) _Pragma("unroll") for (int k = 0; k < 2; ++k) dst[m][k] = *(const LAS bf16x8*)(lds + PG8_SA(b, h) + aoff + m * 2048 + k * 1024); } while (0)
; #define PG8_LDB(dst, b, h) do { _Pragma("unroll") for (int n = 0; n < 2; ++n) _Pragma("unroll") for (int k = 0; k < 2; ++k) dst[n][k] = *(const LAS bf16x8*)(lds + PG8_SB(b, h) + boff + n * 2048 + k * 1024); } while (0)
; #define PG8_MMA(ai, bj, At, Bt_) do { __builtin_amdgcn_s_setprio(1); _Pragma("unroll") for (int m = 0; m < 4; ++m) _Pragma("unroll") for (int n = 0; n < 2; ++n) _Pragma("unroll") for (int k = 0; k < 2; ++k) \
;         acc[ai][bj][m][n] = __builtin_amdgcn_mfma_f32_16x16x32_bf16(Bt_[n][k], At[m][k], acc[ai][bj][m][n], 0, 0, 0); __builtin_amdgcn_s_setprio(0); } while (0)
; #define PG8_WAIT_V(n) asm volatile("s_waitcnt vmcnt(" #n ")" ::: "memory")
; #define PG8_WAIT_L(n) asm volatile("s_waitcnt lgkmcnt(" #n ")" ::: "memory")
; #define PG8_BAR __builtin_amdgcn_s_barrier()
; #define PG8_SCHED __builtin_amdgcn_sched_barrier(0)
; template <int EK, int SK = -1>
; __device__ __forceinline__ void gemm_phase(LAS unsigned char* lds, const bf16_t* A, const bf16_t* Bt, int nM, int N, int K, const EpiArgs& E) {
;     ...
;             PG8_WAIT_V(8); PG8_WAIT_L(0); PG8_BAR; PG8_MMA(1, 0, At, B0); PG8_MMA(1, 1, At, B1); PG8_BAR; PG8_SCHED;
;             PG8_LDB(B0, 1, 0); PG8_LDB(B1, 1, 1); PG8_SCHED; PG8_LDA(At, 1, 0); PG8_STAGEA(PG8_SA(0, 1), a2 + hstep);
;             PG8_WAIT_V(8); PG8_WAIT_L(0); PG8_BAR; PG8_MMA(0, 0, At, B0); PG8_MMA(0, 1, At, B1); PG8_BAR; PG8_SCHED;
;             PG8_LDA(At, 1, 1); PG8_STAGEB(PG8_SB(1, 0), b3); PG8_STAGEB(PG8_SB(1, 1), b3 + hstep); PG8_STAGEA(PG8_SA(1, 0), a3);
	s_waitcnt lgkmcnt(0)
	v_mfma_f32_16x16x32_bf16 v[46:49], v[150:153], v[192:195], 0
	v_mfma_f32_16x16x32_bf16 v[42:45], v[168:171], v[192:195], 0
	v_mfma_f32_16x16x32_bf16 v[14:17], v[176:179], v[192:195], 0
	v_mfma_f32_16x16x32_bf16 v[10:13], v[184:187], v[192:195], 0
	v_mfma_f32_16x16x32_bf16 v[2:5], v[184:187], v[200:203], 0
	v_mfma_f32_16x16x32_bf16 v[6:9], v[176:179], v[200:203], 0
	v_mfma_f32_16x16x32_bf16 v[34:37], v[168:171], v[200:203], 0
	v_mfma_f32_16x16x32_bf16 v[38:41], v[150:153], v[200:203], 0
	v_mfma_f32_16x16x32_bf16 v[30:33], v[150:153], v[208:211], 0
	v_mfma_f32_16x16x32_bf16 v[26:29], v[168:171], v[208:211], 0
	v_mfma_f32_16x16x32_bf16 v[114:117], v[176:179], v[208:211], 0
	v_mfma_f32_16x16x32_bf16 v[118:121], v[184:187], v[208:211], 0
	v_mfma_f32_16x16x32_bf16 v[126:129], v[184:187], v[216:219], 0
	v_mfma_f32_16x16x32_bf16 v[122:125], v[176:179], v[216:219], 0
	v_mfma_f32_16x16x32_bf16 v[18:21], v[168:171], v[216:219], 0
	v_mfma_f32_16x16x32_bf16 v[22:25], v[150:153], v[216:219], 0
	v_mfma_f32_16x16x32_bf16 v[46:49], v[164:167], v[196:199], v[46:49]
	v_mfma_f32_16x16x32_bf16 v[42:45], v[172:175], v[196:199], v[42:45]
	v_mfma_f32_16x16x32_bf16 v[14:17], v[180:183], v[196:199], v[14:17]
	v_mfma_f32_16x16x32_bf16 v[10:13], v[188:191], v[196:199], v[10:13]
	v_mfma_f32_16x16x32_bf16 v[2:5], v[188:191], v[204:207], v[2:5]
	v_mfma_f32_16x16x32_bf16 v[6:9], v[180:183], v[204:207], v[6:9]
	v_mfma_f32_16x16x32_bf16 v[34:37], v[172:175], v[204:207], v[34:37]
	v_mfma_f32_16x16x32_bf16 v[38:41], v[164:167], v[204:207], v[38:41]
	v_mfma_f32_16x16x32_bf16 v[30:33], v[164:167], v[212:215], v[30:33]
	v_mfma_f32_16x16x32_bf16 v[26:29], v[172:175], v[212:215], v[26:29]
	v_mfma_f32_16x16x32_bf16 v[114:117], v[180:183], v[212:215], v[114:117]
	v_mfma_f32_16x16x32_bf16 v[118:121], v[188:191], v[212:215], v[118:121]
	v_mfma_f32_16x16x32_bf16 v[126:129], v[188:191], v[220:223], v[126:129]
	v_mfma_f32_16x16x32_bf16 v[122:125], v[180:183], v[220:223], v[122:125]
	v_mfma_f32_16x16x32_bf16 v[18:21], v[172:175], v[220:223], v[18:21]
	v_mfma_f32_16x16x32_bf16 v[22:25], v[164:167], v[220:223], v[22:25]
	s_barrier
	s_add_i32 s69, 0, 0x18000
	v_add_u32_e32 v163, s69, v159
	s_add_i32 s91, 0, 0x1c000
	ds_read_b128 v[150:153], v163
	ds_read_b128 v[164:167], v163 offset:1024
	ds_read_b128 v[168:171], v163 offset:2048
	ds_read_b128 v[172:175], v163 offset:3072
	v_add_u32_e32 v163, s91, v159
	ds_read_b128 v[176:179], v163
	ds_read_b128 v[180:183], v163 offset:1024
	ds_read_b128 v[184:187], v163 offset:2048
	ds_read_b128 v[188:191], v163 offset:3072
	s_add_u32 s78, s78, 0x40000
	s_addc_u32 s79, s79, 0
	s_mov_b32 m0, s84
	v_lshl_add_u64 v[230:231], s[78:79], 0, v[130:131]
	ds_read_b128 v[192:195], v162 offset:32768
	ds_read_b128 v[196:199], v162 offset:33792
	ds_read_b128 v[200:203], v162 offset:34816
	ds_read_b128 v[204:207], v162 offset:35840
	ds_read_b128 v[208:211], v162 offset:36864
	ds_read_b128 v[212:215], v162 offset:37888
	ds_read_b128 v[216:219], v162 offset:38912
	ds_read_b128 v[220:223], v162 offset:39936
	global_load_lds_dwordx4 v[230:231], off
	v_lshl_add_u64 v[230:231], s[78:79], 0, v[134:135]
	s_mov_b32 m0, s85
	s_nop 0
	global_load_lds_dwordx4 v[230:231], off
	s_waitcnt vmcnt(8)
	s_waitcnt lgkmcnt(0)
	s_barrier
	s_waitcnt lgkmcnt(0)
	v_mfma_f32_16x16x32_bf16 v[110:113], v[150:153], v[192:195], v[110:113]
	v_mfma_f32_16x16x32_bf16 v[106:109], v[168:171], v[192:195], v[106:109]
	v_mfma_f32_16x16x32_bf16 v[78:81], v[176:179], v[192:195], v[78:81]
	v_mfma_f32_16x16x32_bf16 v[74:77], v[184:187], v[192:195], v[74:77]
	v_mfma_f32_16x16x32_bf16 v[66:69], v[184:187], v[200:203], v[66:69]
	v_mfma_f32_16x16x32_bf16 v[70:73], v[176:179], v[200:203], v[70:73]
	v_mfma_f32_16x16x32_bf16 v[98:101], v[168:171], v[200:203], v[98:101]
	v_mfma_f32_16x16x32_bf16 v[102:105], v[150:153], v[200:203], v[102:105]
	v_mfma_f32_16x16x32_bf16 v[94:97], v[150:153], v[208:211], v[94:97]
	v_mfma_f32_16x16x32_bf16 v[90:93], v[168:171], v[208:211], v[90:93]
	v_mfma_f32_16x16x32_bf16 v[62:65], v[176:179], v[208:211], v[62:65]
	v_mfma_f32_16x16x32_bf16 v[58:61], v[184:187], v[208:211], v[58:61]
	v_mfma_f32_16x16x32_bf16 v[50:53], v[184:187], v[216:219], v[50:53]
	v_mfma_f32_16x16x32_bf16 v[54:57], v[176:179], v[216:219], v[54:57]
	v_mfma_f32_16x16x32_bf16 v[82:85], v[168:171], v[216:219], v[82:85]
	v_mfma_f32_16x16x32_bf16 v[86:89], v[150:153], v[216:219], v[86:89]
	v_mfma_f32_16x16x32_bf16 v[110:113], v[164:167], v[196:199], v[110:113]
	v_mfma_f32_16x16x32_bf16 v[106:109], v[172:175], v[196:199], v[106:109]
	v_mfma_f32_16x16x32_bf16 v[78:81], v[180:183], v[196:199], v[78:81]
	v_mfma_f32_16x16x32_bf16 v[74:77], v[188:191], v[196:199], v[74:77]
	v_mfma_f32_16x16x32_bf16 v[66:69], v[188:191], v[204:207], v[66:69]
	v_mfma_f32_16x16x32_bf16 v[70:73], v[180:183], v[204:207], v[70:73]
	v_mfma_f32_16x16x32_bf16 v[98:101], v[172:175], v[204:207], v[98:101]
	v_mfma_f32_16x16x32_bf16 v[102:105], v[164:167], v[204:207], v[102:105]
	v_mfma_f32_16x16x32_bf16 v[94:97], v[164:167], v[212:215], v[94:97]
	v_mfma_f32_16x16x32_bf16 v[90:93], v[172:175], v[212:215], v[90:93]
	v_mfma_f32_16x16x32_bf16 v[62:65], v[180:183], v[212:215], v[62:65]
	v_mfma_f32_16x16x32_bf16 v[58:61], v[188:191], v[212:215], v[58:61]
	v_mfma_f32_16x16x32_bf16 v[50:53], v[188:191], v[220:223], v[50:53]
	v_mfma_f32_16x16x32_bf16 v[54:57], v[180:183], v[220:223], v[54:57]
	v_mfma_f32_16x16x32_bf16 v[82:85], v[172:175], v[220:223], v[82:85]
	v_mfma_f32_16x16x32_bf16 v[86:89], v[164:167], v[220:223], v[86:89]
	s_barrier
; #define PG8_STAGEA(bufoff, gbase) PG8_STAGE_(bufoff, gbase, voffA)
; #define PG8_STAGEB(bufoff, gbase) PG8_STAGE_(bufoff, gbase, voffB)
; #define PG8_LDA(dst, b, h) do { _Pragma("unroll") for (int m = 0; m < 4; ++m) _Pragma("unroll") for (int k = 0; k < 2; ++k) dst[m][k] = *(const LAS bf16x8*)(lds + PG8_SA(b, h) + aoff + m * 2048 + k * 1024); } while (0)
; #define PG8_LDB(dst, b, h) do { _Pragma("unroll") for (int n = 0; n < 2; ++n) _Pragma("unroll") for (int k = 0; k < 2; ++k) dst[n][k] = *(const LAS bf16x8*)(lds + PG8_SB(b, h) + boff + n * 2048 + k * 1024); } while (0)
; #define PG8_MMA(ai, bj, At, Bt_) do { __builtin_amdgcn_s_setprio(1); _Pragma("unroll") for (int m = 0; m < 4; ++m) _Pragma("unroll") for (int n = 0; n < 2; ++n) _Pragma("unroll") for (int k = 0; k < 2; ++k) \
;         acc[ai][bj][m][n] = __builtin_amdgcn_mfma_f32_16x16x32_bf16(Bt_[n][k], At[m][k], acc[ai][bj][m][n], 0, 0, 0); __builtin_amdgcn_s_setprio(0); } while (0)
; #define PG8_WAIT_V(n) asm volatile("s_waitcnt vmcnt(" #n ")" ::: "memory")
; #define PG8_WAIT_L(n) asm volatile("s_waitcnt lgkmcnt(" #n ")" ::: "memory")
; #define PG8_BAR __builtin_amdgcn_s_barrier()
; #define PG8_SCHED __builtin_amdgcn_sched_barrier(0)
; template <int EK, int SK = -1>
; __device__ __forceinline__ void gemm_phase(LAS unsigned char* lds, const bf16_t* A, const bf16_t* Bt, int nM, int N, int K, const EpiArgs& E) {
;     ...
;         for (int t = 0; t < nt; t += 2) {
;             const bool last = (t == nt - 2);
;             const char* a1 = cA + (size_t)(t + 1) * kstep;
;             const char* a2 = last ? nA : cA + (size_t)(t + 2) * kstep; const char* b2 = last ? nB : cB + (size_t)(t + 2) * kstep;
;             const char* a3 = a2 + kstep; const char* b3 = b2 + kstep;
;             PG8_LDB(B0, 0, 0); PG8_LDB(B1, 0, 1); PG8_SCHED; PG8_LDA(At, 0, 0); PG8_STAGEA(PG8_SA(1, 1), a1 + hstep);
;             PG8_WAIT_V(8); PG8_WAIT_L(0); PG8_BAR; PG8_MMA(0, 0, At, B0); PG8_MMA(0, 1, At, B1); PG8_BAR; PG8_SCHED;
;     ...
;             PG8_LDA(At, 1, 1); PG8_STAGEB(PG8_SB(1, 0), b3); PG8_STAGEB(PG8_SB(1, 1), b3 + hstep); PG8_STAGEA(PG8_SA(1, 0), a3);
;             PG8_WAIT_V(8); PG8_WAIT_L(0); PG8_BAR; PG8_MMA(1, 0, At, B0); PG8_MMA(1, 1, At, B1); PG8_BAR; PG8_SCHED;
	s_add_i32 s69, s69, s83
	v_lshl_add_u64 v[154:155], v[154:155], 0, s[10:11]
	s_mov_b32 m0, s69
	ds_read_b128 v[192:195], v162 offset:49152
	ds_read_b128 v[196:199], v162 offset:50176
	ds_read_b128 v[200:203], v162 offset:51200
	ds_read_b128 v[204:207], v162 offset:52224
	ds_read_b128 v[208:211], v162 offset:53248
	ds_read_b128 v[212:215], v162 offset:54272
	ds_read_b128 v[216:219], v162 offset:55296
	ds_read_b128 v[220:223], v162 offset:56320
	global_load_lds_dwordx4 v[154:155], off
	s_add_i32 m0, s69, 0x2000
	s_add_u32 s76, s76, 0x40080
	v_lshl_add_u64 v[154:155], v[224:225], 0, s[10:11]
	s_addc_u32 s77, s77, 0
	s_add_i32 s69, s91, s83
	global_load_lds_dwordx4 v[154:155], off
	v_lshl_add_u64 v[154:155], s[76:77], 0, v[132:133]
	s_mov_b32 m0, s69
	s_nop 0
	global_load_lds_dwordx4 v[154:155], off
	v_lshl_add_u64 v[154:155], s[76:77], 0, v[136:137]
	s_add_i32 m0, s69, 0x2000
	s_nop 0
	global_load_lds_dwordx4 v[154:155], off
	v_lshl_add_u64 v[154:155], v[226:227], 0, s[10:11]
	s_mov_b32 m0, s86
	s_nop 0
	global_load_lds_dwordx4 v[154:155], off
	v_lshl_add_u64 v[154:155], v[228:229], 0, s[10:11]
	s_mov_b32 m0, s87
	s_nop 0
	global_load_lds_dwordx4 v[154:155], off
	s_waitcnt vmcnt(8)
	s_waitcnt lgkmcnt(0)
	s_barrier
	s_waitcnt lgkmcnt(0)
	v_mfma_f32_16x16x32_bf16 v[46:49], v[150:153], v[192:195], v[46:49]
	v_mfma_f32_16x16x32_bf16 v[42:45], v[168:171], v[192:195], v[42:45]
	v_mfma_f32_16x16x32_bf16 v[14:17], v[176:179], v[192:195], v[14:17]
	v_mfma_f32_16x16x32_bf16 v[10:13], v[184:187], v[192:195], v[10:13]
	v_mfma_f32_16x16x32_bf16 v[2:5], v[184:187], v[200:203], v[2:5]
	v_mfma_f32_16x16x32_bf16 v[6:9], v[176:179], v[200:203], v[6:9]
	v_mfma_f32_16x16x32_bf16 v[34:37], v[168:171], v[200:203], v[34:37]
	v_mfma_f32_16x16x32_bf16 v[38:41], v[150:153], v[200:203], v[38:41]
	v_mfma_f32_16x16x32_bf16 v[30:33], v[150:153], v[208:211], v[30:33]
	v_mfma_f32_16x16x32_bf16 v[26:29], v[168:171], v[208:211], v[26:29]
	v_mfma_f32_16x16x32_bf16 v[114:117], v[176:179], v[208:211], v[114:117]
	v_mfma_f32_16x16x32_bf16 v[118:121], v[184:187], v[208:211], v[118:121]
	v_mfma_f32_16x16x32_bf16 v[126:129], v[184:187], v[216:219], v[126:129]
	v_mfma_f32_16x16x32_bf16 v[122:125], v[176:179], v[216:219], v[122:125]
	v_mfma_f32_16x16x32_bf16 v[18:21], v[168:171], v[216:219], v[18:21]
	v_mfma_f32_16x16x32_bf16 v[22:25], v[150:153], v[216:219], v[22:25]
	v_mfma_f32_16x16x32_bf16 v[46:49], v[164:167], v[196:199], v[46:49]
	v_mfma_f32_16x16x32_bf16 v[42:45], v[172:175], v[196:199], v[42:45]
	v_mfma_f32_16x16x32_bf16 v[14:17], v[180:183], v[196:199], v[14:17]
	v_mfma_f32_16x16x32_bf16 v[10:13], v[188:191], v[196:199], v[10:13]
	v_mfma_f32_16x16x32_bf16 v[2:5], v[188:191], v[204:207], v[2:5]
	v_mfma_f32_16x16x32_bf16 v[6:9], v[180:183], v[204:207], v[6:9]
	v_mfma_f32_16x16x32_bf16 v[34:37], v[172:175], v[204:207], v[34:37]
	v_mfma_f32_16x16x32_bf16 v[38:41], v[164:167], v[204:207], v[38:41]
	v_mfma_f32_16x16x32_bf16 v[30:33], v[164:167], v[212:215], v[30:33]
	v_mfma_f32_16x16x32_bf16 v[26:29], v[172:175], v[212:215], v[26:29]
	v_mfma_f32_16x16x32_bf16 v[114:117], v[180:183], v[212:215], v[114:117]
	v_mfma_f32_16x16x32_bf16 v[118:121], v[188:191], v[212:215], v[118:121]
	v_mfma_f32_16x16x32_bf16 v[126:129], v[188:191], v[220:223], v[126:129]
	v_mfma_f32_16x16x32_bf16 v[122:125], v[180:183], v[220:223], v[122:125]
	v_mfma_f32_16x16x32_bf16 v[18:21], v[172:175], v[220:223], v[18:21]
	v_mfma_f32_16x16x32_bf16 v[22:25], v[164:167], v[220:223], v[22:25]
	s_barrier
	s_add_i32 s59, s59, 2
	s_add_u32 s74, s74, 0x100
	s_addc_u32 s75, s75, 0
	s_cmp_gt_u32 s59, 13
	s_cbranch_scc0 .LBB0_538
	s_branch .Lmy_kexit_2
.LBB0_538:
	v_add_u32_e32 v154, s88, v159
	ds_read_b128 v[150:153], v154
	ds_read_b128 v[164:167], v154 offset:1024
	ds_read_b128 v[168:171], v154 offset:2048
	ds_read_b128 v[172:175], v154 offset:3072
	v_add_u32_e32 v154, s89, v159
	s_add_u32 s69, s38, s74
	ds_read_b128 v[176:179], v154
	ds_read_b128 v[180:183], v154 offset:1024
	ds_read_b128 v[184:187], v154 offset:2048
	ds_read_b128 v[188:191], v154 offset:3072
	s_addc_u32 s76, s39, s75
	s_add_u32 s69, s69, 0x100
	s_addc_u32 s76, s76, 0
	s_add_u32 s91, s54, s74
	s_addc_u32 s77, s55, s75
	s_cmpk_eq_i32 s74, 0x700
	s_cselect_b32 s79, s56, s76
	s_cselect_b32 s78, s57, s69
	s_cselect_b32 s77, s41, s77
	s_cselect_b32 s76, s58, s91
	v_lshl_add_u64 v[154:155], v[146:147], 0, s[74:75]
	s_add_i32 m0, s15, 0xc000
	ds_read_b128 v[192:195], v162
	ds_read_b128 v[196:199], v162 offset:1024
	ds_read_b128 v[200:203], v162 offset:2048
	ds_read_b128 v[204:207], v162 offset:3072
	ds_read_b128 v[208:211], v162 offset:4096
	ds_read_b128 v[212:215], v162 offset:5120
	ds_read_b128 v[216:219], v162 offset:6144
	ds_read_b128 v[220:223], v162 offset:7168
	global_load_lds_dwordx4 v[154:155], off
	v_lshl_add_u64 v[154:155], v[148:149], 0, s[74:75]
	s_add_i32 m0, s15, 0xe000
	s_nop 0
	global_load_lds_dwordx4 v[154:155], off
	s_waitcnt vmcnt(8)
	s_waitcnt lgkmcnt(0)
	s_barrier
; #define PG8_STAGEA(bufoff, gbase) PG8_STAGE_(bufoff, gbase, voffA)
; #define PG8_STAGEB(bufoff, gbase) PG8_STAGE_(bufoff, gbase, voffB)
; #define PG8_LDA(dst, b, h) do { _Pragma("unroll") for (int m = 0; m < 4; ++m) _Pragma("unroll") for (int k = 0; k < 2; ++k) dst[m][k] = *(const LAS bf16x8*)(lds + PG8_SA(b, h) + aoff + m * 2048 + k * 1024); } while (0)
; #define PG8_LDB(dst, b, h) do { _Pragma("unroll") for (int n = 0; n < 2; ++n) _Pragma("unroll") for (int k = 0; k < 2; ++k) dst[n][k] = *(const LAS bf16x8*)(lds + PG8_SB(b, h) + boff + n * 2048 + k * 1024); } while (0)
; #define PG8_MMA(ai, bj, At, Bt_) do { __builtin_amdgcn_s_setprio(1); _Pragma("unroll") for (int m = 0; m < 4; ++m) _Pragma("unroll") for (int n = 0; n < 2; ++n) _Pragma("unroll") for (int k = 0; k < 2; ++k) \
;         acc[ai][bj][m][n] = __builtin_amdgcn_mfma_f32_16x16x32_bf16(Bt_[n][k], At[m][k], acc[ai][bj][m][n], 0, 0, 0); __builtin_amdgcn_s_setprio(0); } while (0)
; #define PG8_WAIT_V(n) asm volatile("s_waitcnt vmcnt(" #n ")" ::: "memory")
; #define PG8_WAIT_L(n) asm volatile("s_waitcnt lgkmcnt(" #n ")" ::: "memory")
; #define PG8_BAR __builtin_amdgcn_s_barrier()
; #define PG8_SCHED __builtin_amdgcn_sched_barrier(0)
; template <int EK, int SK = -1>
; __device__ __forceinline__ void gemm_phase(LAS unsigned char* lds, const bf16_t* A, const bf16_t* Bt, int nM, int N, int K, const EpiArgs& E) {
;     ...
;             PG8_WAIT_V(8); PG8_WAIT_L(0); PG8_BAR; PG8_MMA(0, 0, At, B0); PG8_MMA(0, 1, At, B1); PG8_BAR; PG8_SCHED;
;             PG8_LDA(At, 0, 1); PG8_STAGEB(PG8_SB(0, 0), b2); PG8_STAGEB(PG8_SB(0, 1), b2 + hstep); PG8_STAGEA(PG8_SA(0, 0), a2);
;             PG8_WAIT_V(8); PG8_WAIT_L(0); PG8_BAR; PG8_MMA(1, 0, At, B0); PG8_MMA(1, 1, At, B1); PG8_BAR; PG8_SCHED;
;             PG8_LDB(B0, 1, 0); PG8_LDB(B1, 1, 1); PG8_SCHED; PG8_LDA(At, 1, 0); PG8_STAGEA(PG8_SA(0, 1), a2 + hstep);
;             PG8_WAIT_V(8); PG8_WAIT_L(0); PG8_BAR; PG8_MMA(0, 0, At, B0); PG8_MMA(0, 1, At, B1); PG8_BAR; PG8_SCHED;
	s_waitcnt lgkmcnt(0)
	v_mfma_f32_16x16x32_bf16 v[110:113], v[150:153], v[192:195], v[110:113]
	v_mfma_f32_16x16x32_bf16 v[106:109], v[168:171], v[192:195], v[106:109]
	v_mfma_f32_16x16x32_bf16 v[78:81], v[176:179], v[192:195], v[78:81]
	v_mfma_f32_16x16x32_bf16 v[74:77], v[184:187], v[192:195], v[74:77]
	v_mfma_f32_16x16x32_bf16 v[66:69], v[184:187], v[200:203], v[66:69]
	v_mfma_f32_16x16x32_bf16 v[70:73], v[176:179], v[200:203], v[70:73]
	v_mfma_f32_16x16x32_bf16 v[98:101], v[168:171], v[200:203], v[98:101]
	v_mfma_f32_16x16x32_bf16 v[102:105], v[150:153], v[200:203], v[102:105]
	v_mfma_f32_16x16x32_bf16 v[94:97], v[150:153], v[208:211], v[94:97]
	v_mfma_f32_16x16x32_bf16 v[90:93], v[168:171], v[208:211], v[90:93]
	v_mfma_f32_16x16x32_bf16 v[62:65], v[176:179], v[208:211], v[62:65]
	v_mfma_f32_16x16x32_bf16 v[58:61], v[184:187], v[208:211], v[58:61]
	v_mfma_f32_16x16x32_bf16 v[50:53], v[184:187], v[216:219], v[50:53]
	v_mfma_f32_16x16x32_bf16 v[54:57], v[176:179], v[216:219], v[54:57]
	v_mfma_f32_16x16x32_bf16 v[82:85], v[168:171], v[216:219], v[82:85]
	v_mfma_f32_16x16x32_bf16 v[86:89], v[150:153], v[216:219], v[86:89]
	v_mfma_f32_16x16x32_bf16 v[110:113], v[164:167], v[196:199], v[110:113]
	v_mfma_f32_16x16x32_bf16 v[106:109], v[172:175], v[196:199], v[106:109]
	v_mfma_f32_16x16x32_bf16 v[78:81], v[180:183], v[196:199], v[78:81]
	v_mfma_f32_16x16x32_bf16 v[74:77], v[188:191], v[196:199], v[74:77]
	v_mfma_f32_16x16x32_bf16 v[66:69], v[188:191], v[204:207], v[66:69]
	v_mfma_f32_16x16x32_bf16 v[70:73], v[180:183], v[204:207], v[70:73]
	v_mfma_f32_16x16x32_bf16 v[98:101], v[172:175], v[204:207], v[98:101]
	v_mfma_f32_16x16x32_bf16 v[102:105], v[164:167], v[204:207], v[102:105]
	v_mfma_f32_16x16x32_bf16 v[94:97], v[164:167], v[212:215], v[94:97]
	v_mfma_f32_16x16x32_bf16 v[90:93], v[172:175], v[212:215], v[90:93]
	v_mfma_f32_16x16x32_bf16 v[62:65], v[180:183], v[212:215], v[62:65]
	v_mfma_f32_16x16x32_bf16 v[58:61], v[188:191], v[212:215], v[58:61]
	v_mfma_f32_16x16x32_bf16 v[50:53], v[188:191], v[220:223], v[50:53]
	v_mfma_f32_16x16x32_bf16 v[54:57], v[180:183], v[220:223], v[54:57]
	v_mfma_f32_16x16x32_bf16 v[82:85], v[172:175], v[220:223], v[82:85]
	v_mfma_f32_16x16x32_bf16 v[86:89], v[164:167], v[220:223], v[86:89]
	s_barrier
	s_add_i32 s69, s88, s83
	v_lshl_add_u64 v[154:155], s[76:77], 0, v[132:133]
	s_mov_b32 m0, s69
	ds_read_b128 v[192:195], v162 offset:16384
	ds_read_b128 v[196:199], v162 offset:17408
	ds_read_b128 v[200:203], v162 offset:18432
	ds_read_b128 v[204:207], v162 offset:19456
	ds_read_b128 v[208:211], v162 offset:20480
	ds_read_b128 v[212:215], v162 offset:21504
	ds_read_b128 v[216:219], v162 offset:22528
	ds_read_b128 v[220:223], v162 offset:23552
	global_load_lds_dwordx4 v[154:155], off
	s_add_i32 m0, s69, 0x2000
	s_add_u32 s92, s76, 0x40000
	v_lshl_add_u64 v[224:225], s[76:77], 0, v[136:137]
	s_addc_u32 s93, s77, 0
	s_add_i32 s69, s89, s83
	global_load_lds_dwordx4 v[224:225], off
	v_lshl_add_u64 v[226:227], s[92:93], 0, v[132:133]
	s_mov_b32 m0, s69
	v_lshl_add_u64 v[228:229], s[78:79], 0, v[134:135]
	global_load_lds_dwordx4 v[226:227], off
	v_lshl_add_u64 v[226:227], s[92:93], 0, v[136:137]
	s_add_i32 m0, s69, 0x2000
	s_nop 0
	global_load_lds_dwordx4 v[226:227], off
	v_lshl_add_u64 v[226:227], s[78:79], 0, v[130:131]
	s_mov_b32 m0, s15
	s_nop 0
	global_load_lds_dwordx4 v[226:227], off
	s_mov_b32 m0, s17
	s_nop 0
	global_load_lds_dwordx4 v[228:229], off
	s_waitcnt vmcnt(8)
	s_waitcnt lgkmcnt(0)
	s_barrier
	s_waitcnt lgkmcnt(0)
	v_mfma_f32_16x16x32_bf16 v[46:49], v[150:153], v[192:195], v[46:49]
	v_mfma_f32_16x16x32_bf16 v[42:45], v[168:171], v[192:195], v[42:45]
	v_mfma_f32_16x16x32_bf16 v[14:17], v[176:179], v[192:195], v[14:17]
	v_mfma_f32_16x16x32_bf16 v[10:13], v[184:187], v[192:195], v[10:13]
	v_mfma_f32_16x16x32_bf16 v[2:5], v[184:187], v[200:203], v[2:5]
	v_mfma_f32_16x16x32_bf16 v[6:9], v[176:179], v[200:203], v[6:9]
	v_mfma_f32_16x16x32_bf16 v[34:37], v[168:171], v[200:203], v[34:37]
	v_mfma_f32_16x16x32_bf16 v[38:41], v[150:153], v[200:203], v[38:41]
	v_mfma_f32_16x16x32_bf16 v[30:33], v[150:153], v[208:211], v[30:33]
	v_mfma_f32_16x16x32_bf16 v[26:29], v[168:171], v[208:211], v[26:29]
	v_mfma_f32_16x16x32_bf16 v[114:117], v[176:179], v[208:211], v[114:117]
	v_mfma_f32_16x16x32_bf16 v[118:121], v[184:187], v[208:211], v[118:121]
	v_mfma_f32_16x16x32_bf16 v[126:129], v[184:187], v[216:219], v[126:129]
	v_mfma_f32_16x16x32_bf16 v[122:125], v[176:179], v[216:219], v[122:125]
	v_mfma_f32_16x16x32_bf16 v[18:21], v[168:171], v[216:219], v[18:21]
	v_mfma_f32_16x16x32_bf16 v[22:25], v[150:153], v[216:219], v[22:25]
	v_mfma_f32_16x16x32_bf16 v[46:49], v[164:167], v[196:199], v[46:49]
	v_mfma_f32_16x16x32_bf16 v[42:45], v[172:175], v[196:199], v[42:45]
	v_mfma_f32_16x16x32_bf16 v[14:17], v[180:183], v[196:199], v[14:17]
	v_mfma_f32_16x16x32_bf16 v[10:13], v[188:191], v[196:199], v[10:13]
	v_mfma_f32_16x16x32_bf16 v[2:5], v[188:191], v[204:207], v[2:5]
	v_mfma_f32_16x16x32_bf16 v[6:9], v[180:183], v[204:207], v[6:9]
	v_mfma_f32_16x16x32_bf16 v[34:37], v[172:175], v[204:207], v[34:37]
	v_mfma_f32_16x16x32_bf16 v[38:41], v[164:167], v[204:207], v[38:41]
	v_mfma_f32_16x16x32_bf16 v[30:33], v[164:167], v[212:215], v[30:33]
	v_mfma_f32_16x16x32_bf16 v[26:29], v[172:175], v[212:215], v[26:29]
	v_mfma_f32_16x16x32_bf16 v[114:117], v[180:183], v[212:215], v[114:117]
	v_mfma_f32_16x16x32_bf16 v[118:121], v[188:191], v[212:215], v[118:121]
	v_mfma_f32_16x16x32_bf16 v[126:129], v[188:191], v[220:223], v[126:129]
	v_mfma_f32_16x16x32_bf16 v[122:125], v[180:183], v[220:223], v[122:125]
	v_mfma_f32_16x16x32_bf16 v[18:21], v[172:175], v[220:223], v[18:21]
	v_mfma_f32_16x16x32_bf16 v[22:25], v[164:167], v[220:223], v[22:25]
	s_barrier
; #define PG8_STAGEA(bufoff, gbase) PG8_STAGE_(bufoff, gbase, voffA)
; #define PG8_STAGEB(bufoff, gbase) PG8_STAGE_(bufoff, gbase, voffB)
; #define PG8_LDA(dst, b, h) do { _Pragma("unroll") for (int m = 0; m < 4; ++m) _Pragma("unroll") for (int k = 0; k < 2; ++k) dst[m][k] = *(const LAS bf16x8*)(lds + PG8_SA(b, h) + aoff + m * 2048 + k * 1024); } while (0)
; #define PG8_LDB(dst, b, h) do { _Pragma("unroll") for (int n = 0; n < 2; ++n) _Pragma("unroll") for (int k = 0; k < 2; ++k) dst[n][k] = *(const LAS bf16x8*)(lds + PG8_SB(b, h) + boff + n * 2048 + k * 1024); } while (0)
; #define PG8_MMA(ai, bj, At, Bt_) do { __builtin_amdgcn_s_setprio(1); _Pragma("unroll") for (int m = 0; m < 4; ++m) _Pragma("unroll") for (int n = 0; n < 2; ++n) _Pragma("unroll") for (int k = 0; k < 2; ++k) \
;         acc[ai][bj][m][n] = __builtin_amdgcn_mfma_f32_16x16x32_bf16(Bt_[n][k], At[m][k], acc[ai][bj][m][n], 0, 0, 0); __builtin_amdgcn_s_setprio(0); } while (0)
; #define PG8_WAIT_V(n) asm volatile("s_waitcnt vmcnt(" #n ")" ::: "memory")
; #define PG8_WAIT_L(n) asm volatile("s_waitcnt lgkmcnt(" #n ")" ::: "memory")
; #define PG8_BAR __builtin_amdgcn_s_barrier()
; #define PG8_SCHED __builtin_amdgcn_sched_barrier(0)
; template <int EK, int SK = -1>
; __device__ __forceinline__ void gemm_phase(LAS unsigned char* lds, const bf16_t* A, const bf16_t* Bt, int nM, int N, int K, const EpiArgs& E) {
;     ...
;             PG8_LDB(B0, 1, 0); PG8_LDB(B1, 1, 1); PG8_SCHED; PG8_LDA(At, 1, 0); PG8_STAGEA(PG8_SA(0, 1), a2 + hstep);
;             PG8_WAIT_V(8); PG8_WAIT_L(0); PG8_BAR; PG8_MMA(0, 0, At, B0); PG8_MMA(0, 1, At, B1); PG8_BAR; PG8_SCHED;
;             PG8_LDA(At, 1, 1); PG8_STAGEB(PG8_SB(1, 0), b3); PG8_STAGEB(PG8_SB(1, 1), b3 + hstep); PG8_STAGEA(PG8_SA(1, 0), a3);
;             PG8_WAIT_V(8); PG8_WAIT_L(0); PG8_BAR; PG8_MMA(1, 0, At, B0); PG8_MMA(1, 1, At, B1); PG8_BAR; PG8_SCHED;
	s_add_i32 s69, 0, 0x18000
	v_add_u32_e32 v163, s69, v159
	s_add_i32 s91, 0, 0x1c000
	ds_read_b128 v[150:153], v163
	ds_read_b128 v[164:167], v163 offset:1024
	ds_read_b128 v[168:171], v163 offset:2048
	ds_read_b128 v[172:175], v163 offset:3072
	v_add_u32_e32 v163, s91, v159
	ds_read_b128 v[176:179], v163
	ds_read_b128 v[180:183], v163 offset:1024
	ds_read_b128 v[184:187], v163 offset:2048
	ds_read_b128 v[188:191], v163 offset:3072
	s_add_u32 s78, s78, 0x40000
	s_addc_u32 s79, s79, 0
	s_mov_b32 m0, s84
	v_lshl_add_u64 v[230:231], s[78:79], 0, v[130:131]
	ds_read_b128 v[192:195], v162 offset:32768
	ds_read_b128 v[196:199], v162 offset:33792
	ds_read_b128 v[200:203], v162 offset:34816
	ds_read_b128 v[204:207], v162 offset:35840
	ds_read_b128 v[208:211], v162 offset:36864
	ds_read_b128 v[212:215], v162 offset:37888
	ds_read_b128 v[216:219], v162 offset:38912
	ds_read_b128 v[220:223], v162 offset:39936
	global_load_lds_dwordx4 v[230:231], off
	v_lshl_add_u64 v[230:231], s[78:79], 0, v[134:135]
	s_mov_b32 m0, s85
	s_nop 0
	global_load_lds_dwordx4 v[230:231], off
	s_waitcnt vmcnt(8)
	s_waitcnt lgkmcnt(0)
	s_barrier
	s_waitcnt lgkmcnt(0)
	v_mfma_f32_16x16x32_bf16 v[110:113], v[150:153], v[192:195], v[110:113]
	v_mfma_f32_16x16x32_bf16 v[106:109], v[168:171], v[192:195], v[106:109]
	v_mfma_f32_16x16x32_bf16 v[78:81], v[176:179], v[192:195], v[78:81]
	v_mfma_f32_16x16x32_bf16 v[74:77], v[184:187], v[192:195], v[74:77]
	v_mfma_f32_16x16x32_bf16 v[66:69], v[184:187], v[200:203], v[66:69]
	v_mfma_f32_16x16x32_bf16 v[70:73], v[176:179], v[200:203], v[70:73]
	v_mfma_f32_16x16x32_bf16 v[98:101], v[168:171], v[200:203], v[98:101]
	v_mfma_f32_16x16x32_bf16 v[102:105], v[150:153], v[200:203], v[102:105]
	v_mfma_f32_16x16x32_bf16 v[94:97], v[150:153], v[208:211], v[94:97]
	v_mfma_f32_16x16x32_bf16 v[90:93], v[168:171], v[208:211], v[90:93]
	v_mfma_f32_16x16x32_bf16 v[62:65], v[176:179], v[208:211], v[62:65]
	v_mfma_f32_16x16x32_bf16 v[58:61], v[184:187], v[208:211], v[58:61]
	v_mfma_f32_16x16x32_bf16 v[50:53], v[184:187], v[216:219], v[50:53]
	v_mfma_f32_16x16x32_bf16 v[54:57], v[176:179], v[216:219], v[54:57]
	v_mfma_f32_16x16x32_bf16 v[82:85], v[168:171], v[216:219], v[82:85]
	v_mfma_f32_16x16x32_bf16 v[86:89], v[150:153], v[216:219], v[86:89]
	v_mfma_f32_16x16x32_bf16 v[110:113], v[164:167], v[196:199], v[110:113]
	v_mfma_f32_16x16x32_bf16 v[106:109], v[172:175], v[196:199], v[106:109]
	v_mfma_f32_16x16x32_bf16 v[78:81], v[180:183], v[196:199], v[78:81]
	v_mfma_f32_16x16x32_bf16 v[74:77], v[188:191], v[196:199], v[74:77]
	v_mfma_f32_16x16x32_bf16 v[66:69], v[188:191], v[204:207], v[66:69]
	v_mfma_f32_16x16x32_bf16 v[70:73], v[180:183], v[204:207], v[70:73]
	v_mfma_f32_16x16x32_bf16 v[98:101], v[172:175], v[204:207], v[98:101]
	v_mfma_f32_16x16x32_bf16 v[102:105], v[164:167], v[204:207], v[102:105]
	v_mfma_f32_16x16x32_bf16 v[94:97], v[164:167], v[212:215], v[94:97]
	v_mfma_f32_16x16x32_bf16 v[90:93], v[172:175], v[212:215], v[90:93]
	v_mfma_f32_16x16x32_bf16 v[62:65], v[180:183], v[212:215], v[62:65]
	v_mfma_f32_16x16x32_bf16 v[58:61], v[188:191], v[212:215], v[58:61]
	v_mfma_f32_16x16x32_bf16 v[50:53], v[188:191], v[220:223], v[50:53]
	v_mfma_f32_16x16x32_bf16 v[54:57], v[180:183], v[220:223], v[54:57]
	v_mfma_f32_16x16x32_bf16 v[82:85], v[172:175], v[220:223], v[82:85]
	v_mfma_f32_16x16x32_bf16 v[86:89], v[164:167], v[220:223], v[86:89]
	s_barrier
	s_add_i32 s69, s69, s83
	v_lshl_add_u64 v[154:155], v[154:155], 0, s[10:11]
	s_mov_b32 m0, s69
	ds_read_b128 v[192:195], v162 offset:49152
	ds_read_b128 v[196:199], v162 offset:50176
	ds_read_b128 v[200:203], v162 offset:51200
	ds_read_b128 v[204:207], v162 offset:52224
	ds_read_b128 v[208:211], v162 offset:53248
	ds_read_b128 v[212:215], v162 offset:54272
	ds_read_b128 v[216:219], v162 offset:55296
	ds_read_b128 v[220:223], v162 offset:56320
	global_load_lds_dwordx4 v[154:155], off
	s_add_i32 m0, s69, 0x2000
	s_add_u32 s76, s76, 0x40080
	v_lshl_add_u64 v[154:155], v[224:225], 0, s[10:11]
	s_addc_u32 s77, s77, 0
	s_add_i32 s69, s91, s83
	global_load_lds_dwordx4 v[154:155], off
	v_lshl_add_u64 v[154:155], s[76:77], 0, v[132:133]
	s_mov_b32 m0, s69
	s_nop 0
	global_load_lds_dwordx4 v[154:155], off
	v_lshl_add_u64 v[154:155], s[76:77], 0, v[136:137]
	s_add_i32 m0, s69, 0x2000
	s_nop 0
	global_load_lds_dwordx4 v[154:155], off
	v_lshl_add_u64 v[154:155], v[226:227], 0, s[10:11]
	s_mov_b32 m0, s86
	s_nop 0
	global_load_lds_dwordx4 v[154:155], off
	v_lshl_add_u64 v[154:155], v[228:229], 0, s[10:11]
	s_mov_b32 m0, s87
	s_nop 0
	global_load_lds_dwordx4 v[154:155], off
	s_waitcnt vmcnt(8)
	s_waitcnt lgkmcnt(0)
	s_barrier
	s_waitcnt lgkmcnt(0)
	v_mfma_f32_16x16x32_bf16 v[46:49], v[150:153], v[192:195], v[46:49]
	v_mfma_f32_16x16x32_bf16 v[42:45], v[168:171], v[192:195], v[42:45]
	v_mfma_f32_16x16x32_bf16 v[14:17], v[176:179], v[192:195], v[14:17]
	v_mfma_f32_16x16x32_bf16 v[10:13], v[184:187], v[192:195], v[10:13]
	v_mfma_f32_16x16x32_bf16 v[2:5], v[184:187], v[200:203], v[2:5]
	v_mfma_f32_16x16x32_bf16 v[6:9], v[176:179], v[200:203], v[6:9]
	v_mfma_f32_16x16x32_bf16 v[34:37], v[168:171], v[200:203], v[34:37]
	v_mfma_f32_16x16x32_bf16 v[38:41], v[150:153], v[200:203], v[38:41]
	v_mfma_f32_16x16x32_bf16 v[30:33], v[150:153], v[208:211], v[30:33]
	v_mfma_f32_16x16x32_bf16 v[26:29], v[168:171], v[208:211], v[26:29]
	v_mfma_f32_16x16x32_bf16 v[114:117], v[176:179], v[208:211], v[114:117]
	v_mfma_f32_16x16x32_bf16 v[118:121], v[184:187], v[208:211], v[118:121]
	v_mfma_f32_16x16x32_bf16 v[126:129], v[184:187], v[216:219], v[126:129]
	v_mfma_f32_16x16x32_bf16 v[122:125], v[176:179], v[216:219], v[122:125]
	v_mfma_f32_16x16x32_bf16 v[18:21], v[168:171], v[216:219], v[18:21]
	v_mfma_f32_16x16x32_bf16 v[22:25], v[150:153], v[216:219], v[22:25]
	v_mfma_f32_16x16x32_bf16 v[46:49], v[164:167], v[196:199], v[46:49]
	v_mfma_f32_16x16x32_bf16 v[42:45], v[172:175], v[196:199], v[42:45]
	v_mfma_f32_16x16x32_bf16 v[14:17], v[180:183], v[196:199], v[14:17]
	v_mfma_f32_16x16x32_bf16 v[10:13], v[188:191], v[196:199], v[10:13]
	v_mfma_f32_16x16x32_bf16 v[2:5], v[188:191], v[204:207], v[2:5]
	v_mfma_f32_16x16x32_bf16 v[6:9], v[180:183], v[204:207], v[6:9]
	v_mfma_f32_16x16x32_bf16 v[34:37], v[172:175], v[204:207], v[34:37]
	v_mfma_f32_16x16x32_bf16 v[38:41], v[164:167], v[204:207], v[38:41]
	v_mfma_f32_16x16x32_bf16 v[30:33], v[164:167], v[212:215], v[30:33]
	v_mfma_f32_16x16x32_bf16 v[26:29], v[172:175], v[212:215], v[26:29]
	v_mfma_f32_16x16x32_bf16 v[114:117], v[180:183], v[212:215], v[114:117]
	v_mfma_f32_16x16x32_bf16 v[118:121], v[188:191], v[212:215], v[118:121]
	v_mfma_f32_16x16x32_bf16 v[126:129], v[188:191], v[220:223], v[126:129]
	v_mfma_f32_16x16x32_bf16 v[122:125], v[180:183], v[220:223], v[122:125]
	v_mfma_f32_16x16x32_bf16 v[18:21], v[172:175], v[220:223], v[18:21]
	v_mfma_f32_16x16x32_bf16 v[22:25], v[164:167], v[220:223], v[22:25]
	s_barrier
	s_add_i32 s59, s59, 2
	s_add_u32 s74, s74, 0x100
	s_addc_u32 s75, s75, 0
	s_cmp_gt_u32 s59, 13
	s_cbranch_scc0 .LBB0_538

; #define PG8_STAGEA(bufoff, gbase) PG8_STAGE_(bufoff, gbase, voffA)
; #define PG8_STAGEB(bufoff, gbase) PG8_STAGE_(bufoff, gbase, voffB)
; #define PG8_LDA(dst, b, h) do { _Pragma("unroll") for (int m = 0; m < 4; ++m) _Pragma("unroll") for (int k = 0; k < 2; ++k) dst[m][k] = *(const LAS bf16x8*)(lds + PG8_SA(b, h) + aoff + m * 2048 + k * 1024); } while (0)
; #define PG8_LDB(dst, b, h) do { _Pragma("unroll") for (int n = 0; n < 2; ++n) _Pragma("unroll") for (int k = 0; k < 2; ++k) dst[n][k] = *(const LAS bf16x8*)(lds + PG8_SB(b, h) + boff + n * 2048 + k * 1024); } while (0)
; #define PG8_MMA(ai, bj, At, Bt_) do { __builtin_amdgcn_s_setprio(1); _Pragma("unroll") for (int m = 0; m < 4; ++m) _Pragma("unroll") for (int n = 0; n < 2; ++n) _Pragma("unroll") for (int k = 0; k < 2; ++k) \
;         acc[ai][bj][m][n] = __builtin_amdgcn_mfma_f32_16x16x32_bf16(Bt_[n][k], At[m][k], acc[ai][bj][m][n], 0, 0, 0); __builtin_amdgcn_s_setprio(0); } while (0)
; #define PG8_WAIT_V(n) asm volatile("s_waitcnt vmcnt(" #n ")" ::: "memory")
; #define PG8_WAIT_L(n) asm volatile("s_waitcnt lgkmcnt(" #n ")" ::: "memory")
; #define PG8_BAR __builtin_amdgcn_s_barrier()
; template <int EK, int SK = -1>
; __device__ __forceinline__ void gemm_phase(LAS unsigned char* lds, const bf16_t* A, const bf16_t* Bt, int nM, int N, int K, const EpiArgs& E) {
;     ...
;         const bool has_next = S.next(ui + 1, nxt);
;         const char* nA = has_next ? (const char*)A + (size_t)nxt.pm * tstep : cA; const char* nB = has_next ? (const char*)Bt + (size_t)nxt.pn * tstep : cB;
;         for (int t = 0; t < nt; t += 2) {
;             const bool last = (t == nt - 2);
;             const char* a1 = cA + (size_t)(t + 1) * kstep;
;             const char* a2 = last ? nA : cA + (size_t)(t + 2) * kstep; const char* b2 = last ? nB : cB + (size_t)(t + 2) * kstep;
;             const char* a3 = a2 + kstep; const char* b3 = b2 + kstep;
;             PG8_LDB(B0, 0, 0); PG8_LDB(B1, 0, 1); PG8_SCHED; PG8_LDA(At, 0, 0); PG8_STAGEA(PG8_SA(1, 1), a1 + hstep);
;             PG8_WAIT_V(8); PG8_WAIT_L(0); PG8_BAR; PG8_MMA(0, 0, At, B0); PG8_MMA(0, 1, At, B1); PG8_BAR; PG8_SCHED;
;             PG8_LDA(At, 0, 1); PG8_STAGEB(PG8_SB(0, 0), b2); PG8_STAGEB(PG8_SB(0, 1), b2 + hstep); PG8_STAGEA(PG8_SA(0, 0), a2);
;             PG8_WAIT_V(8); PG8_WAIT_L(0); PG8_BAR; PG8_MMA(1, 0, At, B0); PG8_MMA(1, 1, At, B1); PG8_BAR; PG8_SCHED;
.LBB0_792:
	s_add_u32 s77, s38, 0x100
	s_addc_u32 s78, s39, 0
	v_lshl_add_u64 v[146:147], s[14:15], 0, v[138:139]
	v_lshl_add_u64 v[148:149], s[14:15], 0, v[140:141]
	s_mov_b32 s20, -2
	s_mov_b64 s[38:39], 0
	v_add_u32_e32 v150, s71, v152
	ds_read_b128 v[156:159], v150
	ds_read_b128 v[160:163], v150 offset:1024
	ds_read_b128 v[164:167], v150 offset:2048
	ds_read_b128 v[168:171], v150 offset:3072
	v_add_u32_e32 v150, s72, v152
	s_add_u32 s40, s14, s38
	ds_read_b128 v[172:175], v150
	ds_read_b128 v[176:179], v150 offset:1024
	ds_read_b128 v[180:183], v150 offset:2048
	ds_read_b128 v[184:187], v150 offset:3072
	s_addc_u32 s41, s15, s39
	s_add_u32 s40, s40, 0x100
	s_addc_u32 s41, s41, 0
	s_add_u32 s79, s77, s38
	s_addc_u32 s80, s78, s39
	s_cmpk_eq_i32 s38, 0x1500
	s_cselect_b32 s43, s37, s41
	s_cselect_b32 s42, s36, s40
	s_cselect_b32 s41, s11, s80
	s_cselect_b32 s40, s10, s79
	v_lshl_add_u64 v[150:151], v[146:147], 0, s[38:39]
	s_add_i32 m0, s55, 0xc000
	ds_read_b128 v[188:191], v154
	ds_read_b128 v[192:195], v154 offset:1024
	ds_read_b128 v[196:199], v154 offset:2048
	ds_read_b128 v[200:203], v154 offset:3072
	ds_read_b128 v[204:207], v154 offset:4096
	ds_read_b128 v[208:211], v154 offset:5120
	ds_read_b128 v[212:215], v154 offset:6144
	ds_read_b128 v[216:219], v154 offset:7168
	global_load_lds_dwordx4 v[150:151], off
	v_lshl_add_u64 v[150:151], v[148:149], 0, s[38:39]
	s_add_i32 m0, s55, 0xe000
	s_nop 0
	global_load_lds_dwordx4 v[150:151], off
	s_waitcnt vmcnt(8)
	s_waitcnt lgkmcnt(0)
	s_barrier
	s_waitcnt lgkmcnt(0)
	v_mfma_f32_16x16x32_bf16 v[126:129], v[156:159], v[188:191], 0
	v_mfma_f32_16x16x32_bf16 v[122:125], v[164:167], v[188:191], 0
	v_mfma_f32_16x16x32_bf16 v[94:97], v[172:175], v[188:191], 0
	v_mfma_f32_16x16x32_bf16 v[90:93], v[180:183], v[188:191], 0
	v_mfma_f32_16x16x32_bf16 v[82:85], v[180:183], v[196:199], 0
	v_mfma_f32_16x16x32_bf16 v[86:89], v[172:175], v[196:199], 0
	v_mfma_f32_16x16x32_bf16 v[114:117], v[164:167], v[196:199], 0
	v_mfma_f32_16x16x32_bf16 v[118:121], v[156:159], v[196:199], 0
	v_mfma_f32_16x16x32_bf16 v[110:113], v[156:159], v[204:207], 0
	v_mfma_f32_16x16x32_bf16 v[106:109], v[164:167], v[204:207], 0
	v_mfma_f32_16x16x32_bf16 v[78:81], v[172:175], v[204:207], 0
	v_mfma_f32_16x16x32_bf16 v[74:77], v[180:183], v[204:207], 0
	v_mfma_f32_16x16x32_bf16 v[66:69], v[180:183], v[212:215], 0
	v_mfma_f32_16x16x32_bf16 v[70:73], v[172:175], v[212:215], 0
	v_mfma_f32_16x16x32_bf16 v[98:101], v[164:167], v[212:215], 0
	v_mfma_f32_16x16x32_bf16 v[102:105], v[156:159], v[212:215], 0
	v_mfma_f32_16x16x32_bf16 v[126:129], v[160:163], v[192:195], v[126:129]
	v_mfma_f32_16x16x32_bf16 v[122:125], v[168:171], v[192:195], v[122:125]
	v_mfma_f32_16x16x32_bf16 v[94:97], v[176:179], v[192:195], v[94:97]
	v_mfma_f32_16x16x32_bf16 v[90:93], v[184:187], v[192:195], v[90:93]
	v_mfma_f32_16x16x32_bf16 v[82:85], v[184:187], v[200:203], v[82:85]
	v_mfma_f32_16x16x32_bf16 v[86:89], v[176:179], v[200:203], v[86:89]
	v_mfma_f32_16x16x32_bf16 v[114:117], v[168:171], v[200:203], v[114:117]
	v_mfma_f32_16x16x32_bf16 v[118:121], v[160:163], v[200:203], v[118:121]
	v_mfma_f32_16x16x32_bf16 v[110:113], v[160:163], v[208:211], v[110:113]
	v_mfma_f32_16x16x32_bf16 v[106:109], v[168:171], v[208:211], v[106:109]
	v_mfma_f32_16x16x32_bf16 v[78:81], v[176:179], v[208:211], v[78:81]
	v_mfma_f32_16x16x32_bf16 v[74:77], v[184:187], v[208:211], v[74:77]
	v_mfma_f32_16x16x32_bf16 v[66:69], v[184:187], v[216:219], v[66:69]
	v_mfma_f32_16x16x32_bf16 v[70:73], v[176:179], v[216:219], v[70:73]
	v_mfma_f32_16x16x32_bf16 v[98:101], v[168:171], v[216:219], v[98:101]
	v_mfma_f32_16x16x32_bf16 v[102:105], v[160:163], v[216:219], v[102:105]
	s_barrier
	s_add_i32 s79, s71, s54
	v_lshl_add_u64 v[150:151], s[40:41], 0, v[132:133]
	s_mov_b32 m0, s79
	ds_read_b128 v[188:191], v154 offset:16384
	ds_read_b128 v[192:195], v154 offset:17408
	ds_read_b128 v[196:199], v154 offset:18432
	ds_read_b128 v[200:203], v154 offset:19456
	ds_read_b128 v[204:207], v154 offset:20480
	ds_read_b128 v[208:211], v154 offset:21504
	ds_read_b128 v[212:215], v154 offset:22528
	ds_read_b128 v[216:219], v154 offset:23552
	global_load_lds_dwordx4 v[150:151], off
	s_add_i32 m0, s79, 0x2000
	s_add_u32 s80, s40, 0xb0000
	v_lshl_add_u64 v[220:221], s[40:41], 0, v[136:137]
	s_addc_u32 s81, s41, 0
	s_add_i32 s79, s72, s54
	global_load_lds_dwordx4 v[220:221], off
	v_lshl_add_u64 v[222:223], s[80:81], 0, v[132:133]
	s_mov_b32 m0, s79
	v_lshl_add_u64 v[224:225], s[42:43], 0, v[134:135]
	global_load_lds_dwordx4 v[222:223], off
	v_lshl_add_u64 v[222:223], s[80:81], 0, v[136:137]
	s_add_i32 m0, s79, 0x2000
	s_nop 0
	global_load_lds_dwordx4 v[222:223], off
	v_lshl_add_u64 v[222:223], s[42:43], 0, v[130:131]
	s_mov_b32 m0, s55
	s_nop 0
	global_load_lds_dwordx4 v[222:223], off
	s_mov_b32 m0, s56
	s_nop 0
	global_load_lds_dwordx4 v[224:225], off
	s_waitcnt vmcnt(8)
	s_waitcnt lgkmcnt(0)
	s_barrier
; #define PG8_STAGEA(bufoff, gbase) PG8_STAGE_(bufoff, gbase, voffA)
; #define PG8_STAGEB(bufoff, gbase) PG8_STAGE_(bufoff, gbase, voffB)
; #define PG8_LDA(dst, b, h) do { _Pragma("unroll") for (int m = 0; m < 4; ++m) _Pragma("unroll") for (int k = 0; k < 2; ++k) dst[m][k] = *(const LAS bf16x8*)(lds + PG8_SA(b, h) + aoff + m * 2048 + k * 1024); } while (0)
; #define PG8_LDB(dst, b, h) do { _Pragma("unroll") for (int n = 0; n < 2; ++n) _Pragma("unroll") for (int k = 0; k < 2; ++k) dst[n][k] = *(const LAS bf16x8*)(lds + PG8_SB(b, h) + boff + n * 2048 + k * 1024); } while (0)
; #define PG8_MMA(ai, bj, At, Bt_) do { __builtin_amdgcn_s_setprio(1); _Pragma("unroll") for (int m = 0; m < 4; ++m) _Pragma("unroll") for (int n = 0; n < 2; ++n) _Pragma("unroll") for (int k = 0; k < 2; ++k) \
;         acc[ai][bj][m][n] = __builtin_amdgcn_mfma_f32_16x16x32_bf16(Bt_[n][k], At[m][k], acc[ai][bj][m][n], 0, 0, 0); __builtin_amdgcn_s_setprio(0); } while (0)
; #define PG8_WAIT_V(n) asm volatile("s_waitcnt vmcnt(" #n ")" ::: "memory")
; #define PG8_WAIT_L(n) asm volatile("s_waitcnt lgkmcnt(" #n ")" ::: "memory")
; #define PG8_BAR __builtin_amdgcn_s_barrier()
; #define PG8_SCHED __builtin_amdgcn_sched_barrier(0)
; template <int EK, int SK = -1>
; __device__ __forceinline__ void gemm_phase(LAS unsigned char* lds, const bf16_t* A, const bf16_t* Bt, int nM, int N, int K, const EpiArgs& E) {
;     ...
;             PG8_WAIT_V(8); PG8_WAIT_L(0); PG8_BAR; PG8_MMA(1, 0, At, B0); PG8_MMA(1, 1, At, B1); PG8_BAR; PG8_SCHED;
;             PG8_LDB(B0, 1, 0); PG8_LDB(B1, 1, 1); PG8_SCHED; PG8_LDA(At, 1, 0); PG8_STAGEA(PG8_SA(0, 1), a2 + hstep);
;             PG8_WAIT_V(8); PG8_WAIT_L(0); PG8_BAR; PG8_MMA(0, 0, At, B0); PG8_MMA(0, 1, At, B1); PG8_BAR; PG8_SCHED;
;             PG8_LDA(At, 1, 1); PG8_STAGEB(PG8_SB(1, 0), b3); PG8_STAGEB(PG8_SB(1, 1), b3 + hstep); PG8_STAGEA(PG8_SA(1, 0), a3);
	s_waitcnt lgkmcnt(0)
	v_mfma_f32_16x16x32_bf16 v[62:65], v[156:159], v[188:191], 0
	v_mfma_f32_16x16x32_bf16 v[58:61], v[164:167], v[188:191], 0
	v_mfma_f32_16x16x32_bf16 v[30:33], v[172:175], v[188:191], 0
	v_mfma_f32_16x16x32_bf16 v[26:29], v[180:183], v[188:191], 0
	v_mfma_f32_16x16x32_bf16 v[18:21], v[180:183], v[196:199], 0
	v_mfma_f32_16x16x32_bf16 v[22:25], v[172:175], v[196:199], 0
	v_mfma_f32_16x16x32_bf16 v[50:53], v[164:167], v[196:199], 0
	v_mfma_f32_16x16x32_bf16 v[54:57], v[156:159], v[196:199], 0
	v_mfma_f32_16x16x32_bf16 v[46:49], v[156:159], v[204:207], 0
	v_mfma_f32_16x16x32_bf16 v[42:45], v[164:167], v[204:207], 0
	v_mfma_f32_16x16x32_bf16 v[14:17], v[172:175], v[204:207], 0
	v_mfma_f32_16x16x32_bf16 v[10:13], v[180:183], v[204:207], 0
	v_mfma_f32_16x16x32_bf16 v[2:5], v[180:183], v[212:215], 0
	v_mfma_f32_16x16x32_bf16 v[6:9], v[172:175], v[212:215], 0
	v_mfma_f32_16x16x32_bf16 v[34:37], v[164:167], v[212:215], 0
	v_mfma_f32_16x16x32_bf16 v[38:41], v[156:159], v[212:215], 0
	v_mfma_f32_16x16x32_bf16 v[62:65], v[160:163], v[192:195], v[62:65]
	v_mfma_f32_16x16x32_bf16 v[58:61], v[168:171], v[192:195], v[58:61]
	v_mfma_f32_16x16x32_bf16 v[30:33], v[176:179], v[192:195], v[30:33]
	v_mfma_f32_16x16x32_bf16 v[26:29], v[184:187], v[192:195], v[26:29]
	v_mfma_f32_16x16x32_bf16 v[18:21], v[184:187], v[200:203], v[18:21]
	v_mfma_f32_16x16x32_bf16 v[22:25], v[176:179], v[200:203], v[22:25]
	v_mfma_f32_16x16x32_bf16 v[50:53], v[168:171], v[200:203], v[50:53]
	v_mfma_f32_16x16x32_bf16 v[54:57], v[160:163], v[200:203], v[54:57]
	v_mfma_f32_16x16x32_bf16 v[46:49], v[160:163], v[208:211], v[46:49]
	v_mfma_f32_16x16x32_bf16 v[42:45], v[168:171], v[208:211], v[42:45]
	v_mfma_f32_16x16x32_bf16 v[14:17], v[176:179], v[208:211], v[14:17]
	v_mfma_f32_16x16x32_bf16 v[10:13], v[184:187], v[208:211], v[10:13]
	v_mfma_f32_16x16x32_bf16 v[2:5], v[184:187], v[216:219], v[2:5]
	v_mfma_f32_16x16x32_bf16 v[6:9], v[176:179], v[216:219], v[6:9]
	v_mfma_f32_16x16x32_bf16 v[34:37], v[168:171], v[216:219], v[34:37]
	v_mfma_f32_16x16x32_bf16 v[38:41], v[160:163], v[216:219], v[38:41]
	s_barrier
	s_add_i32 s79, 0, 0x18000
	s_add_i32 s80, 0, 0x1c000
	v_add_u32_e32 v168, s79, v152
	v_add_u32_e32 v184, s80, v152
	ds_read_b128 v[156:159], v168
	ds_read_b128 v[160:163], v168 offset:1024
	ds_read_b128 v[164:167], v168 offset:2048
	ds_read_b128 v[168:171], v168 offset:3072
	ds_read_b128 v[172:175], v184
	ds_read_b128 v[176:179], v184 offset:1024
	ds_read_b128 v[180:183], v184 offset:2048
	ds_read_b128 v[184:187], v184 offset:3072
	s_add_u32 s42, s42, 0xb0000
	s_addc_u32 s43, s43, 0
	s_mov_b32 m0, s57
	v_lshl_add_u64 v[226:227], s[42:43], 0, v[130:131]
	ds_read_b128 v[188:191], v154 offset:32768
	ds_read_b128 v[192:195], v154 offset:33792
	ds_read_b128 v[196:199], v154 offset:34816
	ds_read_b128 v[200:203], v154 offset:35840
	ds_read_b128 v[204:207], v154 offset:36864
	ds_read_b128 v[208:211], v154 offset:37888
	ds_read_b128 v[212:215], v154 offset:38912
	ds_read_b128 v[216:219], v154 offset:39936
	global_load_lds_dwordx4 v[226:227], off
	v_lshl_add_u64 v[226:227], s[42:43], 0, v[134:135]
	s_mov_b32 m0, s58
	s_nop 0
	global_load_lds_dwordx4 v[226:227], off
	s_waitcnt vmcnt(8)
	s_waitcnt lgkmcnt(0)
	s_barrier
	s_waitcnt lgkmcnt(0)
	v_mfma_f32_16x16x32_bf16 v[126:129], v[156:159], v[188:191], v[126:129]
	v_mfma_f32_16x16x32_bf16 v[122:125], v[164:167], v[188:191], v[122:125]
	v_mfma_f32_16x16x32_bf16 v[94:97], v[172:175], v[188:191], v[94:97]
	v_mfma_f32_16x16x32_bf16 v[90:93], v[180:183], v[188:191], v[90:93]
	v_mfma_f32_16x16x32_bf16 v[82:85], v[180:183], v[196:199], v[82:85]
	v_mfma_f32_16x16x32_bf16 v[86:89], v[172:175], v[196:199], v[86:89]
	v_mfma_f32_16x16x32_bf16 v[114:117], v[164:167], v[196:199], v[114:117]
	v_mfma_f32_16x16x32_bf16 v[118:121], v[156:159], v[196:199], v[118:121]
	v_mfma_f32_16x16x32_bf16 v[110:113], v[156:159], v[204:207], v[110:113]
	v_mfma_f32_16x16x32_bf16 v[106:109], v[164:167], v[204:207], v[106:109]
	v_mfma_f32_16x16x32_bf16 v[78:81], v[172:175], v[204:207], v[78:81]
	v_mfma_f32_16x16x32_bf16 v[74:77], v[180:183], v[204:207], v[74:77]
	v_mfma_f32_16x16x32_bf16 v[66:69], v[180:183], v[212:215], v[66:69]
	v_mfma_f32_16x16x32_bf16 v[70:73], v[172:175], v[212:215], v[70:73]
	v_mfma_f32_16x16x32_bf16 v[98:101], v[164:167], v[212:215], v[98:101]
	v_mfma_f32_16x16x32_bf16 v[102:105], v[156:159], v[212:215], v[102:105]
	v_mfma_f32_16x16x32_bf16 v[126:129], v[160:163], v[192:195], v[126:129]
	v_mfma_f32_16x16x32_bf16 v[122:125], v[168:171], v[192:195], v[122:125]
	v_mfma_f32_16x16x32_bf16 v[94:97], v[176:179], v[192:195], v[94:97]
	v_mfma_f32_16x16x32_bf16 v[90:93], v[184:187], v[192:195], v[90:93]
	v_mfma_f32_16x16x32_bf16 v[82:85], v[184:187], v[200:203], v[82:85]
	v_mfma_f32_16x16x32_bf16 v[86:89], v[176:179], v[200:203], v[86:89]
	v_mfma_f32_16x16x32_bf16 v[114:117], v[168:171], v[200:203], v[114:117]
	v_mfma_f32_16x16x32_bf16 v[118:121], v[160:163], v[200:203], v[118:121]
	v_mfma_f32_16x16x32_bf16 v[110:113], v[160:163], v[208:211], v[110:113]
	v_mfma_f32_16x16x32_bf16 v[106:109], v[168:171], v[208:211], v[106:109]
	v_mfma_f32_16x16x32_bf16 v[78:81], v[176:179], v[208:211], v[78:81]
	v_mfma_f32_16x16x32_bf16 v[74:77], v[184:187], v[208:211], v[74:77]
	v_mfma_f32_16x16x32_bf16 v[66:69], v[184:187], v[216:219], v[66:69]
	v_mfma_f32_16x16x32_bf16 v[70:73], v[176:179], v[216:219], v[70:73]
	v_mfma_f32_16x16x32_bf16 v[98:101], v[168:171], v[216:219], v[98:101]
	v_mfma_f32_16x16x32_bf16 v[102:105], v[160:163], v[216:219], v[102:105]
	s_barrier
; #define PG8_STAGEA(bufoff, gbase) PG8_STAGE_(bufoff, gbase, voffA)
; #define PG8_STAGEB(bufoff, gbase) PG8_STAGE_(bufoff, gbase, voffB)
; #define PG8_LDA(dst, b, h) do { _Pragma("unroll") for (int m = 0; m < 4; ++m) _Pragma("unroll") for (int k = 0; k < 2; ++k) dst[m][k] = *(const LAS bf16x8*)(lds + PG8_SA(b, h) + aoff + m * 2048 + k * 1024); } while (0)
; #define PG8_LDB(dst, b, h) do { _Pragma("unroll") for (int n = 0; n < 2; ++n) _Pragma("unroll") for (int k = 0; k < 2; ++k) dst[n][k] = *(const LAS bf16x8*)(lds + PG8_SB(b, h) + boff + n * 2048 + k * 1024); } while (0)
; #define PG8_MMA(ai, bj, At, Bt_) do { __builtin_amdgcn_s_setprio(1); _Pragma("unroll") for (int m = 0; m < 4; ++m) _Pragma("unroll") for (int n = 0; n < 2; ++n) _Pragma("unroll") for (int k = 0; k < 2; ++k) \
;         acc[ai][bj][m][n] = __builtin_amdgcn_mfma_f32_16x16x32_bf16(Bt_[n][k], At[m][k], acc[ai][bj][m][n], 0, 0, 0); __builtin_amdgcn_s_setprio(0); } while (0)
; #define PG8_WAIT_V(n) asm volatile("s_waitcnt vmcnt(" #n ")" ::: "memory")
; #define PG8_WAIT_L(n) asm volatile("s_waitcnt lgkmcnt(" #n ")" ::: "memory")
; #define PG8_BAR __builtin_amdgcn_s_barrier()
; #define PG8_SCHED __builtin_amdgcn_sched_barrier(0)
; template <int EK, int SK = -1>
; __device__ __forceinline__ void gemm_phase(LAS unsigned char* lds, const bf16_t* A, const bf16_t* Bt, int nM, int N, int K, const EpiArgs& E) {
;     ...
;         for (int t = 0; t < nt; t += 2) {
;             const bool last = (t == nt - 2);
;             const char* a1 = cA + (size_t)(t + 1) * kstep;
;             const char* a2 = last ? nA : cA + (size_t)(t + 2) * kstep; const char* b2 = last ? nB : cB + (size_t)(t + 2) * kstep;
;             const char* a3 = a2 + kstep; const char* b3 = b2 + kstep;
;             PG8_LDB(B0, 0, 0); PG8_LDB(B1, 0, 1); PG8_SCHED; PG8_LDA(At, 0, 0); PG8_STAGEA(PG8_SA(1, 1), a1 + hstep);
;             PG8_WAIT_V(8); PG8_WAIT_L(0); PG8_BAR; PG8_MMA(0, 0, At, B0); PG8_MMA(0, 1, At, B1); PG8_BAR; PG8_SCHED;
;     ...
;             PG8_LDA(At, 1, 1); PG8_STAGEB(PG8_SB(1, 0), b3); PG8_STAGEB(PG8_SB(1, 1), b3 + hstep); PG8_STAGEA(PG8_SA(1, 0), a3);
;             PG8_WAIT_V(8); PG8_WAIT_L(0); PG8_BAR; PG8_MMA(1, 0, At, B0); PG8_MMA(1, 1, At, B1); PG8_BAR; PG8_SCHED;
	s_add_i32 s42, s79, s54
	v_lshl_add_u64 v[150:151], v[150:151], 0, s[22:23]
	s_mov_b32 m0, s42
	ds_read_b128 v[188:191], v154 offset:49152
	ds_read_b128 v[192:195], v154 offset:50176
	ds_read_b128 v[196:199], v154 offset:51200
	ds_read_b128 v[200:203], v154 offset:52224
	ds_read_b128 v[204:207], v154 offset:53248
	ds_read_b128 v[208:211], v154 offset:54272
	ds_read_b128 v[212:215], v154 offset:55296
	ds_read_b128 v[216:219], v154 offset:56320
	global_load_lds_dwordx4 v[150:151], off
	s_add_i32 m0, s42, 0x2000
	s_add_u32 s40, s40, 0xb0080
	v_lshl_add_u64 v[150:151], v[220:221], 0, s[22:23]
	s_addc_u32 s41, s41, 0
	s_add_i32 s42, s80, s54
	global_load_lds_dwordx4 v[150:151], off
	v_lshl_add_u64 v[150:151], s[40:41], 0, v[132:133]
	s_mov_b32 m0, s42
	s_nop 0
	global_load_lds_dwordx4 v[150:151], off
	v_lshl_add_u64 v[150:151], s[40:41], 0, v[136:137]
	s_add_i32 m0, s42, 0x2000
	s_nop 0
	global_load_lds_dwordx4 v[150:151], off
	v_lshl_add_u64 v[150:151], v[222:223], 0, s[22:23]
	s_mov_b32 m0, s69
	s_nop 0
	global_load_lds_dwordx4 v[150:151], off
	v_lshl_add_u64 v[150:151], v[224:225], 0, s[22:23]
	s_mov_b32 m0, s70
	s_nop 0
	global_load_lds_dwordx4 v[150:151], off
	s_waitcnt vmcnt(8)
	s_waitcnt lgkmcnt(0)
	s_barrier
	s_waitcnt lgkmcnt(0)
	v_mfma_f32_16x16x32_bf16 v[62:65], v[156:159], v[188:191], v[62:65]
	v_mfma_f32_16x16x32_bf16 v[58:61], v[164:167], v[188:191], v[58:61]
	v_mfma_f32_16x16x32_bf16 v[30:33], v[172:175], v[188:191], v[30:33]
	v_mfma_f32_16x16x32_bf16 v[26:29], v[180:183], v[188:191], v[26:29]
	v_mfma_f32_16x16x32_bf16 v[18:21], v[180:183], v[196:199], v[18:21]
	v_mfma_f32_16x16x32_bf16 v[22:25], v[172:175], v[196:199], v[22:25]
	v_mfma_f32_16x16x32_bf16 v[50:53], v[164:167], v[196:199], v[50:53]
	v_mfma_f32_16x16x32_bf16 v[54:57], v[156:159], v[196:199], v[54:57]
	v_mfma_f32_16x16x32_bf16 v[46:49], v[156:159], v[204:207], v[46:49]
	v_mfma_f32_16x16x32_bf16 v[42:45], v[164:167], v[204:207], v[42:45]
	v_mfma_f32_16x16x32_bf16 v[14:17], v[172:175], v[204:207], v[14:17]
	v_mfma_f32_16x16x32_bf16 v[10:13], v[180:183], v[204:207], v[10:13]
	v_mfma_f32_16x16x32_bf16 v[2:5], v[180:183], v[212:215], v[2:5]
	v_mfma_f32_16x16x32_bf16 v[6:9], v[172:175], v[212:215], v[6:9]
	v_mfma_f32_16x16x32_bf16 v[34:37], v[164:167], v[212:215], v[34:37]
	v_mfma_f32_16x16x32_bf16 v[38:41], v[156:159], v[212:215], v[38:41]
	v_mfma_f32_16x16x32_bf16 v[62:65], v[160:163], v[192:195], v[62:65]
	v_mfma_f32_16x16x32_bf16 v[58:61], v[168:171], v[192:195], v[58:61]
	v_mfma_f32_16x16x32_bf16 v[30:33], v[176:179], v[192:195], v[30:33]
	v_mfma_f32_16x16x32_bf16 v[26:29], v[184:187], v[192:195], v[26:29]
	v_mfma_f32_16x16x32_bf16 v[18:21], v[184:187], v[200:203], v[18:21]
	v_mfma_f32_16x16x32_bf16 v[22:25], v[176:179], v[200:203], v[22:25]
	v_mfma_f32_16x16x32_bf16 v[50:53], v[168:171], v[200:203], v[50:53]
	v_mfma_f32_16x16x32_bf16 v[54:57], v[160:163], v[200:203], v[54:57]
	v_mfma_f32_16x16x32_bf16 v[46:49], v[160:163], v[208:211], v[46:49]
	v_mfma_f32_16x16x32_bf16 v[42:45], v[168:171], v[208:211], v[42:45]
	v_mfma_f32_16x16x32_bf16 v[14:17], v[176:179], v[208:211], v[14:17]
	v_mfma_f32_16x16x32_bf16 v[10:13], v[184:187], v[208:211], v[10:13]
	v_mfma_f32_16x16x32_bf16 v[2:5], v[184:187], v[216:219], v[2:5]
	v_mfma_f32_16x16x32_bf16 v[6:9], v[176:179], v[216:219], v[6:9]
	v_mfma_f32_16x16x32_bf16 v[34:37], v[168:171], v[216:219], v[34:37]
	v_mfma_f32_16x16x32_bf16 v[38:41], v[160:163], v[216:219], v[38:41]
	s_barrier
	s_add_i32 s20, s20, 2
	s_add_u32 s38, s38, 0x100
	s_addc_u32 s39, s39, 0
	s_cmp_gt_u32 s20, 41
	s_cbranch_scc0 .LBB0_793
	s_branch .Lmy_kexit_3
.LBB0_793:
	v_add_u32_e32 v150, s71, v152
	ds_read_b128 v[156:159], v150
	ds_read_b128 v[160:163], v150 offset:1024
	ds_read_b128 v[164:167], v150 offset:2048
	ds_read_b128 v[168:171], v150 offset:3072
	v_add_u32_e32 v150, s72, v152
	s_add_u32 s40, s14, s38
	ds_read_b128 v[172:175], v150
	ds_read_b128 v[176:179], v150 offset:1024
	ds_read_b128 v[180:183], v150 offset:2048
	ds_read_b128 v[184:187], v150 offset:3072
	s_addc_u32 s41, s15, s39
	s_add_u32 s40, s40, 0x100
	s_addc_u32 s41, s41, 0
	s_add_u32 s79, s77, s38
	s_addc_u32 s80, s78, s39
	s_cmpk_eq_i32 s38, 0x1500
	s_cselect_b32 s43, s37, s41
	s_cselect_b32 s42, s36, s40
	s_cselect_b32 s41, s11, s80
	s_cselect_b32 s40, s10, s79
	v_lshl_add_u64 v[150:151], v[146:147], 0, s[38:39]
	s_add_i32 m0, s55, 0xc000
	ds_read_b128 v[188:191], v154
	ds_read_b128 v[192:195], v154 offset:1024
	ds_read_b128 v[196:199], v154 offset:2048
	ds_read_b128 v[200:203], v154 offset:3072
	ds_read_b128 v[204:207], v154 offset:4096
	ds_read_b128 v[208:211], v154 offset:5120
	ds_read_b128 v[212:215], v154 offset:6144
	ds_read_b128 v[216:219], v154 offset:7168
	global_load_lds_dwordx4 v[150:151], off
	v_lshl_add_u64 v[150:151], v[148:149], 0, s[38:39]
	s_add_i32 m0, s55, 0xe000
	s_nop 0
	global_load_lds_dwordx4 v[150:151], off
	s_waitcnt vmcnt(8)
	s_waitcnt lgkmcnt(0)
	s_barrier
; #define PG8_STAGEA(bufoff, gbase) PG8_STAGE_(bufoff, gbase, voffA)
; #define PG8_STAGEB(bufoff, gbase) PG8_STAGE_(bufoff, gbase, voffB)
; #define PG8_LDA(dst, b, h) do { _Pragma("unroll") for (int m = 0; m < 4; ++m) _Pragma("unroll") for (int k = 0; k < 2; ++k) dst[m][k] = *(const LAS bf16x8*)(lds + PG8_SA(b, h) + aoff + m * 2048 + k * 1024); } while (0)
; #define PG8_LDB(dst, b, h) do { _Pragma("unroll") for (int n = 0; n < 2; ++n) _Pragma("unroll") for (int k = 0; k < 2; ++k) dst[n][k] = *(const LAS bf16x8*)(lds + PG8_SB(b, h) + boff + n * 2048 + k * 1024); } while (0)
; #define PG8_MMA(ai, bj, At, Bt_) do { __builtin_amdgcn_s_setprio(1); _Pragma("unroll") for (int m = 0; m < 4; ++m) _Pragma("unroll") for (int n = 0; n < 2; ++n) _Pragma("unroll") for (int k = 0; k < 2; ++k) \
;         acc[ai][bj][m][n] = __builtin_amdgcn_mfma_f32_16x16x32_bf16(Bt_[n][k], At[m][k], acc[ai][bj][m][n], 0, 0, 0); __builtin_amdgcn_s_setprio(0); } while (0)
; #define PG8_WAIT_V(n) asm volatile("s_waitcnt vmcnt(" #n ")" ::: "memory")
; #define PG8_WAIT_L(n) asm volatile("s_waitcnt lgkmcnt(" #n ")" ::: "memory")
; #define PG8_BAR __builtin_amdgcn_s_barrier()
; #define PG8_SCHED __builtin_amdgcn_sched_barrier(0)
; template <int EK, int SK = -1>
; __device__ __forceinline__ void gemm_phase(LAS unsigned char* lds, const bf16_t* A, const bf16_t* Bt, int nM, int N, int K, const EpiArgs& E) {
;     ...
;             PG8_WAIT_V(8); PG8_WAIT_L(0); PG8_BAR; PG8_MMA(0, 0, At, B0); PG8_MMA(0, 1, At, B1); PG8_BAR; PG8_SCHED;
;             PG8_LDA(At, 0, 1); PG8_STAGEB(PG8_SB(0, 0), b2); PG8_STAGEB(PG8_SB(0, 1), b2 + hstep); PG8_STAGEA(PG8_SA(0, 0), a2);
;             PG8_WAIT_V(8); PG8_WAIT_L(0); PG8_BAR; PG8_MMA(1, 0, At, B0); PG8_MMA(1, 1, At, B1); PG8_BAR; PG8_SCHED;
;             PG8_LDB(B0, 1, 0); PG8_LDB(B1, 1, 1); PG8_SCHED; PG8_LDA(At, 1, 0); PG8_STAGEA(PG8_SA(0, 1), a2 + hstep);
;             PG8_WAIT_V(8); PG8_WAIT_L(0); PG8_BAR; PG8_MMA(0, 0, At, B0); PG8_MMA(0, 1, At, B1); PG8_BAR; PG8_SCHED;
	s_waitcnt lgkmcnt(0)
	v_mfma_f32_16x16x32_bf16 v[126:129], v[156:159], v[188:191], v[126:129]
	v_mfma_f32_16x16x32_bf16 v[122:125], v[164:167], v[188:191], v[122:125]
	v_mfma_f32_16x16x32_bf16 v[94:97], v[172:175], v[188:191], v[94:97]
	v_mfma_f32_16x16x32_bf16 v[90:93], v[180:183], v[188:191], v[90:93]
	v_mfma_f32_16x16x32_bf16 v[82:85], v[180:183], v[196:199], v[82:85]
	v_mfma_f32_16x16x32_bf16 v[86:89], v[172:175], v[196:199], v[86:89]
	v_mfma_f32_16x16x32_bf16 v[114:117], v[164:167], v[196:199], v[114:117]
	v_mfma_f32_16x16x32_bf16 v[118:121], v[156:159], v[196:199], v[118:121]
	v_mfma_f32_16x16x32_bf16 v[110:113], v[156:159], v[204:207], v[110:113]
	v_mfma_f32_16x16x32_bf16 v[106:109], v[164:167], v[204:207], v[106:109]
	v_mfma_f32_16x16x32_bf16 v[78:81], v[172:175], v[204:207], v[78:81]
	v_mfma_f32_16x16x32_bf16 v[74:77], v[180:183], v[204:207], v[74:77]
	v_mfma_f32_16x16x32_bf16 v[66:69], v[180:183], v[212:215], v[66:69]
	v_mfma_f32_16x16x32_bf16 v[70:73], v[172:175], v[212:215], v[70:73]
	v_mfma_f32_16x16x32_bf16 v[98:101], v[164:167], v[212:215], v[98:101]
	v_mfma_f32_16x16x32_bf16 v[102:105], v[156:159], v[212:215], v[102:105]
	v_mfma_f32_16x16x32_bf16 v[126:129], v[160:163], v[192:195], v[126:129]
	v_mfma_f32_16x16x32_bf16 v[122:125], v[168:171], v[192:195], v[122:125]
	v_mfma_f32_16x16x32_bf16 v[94:97], v[176:179], v[192:195], v[94:97]
	v_mfma_f32_16x16x32_bf16 v[90:93], v[184:187], v[192:195], v[90:93]
	v_mfma_f32_16x16x32_bf16 v[82:85], v[184:187], v[200:203], v[82:85]
	v_mfma_f32_16x16x32_bf16 v[86:89], v[176:179], v[200:203], v[86:89]
	v_mfma_f32_16x16x32_bf16 v[114:117], v[168:171], v[200:203], v[114:117]
	v_mfma_f32_16x16x32_bf16 v[118:121], v[160:163], v[200:203], v[118:121]
	v_mfma_f32_16x16x32_bf16 v[110:113], v[160:163], v[208:211], v[110:113]
	v_mfma_f32_16x16x32_bf16 v[106:109], v[168:171], v[208:211], v[106:109]
	v_mfma_f32_16x16x32_bf16 v[78:81], v[176:179], v[208:211], v[78:81]
	v_mfma_f32_16x16x32_bf16 v[74:77], v[184:187], v[208:211], v[74:77]
	v_mfma_f32_16x16x32_bf16 v[66:69], v[184:187], v[216:219], v[66:69]
	v_mfma_f32_16x16x32_bf16 v[70:73], v[176:179], v[216:219], v[70:73]
	v_mfma_f32_16x16x32_bf16 v[98:101], v[168:171], v[216:219], v[98:101]
	v_mfma_f32_16x16x32_bf16 v[102:105], v[160:163], v[216:219], v[102:105]
	s_barrier
	s_add_i32 s79, s71, s54
	v_lshl_add_u64 v[150:151], s[40:41], 0, v[132:133]
	s_mov_b32 m0, s79
	ds_read_b128 v[188:191], v154 offset:16384
	ds_read_b128 v[192:195], v154 offset:17408
	ds_read_b128 v[196:199], v154 offset:18432
	ds_read_b128 v[200:203], v154 offset:19456
	ds_read_b128 v[204:207], v154 offset:20480
	ds_read_b128 v[208:211], v154 offset:21504
	ds_read_b128 v[212:215], v154 offset:22528
	ds_read_b128 v[216:219], v154 offset:23552
	global_load_lds_dwordx4 v[150:151], off
	s_add_i32 m0, s79, 0x2000
	s_add_u32 s80, s40, 0xb0000
	v_lshl_add_u64 v[220:221], s[40:41], 0, v[136:137]
	s_addc_u32 s81, s41, 0
	s_add_i32 s79, s72, s54
	global_load_lds_dwordx4 v[220:221], off
	v_lshl_add_u64 v[222:223], s[80:81], 0, v[132:133]
	s_mov_b32 m0, s79
	v_lshl_add_u64 v[224:225], s[42:43], 0, v[134:135]
	global_load_lds_dwordx4 v[222:223], off
	v_lshl_add_u64 v[222:223], s[80:81], 0, v[136:137]
	s_add_i32 m0, s79, 0x2000
	s_nop 0
	global_load_lds_dwordx4 v[222:223], off
	v_lshl_add_u64 v[222:223], s[42:43], 0, v[130:131]
	s_mov_b32 m0, s55
	s_nop 0
	global_load_lds_dwordx4 v[222:223], off
	s_mov_b32 m0, s56
	s_nop 0
	global_load_lds_dwordx4 v[224:225], off
	s_waitcnt vmcnt(8)
	s_waitcnt lgkmcnt(0)
	s_barrier
	s_waitcnt lgkmcnt(0)
	v_mfma_f32_16x16x32_bf16 v[62:65], v[156:159], v[188:191], v[62:65]
	v_mfma_f32_16x16x32_bf16 v[58:61], v[164:167], v[188:191], v[58:61]
	v_mfma_f32_16x16x32_bf16 v[30:33], v[172:175], v[188:191], v[30:33]
	v_mfma_f32_16x16x32_bf16 v[26:29], v[180:183], v[188:191], v[26:29]
	v_mfma_f32_16x16x32_bf16 v[18:21], v[180:183], v[196:199], v[18:21]
	v_mfma_f32_16x16x32_bf16 v[22:25], v[172:175], v[196:199], v[22:25]
	v_mfma_f32_16x16x32_bf16 v[50:53], v[164:167], v[196:199], v[50:53]
	v_mfma_f32_16x16x32_bf16 v[54:57], v[156:159], v[196:199], v[54:57]
	v_mfma_f32_16x16x32_bf16 v[46:49], v[156:159], v[204:207], v[46:49]
	v_mfma_f32_16x16x32_bf16 v[42:45], v[164:167], v[204:207], v[42:45]
	v_mfma_f32_16x16x32_bf16 v[14:17], v[172:175], v[204:207], v[14:17]
	v_mfma_f32_16x16x32_bf16 v[10:13], v[180:183], v[204:207], v[10:13]
	v_mfma_f32_16x16x32_bf16 v[2:5], v[180:183], v[212:215], v[2:5]
	v_mfma_f32_16x16x32_bf16 v[6:9], v[172:175], v[212:215], v[6:9]
	v_mfma_f32_16x16x32_bf16 v[34:37], v[164:167], v[212:215], v[34:37]
	v_mfma_f32_16x16x32_bf16 v[38:41], v[156:159], v[212:215], v[38:41]
	v_mfma_f32_16x16x32_bf16 v[62:65], v[160:163], v[192:195], v[62:65]
	v_mfma_f32_16x16x32_bf16 v[58:61], v[168:171], v[192:195], v[58:61]
	v_mfma_f32_16x16x32_bf16 v[30:33], v[176:179], v[192:195], v[30:33]
	v_mfma_f32_16x16x32_bf16 v[26:29], v[184:187], v[192:195], v[26:29]
	v_mfma_f32_16x16x32_bf16 v[18:21], v[184:187], v[200:203], v[18:21]
	v_mfma_f32_16x16x32_bf16 v[22:25], v[176:179], v[200:203], v[22:25]
	v_mfma_f32_16x16x32_bf16 v[50:53], v[168:171], v[200:203], v[50:53]
	v_mfma_f32_16x16x32_bf16 v[54:57], v[160:163], v[200:203], v[54:57]
	v_mfma_f32_16x16x32_bf16 v[46:49], v[160:163], v[208:211], v[46:49]
	v_mfma_f32_16x16x32_bf16 v[42:45], v[168:171], v[208:211], v[42:45]
	v_mfma_f32_16x16x32_bf16 v[14:17], v[176:179], v[208:211], v[14:17]
	v_mfma_f32_16x16x32_bf16 v[10:13], v[184:187], v[208:211], v[10:13]
	v_mfma_f32_16x16x32_bf16 v[2:5], v[184:187], v[216:219], v[2:5]
	v_mfma_f32_16x16x32_bf16 v[6:9], v[176:179], v[216:219], v[6:9]
	v_mfma_f32_16x16x32_bf16 v[34:37], v[168:171], v[216:219], v[34:37]
	v_mfma_f32_16x16x32_bf16 v[38:41], v[160:163], v[216:219], v[38:41]
	s_barrier
; #define PG8_STAGEA(bufoff, gbase) PG8_STAGE_(bufoff, gbase, voffA)
; #define PG8_STAGEB(bufoff, gbase) PG8_STAGE_(bufoff, gbase, voffB)
; #define PG8_LDA(dst, b, h) do { _Pragma("unroll") for (int m = 0; m < 4; ++m) _Pragma("unroll") for (int k = 0; k < 2; ++k) dst[m][k] = *(const LAS bf16x8*)(lds + PG8_SA(b, h) + aoff + m * 2048 + k * 1024); } while (0)
; #define PG8_LDB(dst, b, h) do { _Pragma("unroll") for (int n = 0; n < 2; ++n) _Pragma("unroll") for (int k = 0; k < 2; ++k) dst[n][k] = *(const LAS bf16x8*)(lds + PG8_SB(b, h) + boff + n * 2048 + k * 1024); } while (0)
; #define PG8_MMA(ai, bj, At, Bt_) do { __builtin_amdgcn_s_setprio(1); _Pragma("unroll") for (int m = 0; m < 4; ++m) _Pragma("unroll") for (int n = 0; n < 2; ++n) _Pragma("unroll") for (int k = 0; k < 2; ++k) \
;         acc[ai][bj][m][n] = __builtin_amdgcn_mfma_f32_16x16x32_bf16(Bt_[n][k], At[m][k], acc[ai][bj][m][n], 0, 0, 0); __builtin_amdgcn_s_setprio(0); } while (0)
; #define PG8_WAIT_V(n) asm volatile("s_waitcnt vmcnt(" #n ")" ::: "memory")
; #define PG8_WAIT_L(n) asm volatile("s_waitcnt lgkmcnt(" #n ")" ::: "memory")
; #define PG8_BAR __builtin_amdgcn_s_barrier()
; #define PG8_SCHED __builtin_amdgcn_sched_barrier(0)
; template <int EK, int SK = -1>
; __device__ __forceinline__ void gemm_phase(LAS unsigned char* lds, const bf16_t* A, const bf16_t* Bt, int nM, int N, int K, const EpiArgs& E) {
;     ...
;             PG8_LDB(B0, 1, 0); PG8_LDB(B1, 1, 1); PG8_SCHED; PG8_LDA(At, 1, 0); PG8_STAGEA(PG8_SA(0, 1), a2 + hstep);
;             PG8_WAIT_V(8); PG8_WAIT_L(0); PG8_BAR; PG8_MMA(0, 0, At, B0); PG8_MMA(0, 1, At, B1); PG8_BAR; PG8_SCHED;
;             PG8_LDA(At, 1, 1); PG8_STAGEB(PG8_SB(1, 0), b3); PG8_STAGEB(PG8_SB(1, 1), b3 + hstep); PG8_STAGEA(PG8_SA(1, 0), a3);
;             PG8_WAIT_V(8); PG8_WAIT_L(0); PG8_BAR; PG8_MMA(1, 0, At, B0); PG8_MMA(1, 1, At, B1); PG8_BAR; PG8_SCHED;
	s_add_i32 s79, 0, 0x18000
	s_add_i32 s80, 0, 0x1c000
	v_add_u32_e32 v168, s79, v152
	v_add_u32_e32 v184, s80, v152
	ds_read_b128 v[156:159], v168
	ds_read_b128 v[160:163], v168 offset:1024
	ds_read_b128 v[164:167], v168 offset:2048
	ds_read_b128 v[168:171], v168 offset:3072
	ds_read_b128 v[172:175], v184
	ds_read_b128 v[176:179], v184 offset:1024
	ds_read_b128 v[180:183], v184 offset:2048
	ds_read_b128 v[184:187], v184 offset:3072
	s_add_u32 s42, s42, 0xb0000
	s_addc_u32 s43, s43, 0
	s_mov_b32 m0, s57
	v_lshl_add_u64 v[226:227], s[42:43], 0, v[130:131]
	ds_read_b128 v[188:191], v154 offset:32768
	ds_read_b128 v[192:195], v154 offset:33792
	ds_read_b128 v[196:199], v154 offset:34816
	ds_read_b128 v[200:203], v154 offset:35840
	ds_read_b128 v[204:207], v154 offset:36864
	ds_read_b128 v[208:211], v154 offset:37888
	ds_read_b128 v[212:215], v154 offset:38912
	ds_read_b128 v[216:219], v154 offset:39936
	global_load_lds_dwordx4 v[226:227], off
	v_lshl_add_u64 v[226:227], s[42:43], 0, v[134:135]
	s_mov_b32 m0, s58
	s_nop 0
	global_load_lds_dwordx4 v[226:227], off
	s_waitcnt vmcnt(8)
	s_waitcnt lgkmcnt(0)
	s_barrier
	s_waitcnt lgkmcnt(0)
	v_mfma_f32_16x16x32_bf16 v[126:129], v[156:159], v[188:191], v[126:129]
	v_mfma_f32_16x16x32_bf16 v[122:125], v[164:167], v[188:191], v[122:125]
	v_mfma_f32_16x16x32_bf16 v[94:97], v[172:175], v[188:191], v[94:97]
	v_mfma_f32_16x16x32_bf16 v[90:93], v[180:183], v[188:191], v[90:93]
	v_mfma_f32_16x16x32_bf16 v[82:85], v[180:183], v[196:199], v[82:85]
	v_mfma_f32_16x16x32_bf16 v[86:89], v[172:175], v[196:199], v[86:89]
	v_mfma_f32_16x16x32_bf16 v[114:117], v[164:167], v[196:199], v[114:117]
	v_mfma_f32_16x16x32_bf16 v[118:121], v[156:159], v[196:199], v[118:121]
	v_mfma_f32_16x16x32_bf16 v[110:113], v[156:159], v[204:207], v[110:113]
	v_mfma_f32_16x16x32_bf16 v[106:109], v[164:167], v[204:207], v[106:109]
	v_mfma_f32_16x16x32_bf16 v[78:81], v[172:175], v[204:207], v[78:81]
	v_mfma_f32_16x16x32_bf16 v[74:77], v[180:183], v[204:207], v[74:77]
	v_mfma_f32_16x16x32_bf16 v[66:69], v[180:183], v[212:215], v[66:69]
	v_mfma_f32_16x16x32_bf16 v[70:73], v[172:175], v[212:215], v[70:73]
	v_mfma_f32_16x16x32_bf16 v[98:101], v[164:167], v[212:215], v[98:101]
	v_mfma_f32_16x16x32_bf16 v[102:105], v[156:159], v[212:215], v[102:105]
	v_mfma_f32_16x16x32_bf16 v[126:129], v[160:163], v[192:195], v[126:129]
	v_mfma_f32_16x16x32_bf16 v[122:125], v[168:171], v[192:195], v[122:125]
	v_mfma_f32_16x16x32_bf16 v[94:97], v[176:179], v[192:195], v[94:97]
	v_mfma_f32_16x16x32_bf16 v[90:93], v[184:187], v[192:195], v[90:93]
	v_mfma_f32_16x16x32_bf16 v[82:85], v[184:187], v[200:203], v[82:85]
	v_mfma_f32_16x16x32_bf16 v[86:89], v[176:179], v[200:203], v[86:89]
	v_mfma_f32_16x16x32_bf16 v[114:117], v[168:171], v[200:203], v[114:117]
	v_mfma_f32_16x16x32_bf16 v[118:121], v[160:163], v[200:203], v[118:121]
	v_mfma_f32_16x16x32_bf16 v[110:113], v[160:163], v[208:211], v[110:113]
	v_mfma_f32_16x16x32_bf16 v[106:109], v[168:171], v[208:211], v[106:109]
	v_mfma_f32_16x16x32_bf16 v[78:81], v[176:179], v[208:211], v[78:81]
	v_mfma_f32_16x16x32_bf16 v[74:77], v[184:187], v[208:211], v[74:77]
	v_mfma_f32_16x16x32_bf16 v[66:69], v[184:187], v[216:219], v[66:69]
	v_mfma_f32_16x16x32_bf16 v[70:73], v[176:179], v[216:219], v[70:73]
	v_mfma_f32_16x16x32_bf16 v[98:101], v[168:171], v[216:219], v[98:101]
	v_mfma_f32_16x16x32_bf16 v[102:105], v[160:163], v[216:219], v[102:105]
	s_barrier
	s_add_i32 s42, s79, s54
	v_lshl_add_u64 v[150:151], v[150:151], 0, s[22:23]
	s_mov_b32 m0, s42
	ds_read_b128 v[188:191], v154 offset:49152
	ds_read_b128 v[192:195], v154 offset:50176
	ds_read_b128 v[196:199], v154 offset:51200
	ds_read_b128 v[200:203], v154 offset:52224
	ds_read_b128 v[204:207], v154 offset:53248
	ds_read_b128 v[208:211], v154 offset:54272
	ds_read_b128 v[212:215], v154 offset:55296
	ds_read_b128 v[216:219], v154 offset:56320
	global_load_lds_dwordx4 v[150:151], off
	s_add_i32 m0, s42, 0x2000
	s_add_u32 s40, s40, 0xb0080
	v_lshl_add_u64 v[150:151], v[220:221], 0, s[22:23]
	s_addc_u32 s41, s41, 0
	s_add_i32 s42, s80, s54
	global_load_lds_dwordx4 v[150:151], off
	v_lshl_add_u64 v[150:151], s[40:41], 0, v[132:133]
	s_mov_b32 m0, s42
	s_nop 0
	global_load_lds_dwordx4 v[150:151], off
	v_lshl_add_u64 v[150:151], s[40:41], 0, v[136:137]
	s_add_i32 m0, s42, 0x2000
	s_nop 0
	global_load_lds_dwordx4 v[150:151], off
	v_lshl_add_u64 v[150:151], v[222:223], 0, s[22:23]
	s_mov_b32 m0, s69
	s_nop 0
	global_load_lds_dwordx4 v[150:151], off
	v_lshl_add_u64 v[150:151], v[224:225], 0, s[22:23]
	s_mov_b32 m0, s70
	s_nop 0
	global_load_lds_dwordx4 v[150:151], off
	s_waitcnt vmcnt(8)
	s_waitcnt lgkmcnt(0)
	s_barrier
	s_waitcnt lgkmcnt(0)
	v_mfma_f32_16x16x32_bf16 v[62:65], v[156:159], v[188:191], v[62:65]
	v_mfma_f32_16x16x32_bf16 v[58:61], v[164:167], v[188:191], v[58:61]
	v_mfma_f32_16x16x32_bf16 v[30:33], v[172:175], v[188:191], v[30:33]
	v_mfma_f32_16x16x32_bf16 v[26:29], v[180:183], v[188:191], v[26:29]
	v_mfma_f32_16x16x32_bf16 v[18:21], v[180:183], v[196:199], v[18:21]
	v_mfma_f32_16x16x32_bf16 v[22:25], v[172:175], v[196:199], v[22:25]
	v_mfma_f32_16x16x32_bf16 v[50:53], v[164:167], v[196:199], v[50:53]
	v_mfma_f32_16x16x32_bf16 v[54:57], v[156:159], v[196:199], v[54:57]
	v_mfma_f32_16x16x32_bf16 v[46:49], v[156:159], v[204:207], v[46:49]
	v_mfma_f32_16x16x32_bf16 v[42:45], v[164:167], v[204:207], v[42:45]
	v_mfma_f32_16x16x32_bf16 v[14:17], v[172:175], v[204:207], v[14:17]
	v_mfma_f32_16x16x32_bf16 v[10:13], v[180:183], v[204:207], v[10:13]
	v_mfma_f32_16x16x32_bf16 v[2:5], v[180:183], v[212:215], v[2:5]
	v_mfma_f32_16x16x32_bf16 v[6:9], v[172:175], v[212:215], v[6:9]
	v_mfma_f32_16x16x32_bf16 v[34:37], v[164:167], v[212:215], v[34:37]
	v_mfma_f32_16x16x32_bf16 v[38:41], v[156:159], v[212:215], v[38:41]
	v_mfma_f32_16x16x32_bf16 v[62:65], v[160:163], v[192:195], v[62:65]
	v_mfma_f32_16x16x32_bf16 v[58:61], v[168:171], v[192:195], v[58:61]
	v_mfma_f32_16x16x32_bf16 v[30:33], v[176:179], v[192:195], v[30:33]
	v_mfma_f32_16x16x32_bf16 v[26:29], v[184:187], v[192:195], v[26:29]
	v_mfma_f32_16x16x32_bf16 v[18:21], v[184:187], v[200:203], v[18:21]
	v_mfma_f32_16x16x32_bf16 v[22:25], v[176:179], v[200:203], v[22:25]
	v_mfma_f32_16x16x32_bf16 v[50:53], v[168:171], v[200:203], v[50:53]
	v_mfma_f32_16x16x32_bf16 v[54:57], v[160:163], v[200:203], v[54:57]
	v_mfma_f32_16x16x32_bf16 v[46:49], v[160:163], v[208:211], v[46:49]
	v_mfma_f32_16x16x32_bf16 v[42:45], v[168:171], v[208:211], v[42:45]
	v_mfma_f32_16x16x32_bf16 v[14:17], v[176:179], v[208:211], v[14:17]
	v_mfma_f32_16x16x32_bf16 v[10:13], v[184:187], v[208:211], v[10:13]
	v_mfma_f32_16x16x32_bf16 v[2:5], v[184:187], v[216:219], v[2:5]
	v_mfma_f32_16x16x32_bf16 v[6:9], v[176:179], v[216:219], v[6:9]
	v_mfma_f32_16x16x32_bf16 v[34:37], v[168:171], v[216:219], v[34:37]
	v_mfma_f32_16x16x32_bf16 v[38:41], v[160:163], v[216:219], v[38:41]
	s_barrier
	s_add_i32 s20, s20, 2
	s_add_u32 s38, s38, 0x100
	s_addc_u32 s39, s39, 0
	s_cmp_gt_u32 s20, 41
	s_cbranch_scc0 .LBB0_793

; #define PG8_STAGEA(bufoff, gbase) PG8_STAGE_(bufoff, gbase, voffA)
; #define PG8_STAGEB(bufoff, gbase) PG8_STAGE_(bufoff, gbase, voffB)
; #define PG8_LDA(dst, b, h) do { _Pragma("unroll") for (int m = 0; m < 4; ++m) _Pragma("unroll") for (int k = 0; k < 2; ++k) dst[m][k] = *(const LAS bf16x8*)(lds + PG8_SA(b, h) + aoff + m * 2048 + k * 1024); } while (0)
; #define PG8_LDB(dst, b, h) do { _Pragma("unroll") for (int n = 0; n < 2; ++n) _Pragma("unroll") for (int k = 0; k < 2; ++k) dst[n][k] = *(const LAS bf16x8*)(lds + PG8_SB(b, h) + boff + n * 2048 + k * 1024); } while (0)
; #define PG8_MMA(ai, bj, At, Bt_) do { __builtin_amdgcn_s_setprio(1); _Pragma("unroll") for (int m = 0; m < 4; ++m) _Pragma("unroll") for (int n = 0; n < 2; ++n) _Pragma("unroll") for (int k = 0; k < 2; ++k) \
;         acc[ai][bj][m][n] = __builtin_amdgcn_mfma_f32_16x16x32_bf16(Bt_[n][k], At[m][k], acc[ai][bj][m][n], 0, 0, 0); __builtin_amdgcn_s_setprio(0); } while (0)
; #define PG8_WAIT_V(n) asm volatile("s_waitcnt vmcnt(" #n ")" ::: "memory")
; #define PG8_WAIT_L(n) asm volatile("s_waitcnt lgkmcnt(" #n ")" ::: "memory")
; #define PG8_BAR __builtin_amdgcn_s_barrier()
; template <int EK, int SK = -1>
; __device__ __forceinline__ void gemm_phase(LAS unsigned char* lds, const bf16_t* A, const bf16_t* Bt, int nM, int N, int K, const EpiArgs& E) {
;     ...
;         const bool has_next = S.next(ui + 1, nxt);
;         const char* nA = has_next ? (const char*)A + (size_t)nxt.pm * tstep : cA; const char* nB = has_next ? (const char*)Bt + (size_t)nxt.pn * tstep : cB;
;         for (int t = 0; t < nt; t += 2) {
;             const bool last = (t == nt - 2);
;             const char* a1 = cA + (size_t)(t + 1) * kstep;
;             const char* a2 = last ? nA : cA + (size_t)(t + 2) * kstep; const char* b2 = last ? nB : cB + (size_t)(t + 2) * kstep;
;             const char* a3 = a2 + kstep; const char* b3 = b2 + kstep;
;             PG8_LDB(B0, 0, 0); PG8_LDB(B1, 0, 1); PG8_SCHED; PG8_LDA(At, 0, 0); PG8_STAGEA(PG8_SA(1, 1), a1 + hstep);
;             PG8_WAIT_V(8); PG8_WAIT_L(0); PG8_BAR; PG8_MMA(0, 0, At, B0); PG8_MMA(0, 1, At, B1); PG8_BAR; PG8_SCHED;
;             PG8_LDA(At, 0, 1); PG8_STAGEB(PG8_SB(0, 0), b2); PG8_STAGEB(PG8_SB(0, 1), b2 + hstep); PG8_STAGEA(PG8_SA(0, 0), a2);
;             PG8_WAIT_V(8); PG8_WAIT_L(0); PG8_BAR; PG8_MMA(1, 0, At, B0); PG8_MMA(1, 1, At, B1); PG8_BAR; PG8_SCHED;
.LBB0_928:
	s_add_u32 s86, s76, 0x100
	s_addc_u32 s87, s77, 0
	s_ashr_i32 s71, s70, 31
	s_lshl_b64 s[10:11], s[70:71], 19
	s_add_u32 s74, s62, s10
	s_addc_u32 s75, s63, s11
	s_and_b64 s[10:11], s[8:9], exec
	s_cselect_b32 s14, s75, s37
	s_cselect_b32 s71, s74, s36
	s_ashr_i32 s69, s68, 31
	s_lshl_b64 s[10:11], s[68:69], 19
	s_add_u32 s72, s43, s10
	s_addc_u32 s73, s45, s11
	s_and_b64 s[10:11], s[8:9], exec
	s_cselect_b32 s69, s73, s77
	s_cselect_b32 s88, s72, s76
	s_waitcnt lgkmcnt(0)
	v_lshl_add_u64 v[146:147], s[36:37], 0, v[138:139]
	v_lshl_add_u64 v[148:149], s[36:37], 0, v[140:141]
	s_mov_b32 s89, -2
	s_mov_b64 s[10:11], 0
	v_add_u32_e32 v158, s82, v160
	ds_read_b128 v[150:153], v158
	ds_read_b128 v[154:157], v158 offset:1024
	ds_read_b128 v[166:169], v158 offset:2048
	ds_read_b128 v[170:173], v158 offset:3072
	v_add_u32_e32 v158, s83, v160
	s_add_u32 s76, s36, s10
	ds_read_b128 v[174:177], v158
	ds_read_b128 v[178:181], v158 offset:1024
	ds_read_b128 v[182:185], v158 offset:2048
	ds_read_b128 v[186:189], v158 offset:3072
	s_addc_u32 s77, s37, s11
	s_add_u32 s76, s76, 0x100
	s_addc_u32 s77, s77, 0
	s_add_u32 s90, s86, s10
	s_addc_u32 s91, s87, s11
	s_cmpk_eq_i32 s10, 0x700
	s_cselect_b32 s79, s14, s77
	s_cselect_b32 s78, s71, s76
	s_cselect_b32 s77, s69, s91
	s_cselect_b32 s76, s88, s90
	v_lshl_add_u64 v[158:159], v[146:147], 0, s[10:11]
	s_add_i32 m0, s23, 0xc000
	ds_read_b128 v[190:193], v163
	ds_read_b128 v[194:197], v163 offset:1024
	ds_read_b128 v[198:201], v163 offset:2048
	ds_read_b128 v[202:205], v163 offset:3072
	ds_read_b128 v[206:209], v163 offset:4096
	ds_read_b128 v[210:213], v163 offset:5120
	ds_read_b128 v[214:217], v163 offset:6144
	ds_read_b128 v[218:221], v163 offset:7168
	global_load_lds_dwordx4 v[158:159], off
	v_lshl_add_u64 v[158:159], v[148:149], 0, s[10:11]
	s_add_i32 m0, s23, 0xe000
	s_nop 0
	global_load_lds_dwordx4 v[158:159], off
	s_waitcnt vmcnt(8)
	s_waitcnt lgkmcnt(0)
	s_barrier
	s_waitcnt lgkmcnt(0)
	v_mfma_f32_16x16x32_bf16 v[110:113], v[150:153], v[190:193], 0
	v_mfma_f32_16x16x32_bf16 v[106:109], v[166:169], v[190:193], 0
	v_mfma_f32_16x16x32_bf16 v[78:81], v[174:177], v[190:193], 0
	v_mfma_f32_16x16x32_bf16 v[74:77], v[182:185], v[190:193], 0
	v_mfma_f32_16x16x32_bf16 v[66:69], v[182:185], v[198:201], 0
	v_mfma_f32_16x16x32_bf16 v[70:73], v[174:177], v[198:201], 0
	v_mfma_f32_16x16x32_bf16 v[98:101], v[166:169], v[198:201], 0
	v_mfma_f32_16x16x32_bf16 v[102:105], v[150:153], v[198:201], 0
	v_mfma_f32_16x16x32_bf16 v[94:97], v[150:153], v[206:209], 0
	v_mfma_f32_16x16x32_bf16 v[90:93], v[166:169], v[206:209], 0
	v_mfma_f32_16x16x32_bf16 v[62:65], v[174:177], v[206:209], 0
	v_mfma_f32_16x16x32_bf16 v[58:61], v[182:185], v[206:209], 0
	v_mfma_f32_16x16x32_bf16 v[50:53], v[182:185], v[214:217], 0
	v_mfma_f32_16x16x32_bf16 v[54:57], v[174:177], v[214:217], 0
	v_mfma_f32_16x16x32_bf16 v[82:85], v[166:169], v[214:217], 0
	v_mfma_f32_16x16x32_bf16 v[86:89], v[150:153], v[214:217], 0
	v_mfma_f32_16x16x32_bf16 v[110:113], v[154:157], v[194:197], v[110:113]
	v_mfma_f32_16x16x32_bf16 v[106:109], v[170:173], v[194:197], v[106:109]
	v_mfma_f32_16x16x32_bf16 v[78:81], v[178:181], v[194:197], v[78:81]
	v_mfma_f32_16x16x32_bf16 v[74:77], v[186:189], v[194:197], v[74:77]
	v_mfma_f32_16x16x32_bf16 v[66:69], v[186:189], v[202:205], v[66:69]
	v_mfma_f32_16x16x32_bf16 v[70:73], v[178:181], v[202:205], v[70:73]
	v_mfma_f32_16x16x32_bf16 v[98:101], v[170:173], v[202:205], v[98:101]
	v_mfma_f32_16x16x32_bf16 v[102:105], v[154:157], v[202:205], v[102:105]
	v_mfma_f32_16x16x32_bf16 v[94:97], v[154:157], v[210:213], v[94:97]
	v_mfma_f32_16x16x32_bf16 v[90:93], v[170:173], v[210:213], v[90:93]
	v_mfma_f32_16x16x32_bf16 v[62:65], v[178:181], v[210:213], v[62:65]
	v_mfma_f32_16x16x32_bf16 v[58:61], v[186:189], v[210:213], v[58:61]
	v_mfma_f32_16x16x32_bf16 v[50:53], v[186:189], v[218:221], v[50:53]
	v_mfma_f32_16x16x32_bf16 v[54:57], v[178:181], v[218:221], v[54:57]
	v_mfma_f32_16x16x32_bf16 v[82:85], v[170:173], v[218:221], v[82:85]
	v_mfma_f32_16x16x32_bf16 v[86:89], v[154:157], v[218:221], v[86:89]
	s_barrier
	s_add_i32 s90, s82, s53
	v_lshl_add_u64 v[158:159], s[76:77], 0, v[132:133]
	s_mov_b32 m0, s90
	ds_read_b128 v[190:193], v163 offset:16384
	ds_read_b128 v[194:197], v163 offset:17408
	ds_read_b128 v[198:201], v163 offset:18432
	ds_read_b128 v[202:205], v163 offset:19456
	ds_read_b128 v[206:209], v163 offset:20480
	ds_read_b128 v[210:213], v163 offset:21504
	ds_read_b128 v[214:217], v163 offset:22528
	ds_read_b128 v[218:221], v163 offset:23552
	global_load_lds_dwordx4 v[158:159], off
	s_add_i32 m0, s90, 0x2000
	s_add_u32 s90, s76, 0x40000
	v_lshl_add_u64 v[222:223], s[76:77], 0, v[136:137]
	s_addc_u32 s91, s77, 0
	s_add_i32 s92, s83, s53
	global_load_lds_dwordx4 v[222:223], off
	v_lshl_add_u64 v[224:225], s[90:91], 0, v[132:133]
	s_mov_b32 m0, s92
	v_lshl_add_u64 v[226:227], s[78:79], 0, v[134:135]
	global_load_lds_dwordx4 v[224:225], off
	v_lshl_add_u64 v[224:225], s[90:91], 0, v[136:137]
	s_add_i32 m0, s92, 0x2000
	s_nop 0
	global_load_lds_dwordx4 v[224:225], off
	v_lshl_add_u64 v[224:225], s[78:79], 0, v[130:131]
	s_mov_b32 m0, s23
	s_nop 0
	global_load_lds_dwordx4 v[224:225], off
	s_mov_b32 m0, s27
	s_nop 0
	global_load_lds_dwordx4 v[226:227], off
	s_waitcnt vmcnt(8)
	s_waitcnt lgkmcnt(0)
	s_barrier
; #define PG8_STAGEA(bufoff, gbase) PG8_STAGE_(bufoff, gbase, voffA)
; #define PG8_STAGEB(bufoff, gbase) PG8_STAGE_(bufoff, gbase, voffB)
; #define PG8_LDA(dst, b, h) do { _Pragma("unroll") for (int m = 0; m < 4; ++m) _Pragma("unroll") for (int k = 0; k < 2; ++k) dst[m][k] = *(const LAS bf16x8*)(lds + PG8_SA(b, h) + aoff + m * 2048 + k * 1024); } while (0)
; #define PG8_LDB(dst, b, h) do { _Pragma("unroll") for (int n = 0; n < 2; ++n) _Pragma("unroll") for (int k = 0; k < 2; ++k) dst[n][k] = *(const LAS bf16x8*)(lds + PG8_SB(b, h) + boff + n * 2048 + k * 1024); } while (0)
; #define PG8_MMA(ai, bj, At, Bt_) do { __builtin_amdgcn_s_setprio(1); _Pragma("unroll") for (int m = 0; m < 4; ++m) _Pragma("unroll") for (int n = 0; n < 2; ++n) _Pragma("unroll") for (int k = 0; k < 2; ++k) \
;         acc[ai][bj][m][n] = __builtin_amdgcn_mfma_f32_16x16x32_bf16(Bt_[n][k], At[m][k], acc[ai][bj][m][n], 0, 0, 0); __builtin_amdgcn_s_setprio(0); } while (0)
; #define PG8_WAIT_V(n) asm volatile("s_waitcnt vmcnt(" #n ")" ::: "memory")
; #define PG8_WAIT_L(n) asm volatile("s_waitcnt lgkmcnt(" #n ")" ::: "memory")
; #define PG8_BAR __builtin_amdgcn_s_barrier()
; #define PG8_SCHED __builtin_amdgcn_sched_barrier(0)
; template <int EK, int SK = -1>
; __device__ __forceinline__ void gemm_phase(LAS unsigned char* lds, const bf16_t* A, const bf16_t* Bt, int nM, int N, int K, const EpiArgs& E) {
;     ...
;             PG8_WAIT_V(8); PG8_WAIT_L(0); PG8_BAR; PG8_MMA(1, 0, At, B0); PG8_MMA(1, 1, At, B1); PG8_BAR; PG8_SCHED;
;             PG8_LDB(B0, 1, 0); PG8_LDB(B1, 1, 1); PG8_SCHED; PG8_LDA(At, 1, 0); PG8_STAGEA(PG8_SA(0, 1), a2 + hstep);
;             PG8_WAIT_V(8); PG8_WAIT_L(0); PG8_BAR; PG8_MMA(0, 0, At, B0); PG8_MMA(0, 1, At, B1); PG8_BAR; PG8_SCHED;
;             PG8_LDA(At, 1, 1); PG8_STAGEB(PG8_SB(1, 0), b3); PG8_STAGEB(PG8_SB(1, 1), b3 + hstep); PG8_STAGEA(PG8_SA(1, 0), a3);
	s_waitcnt lgkmcnt(0)
	v_mfma_f32_16x16x32_bf16 v[46:49], v[150:153], v[190:193], 0
	v_mfma_f32_16x16x32_bf16 v[42:45], v[166:169], v[190:193], 0
	v_mfma_f32_16x16x32_bf16 v[14:17], v[174:177], v[190:193], 0
	v_mfma_f32_16x16x32_bf16 v[10:13], v[182:185], v[190:193], 0
	v_mfma_f32_16x16x32_bf16 v[2:5], v[182:185], v[198:201], 0
	v_mfma_f32_16x16x32_bf16 v[6:9], v[174:177], v[198:201], 0
	v_mfma_f32_16x16x32_bf16 v[34:37], v[166:169], v[198:201], 0
	v_mfma_f32_16x16x32_bf16 v[38:41], v[150:153], v[198:201], 0
	v_mfma_f32_16x16x32_bf16 v[30:33], v[150:153], v[206:209], 0
	v_mfma_f32_16x16x32_bf16 v[26:29], v[166:169], v[206:209], 0
	v_mfma_f32_16x16x32_bf16 v[114:117], v[174:177], v[206:209], 0
	v_mfma_f32_16x16x32_bf16 v[118:121], v[182:185], v[206:209], 0
	v_mfma_f32_16x16x32_bf16 v[126:129], v[182:185], v[214:217], 0
	v_mfma_f32_16x16x32_bf16 v[122:125], v[174:177], v[214:217], 0
	v_mfma_f32_16x16x32_bf16 v[18:21], v[166:169], v[214:217], 0
	v_mfma_f32_16x16x32_bf16 v[22:25], v[150:153], v[214:217], 0
	v_mfma_f32_16x16x32_bf16 v[46:49], v[154:157], v[194:197], v[46:49]
	v_mfma_f32_16x16x32_bf16 v[42:45], v[170:173], v[194:197], v[42:45]
	v_mfma_f32_16x16x32_bf16 v[14:17], v[178:181], v[194:197], v[14:17]
	v_mfma_f32_16x16x32_bf16 v[10:13], v[186:189], v[194:197], v[10:13]
	v_mfma_f32_16x16x32_bf16 v[2:5], v[186:189], v[202:205], v[2:5]
	v_mfma_f32_16x16x32_bf16 v[6:9], v[178:181], v[202:205], v[6:9]
	v_mfma_f32_16x16x32_bf16 v[34:37], v[170:173], v[202:205], v[34:37]
	v_mfma_f32_16x16x32_bf16 v[38:41], v[154:157], v[202:205], v[38:41]
	v_mfma_f32_16x16x32_bf16 v[30:33], v[154:157], v[210:213], v[30:33]
	v_mfma_f32_16x16x32_bf16 v[26:29], v[170:173], v[210:213], v[26:29]
	v_mfma_f32_16x16x32_bf16 v[114:117], v[178:181], v[210:213], v[114:117]
	v_mfma_f32_16x16x32_bf16 v[118:121], v[186:189], v[210:213], v[118:121]
	v_mfma_f32_16x16x32_bf16 v[126:129], v[186:189], v[218:221], v[126:129]
	v_mfma_f32_16x16x32_bf16 v[122:125], v[178:181], v[218:221], v[122:125]
	v_mfma_f32_16x16x32_bf16 v[18:21], v[170:173], v[218:221], v[18:21]
	v_mfma_f32_16x16x32_bf16 v[22:25], v[154:157], v[218:221], v[22:25]
	s_barrier
	s_add_i32 s90, 0, 0x18000
	v_add_u32_e32 v165, s90, v160
	s_add_i32 s91, 0, 0x1c000
	ds_read_b128 v[150:153], v165
	ds_read_b128 v[154:157], v165 offset:1024
	ds_read_b128 v[166:169], v165 offset:2048
	ds_read_b128 v[170:173], v165 offset:3072
	v_add_u32_e32 v165, s91, v160
	ds_read_b128 v[174:177], v165
	ds_read_b128 v[178:181], v165 offset:1024
	ds_read_b128 v[182:185], v165 offset:2048
	ds_read_b128 v[186:189], v165 offset:3072
	s_add_u32 s78, s78, 0x40000
	s_addc_u32 s79, s79, 0
	s_mov_b32 m0, s55
	v_lshl_add_u64 v[228:229], s[78:79], 0, v[130:131]
	ds_read_b128 v[190:193], v163 offset:32768
	ds_read_b128 v[194:197], v163 offset:33792
	ds_read_b128 v[198:201], v163 offset:34816
	ds_read_b128 v[202:205], v163 offset:35840
	ds_read_b128 v[206:209], v163 offset:36864
	ds_read_b128 v[210:213], v163 offset:37888
	ds_read_b128 v[214:217], v163 offset:38912
	ds_read_b128 v[218:221], v163 offset:39936
	global_load_lds_dwordx4 v[228:229], off
	v_lshl_add_u64 v[228:229], s[78:79], 0, v[134:135]
	s_mov_b32 m0, s57
	s_nop 0
	global_load_lds_dwordx4 v[228:229], off
	s_waitcnt vmcnt(8)
	s_waitcnt lgkmcnt(0)
	s_barrier
	s_waitcnt lgkmcnt(0)
	v_mfma_f32_16x16x32_bf16 v[110:113], v[150:153], v[190:193], v[110:113]
	v_mfma_f32_16x16x32_bf16 v[106:109], v[166:169], v[190:193], v[106:109]
	v_mfma_f32_16x16x32_bf16 v[78:81], v[174:177], v[190:193], v[78:81]
	v_mfma_f32_16x16x32_bf16 v[74:77], v[182:185], v[190:193], v[74:77]
	v_mfma_f32_16x16x32_bf16 v[66:69], v[182:185], v[198:201], v[66:69]
	v_mfma_f32_16x16x32_bf16 v[70:73], v[174:177], v[198:201], v[70:73]
	v_mfma_f32_16x16x32_bf16 v[98:101], v[166:169], v[198:201], v[98:101]
	v_mfma_f32_16x16x32_bf16 v[102:105], v[150:153], v[198:201], v[102:105]
	v_mfma_f32_16x16x32_bf16 v[94:97], v[150:153], v[206:209], v[94:97]
	v_mfma_f32_16x16x32_bf16 v[90:93], v[166:169], v[206:209], v[90:93]
	v_mfma_f32_16x16x32_bf16 v[62:65], v[174:177], v[206:209], v[62:65]
	v_mfma_f32_16x16x32_bf16 v[58:61], v[182:185], v[206:209], v[58:61]
	v_mfma_f32_16x16x32_bf16 v[50:53], v[182:185], v[214:217], v[50:53]
	v_mfma_f32_16x16x32_bf16 v[54:57], v[174:177], v[214:217], v[54:57]
	v_mfma_f32_16x16x32_bf16 v[82:85], v[166:169], v[214:217], v[82:85]
	v_mfma_f32_16x16x32_bf16 v[86:89], v[150:153], v[214:217], v[86:89]
	v_mfma_f32_16x16x32_bf16 v[110:113], v[154:157], v[194:197], v[110:113]
	v_mfma_f32_16x16x32_bf16 v[106:109], v[170:173], v[194:197], v[106:109]
	v_mfma_f32_16x16x32_bf16 v[78:81], v[178:181], v[194:197], v[78:81]
	v_mfma_f32_16x16x32_bf16 v[74:77], v[186:189], v[194:197], v[74:77]
	v_mfma_f32_16x16x32_bf16 v[66:69], v[186:189], v[202:205], v[66:69]
	v_mfma_f32_16x16x32_bf16 v[70:73], v[178:181], v[202:205], v[70:73]
	v_mfma_f32_16x16x32_bf16 v[98:101], v[170:173], v[202:205], v[98:101]
	v_mfma_f32_16x16x32_bf16 v[102:105], v[154:157], v[202:205], v[102:105]
	v_mfma_f32_16x16x32_bf16 v[94:97], v[154:157], v[210:213], v[94:97]
	v_mfma_f32_16x16x32_bf16 v[90:93], v[170:173], v[210:213], v[90:93]
	v_mfma_f32_16x16x32_bf16 v[62:65], v[178:181], v[210:213], v[62:65]
	v_mfma_f32_16x16x32_bf16 v[58:61], v[186:189], v[210:213], v[58:61]
	v_mfma_f32_16x16x32_bf16 v[50:53], v[186:189], v[218:221], v[50:53]
	v_mfma_f32_16x16x32_bf16 v[54:57], v[178:181], v[218:221], v[54:57]
	v_mfma_f32_16x16x32_bf16 v[82:85], v[170:173], v[218:221], v[82:85]
	v_mfma_f32_16x16x32_bf16 v[86:89], v[154:157], v[218:221], v[86:89]
	s_barrier
; #define PG8_STAGEA(bufoff, gbase) PG8_STAGE_(bufoff, gbase, voffA)
; #define PG8_STAGEB(bufoff, gbase) PG8_STAGE_(bufoff, gbase, voffB)
; #define PG8_LDA(dst, b, h) do { _Pragma("unroll") for (int m = 0; m < 4; ++m) _Pragma("unroll") for (int k = 0; k < 2; ++k) dst[m][k] = *(const LAS bf16x8*)(lds + PG8_SA(b, h) + aoff + m * 2048 + k * 1024); } while (0)
; #define PG8_LDB(dst, b, h) do { _Pragma("unroll") for (int n = 0; n < 2; ++n) _Pragma("unroll") for (int k = 0; k < 2; ++k) dst[n][k] = *(const LAS bf16x8*)(lds + PG8_SB(b, h) + boff + n * 2048 + k * 1024); } while (0)
; #define PG8_MMA(ai, bj, At, Bt_) do { __builtin_amdgcn_s_setprio(1); _Pragma("unroll") for (int m = 0; m < 4; ++m) _Pragma("unroll") for (int n = 0; n < 2; ++n) _Pragma("unroll") for (int k = 0; k < 2; ++k) \
;         acc[ai][bj][m][n] = __builtin_amdgcn_mfma_f32_16x16x32_bf16(Bt_[n][k], At[m][k], acc[ai][bj][m][n], 0, 0, 0); __builtin_amdgcn_s_setprio(0); } while (0)
; #define PG8_WAIT_V(n) asm volatile("s_waitcnt vmcnt(" #n ")" ::: "memory")
; #define PG8_WAIT_L(n) asm volatile("s_waitcnt lgkmcnt(" #n ")" ::: "memory")
; #define PG8_BAR __builtin_amdgcn_s_barrier()
; #define PG8_SCHED __builtin_amdgcn_sched_barrier(0)
; template <int EK, int SK = -1>
; __device__ __forceinline__ void gemm_phase(LAS unsigned char* lds, const bf16_t* A, const bf16_t* Bt, int nM, int N, int K, const EpiArgs& E) {
;     ...
;         for (int t = 0; t < nt; t += 2) {
;             const bool last = (t == nt - 2);
;             const char* a1 = cA + (size_t)(t + 1) * kstep;
;             const char* a2 = last ? nA : cA + (size_t)(t + 2) * kstep; const char* b2 = last ? nB : cB + (size_t)(t + 2) * kstep;
;             const char* a3 = a2 + kstep; const char* b3 = b2 + kstep;
;             PG8_LDB(B0, 0, 0); PG8_LDB(B1, 0, 1); PG8_SCHED; PG8_LDA(At, 0, 0); PG8_STAGEA(PG8_SA(1, 1), a1 + hstep);
;             PG8_WAIT_V(8); PG8_WAIT_L(0); PG8_BAR; PG8_MMA(0, 0, At, B0); PG8_MMA(0, 1, At, B1); PG8_BAR; PG8_SCHED;
;     ...
;             PG8_LDA(At, 1, 1); PG8_STAGEB(PG8_SB(1, 0), b3); PG8_STAGEB(PG8_SB(1, 1), b3 + hstep); PG8_STAGEA(PG8_SA(1, 0), a3);
;             PG8_WAIT_V(8); PG8_WAIT_L(0); PG8_BAR; PG8_MMA(1, 0, At, B0); PG8_MMA(1, 1, At, B1); PG8_BAR; PG8_SCHED;
	s_add_i32 s78, s90, s53
	v_lshl_add_u64 v[158:159], v[158:159], 0, s[16:17]
	s_mov_b32 m0, s78
	ds_read_b128 v[190:193], v163 offset:49152
	ds_read_b128 v[194:197], v163 offset:50176
	ds_read_b128 v[198:201], v163 offset:51200
	ds_read_b128 v[202:205], v163 offset:52224
	ds_read_b128 v[206:209], v163 offset:53248
	ds_read_b128 v[210:213], v163 offset:54272
	ds_read_b128 v[214:217], v163 offset:55296
	ds_read_b128 v[218:221], v163 offset:56320
	global_load_lds_dwordx4 v[158:159], off
	s_add_i32 m0, s78, 0x2000
	s_add_u32 s76, s76, 0x40080
	v_lshl_add_u64 v[158:159], v[222:223], 0, s[16:17]
	s_addc_u32 s77, s77, 0
	s_add_i32 s78, s91, s53
	global_load_lds_dwordx4 v[158:159], off
	v_lshl_add_u64 v[158:159], s[76:77], 0, v[132:133]
	s_mov_b32 m0, s78
	s_nop 0
	global_load_lds_dwordx4 v[158:159], off
	v_lshl_add_u64 v[158:159], s[76:77], 0, v[136:137]
	s_add_i32 m0, s78, 0x2000
	s_nop 0
	global_load_lds_dwordx4 v[158:159], off
	v_lshl_add_u64 v[158:159], v[224:225], 0, s[16:17]
	s_mov_b32 m0, s80
	s_nop 0
	global_load_lds_dwordx4 v[158:159], off
	v_lshl_add_u64 v[158:159], v[226:227], 0, s[16:17]
	s_mov_b32 m0, s81
	s_nop 0
	global_load_lds_dwordx4 v[158:159], off
	s_waitcnt vmcnt(8)
	s_waitcnt lgkmcnt(0)
	s_barrier
	s_waitcnt lgkmcnt(0)
	v_mfma_f32_16x16x32_bf16 v[46:49], v[150:153], v[190:193], v[46:49]
	v_mfma_f32_16x16x32_bf16 v[42:45], v[166:169], v[190:193], v[42:45]
	v_mfma_f32_16x16x32_bf16 v[14:17], v[174:177], v[190:193], v[14:17]
	v_mfma_f32_16x16x32_bf16 v[10:13], v[182:185], v[190:193], v[10:13]
	v_mfma_f32_16x16x32_bf16 v[2:5], v[182:185], v[198:201], v[2:5]
	v_mfma_f32_16x16x32_bf16 v[6:9], v[174:177], v[198:201], v[6:9]
	v_mfma_f32_16x16x32_bf16 v[34:37], v[166:169], v[198:201], v[34:37]
	v_mfma_f32_16x16x32_bf16 v[38:41], v[150:153], v[198:201], v[38:41]
	v_mfma_f32_16x16x32_bf16 v[30:33], v[150:153], v[206:209], v[30:33]
	v_mfma_f32_16x16x32_bf16 v[26:29], v[166:169], v[206:209], v[26:29]
	v_mfma_f32_16x16x32_bf16 v[114:117], v[174:177], v[206:209], v[114:117]
	v_mfma_f32_16x16x32_bf16 v[118:121], v[182:185], v[206:209], v[118:121]
	v_mfma_f32_16x16x32_bf16 v[126:129], v[182:185], v[214:217], v[126:129]
	v_mfma_f32_16x16x32_bf16 v[122:125], v[174:177], v[214:217], v[122:125]
	v_mfma_f32_16x16x32_bf16 v[18:21], v[166:169], v[214:217], v[18:21]
	v_mfma_f32_16x16x32_bf16 v[22:25], v[150:153], v[214:217], v[22:25]
	v_mfma_f32_16x16x32_bf16 v[46:49], v[154:157], v[194:197], v[46:49]
	v_mfma_f32_16x16x32_bf16 v[42:45], v[170:173], v[194:197], v[42:45]
	v_mfma_f32_16x16x32_bf16 v[14:17], v[178:181], v[194:197], v[14:17]
	v_mfma_f32_16x16x32_bf16 v[10:13], v[186:189], v[194:197], v[10:13]
	v_mfma_f32_16x16x32_bf16 v[2:5], v[186:189], v[202:205], v[2:5]
	v_mfma_f32_16x16x32_bf16 v[6:9], v[178:181], v[202:205], v[6:9]
	v_mfma_f32_16x16x32_bf16 v[34:37], v[170:173], v[202:205], v[34:37]
	v_mfma_f32_16x16x32_bf16 v[38:41], v[154:157], v[202:205], v[38:41]
	v_mfma_f32_16x16x32_bf16 v[30:33], v[154:157], v[210:213], v[30:33]
	v_mfma_f32_16x16x32_bf16 v[26:29], v[170:173], v[210:213], v[26:29]
	v_mfma_f32_16x16x32_bf16 v[114:117], v[178:181], v[210:213], v[114:117]
	v_mfma_f32_16x16x32_bf16 v[118:121], v[186:189], v[210:213], v[118:121]
	v_mfma_f32_16x16x32_bf16 v[126:129], v[186:189], v[218:221], v[126:129]
	v_mfma_f32_16x16x32_bf16 v[122:125], v[178:181], v[218:221], v[122:125]
	v_mfma_f32_16x16x32_bf16 v[18:21], v[170:173], v[218:221], v[18:21]
	v_mfma_f32_16x16x32_bf16 v[22:25], v[154:157], v[218:221], v[22:25]
	s_barrier
	s_add_i32 s89, s89, 2
	s_add_u32 s10, s10, 0x100
	s_addc_u32 s11, s11, 0
	s_cmp_gt_u32 s89, 13
	s_cbranch_scc0 .LBB0_929
	s_branch .Lmy_kexit_4
.LBB0_929:
	v_add_u32_e32 v158, s82, v160
	ds_read_b128 v[150:153], v158
	ds_read_b128 v[154:157], v158 offset:1024
	ds_read_b128 v[166:169], v158 offset:2048
	ds_read_b128 v[170:173], v158 offset:3072
	v_add_u32_e32 v158, s83, v160
	s_add_u32 s76, s36, s10
	ds_read_b128 v[174:177], v158
	ds_read_b128 v[178:181], v158 offset:1024
	ds_read_b128 v[182:185], v158 offset:2048
	ds_read_b128 v[186:189], v158 offset:3072
	s_addc_u32 s77, s37, s11
	s_add_u32 s76, s76, 0x100
	s_addc_u32 s77, s77, 0
	s_add_u32 s90, s86, s10
	s_addc_u32 s91, s87, s11
	s_cmpk_eq_i32 s10, 0x700
	s_cselect_b32 s79, s14, s77
	s_cselect_b32 s78, s71, s76
	s_cselect_b32 s77, s69, s91
	s_cselect_b32 s76, s88, s90
	v_lshl_add_u64 v[158:159], v[146:147], 0, s[10:11]
	s_add_i32 m0, s23, 0xc000
	ds_read_b128 v[190:193], v163
	ds_read_b128 v[194:197], v163 offset:1024
	ds_read_b128 v[198:201], v163 offset:2048
	ds_read_b128 v[202:205], v163 offset:3072
	ds_read_b128 v[206:209], v163 offset:4096
	ds_read_b128 v[210:213], v163 offset:5120
	ds_read_b128 v[214:217], v163 offset:6144
	ds_read_b128 v[218:221], v163 offset:7168
	global_load_lds_dwordx4 v[158:159], off
	v_lshl_add_u64 v[158:159], v[148:149], 0, s[10:11]
	s_add_i32 m0, s23, 0xe000
	s_nop 0
	global_load_lds_dwordx4 v[158:159], off
	s_waitcnt vmcnt(8)
	s_waitcnt lgkmcnt(0)
	s_barrier
; #define PG8_STAGEA(bufoff, gbase) PG8_STAGE_(bufoff, gbase, voffA)
; #define PG8_STAGEB(bufoff, gbase) PG8_STAGE_(bufoff, gbase, voffB)
; #define PG8_LDA(dst, b, h) do { _Pragma("unroll") for (int m = 0; m < 4; ++m) _Pragma("unroll") for (int k = 0; k < 2; ++k) dst[m][k] = *(const LAS bf16x8*)(lds + PG8_SA(b, h) + aoff + m * 2048 + k * 1024); } while (0)
; #define PG8_LDB(dst, b, h) do { _Pragma("unroll") for (int n = 0; n < 2; ++n) _Pragma("unroll") for (int k = 0; k < 2; ++k) dst[n][k] = *(const LAS bf16x8*)(lds + PG8_SB(b, h) + boff + n * 2048 + k * 1024); } while (0)
; #define PG8_MMA(ai, bj, At, Bt_) do { __builtin_amdgcn_s_setprio(1); _Pragma("unroll") for (int m = 0; m < 4; ++m) _Pragma("unroll") for (int n = 0; n < 2; ++n) _Pragma("unroll") for (int k = 0; k < 2; ++k) \
;         acc[ai][bj][m][n] = __builtin_amdgcn_mfma_f32_16x16x32_bf16(Bt_[n][k], At[m][k], acc[ai][bj][m][n], 0, 0, 0); __builtin_amdgcn_s_setprio(0); } while (0)
; #define PG8_WAIT_V(n) asm volatile("s_waitcnt vmcnt(" #n ")" ::: "memory")
; #define PG8_WAIT_L(n) asm volatile("s_waitcnt lgkmcnt(" #n ")" ::: "memory")
; #define PG8_BAR __builtin_amdgcn_s_barrier()
; #define PG8_SCHED __builtin_amdgcn_sched_barrier(0)
; template <int EK, int SK = -1>
; __device__ __forceinline__ void gemm_phase(LAS unsigned char* lds, const bf16_t* A, const bf16_t* Bt, int nM, int N, int K, const EpiArgs& E) {
;     ...
;             PG8_WAIT_V(8); PG8_WAIT_L(0); PG8_BAR; PG8_MMA(0, 0, At, B0); PG8_MMA(0, 1, At, B1); PG8_BAR; PG8_SCHED;
;             PG8_LDA(At, 0, 1); PG8_STAGEB(PG8_SB(0, 0), b2); PG8_STAGEB(PG8_SB(0, 1), b2 + hstep); PG8_STAGEA(PG8_SA(0, 0), a2);
;             PG8_WAIT_V(8); PG8_WAIT_L(0); PG8_BAR; PG8_MMA(1, 0, At, B0); PG8_MMA(1, 1, At, B1); PG8_BAR; PG8_SCHED;
;             PG8_LDB(B0, 1, 0); PG8_LDB(B1, 1, 1); PG8_SCHED; PG8_LDA(At, 1, 0); PG8_STAGEA(PG8_SA(0, 1), a2 + hstep);
;             PG8_WAIT_V(8); PG8_WAIT_L(0); PG8_BAR; PG8_MMA(0, 0, At, B0); PG8_MMA(0, 1, At, B1); PG8_BAR; PG8_SCHED;
	s_waitcnt lgkmcnt(0)
	v_mfma_f32_16x16x32_bf16 v[110:113], v[150:153], v[190:193], v[110:113]
	v_mfma_f32_16x16x32_bf16 v[106:109], v[166:169], v[190:193], v[106:109]
	v_mfma_f32_16x16x32_bf16 v[78:81], v[174:177], v[190:193], v[78:81]
	v_mfma_f32_16x16x32_bf16 v[74:77], v[182:185], v[190:193], v[74:77]
	v_mfma_f32_16x16x32_bf16 v[66:69], v[182:185], v[198:201], v[66:69]
	v_mfma_f32_16x16x32_bf16 v[70:73], v[174:177], v[198:201], v[70:73]
	v_mfma_f32_16x16x32_bf16 v[98:101], v[166:169], v[198:201], v[98:101]
	v_mfma_f32_16x16x32_bf16 v[102:105], v[150:153], v[198:201], v[102:105]
	v_mfma_f32_16x16x32_bf16 v[94:97], v[150:153], v[206:209], v[94:97]
	v_mfma_f32_16x16x32_bf16 v[90:93], v[166:169], v[206:209], v[90:93]
	v_mfma_f32_16x16x32_bf16 v[62:65], v[174:177], v[206:209], v[62:65]
	v_mfma_f32_16x16x32_bf16 v[58:61], v[182:185], v[206:209], v[58:61]
	v_mfma_f32_16x16x32_bf16 v[50:53], v[182:185], v[214:217], v[50:53]
	v_mfma_f32_16x16x32_bf16 v[54:57], v[174:177], v[214:217], v[54:57]
	v_mfma_f32_16x16x32_bf16 v[82:85], v[166:169], v[214:217], v[82:85]
	v_mfma_f32_16x16x32_bf16 v[86:89], v[150:153], v[214:217], v[86:89]
	v_mfma_f32_16x16x32_bf16 v[110:113], v[154:157], v[194:197], v[110:113]
	v_mfma_f32_16x16x32_bf16 v[106:109], v[170:173], v[194:197], v[106:109]
	v_mfma_f32_16x16x32_bf16 v[78:81], v[178:181], v[194:197], v[78:81]
	v_mfma_f32_16x16x32_bf16 v[74:77], v[186:189], v[194:197], v[74:77]
	v_mfma_f32_16x16x32_bf16 v[66:69], v[186:189], v[202:205], v[66:69]
	v_mfma_f32_16x16x32_bf16 v[70:73], v[178:181], v[202:205], v[70:73]
	v_mfma_f32_16x16x32_bf16 v[98:101], v[170:173], v[202:205], v[98:101]
	v_mfma_f32_16x16x32_bf16 v[102:105], v[154:157], v[202:205], v[102:105]
	v_mfma_f32_16x16x32_bf16 v[94:97], v[154:157], v[210:213], v[94:97]
	v_mfma_f32_16x16x32_bf16 v[90:93], v[170:173], v[210:213], v[90:93]
	v_mfma_f32_16x16x32_bf16 v[62:65], v[178:181], v[210:213], v[62:65]
	v_mfma_f32_16x16x32_bf16 v[58:61], v[186:189], v[210:213], v[58:61]
	v_mfma_f32_16x16x32_bf16 v[50:53], v[186:189], v[218:221], v[50:53]
	v_mfma_f32_16x16x32_bf16 v[54:57], v[178:181], v[218:221], v[54:57]
	v_mfma_f32_16x16x32_bf16 v[82:85], v[170:173], v[218:221], v[82:85]
	v_mfma_f32_16x16x32_bf16 v[86:89], v[154:157], v[218:221], v[86:89]
	s_barrier
	s_add_i32 s90, s82, s53
	v_lshl_add_u64 v[158:159], s[76:77], 0, v[132:133]
	s_mov_b32 m0, s90
	ds_read_b128 v[190:193], v163 offset:16384
	ds_read_b128 v[194:197], v163 offset:17408
	ds_read_b128 v[198:201], v163 offset:18432
	ds_read_b128 v[202:205], v163 offset:19456
	ds_read_b128 v[206:209], v163 offset:20480
	ds_read_b128 v[210:213], v163 offset:21504
	ds_read_b128 v[214:217], v163 offset:22528
	ds_read_b128 v[218:221], v163 offset:23552
	global_load_lds_dwordx4 v[158:159], off
	s_add_i32 m0, s90, 0x2000
	s_add_u32 s90, s76, 0x40000
	v_lshl_add_u64 v[222:223], s[76:77], 0, v[136:137]
	s_addc_u32 s91, s77, 0
	s_add_i32 s92, s83, s53
	global_load_lds_dwordx4 v[222:223], off
	v_lshl_add_u64 v[224:225], s[90:91], 0, v[132:133]
	s_mov_b32 m0, s92
	v_lshl_add_u64 v[226:227], s[78:79], 0, v[134:135]
	global_load_lds_dwordx4 v[224:225], off
	v_lshl_add_u64 v[224:225], s[90:91], 0, v[136:137]
	s_add_i32 m0, s92, 0x2000
	s_nop 0
	global_load_lds_dwordx4 v[224:225], off
	v_lshl_add_u64 v[224:225], s[78:79], 0, v[130:131]
	s_mov_b32 m0, s23
	s_nop 0
	global_load_lds_dwordx4 v[224:225], off
	s_mov_b32 m0, s27
	s_nop 0
	global_load_lds_dwordx4 v[226:227], off
	s_waitcnt vmcnt(8)
	s_waitcnt lgkmcnt(0)
	s_barrier
	s_waitcnt lgkmcnt(0)
	v_mfma_f32_16x16x32_bf16 v[46:49], v[150:153], v[190:193], v[46:49]
	v_mfma_f32_16x16x32_bf16 v[42:45], v[166:169], v[190:193], v[42:45]
	v_mfma_f32_16x16x32_bf16 v[14:17], v[174:177], v[190:193], v[14:17]
	v_mfma_f32_16x16x32_bf16 v[10:13], v[182:185], v[190:193], v[10:13]
	v_mfma_f32_16x16x32_bf16 v[2:5], v[182:185], v[198:201], v[2:5]
	v_mfma_f32_16x16x32_bf16 v[6:9], v[174:177], v[198:201], v[6:9]
	v_mfma_f32_16x16x32_bf16 v[34:37], v[166:169], v[198:201], v[34:37]
	v_mfma_f32_16x16x32_bf16 v[38:41], v[150:153], v[198:201], v[38:41]
	v_mfma_f32_16x16x32_bf16 v[30:33], v[150:153], v[206:209], v[30:33]
	v_mfma_f32_16x16x32_bf16 v[26:29], v[166:169], v[206:209], v[26:29]
	v_mfma_f32_16x16x32_bf16 v[114:117], v[174:177], v[206:209], v[114:117]
	v_mfma_f32_16x16x32_bf16 v[118:121], v[182:185], v[206:209], v[118:121]
	v_mfma_f32_16x16x32_bf16 v[126:129], v[182:185], v[214:217], v[126:129]
	v_mfma_f32_16x16x32_bf16 v[122:125], v[174:177], v[214:217], v[122:125]
	v_mfma_f32_16x16x32_bf16 v[18:21], v[166:169], v[214:217], v[18:21]
	v_mfma_f32_16x16x32_bf16 v[22:25], v[150:153], v[214:217], v[22:25]
	v_mfma_f32_16x16x32_bf16 v[46:49], v[154:157], v[194:197], v[46:49]
	v_mfma_f32_16x16x32_bf16 v[42:45], v[170:173], v[194:197], v[42:45]
	v_mfma_f32_16x16x32_bf16 v[14:17], v[178:181], v[194:197], v[14:17]
	v_mfma_f32_16x16x32_bf16 v[10:13], v[186:189], v[194:197], v[10:13]
	v_mfma_f32_16x16x32_bf16 v[2:5], v[186:189], v[202:205], v[2:5]
	v_mfma_f32_16x16x32_bf16 v[6:9], v[178:181], v[202:205], v[6:9]
	v_mfma_f32_16x16x32_bf16 v[34:37], v[170:173], v[202:205], v[34:37]
	v_mfma_f32_16x16x32_bf16 v[38:41], v[154:157], v[202:205], v[38:41]
	v_mfma_f32_16x16x32_bf16 v[30:33], v[154:157], v[210:213], v[30:33]
	v_mfma_f32_16x16x32_bf16 v[26:29], v[170:173], v[210:213], v[26:29]
	v_mfma_f32_16x16x32_bf16 v[114:117], v[178:181], v[210:213], v[114:117]
	v_mfma_f32_16x16x32_bf16 v[118:121], v[186:189], v[210:213], v[118:121]
	v_mfma_f32_16x16x32_bf16 v[126:129], v[186:189], v[218:221], v[126:129]
	v_mfma_f32_16x16x32_bf16 v[122:125], v[178:181], v[218:221], v[122:125]
	v_mfma_f32_16x16x32_bf16 v[18:21], v[170:173], v[218:221], v[18:21]
	v_mfma_f32_16x16x32_bf16 v[22:25], v[154:157], v[218:221], v[22:25]
	s_barrier
; #define PG8_STAGEA(bufoff, gbase) PG8_STAGE_(bufoff, gbase, voffA)
; #define PG8_STAGEB(bufoff, gbase) PG8_STAGE_(bufoff, gbase, voffB)
; #define PG8_LDA(dst, b, h) do { _Pragma("unroll") for (int m = 0; m < 4; ++m) _Pragma("unroll") for (int k = 0; k < 2; ++k) dst[m][k] = *(const LAS bf16x8*)(lds + PG8_SA(b, h) + aoff + m * 2048 + k * 1024); } while (0)
; #define PG8_LDB(dst, b, h) do { _Pragma("unroll") for (int n = 0; n < 2; ++n) _Pragma("unroll") for (int k = 0; k < 2; ++k) dst[n][k] = *(const LAS bf16x8*)(lds + PG8_SB(b, h) + boff + n * 2048 + k * 1024); } while (0)
; #define PG8_MMA(ai, bj, At, Bt_) do { __builtin_amdgcn_s_setprio(1); _Pragma("unroll") for (int m = 0; m < 4; ++m) _Pragma("unroll") for (int n = 0; n < 2; ++n) _Pragma("unroll") for (int k = 0; k < 2; ++k) \
;         acc[ai][bj][m][n] = __builtin_amdgcn_mfma_f32_16x16x32_bf16(Bt_[n][k], At[m][k], acc[ai][bj][m][n], 0, 0, 0); __builtin_amdgcn_s_setprio(0); } while (0)
; #define PG8_WAIT_V(n) asm volatile("s_waitcnt vmcnt(" #n ")" ::: "memory")
; #define PG8_WAIT_L(n) asm volatile("s_waitcnt lgkmcnt(" #n ")" ::: "memory")
; #define PG8_BAR __builtin_amdgcn_s_barrier()
; #define PG8_SCHED __builtin_amdgcn_sched_barrier(0)
; template <int EK, int SK = -1>
; __device__ __forceinline__ void gemm_phase(LAS unsigned char* lds, const bf16_t* A, const bf16_t* Bt, int nM, int N, int K, const EpiArgs& E) {
;     ...
;             PG8_LDB(B0, 1, 0); PG8_LDB(B1, 1, 1); PG8_SCHED; PG8_LDA(At, 1, 0); PG8_STAGEA(PG8_SA(0, 1), a2 + hstep);
;             PG8_WAIT_V(8); PG8_WAIT_L(0); PG8_BAR; PG8_MMA(0, 0, At, B0); PG8_MMA(0, 1, At, B1); PG8_BAR; PG8_SCHED;
;             PG8_LDA(At, 1, 1); PG8_STAGEB(PG8_SB(1, 0), b3); PG8_STAGEB(PG8_SB(1, 1), b3 + hstep); PG8_STAGEA(PG8_SA(1, 0), a3);
;             PG8_WAIT_V(8); PG8_WAIT_L(0); PG8_BAR; PG8_MMA(1, 0, At, B0); PG8_MMA(1, 1, At, B1); PG8_BAR; PG8_SCHED;
;         }
	s_add_i32 s90, 0, 0x18000
	v_add_u32_e32 v165, s90, v160
	s_add_i32 s91, 0, 0x1c000
	ds_read_b128 v[150:153], v165
	ds_read_b128 v[154:157], v165 offset:1024
	ds_read_b128 v[166:169], v165 offset:2048
	ds_read_b128 v[170:173], v165 offset:3072
	v_add_u32_e32 v165, s91, v160
	ds_read_b128 v[174:177], v165
	ds_read_b128 v[178:181], v165 offset:1024
	ds_read_b128 v[182:185], v165 offset:2048
	ds_read_b128 v[186:189], v165 offset:3072
	s_add_u32 s78, s78, 0x40000
	s_addc_u32 s79, s79, 0
	s_mov_b32 m0, s55
	v_lshl_add_u64 v[228:229], s[78:79], 0, v[130:131]
	ds_read_b128 v[190:193], v163 offset:32768
	ds_read_b128 v[194:197], v163 offset:33792
	ds_read_b128 v[198:201], v163 offset:34816
	ds_read_b128 v[202:205], v163 offset:35840
	ds_read_b128 v[206:209], v163 offset:36864
	ds_read_b128 v[210:213], v163 offset:37888
	ds_read_b128 v[214:217], v163 offset:38912
	ds_read_b128 v[218:221], v163 offset:39936
	global_load_lds_dwordx4 v[228:229], off
	v_lshl_add_u64 v[228:229], s[78:79], 0, v[134:135]
	s_mov_b32 m0, s57
	s_nop 0
	global_load_lds_dwordx4 v[228:229], off
	s_waitcnt vmcnt(8)
	s_waitcnt lgkmcnt(0)
	s_barrier
	s_waitcnt lgkmcnt(0)
	v_mfma_f32_16x16x32_bf16 v[110:113], v[150:153], v[190:193], v[110:113]
	v_mfma_f32_16x16x32_bf16 v[106:109], v[166:169], v[190:193], v[106:109]
	v_mfma_f32_16x16x32_bf16 v[78:81], v[174:177], v[190:193], v[78:81]
	v_mfma_f32_16x16x32_bf16 v[74:77], v[182:185], v[190:193], v[74:77]
	v_mfma_f32_16x16x32_bf16 v[66:69], v[182:185], v[198:201], v[66:69]
	v_mfma_f32_16x16x32_bf16 v[70:73], v[174:177], v[198:201], v[70:73]
	v_mfma_f32_16x16x32_bf16 v[98:101], v[166:169], v[198:201], v[98:101]
	v_mfma_f32_16x16x32_bf16 v[102:105], v[150:153], v[198:201], v[102:105]
	v_mfma_f32_16x16x32_bf16 v[94:97], v[150:153], v[206:209], v[94:97]
	v_mfma_f32_16x16x32_bf16 v[90:93], v[166:169], v[206:209], v[90:93]
	v_mfma_f32_16x16x32_bf16 v[62:65], v[174:177], v[206:209], v[62:65]
	v_mfma_f32_16x16x32_bf16 v[58:61], v[182:185], v[206:209], v[58:61]
	v_mfma_f32_16x16x32_bf16 v[50:53], v[182:185], v[214:217], v[50:53]
	v_mfma_f32_16x16x32_bf16 v[54:57], v[174:177], v[214:217], v[54:57]
	v_mfma_f32_16x16x32_bf16 v[82:85], v[166:169], v[214:217], v[82:85]
	v_mfma_f32_16x16x32_bf16 v[86:89], v[150:153], v[214:217], v[86:89]
	v_mfma_f32_16x16x32_bf16 v[110:113], v[154:157], v[194:197], v[110:113]
	v_mfma_f32_16x16x32_bf16 v[106:109], v[170:173], v[194:197], v[106:109]
	v_mfma_f32_16x16x32_bf16 v[78:81], v[178:181], v[194:197], v[78:81]
	v_mfma_f32_16x16x32_bf16 v[74:77], v[186:189], v[194:197], v[74:77]
	v_mfma_f32_16x16x32_bf16 v[66:69], v[186:189], v[202:205], v[66:69]
	v_mfma_f32_16x16x32_bf16 v[70:73], v[178:181], v[202:205], v[70:73]
	v_mfma_f32_16x16x32_bf16 v[98:101], v[170:173], v[202:205], v[98:101]
	v_mfma_f32_16x16x32_bf16 v[102:105], v[154:157], v[202:205], v[102:105]
	v_mfma_f32_16x16x32_bf16 v[94:97], v[154:157], v[210:213], v[94:97]
	v_mfma_f32_16x16x32_bf16 v[90:93], v[170:173], v[210:213], v[90:93]
	v_mfma_f32_16x16x32_bf16 v[62:65], v[178:181], v[210:213], v[62:65]
	v_mfma_f32_16x16x32_bf16 v[58:61], v[186:189], v[210:213], v[58:61]
	v_mfma_f32_16x16x32_bf16 v[50:53], v[186:189], v[218:221], v[50:53]
	v_mfma_f32_16x16x32_bf16 v[54:57], v[178:181], v[218:221], v[54:57]
	v_mfma_f32_16x16x32_bf16 v[82:85], v[170:173], v[218:221], v[82:85]
	v_mfma_f32_16x16x32_bf16 v[86:89], v[154:157], v[218:221], v[86:89]
	s_barrier
	s_add_i32 s78, s90, s53
	v_lshl_add_u64 v[158:159], v[158:159], 0, s[16:17]
	s_mov_b32 m0, s78
	ds_read_b128 v[190:193], v163 offset:49152
	ds_read_b128 v[194:197], v163 offset:50176
	ds_read_b128 v[198:201], v163 offset:51200
	ds_read_b128 v[202:205], v163 offset:52224
	ds_read_b128 v[206:209], v163 offset:53248
	ds_read_b128 v[210:213], v163 offset:54272
	ds_read_b128 v[214:217], v163 offset:55296
	ds_read_b128 v[218:221], v163 offset:56320
	global_load_lds_dwordx4 v[158:159], off
	s_add_i32 m0, s78, 0x2000
	s_add_u32 s76, s76, 0x40080
	v_lshl_add_u64 v[158:159], v[222:223], 0, s[16:17]
	s_addc_u32 s77, s77, 0
	s_add_i32 s78, s91, s53
	global_load_lds_dwordx4 v[158:159], off
	v_lshl_add_u64 v[158:159], s[76:77], 0, v[132:133]
	s_mov_b32 m0, s78
	s_nop 0
	global_load_lds_dwordx4 v[158:159], off
	v_lshl_add_u64 v[158:159], s[76:77], 0, v[136:137]
	s_add_i32 m0, s78, 0x2000
	s_nop 0
	global_load_lds_dwordx4 v[158:159], off
	v_lshl_add_u64 v[158:159], v[224:225], 0, s[16:17]
	s_mov_b32 m0, s80
	s_nop 0
	global_load_lds_dwordx4 v[158:159], off
	v_lshl_add_u64 v[158:159], v[226:227], 0, s[16:17]
	s_mov_b32 m0, s81
	s_nop 0
	global_load_lds_dwordx4 v[158:159], off
	s_waitcnt vmcnt(8)
	s_waitcnt lgkmcnt(0)
	s_barrier
	s_waitcnt lgkmcnt(0)
	v_mfma_f32_16x16x32_bf16 v[46:49], v[150:153], v[190:193], v[46:49]
	v_mfma_f32_16x16x32_bf16 v[42:45], v[166:169], v[190:193], v[42:45]
	v_mfma_f32_16x16x32_bf16 v[14:17], v[174:177], v[190:193], v[14:17]
	v_mfma_f32_16x16x32_bf16 v[10:13], v[182:185], v[190:193], v[10:13]
	v_mfma_f32_16x16x32_bf16 v[2:5], v[182:185], v[198:201], v[2:5]
	v_mfma_f32_16x16x32_bf16 v[6:9], v[174:177], v[198:201], v[6:9]
	v_mfma_f32_16x16x32_bf16 v[34:37], v[166:169], v[198:201], v[34:37]
	v_mfma_f32_16x16x32_bf16 v[38:41], v[150:153], v[198:201], v[38:41]
	v_mfma_f32_16x16x32_bf16 v[30:33], v[150:153], v[206:209], v[30:33]
	v_mfma_f32_16x16x32_bf16 v[26:29], v[166:169], v[206:209], v[26:29]
	v_mfma_f32_16x16x32_bf16 v[114:117], v[174:177], v[206:209], v[114:117]
	v_mfma_f32_16x16x32_bf16 v[118:121], v[182:185], v[206:209], v[118:121]
	v_mfma_f32_16x16x32_bf16 v[126:129], v[182:185], v[214:217], v[126:129]
	v_mfma_f32_16x16x32_bf16 v[122:125], v[174:177], v[214:217], v[122:125]
	v_mfma_f32_16x16x32_bf16 v[18:21], v[166:169], v[214:217], v[18:21]
	v_mfma_f32_16x16x32_bf16 v[22:25], v[150:153], v[214:217], v[22:25]
	v_mfma_f32_16x16x32_bf16 v[46:49], v[154:157], v[194:197], v[46:49]
	v_mfma_f32_16x16x32_bf16 v[42:45], v[170:173], v[194:197], v[42:45]
	v_mfma_f32_16x16x32_bf16 v[14:17], v[178:181], v[194:197], v[14:17]
	v_mfma_f32_16x16x32_bf16 v[10:13], v[186:189], v[194:197], v[10:13]
	v_mfma_f32_16x16x32_bf16 v[2:5], v[186:189], v[202:205], v[2:5]
	v_mfma_f32_16x16x32_bf16 v[6:9], v[178:181], v[202:205], v[6:9]
	v_mfma_f32_16x16x32_bf16 v[34:37], v[170:173], v[202:205], v[34:37]
	v_mfma_f32_16x16x32_bf16 v[38:41], v[154:157], v[202:205], v[38:41]
	v_mfma_f32_16x16x32_bf16 v[30:33], v[154:157], v[210:213], v[30:33]
	v_mfma_f32_16x16x32_bf16 v[26:29], v[170:173], v[210:213], v[26:29]
	v_mfma_f32_16x16x32_bf16 v[114:117], v[178:181], v[210:213], v[114:117]
	v_mfma_f32_16x16x32_bf16 v[118:121], v[186:189], v[210:213], v[118:121]
	v_mfma_f32_16x16x32_bf16 v[126:129], v[186:189], v[218:221], v[126:129]
	v_mfma_f32_16x16x32_bf16 v[122:125], v[178:181], v[218:221], v[122:125]
	v_mfma_f32_16x16x32_bf16 v[18:21], v[170:173], v[218:221], v[18:21]
	v_mfma_f32_16x16x32_bf16 v[22:25], v[154:157], v[218:221], v[22:25]
	s_barrier
	s_add_i32 s89, s89, 2
	s_add_u32 s10, s10, 0x100
	s_addc_u32 s11, s11, 0
	s_cmp_gt_u32 s89, 13
	s_cbranch_scc0 .LBB0_929

; #define PG8_STAGEA(bufoff, gbase) PG8_STAGE_(bufoff, gbase, voffA)
; #define PG8_STAGEB(bufoff, gbase) PG8_STAGE_(bufoff, gbase, voffB)
; #define PG8_LDA(dst, b, h) do { _Pragma("unroll") for (int m = 0; m < 4; ++m) _Pragma("unroll") for (int k = 0; k < 2; ++k) dst[m][k] = *(const LAS bf16x8*)(lds + PG8_SA(b, h) + aoff + m * 2048 + k * 1024); } while (0)
; #define PG8_LDB(dst, b, h) do { _Pragma("unroll") for (int n = 0; n < 2; ++n) _Pragma("unroll") for (int k = 0; k < 2; ++k) dst[n][k] = *(const LAS bf16x8*)(lds + PG8_SB(b, h) + boff + n * 2048 + k * 1024); } while (0)
; #define PG8_MMA(ai, bj, At, Bt_) do { __builtin_amdgcn_s_setprio(1); _Pragma("unroll") for (int m = 0; m < 4; ++m) _Pragma("unroll") for (int n = 0; n < 2; ++n) _Pragma("unroll") for (int k = 0; k < 2; ++k) \
;         acc[ai][bj][m][n] = __builtin_amdgcn_mfma_f32_16x16x32_bf16(Bt_[n][k], At[m][k], acc[ai][bj][m][n], 0, 0, 0); __builtin_amdgcn_s_setprio(0); } while (0)
; #define PG8_WAIT_V(n) asm volatile("s_waitcnt vmcnt(" #n ")" ::: "memory")
; #define PG8_WAIT_L(n) asm volatile("s_waitcnt lgkmcnt(" #n ")" ::: "memory")
; #define PG8_BAR __builtin_amdgcn_s_barrier()
; template <int EK, int SK = -1>
; __device__ __forceinline__ void gemm_phase(LAS unsigned char* lds, const bf16_t* A, const bf16_t* Bt, int nM, int N, int K, const EpiArgs& E) {
;     ...
;         const bool has_next = S.next(ui + 1, nxt);
;         const char* nA = has_next ? (const char*)A + (size_t)nxt.pm * tstep : cA; const char* nB = has_next ? (const char*)Bt + (size_t)nxt.pn * tstep : cB;
;         for (int t = 0; t < nt; t += 2) {
;             const bool last = (t == nt - 2);
;             const char* a1 = cA + (size_t)(t + 1) * kstep;
;             const char* a2 = last ? nA : cA + (size_t)(t + 2) * kstep; const char* b2 = last ? nB : cB + (size_t)(t + 2) * kstep;
;             const char* a3 = a2 + kstep; const char* b3 = b2 + kstep;
;             PG8_LDB(B0, 0, 0); PG8_LDB(B1, 0, 1); PG8_SCHED; PG8_LDA(At, 0, 0); PG8_STAGEA(PG8_SA(1, 1), a1 + hstep);
;             PG8_WAIT_V(8); PG8_WAIT_L(0); PG8_BAR; PG8_MMA(0, 0, At, B0); PG8_MMA(0, 1, At, B1); PG8_BAR; PG8_SCHED;
;             PG8_LDA(At, 0, 1); PG8_STAGEB(PG8_SB(0, 0), b2); PG8_STAGEB(PG8_SB(0, 1), b2 + hstep); PG8_STAGEA(PG8_SA(0, 0), a2);
;             PG8_WAIT_V(8); PG8_WAIT_L(0); PG8_BAR; PG8_MMA(1, 0, At, B0); PG8_MMA(1, 1, At, B1); PG8_BAR; PG8_SCHED;
.LBB0_1119:
	s_add_u32 s73, s46, 0x100
	s_addc_u32 s74, s47, 0
	s_ashr_i32 s41, s40, 31
	s_lshl_b64 s[42:43], s[40:41], 19
	s_add_u32 s44, s66, s42
	s_addc_u32 s45, s67, s43
	s_and_b64 s[42:43], s[8:9], exec
	s_cselect_b32 s22, s45, s19
	s_cselect_b32 s41, s44, s18
	s_ashr_i32 s39, s38, 31
	s_lshl_b64 s[42:43], s[38:39], 19
	s_add_u32 s42, s52, s42
	s_addc_u32 s43, s53, s43
	s_and_b64 s[48:49], s[8:9], exec
	s_cselect_b32 s39, s43, s47
	s_cselect_b32 s75, s42, s46
	v_lshl_add_u64 v[146:147], s[18:19], 0, v[138:139]
	v_lshl_add_u64 v[148:149], s[18:19], 0, v[140:141]
	s_mov_b32 s76, -2
	s_mov_b64 s[46:47], 0
	v_add_u32_e32 v150, s69, v152
	ds_read_b128 v[156:159], v150
	ds_read_b128 v[160:163], v150 offset:1024
	ds_read_b128 v[164:167], v150 offset:2048
	ds_read_b128 v[168:171], v150 offset:3072
	v_add_u32_e32 v150, s70, v152
	s_add_u32 s48, s18, s46
	ds_read_b128 v[172:175], v150
	ds_read_b128 v[176:179], v150 offset:1024
	ds_read_b128 v[180:183], v150 offset:2048
	ds_read_b128 v[184:187], v150 offset:3072
	s_addc_u32 s49, s19, s47
	s_add_u32 s48, s48, 0x100
	s_addc_u32 s49, s49, 0
	s_add_u32 s77, s73, s46
	s_addc_u32 s78, s74, s47
	s_cmpk_eq_i32 s46, 0x700
	s_cselect_b32 s51, s22, s49
	s_cselect_b32 s50, s41, s48
	s_cselect_b32 s49, s39, s78
	s_cselect_b32 s48, s75, s77
	v_lshl_add_u64 v[150:151], v[146:147], 0, s[46:47]
	s_add_i32 m0, s15, 0xc000
	ds_read_b128 v[188:191], v154
	ds_read_b128 v[192:195], v154 offset:1024
	ds_read_b128 v[196:199], v154 offset:2048
	ds_read_b128 v[200:203], v154 offset:3072
	ds_read_b128 v[204:207], v154 offset:4096
	ds_read_b128 v[208:211], v154 offset:5120
	ds_read_b128 v[212:215], v154 offset:6144
	ds_read_b128 v[216:219], v154 offset:7168
	global_load_lds_dwordx4 v[150:151], off
	v_lshl_add_u64 v[150:151], v[148:149], 0, s[46:47]
	s_add_i32 m0, s15, 0xe000
	s_nop 0
	global_load_lds_dwordx4 v[150:151], off
	s_waitcnt vmcnt(8)
	s_waitcnt lgkmcnt(0)
	s_barrier
	s_waitcnt lgkmcnt(0)
	v_mfma_f32_16x16x32_bf16 v[126:129], v[156:159], v[188:191], 0
	v_mfma_f32_16x16x32_bf16 v[122:125], v[164:167], v[188:191], 0
	v_mfma_f32_16x16x32_bf16 v[94:97], v[172:175], v[188:191], 0
	v_mfma_f32_16x16x32_bf16 v[90:93], v[180:183], v[188:191], 0
	v_mfma_f32_16x16x32_bf16 v[82:85], v[180:183], v[196:199], 0
	v_mfma_f32_16x16x32_bf16 v[86:89], v[172:175], v[196:199], 0
	v_mfma_f32_16x16x32_bf16 v[114:117], v[164:167], v[196:199], 0
	v_mfma_f32_16x16x32_bf16 v[118:121], v[156:159], v[196:199], 0
	v_mfma_f32_16x16x32_bf16 v[110:113], v[156:159], v[204:207], 0
	v_mfma_f32_16x16x32_bf16 v[106:109], v[164:167], v[204:207], 0
	v_mfma_f32_16x16x32_bf16 v[78:81], v[172:175], v[204:207], 0
	v_mfma_f32_16x16x32_bf16 v[74:77], v[180:183], v[204:207], 0
	v_mfma_f32_16x16x32_bf16 v[66:69], v[180:183], v[212:215], 0
	v_mfma_f32_16x16x32_bf16 v[70:73], v[172:175], v[212:215], 0
	v_mfma_f32_16x16x32_bf16 v[98:101], v[164:167], v[212:215], 0
	v_mfma_f32_16x16x32_bf16 v[102:105], v[156:159], v[212:215], 0
	v_mfma_f32_16x16x32_bf16 v[126:129], v[160:163], v[192:195], v[126:129]
	v_mfma_f32_16x16x32_bf16 v[122:125], v[168:171], v[192:195], v[122:125]
	v_mfma_f32_16x16x32_bf16 v[94:97], v[176:179], v[192:195], v[94:97]
	v_mfma_f32_16x16x32_bf16 v[90:93], v[184:187], v[192:195], v[90:93]
	v_mfma_f32_16x16x32_bf16 v[82:85], v[184:187], v[200:203], v[82:85]
	v_mfma_f32_16x16x32_bf16 v[86:89], v[176:179], v[200:203], v[86:89]
	v_mfma_f32_16x16x32_bf16 v[114:117], v[168:171], v[200:203], v[114:117]
	v_mfma_f32_16x16x32_bf16 v[118:121], v[160:163], v[200:203], v[118:121]
	v_mfma_f32_16x16x32_bf16 v[110:113], v[160:163], v[208:211], v[110:113]
	v_mfma_f32_16x16x32_bf16 v[106:109], v[168:171], v[208:211], v[106:109]
	v_mfma_f32_16x16x32_bf16 v[78:81], v[176:179], v[208:211], v[78:81]
	v_mfma_f32_16x16x32_bf16 v[74:77], v[184:187], v[208:211], v[74:77]
	v_mfma_f32_16x16x32_bf16 v[66:69], v[184:187], v[216:219], v[66:69]
	v_mfma_f32_16x16x32_bf16 v[70:73], v[176:179], v[216:219], v[70:73]
	v_mfma_f32_16x16x32_bf16 v[98:101], v[168:171], v[216:219], v[98:101]
	v_mfma_f32_16x16x32_bf16 v[102:105], v[160:163], v[216:219], v[102:105]
	s_barrier
	s_add_i32 s77, s69, s54
	v_lshl_add_u64 v[150:151], s[48:49], 0, v[132:133]
	s_mov_b32 m0, s77
	ds_read_b128 v[188:191], v154 offset:16384
	ds_read_b128 v[192:195], v154 offset:17408
	ds_read_b128 v[196:199], v154 offset:18432
	ds_read_b128 v[200:203], v154 offset:19456
	ds_read_b128 v[204:207], v154 offset:20480
	ds_read_b128 v[208:211], v154 offset:21504
	ds_read_b128 v[212:215], v154 offset:22528
	ds_read_b128 v[216:219], v154 offset:23552
	global_load_lds_dwordx4 v[150:151], off
	s_add_i32 m0, s77, 0x2000
	s_add_u32 s78, s48, 0x40000
	v_lshl_add_u64 v[220:221], s[48:49], 0, v[136:137]
	s_addc_u32 s79, s49, 0
	s_add_i32 s77, s70, s54
	global_load_lds_dwordx4 v[220:221], off
	v_lshl_add_u64 v[222:223], s[78:79], 0, v[132:133]
	s_mov_b32 m0, s77
	v_lshl_add_u64 v[224:225], s[50:51], 0, v[134:135]
	global_load_lds_dwordx4 v[222:223], off
	v_lshl_add_u64 v[222:223], s[78:79], 0, v[136:137]
	s_add_i32 m0, s77, 0x2000
	s_nop 0
	global_load_lds_dwordx4 v[222:223], off
	v_lshl_add_u64 v[222:223], s[50:51], 0, v[130:131]
	s_mov_b32 m0, s15
	s_nop 0
	global_load_lds_dwordx4 v[222:223], off
	s_mov_b32 m0, s17
	s_nop 0
	global_load_lds_dwordx4 v[224:225], off
	s_waitcnt vmcnt(8)
	s_waitcnt lgkmcnt(0)
	s_barrier
; #define PG8_STAGEA(bufoff, gbase) PG8_STAGE_(bufoff, gbase, voffA)
; #define PG8_STAGEB(bufoff, gbase) PG8_STAGE_(bufoff, gbase, voffB)
; #define PG8_LDA(dst, b, h) do { _Pragma("unroll") for (int m = 0; m < 4; ++m) _Pragma("unroll") for (int k = 0; k < 2; ++k) dst[m][k] = *(const LAS bf16x8*)(lds + PG8_SA(b, h) + aoff + m * 2048 + k * 1024); } while (0)
; #define PG8_LDB(dst, b, h) do { _Pragma("unroll") for (int n = 0; n < 2; ++n) _Pragma("unroll") for (int k = 0; k < 2; ++k) dst[n][k] = *(const LAS bf16x8*)(lds + PG8_SB(b, h) + boff + n * 2048 + k * 1024); } while (0)
; #define PG8_MMA(ai, bj, At, Bt_) do { __builtin_amdgcn_s_setprio(1); _Pragma("unroll") for (int m = 0; m < 4; ++m) _Pragma("unroll") for (int n = 0; n < 2; ++n) _Pragma("unroll") for (int k = 0; k < 2; ++k) \
;         acc[ai][bj][m][n] = __builtin_amdgcn_mfma_f32_16x16x32_bf16(Bt_[n][k], At[m][k], acc[ai][bj][m][n], 0, 0, 0); __builtin_amdgcn_s_setprio(0); } while (0)
; #define PG8_WAIT_V(n) asm volatile("s_waitcnt vmcnt(" #n ")" ::: "memory")
; #define PG8_WAIT_L(n) asm volatile("s_waitcnt lgkmcnt(" #n ")" ::: "memory")
; #define PG8_BAR __builtin_amdgcn_s_barrier()
; #define PG8_SCHED __builtin_amdgcn_sched_barrier(0)
; template <int EK, int SK = -1>
; __device__ __forceinline__ void gemm_phase(LAS unsigned char* lds, const bf16_t* A, const bf16_t* Bt, int nM, int N, int K, const EpiArgs& E) {
;     ...
;             PG8_LDA(At, 0, 1); PG8_STAGEB(PG8_SB(0, 0), b2); PG8_STAGEB(PG8_SB(0, 1), b2 + hstep); PG8_STAGEA(PG8_SA(0, 0), a2);
;             PG8_WAIT_V(8); PG8_WAIT_L(0); PG8_BAR; PG8_MMA(1, 0, At, B0); PG8_MMA(1, 1, At, B1); PG8_BAR; PG8_SCHED;
;             PG8_LDB(B0, 1, 0); PG8_LDB(B1, 1, 1); PG8_SCHED; PG8_LDA(At, 1, 0); PG8_STAGEA(PG8_SA(0, 1), a2 + hstep);
;             PG8_WAIT_V(8); PG8_WAIT_L(0); PG8_BAR; PG8_MMA(0, 0, At, B0); PG8_MMA(0, 1, At, B1); PG8_BAR; PG8_SCHED;
	s_waitcnt lgkmcnt(0)
	v_mfma_f32_16x16x32_bf16 v[62:65], v[156:159], v[188:191], 0
	v_mfma_f32_16x16x32_bf16 v[58:61], v[164:167], v[188:191], 0
	v_mfma_f32_16x16x32_bf16 v[30:33], v[172:175], v[188:191], 0
	v_mfma_f32_16x16x32_bf16 v[26:29], v[180:183], v[188:191], 0
	v_mfma_f32_16x16x32_bf16 v[18:21], v[180:183], v[196:199], 0
	v_mfma_f32_16x16x32_bf16 v[22:25], v[172:175], v[196:199], 0
	v_mfma_f32_16x16x32_bf16 v[50:53], v[164:167], v[196:199], 0
	v_mfma_f32_16x16x32_bf16 v[54:57], v[156:159], v[196:199], 0
	v_mfma_f32_16x16x32_bf16 v[46:49], v[156:159], v[204:207], 0
	v_mfma_f32_16x16x32_bf16 v[42:45], v[164:167], v[204:207], 0
	v_mfma_f32_16x16x32_bf16 v[14:17], v[172:175], v[204:207], 0
	v_mfma_f32_16x16x32_bf16 v[10:13], v[180:183], v[204:207], 0
	v_mfma_f32_16x16x32_bf16 v[2:5], v[180:183], v[212:215], 0
	v_mfma_f32_16x16x32_bf16 v[6:9], v[172:175], v[212:215], 0
	v_mfma_f32_16x16x32_bf16 v[34:37], v[164:167], v[212:215], 0
	v_mfma_f32_16x16x32_bf16 v[38:41], v[156:159], v[212:215], 0
	v_mfma_f32_16x16x32_bf16 v[62:65], v[160:163], v[192:195], v[62:65]
	v_mfma_f32_16x16x32_bf16 v[58:61], v[168:171], v[192:195], v[58:61]
	v_mfma_f32_16x16x32_bf16 v[30:33], v[176:179], v[192:195], v[30:33]
	v_mfma_f32_16x16x32_bf16 v[26:29], v[184:187], v[192:195], v[26:29]
	v_mfma_f32_16x16x32_bf16 v[18:21], v[184:187], v[200:203], v[18:21]
	v_mfma_f32_16x16x32_bf16 v[22:25], v[176:179], v[200:203], v[22:25]
	v_mfma_f32_16x16x32_bf16 v[50:53], v[168:171], v[200:203], v[50:53]
	v_mfma_f32_16x16x32_bf16 v[54:57], v[160:163], v[200:203], v[54:57]
	v_mfma_f32_16x16x32_bf16 v[46:49], v[160:163], v[208:211], v[46:49]
	v_mfma_f32_16x16x32_bf16 v[42:45], v[168:171], v[208:211], v[42:45]
	v_mfma_f32_16x16x32_bf16 v[14:17], v[176:179], v[208:211], v[14:17]
	v_mfma_f32_16x16x32_bf16 v[10:13], v[184:187], v[208:211], v[10:13]
	v_mfma_f32_16x16x32_bf16 v[2:5], v[184:187], v[216:219], v[2:5]
	v_mfma_f32_16x16x32_bf16 v[6:9], v[176:179], v[216:219], v[6:9]
	v_mfma_f32_16x16x32_bf16 v[34:37], v[168:171], v[216:219], v[34:37]
	v_mfma_f32_16x16x32_bf16 v[38:41], v[160:163], v[216:219], v[38:41]
	s_barrier
	s_add_i32 s77, 0, 0x18000
	s_add_i32 s78, 0, 0x1c000
	v_add_u32_e32 v168, s77, v152
	v_add_u32_e32 v184, s78, v152
	ds_read_b128 v[156:159], v168
	ds_read_b128 v[160:163], v168 offset:1024
	ds_read_b128 v[164:167], v168 offset:2048
	ds_read_b128 v[168:171], v168 offset:3072
	ds_read_b128 v[172:175], v184
	ds_read_b128 v[176:179], v184 offset:1024
	ds_read_b128 v[180:183], v184 offset:2048
	ds_read_b128 v[184:187], v184 offset:3072
	s_add_u32 s50, s50, 0x40000
	s_addc_u32 s51, s51, 0
	s_mov_b32 m0, s55
	v_lshl_add_u64 v[226:227], s[50:51], 0, v[130:131]
	ds_read_b128 v[188:191], v154 offset:32768
	ds_read_b128 v[192:195], v154 offset:33792
	ds_read_b128 v[196:199], v154 offset:34816
	ds_read_b128 v[200:203], v154 offset:35840
	ds_read_b128 v[204:207], v154 offset:36864
	ds_read_b128 v[208:211], v154 offset:37888
	ds_read_b128 v[212:215], v154 offset:38912
	ds_read_b128 v[216:219], v154 offset:39936
	global_load_lds_dwordx4 v[226:227], off
	v_lshl_add_u64 v[226:227], s[50:51], 0, v[134:135]
	s_mov_b32 m0, s56
	s_nop 0
	global_load_lds_dwordx4 v[226:227], off
	s_waitcnt vmcnt(8)
	s_waitcnt lgkmcnt(0)
	s_barrier
	s_waitcnt lgkmcnt(0)
	v_mfma_f32_16x16x32_bf16 v[126:129], v[156:159], v[188:191], v[126:129]
	v_mfma_f32_16x16x32_bf16 v[122:125], v[164:167], v[188:191], v[122:125]
	v_mfma_f32_16x16x32_bf16 v[94:97], v[172:175], v[188:191], v[94:97]
	v_mfma_f32_16x16x32_bf16 v[90:93], v[180:183], v[188:191], v[90:93]
	v_mfma_f32_16x16x32_bf16 v[82:85], v[180:183], v[196:199], v[82:85]
	v_mfma_f32_16x16x32_bf16 v[86:89], v[172:175], v[196:199], v[86:89]
	v_mfma_f32_16x16x32_bf16 v[114:117], v[164:167], v[196:199], v[114:117]
	v_mfma_f32_16x16x32_bf16 v[118:121], v[156:159], v[196:199], v[118:121]
	v_mfma_f32_16x16x32_bf16 v[110:113], v[156:159], v[204:207], v[110:113]
	v_mfma_f32_16x16x32_bf16 v[106:109], v[164:167], v[204:207], v[106:109]
	v_mfma_f32_16x16x32_bf16 v[78:81], v[172:175], v[204:207], v[78:81]
	v_mfma_f32_16x16x32_bf16 v[74:77], v[180:183], v[204:207], v[74:77]
	v_mfma_f32_16x16x32_bf16 v[66:69], v[180:183], v[212:215], v[66:69]
	v_mfma_f32_16x16x32_bf16 v[70:73], v[172:175], v[212:215], v[70:73]
	v_mfma_f32_16x16x32_bf16 v[98:101], v[164:167], v[212:215], v[98:101]
	v_mfma_f32_16x16x32_bf16 v[102:105], v[156:159], v[212:215], v[102:105]
	v_mfma_f32_16x16x32_bf16 v[126:129], v[160:163], v[192:195], v[126:129]
	v_mfma_f32_16x16x32_bf16 v[122:125], v[168:171], v[192:195], v[122:125]
	v_mfma_f32_16x16x32_bf16 v[94:97], v[176:179], v[192:195], v[94:97]
	v_mfma_f32_16x16x32_bf16 v[90:93], v[184:187], v[192:195], v[90:93]
	v_mfma_f32_16x16x32_bf16 v[82:85], v[184:187], v[200:203], v[82:85]
	v_mfma_f32_16x16x32_bf16 v[86:89], v[176:179], v[200:203], v[86:89]
	v_mfma_f32_16x16x32_bf16 v[114:117], v[168:171], v[200:203], v[114:117]
	v_mfma_f32_16x16x32_bf16 v[118:121], v[160:163], v[200:203], v[118:121]
	v_mfma_f32_16x16x32_bf16 v[110:113], v[160:163], v[208:211], v[110:113]
	v_mfma_f32_16x16x32_bf16 v[106:109], v[168:171], v[208:211], v[106:109]
	v_mfma_f32_16x16x32_bf16 v[78:81], v[176:179], v[208:211], v[78:81]
	v_mfma_f32_16x16x32_bf16 v[74:77], v[184:187], v[208:211], v[74:77]
	v_mfma_f32_16x16x32_bf16 v[66:69], v[184:187], v[216:219], v[66:69]
	v_mfma_f32_16x16x32_bf16 v[70:73], v[176:179], v[216:219], v[70:73]
	v_mfma_f32_16x16x32_bf16 v[98:101], v[168:171], v[216:219], v[98:101]
	v_mfma_f32_16x16x32_bf16 v[102:105], v[160:163], v[216:219], v[102:105]
	s_barrier
; #define PG8_STAGEA(bufoff, gbase) PG8_STAGE_(bufoff, gbase, voffA)
; #define PG8_STAGEB(bufoff, gbase) PG8_STAGE_(bufoff, gbase, voffB)
; #define PG8_LDA(dst, b, h) do { _Pragma("unroll") for (int m = 0; m < 4; ++m) _Pragma("unroll") for (int k = 0; k < 2; ++k) dst[m][k] = *(const LAS bf16x8*)(lds + PG8_SA(b, h) + aoff + m * 2048 + k * 1024); } while (0)
; #define PG8_LDB(dst, b, h) do { _Pragma("unroll") for (int n = 0; n < 2; ++n) _Pragma("unroll") for (int k = 0; k < 2; ++k) dst[n][k] = *(const LAS bf16x8*)(lds + PG8_SB(b, h) + boff + n * 2048 + k * 1024); } while (0)
; #define PG8_MMA(ai, bj, At, Bt_) do { __builtin_amdgcn_s_setprio(1); _Pragma("unroll") for (int m = 0; m < 4; ++m) _Pragma("unroll") for (int n = 0; n < 2; ++n) _Pragma("unroll") for (int k = 0; k < 2; ++k) \
;         acc[ai][bj][m][n] = __builtin_amdgcn_mfma_f32_16x16x32_bf16(Bt_[n][k], At[m][k], acc[ai][bj][m][n], 0, 0, 0); __builtin_amdgcn_s_setprio(0); } while (0)
; #define PG8_WAIT_V(n) asm volatile("s_waitcnt vmcnt(" #n ")" ::: "memory")
; #define PG8_WAIT_L(n) asm volatile("s_waitcnt lgkmcnt(" #n ")" ::: "memory")
; #define PG8_BAR __builtin_amdgcn_s_barrier()
; #define PG8_SCHED __builtin_amdgcn_sched_barrier(0)
; template <int EK, int SK = -1>
; __device__ __forceinline__ void gemm_phase(LAS unsigned char* lds, const bf16_t* A, const bf16_t* Bt, int nM, int N, int K, const EpiArgs& E) {
;     ...
;             PG8_LDB(B0, 0, 0); PG8_LDB(B1, 0, 1); PG8_SCHED; PG8_LDA(At, 0, 0); PG8_STAGEA(PG8_SA(1, 1), a1 + hstep);
;             PG8_WAIT_V(8); PG8_WAIT_L(0); PG8_BAR; PG8_MMA(0, 0, At, B0); PG8_MMA(0, 1, At, B1); PG8_BAR; PG8_SCHED;
;             PG8_LDA(At, 0, 1); PG8_STAGEB(PG8_SB(0, 0), b2); PG8_STAGEB(PG8_SB(0, 1), b2 + hstep); PG8_STAGEA(PG8_SA(0, 0), a2);
;             PG8_WAIT_V(8); PG8_WAIT_L(0); PG8_BAR; PG8_MMA(1, 0, At, B0); PG8_MMA(1, 1, At, B1); PG8_BAR; PG8_SCHED;
;             PG8_LDB(B0, 1, 0); PG8_LDB(B1, 1, 1); PG8_SCHED; PG8_LDA(At, 1, 0); PG8_STAGEA(PG8_SA(0, 1), a2 + hstep);
;             PG8_WAIT_V(8); PG8_WAIT_L(0); PG8_BAR; PG8_MMA(0, 0, At, B0); PG8_MMA(0, 1, At, B1); PG8_BAR; PG8_SCHED;
;             PG8_LDA(At, 1, 1); PG8_STAGEB(PG8_SB(1, 0), b3); PG8_STAGEB(PG8_SB(1, 1), b3 + hstep); PG8_STAGEA(PG8_SA(1, 0), a3);
;             PG8_WAIT_V(8); PG8_WAIT_L(0); PG8_BAR; PG8_MMA(1, 0, At, B0); PG8_MMA(1, 1, At, B1); PG8_BAR; PG8_SCHED;
;         }
	s_add_i32 s50, s77, s54
	v_lshl_add_u64 v[150:151], v[150:151], 0, s[26:27]
	s_mov_b32 m0, s50
	ds_read_b128 v[188:191], v154 offset:49152
	ds_read_b128 v[192:195], v154 offset:50176
	ds_read_b128 v[196:199], v154 offset:51200
	ds_read_b128 v[200:203], v154 offset:52224
	ds_read_b128 v[204:207], v154 offset:53248
	ds_read_b128 v[208:211], v154 offset:54272
	ds_read_b128 v[212:215], v154 offset:55296
	ds_read_b128 v[216:219], v154 offset:56320
	global_load_lds_dwordx4 v[150:151], off
	s_add_i32 m0, s50, 0x2000
	s_add_u32 s48, s48, 0x40080
	v_lshl_add_u64 v[150:151], v[220:221], 0, s[26:27]
	s_addc_u32 s49, s49, 0
	s_add_i32 s50, s78, s54
	global_load_lds_dwordx4 v[150:151], off
	v_lshl_add_u64 v[150:151], s[48:49], 0, v[132:133]
	s_mov_b32 m0, s50
	s_nop 0
	global_load_lds_dwordx4 v[150:151], off
	v_lshl_add_u64 v[150:151], s[48:49], 0, v[136:137]
	s_add_i32 m0, s50, 0x2000
	s_nop 0
	global_load_lds_dwordx4 v[150:151], off
	v_lshl_add_u64 v[150:151], v[222:223], 0, s[26:27]
	s_mov_b32 m0, s59
	s_nop 0
	global_load_lds_dwordx4 v[150:151], off
	v_lshl_add_u64 v[150:151], v[224:225], 0, s[26:27]
	s_mov_b32 m0, s68
	s_nop 0
	global_load_lds_dwordx4 v[150:151], off
	s_waitcnt vmcnt(8)
	s_waitcnt lgkmcnt(0)
	s_barrier
	s_waitcnt lgkmcnt(0)
	v_mfma_f32_16x16x32_bf16 v[62:65], v[156:159], v[188:191], v[62:65]
	v_mfma_f32_16x16x32_bf16 v[58:61], v[164:167], v[188:191], v[58:61]
	v_mfma_f32_16x16x32_bf16 v[30:33], v[172:175], v[188:191], v[30:33]
	v_mfma_f32_16x16x32_bf16 v[26:29], v[180:183], v[188:191], v[26:29]
	v_mfma_f32_16x16x32_bf16 v[18:21], v[180:183], v[196:199], v[18:21]
	v_mfma_f32_16x16x32_bf16 v[22:25], v[172:175], v[196:199], v[22:25]
	v_mfma_f32_16x16x32_bf16 v[50:53], v[164:167], v[196:199], v[50:53]
	v_mfma_f32_16x16x32_bf16 v[54:57], v[156:159], v[196:199], v[54:57]
	v_mfma_f32_16x16x32_bf16 v[46:49], v[156:159], v[204:207], v[46:49]
	v_mfma_f32_16x16x32_bf16 v[42:45], v[164:167], v[204:207], v[42:45]
	v_mfma_f32_16x16x32_bf16 v[14:17], v[172:175], v[204:207], v[14:17]
	v_mfma_f32_16x16x32_bf16 v[10:13], v[180:183], v[204:207], v[10:13]
	v_mfma_f32_16x16x32_bf16 v[2:5], v[180:183], v[212:215], v[2:5]
	v_mfma_f32_16x16x32_bf16 v[6:9], v[172:175], v[212:215], v[6:9]
	v_mfma_f32_16x16x32_bf16 v[34:37], v[164:167], v[212:215], v[34:37]
	v_mfma_f32_16x16x32_bf16 v[38:41], v[156:159], v[212:215], v[38:41]
	v_mfma_f32_16x16x32_bf16 v[62:65], v[160:163], v[192:195], v[62:65]
	v_mfma_f32_16x16x32_bf16 v[58:61], v[168:171], v[192:195], v[58:61]
	v_mfma_f32_16x16x32_bf16 v[30:33], v[176:179], v[192:195], v[30:33]
	v_mfma_f32_16x16x32_bf16 v[26:29], v[184:187], v[192:195], v[26:29]
	v_mfma_f32_16x16x32_bf16 v[18:21], v[184:187], v[200:203], v[18:21]
	v_mfma_f32_16x16x32_bf16 v[22:25], v[176:179], v[200:203], v[22:25]
	v_mfma_f32_16x16x32_bf16 v[50:53], v[168:171], v[200:203], v[50:53]
	v_mfma_f32_16x16x32_bf16 v[54:57], v[160:163], v[200:203], v[54:57]
	v_mfma_f32_16x16x32_bf16 v[46:49], v[160:163], v[208:211], v[46:49]
	v_mfma_f32_16x16x32_bf16 v[42:45], v[168:171], v[208:211], v[42:45]
	v_mfma_f32_16x16x32_bf16 v[14:17], v[176:179], v[208:211], v[14:17]
	v_mfma_f32_16x16x32_bf16 v[10:13], v[184:187], v[208:211], v[10:13]
	v_mfma_f32_16x16x32_bf16 v[2:5], v[184:187], v[216:219], v[2:5]
	v_mfma_f32_16x16x32_bf16 v[6:9], v[176:179], v[216:219], v[6:9]
	v_mfma_f32_16x16x32_bf16 v[34:37], v[168:171], v[216:219], v[34:37]
	v_mfma_f32_16x16x32_bf16 v[38:41], v[160:163], v[216:219], v[38:41]
	s_barrier
	s_add_i32 s76, s76, 2
	s_add_u32 s46, s46, 0x100
	s_addc_u32 s47, s47, 0
	s_cmp_gt_u32 s76, 13
	s_cbranch_scc0 .LBB0_1120
	s_branch .Lmy_kexit_5
.LBB0_1120:
	v_add_u32_e32 v150, s69, v152
	ds_read_b128 v[156:159], v150
	ds_read_b128 v[160:163], v150 offset:1024
	ds_read_b128 v[164:167], v150 offset:2048
	ds_read_b128 v[168:171], v150 offset:3072
	v_add_u32_e32 v150, s70, v152
	s_add_u32 s48, s18, s46
	ds_read_b128 v[172:175], v150
	ds_read_b128 v[176:179], v150 offset:1024
	ds_read_b128 v[180:183], v150 offset:2048
	ds_read_b128 v[184:187], v150 offset:3072
	s_addc_u32 s49, s19, s47
	s_add_u32 s48, s48, 0x100
	s_addc_u32 s49, s49, 0
	s_add_u32 s77, s73, s46
	s_addc_u32 s78, s74, s47
	s_cmpk_eq_i32 s46, 0x700
	s_cselect_b32 s51, s22, s49
	s_cselect_b32 s50, s41, s48
	s_cselect_b32 s49, s39, s78
	s_cselect_b32 s48, s75, s77
	v_lshl_add_u64 v[150:151], v[146:147], 0, s[46:47]
	s_add_i32 m0, s15, 0xc000
	ds_read_b128 v[188:191], v154
	ds_read_b128 v[192:195], v154 offset:1024
	ds_read_b128 v[196:199], v154 offset:2048
	ds_read_b128 v[200:203], v154 offset:3072
	ds_read_b128 v[204:207], v154 offset:4096
	ds_read_b128 v[208:211], v154 offset:5120
	ds_read_b128 v[212:215], v154 offset:6144
	ds_read_b128 v[216:219], v154 offset:7168
	global_load_lds_dwordx4 v[150:151], off
	v_lshl_add_u64 v[150:151], v[148:149], 0, s[46:47]
	s_add_i32 m0, s15, 0xe000
	s_nop 0
	global_load_lds_dwordx4 v[150:151], off
	s_waitcnt vmcnt(8)
	s_waitcnt lgkmcnt(0)
	s_barrier
; #define PG8_STAGEA(bufoff, gbase) PG8_STAGE_(bufoff, gbase, voffA)
; #define PG8_STAGEB(bufoff, gbase) PG8_STAGE_(bufoff, gbase, voffB)
; #define PG8_LDA(dst, b, h) do { _Pragma("unroll") for (int m = 0; m < 4; ++m) _Pragma("unroll") for (int k = 0; k < 2; ++k) dst[m][k] = *(const LAS bf16x8*)(lds + PG8_SA(b, h) + aoff + m * 2048 + k * 1024); } while (0)
; #define PG8_LDB(dst, b, h) do { _Pragma("unroll") for (int n = 0; n < 2; ++n) _Pragma("unroll") for (int k = 0; k < 2; ++k) dst[n][k] = *(const LAS bf16x8*)(lds + PG8_SB(b, h) + boff + n * 2048 + k * 1024); } while (0)
; #define PG8_MMA(ai, bj, At, Bt_) do { __builtin_amdgcn_s_setprio(1); _Pragma("unroll") for (int m = 0; m < 4; ++m) _Pragma("unroll") for (int n = 0; n < 2; ++n) _Pragma("unroll") for (int k = 0; k < 2; ++k) \
;         acc[ai][bj][m][n] = __builtin_amdgcn_mfma_f32_16x16x32_bf16(Bt_[n][k], At[m][k], acc[ai][bj][m][n], 0, 0, 0); __builtin_amdgcn_s_setprio(0); } while (0)
; #define PG8_WAIT_V(n) asm volatile("s_waitcnt vmcnt(" #n ")" ::: "memory")
; #define PG8_WAIT_L(n) asm volatile("s_waitcnt lgkmcnt(" #n ")" ::: "memory")
; #define PG8_BAR __builtin_amdgcn_s_barrier()
; #define PG8_SCHED __builtin_amdgcn_sched_barrier(0)
; template <int EK, int SK = -1>
; __device__ __forceinline__ void gemm_phase(LAS unsigned char* lds, const bf16_t* A, const bf16_t* Bt, int nM, int N, int K, const EpiArgs& E) {
;     ...
;             PG8_LDB(B0, 0, 0); PG8_LDB(B1, 0, 1); PG8_SCHED; PG8_LDA(At, 0, 0); PG8_STAGEA(PG8_SA(1, 1), a1 + hstep);
;             PG8_WAIT_V(8); PG8_WAIT_L(0); PG8_BAR; PG8_MMA(0, 0, At, B0); PG8_MMA(0, 1, At, B1); PG8_BAR; PG8_SCHED;
;             PG8_LDA(At, 0, 1); PG8_STAGEB(PG8_SB(0, 0), b2); PG8_STAGEB(PG8_SB(0, 1), b2 + hstep); PG8_STAGEA(PG8_SA(0, 0), a2);
;             PG8_WAIT_V(8); PG8_WAIT_L(0); PG8_BAR; PG8_MMA(1, 0, At, B0); PG8_MMA(1, 1, At, B1); PG8_BAR; PG8_SCHED;
	s_waitcnt lgkmcnt(0)
	v_mfma_f32_16x16x32_bf16 v[126:129], v[156:159], v[188:191], v[126:129]
	v_mfma_f32_16x16x32_bf16 v[122:125], v[164:167], v[188:191], v[122:125]
	v_mfma_f32_16x16x32_bf16 v[94:97], v[172:175], v[188:191], v[94:97]
	v_mfma_f32_16x16x32_bf16 v[90:93], v[180:183], v[188:191], v[90:93]
	v_mfma_f32_16x16x32_bf16 v[82:85], v[180:183], v[196:199], v[82:85]
	v_mfma_f32_16x16x32_bf16 v[86:89], v[172:175], v[196:199], v[86:89]
	v_mfma_f32_16x16x32_bf16 v[114:117], v[164:167], v[196:199], v[114:117]
	v_mfma_f32_16x16x32_bf16 v[118:121], v[156:159], v[196:199], v[118:121]
	v_mfma_f32_16x16x32_bf16 v[110:113], v[156:159], v[204:207], v[110:113]
	v_mfma_f32_16x16x32_bf16 v[106:109], v[164:167], v[204:207], v[106:109]
	v_mfma_f32_16x16x32_bf16 v[78:81], v[172:175], v[204:207], v[78:81]
	v_mfma_f32_16x16x32_bf16 v[74:77], v[180:183], v[204:207], v[74:77]
	v_mfma_f32_16x16x32_bf16 v[66:69], v[180:183], v[212:215], v[66:69]
	v_mfma_f32_16x16x32_bf16 v[70:73], v[172:175], v[212:215], v[70:73]
	v_mfma_f32_16x16x32_bf16 v[98:101], v[164:167], v[212:215], v[98:101]
	v_mfma_f32_16x16x32_bf16 v[102:105], v[156:159], v[212:215], v[102:105]
	v_mfma_f32_16x16x32_bf16 v[126:129], v[160:163], v[192:195], v[126:129]
	v_mfma_f32_16x16x32_bf16 v[122:125], v[168:171], v[192:195], v[122:125]
	v_mfma_f32_16x16x32_bf16 v[94:97], v[176:179], v[192:195], v[94:97]
	v_mfma_f32_16x16x32_bf16 v[90:93], v[184:187], v[192:195], v[90:93]
	v_mfma_f32_16x16x32_bf16 v[82:85], v[184:187], v[200:203], v[82:85]
	v_mfma_f32_16x16x32_bf16 v[86:89], v[176:179], v[200:203], v[86:89]
	v_mfma_f32_16x16x32_bf16 v[114:117], v[168:171], v[200:203], v[114:117]
	v_mfma_f32_16x16x32_bf16 v[118:121], v[160:163], v[200:203], v[118:121]
	v_mfma_f32_16x16x32_bf16 v[110:113], v[160:163], v[208:211], v[110:113]
	v_mfma_f32_16x16x32_bf16 v[106:109], v[168:171], v[208:211], v[106:109]
	v_mfma_f32_16x16x32_bf16 v[78:81], v[176:179], v[208:211], v[78:81]
	v_mfma_f32_16x16x32_bf16 v[74:77], v[184:187], v[208:211], v[74:77]
	v_mfma_f32_16x16x32_bf16 v[66:69], v[184:187], v[216:219], v[66:69]
	v_mfma_f32_16x16x32_bf16 v[70:73], v[176:179], v[216:219], v[70:73]
	v_mfma_f32_16x16x32_bf16 v[98:101], v[168:171], v[216:219], v[98:101]
	v_mfma_f32_16x16x32_bf16 v[102:105], v[160:163], v[216:219], v[102:105]
	s_barrier
	s_add_i32 s77, s69, s54
	v_lshl_add_u64 v[150:151], s[48:49], 0, v[132:133]
	s_mov_b32 m0, s77
	ds_read_b128 v[188:191], v154 offset:16384
	ds_read_b128 v[192:195], v154 offset:17408
	ds_read_b128 v[196:199], v154 offset:18432
	ds_read_b128 v[200:203], v154 offset:19456
	ds_read_b128 v[204:207], v154 offset:20480
	ds_read_b128 v[208:211], v154 offset:21504
	ds_read_b128 v[212:215], v154 offset:22528
	ds_read_b128 v[216:219], v154 offset:23552
	global_load_lds_dwordx4 v[150:151], off
	s_add_i32 m0, s77, 0x2000
	s_add_u32 s78, s48, 0x40000
	v_lshl_add_u64 v[220:221], s[48:49], 0, v[136:137]
	s_addc_u32 s79, s49, 0
	s_add_i32 s77, s70, s54
	global_load_lds_dwordx4 v[220:221], off
	v_lshl_add_u64 v[222:223], s[78:79], 0, v[132:133]
	s_mov_b32 m0, s77
	v_lshl_add_u64 v[224:225], s[50:51], 0, v[134:135]
	global_load_lds_dwordx4 v[222:223], off
	v_lshl_add_u64 v[222:223], s[78:79], 0, v[136:137]
	s_add_i32 m0, s77, 0x2000
	s_nop 0
	global_load_lds_dwordx4 v[222:223], off
	v_lshl_add_u64 v[222:223], s[50:51], 0, v[130:131]
	s_mov_b32 m0, s15
	s_nop 0
	global_load_lds_dwordx4 v[222:223], off
	s_mov_b32 m0, s17
	s_nop 0
	global_load_lds_dwordx4 v[224:225], off
	s_waitcnt vmcnt(8)
	s_waitcnt lgkmcnt(0)
	s_barrier
	s_waitcnt lgkmcnt(0)
	v_mfma_f32_16x16x32_bf16 v[62:65], v[156:159], v[188:191], v[62:65]
	v_mfma_f32_16x16x32_bf16 v[58:61], v[164:167], v[188:191], v[58:61]
	v_mfma_f32_16x16x32_bf16 v[30:33], v[172:175], v[188:191], v[30:33]
	v_mfma_f32_16x16x32_bf16 v[26:29], v[180:183], v[188:191], v[26:29]
	v_mfma_f32_16x16x32_bf16 v[18:21], v[180:183], v[196:199], v[18:21]
	v_mfma_f32_16x16x32_bf16 v[22:25], v[172:175], v[196:199], v[22:25]
	v_mfma_f32_16x16x32_bf16 v[50:53], v[164:167], v[196:199], v[50:53]
	v_mfma_f32_16x16x32_bf16 v[54:57], v[156:159], v[196:199], v[54:57]
	v_mfma_f32_16x16x32_bf16 v[46:49], v[156:159], v[204:207], v[46:49]
	v_mfma_f32_16x16x32_bf16 v[42:45], v[164:167], v[204:207], v[42:45]
	v_mfma_f32_16x16x32_bf16 v[14:17], v[172:175], v[204:207], v[14:17]
	v_mfma_f32_16x16x32_bf16 v[10:13], v[180:183], v[204:207], v[10:13]
	v_mfma_f32_16x16x32_bf16 v[2:5], v[180:183], v[212:215], v[2:5]
	v_mfma_f32_16x16x32_bf16 v[6:9], v[172:175], v[212:215], v[6:9]
	v_mfma_f32_16x16x32_bf16 v[34:37], v[164:167], v[212:215], v[34:37]
	v_mfma_f32_16x16x32_bf16 v[38:41], v[156:159], v[212:215], v[38:41]
	v_mfma_f32_16x16x32_bf16 v[62:65], v[160:163], v[192:195], v[62:65]
	v_mfma_f32_16x16x32_bf16 v[58:61], v[168:171], v[192:195], v[58:61]
	v_mfma_f32_16x16x32_bf16 v[30:33], v[176:179], v[192:195], v[30:33]
	v_mfma_f32_16x16x32_bf16 v[26:29], v[184:187], v[192:195], v[26:29]
	v_mfma_f32_16x16x32_bf16 v[18:21], v[184:187], v[200:203], v[18:21]
	v_mfma_f32_16x16x32_bf16 v[22:25], v[176:179], v[200:203], v[22:25]
	v_mfma_f32_16x16x32_bf16 v[50:53], v[168:171], v[200:203], v[50:53]
	v_mfma_f32_16x16x32_bf16 v[54:57], v[160:163], v[200:203], v[54:57]
	v_mfma_f32_16x16x32_bf16 v[46:49], v[160:163], v[208:211], v[46:49]
	v_mfma_f32_16x16x32_bf16 v[42:45], v[168:171], v[208:211], v[42:45]
	v_mfma_f32_16x16x32_bf16 v[14:17], v[176:179], v[208:211], v[14:17]
	v_mfma_f32_16x16x32_bf16 v[10:13], v[184:187], v[208:211], v[10:13]
	v_mfma_f32_16x16x32_bf16 v[2:5], v[184:187], v[216:219], v[2:5]
	v_mfma_f32_16x16x32_bf16 v[6:9], v[176:179], v[216:219], v[6:9]
	v_mfma_f32_16x16x32_bf16 v[34:37], v[168:171], v[216:219], v[34:37]
	v_mfma_f32_16x16x32_bf16 v[38:41], v[160:163], v[216:219], v[38:41]
	s_barrier
; #define PG8_STAGEA(bufoff, gbase) PG8_STAGE_(bufoff, gbase, voffA)
; #define PG8_STAGEB(bufoff, gbase) PG8_STAGE_(bufoff, gbase, voffB)
; #define PG8_LDA(dst, b, h) do { _Pragma("unroll") for (int m = 0; m < 4; ++m) _Pragma("unroll") for (int k = 0; k < 2; ++k) dst[m][k] = *(const LAS bf16x8*)(lds + PG8_SA(b, h) + aoff + m * 2048 + k * 1024); } while (0)
; #define PG8_LDB(dst, b, h) do { _Pragma("unroll") for (int n = 0; n < 2; ++n) _Pragma("unroll") for (int k = 0; k < 2; ++k) dst[n][k] = *(const LAS bf16x8*)(lds + PG8_SB(b, h) + boff + n * 2048 + k * 1024); } while (0)
; #define PG8_MMA(ai, bj, At, Bt_) do { __builtin_amdgcn_s_setprio(1); _Pragma("unroll") for (int m = 0; m < 4; ++m) _Pragma("unroll") for (int n = 0; n < 2; ++n) _Pragma("unroll") for (int k = 0; k < 2; ++k) \
;         acc[ai][bj][m][n] = __builtin_amdgcn_mfma_f32_16x16x32_bf16(Bt_[n][k], At[m][k], acc[ai][bj][m][n], 0, 0, 0); __builtin_amdgcn_s_setprio(0); } while (0)
; #define PG8_WAIT_V(n) asm volatile("s_waitcnt vmcnt(" #n ")" ::: "memory")
; #define PG8_WAIT_L(n) asm volatile("s_waitcnt lgkmcnt(" #n ")" ::: "memory")
; #define PG8_BAR __builtin_amdgcn_s_barrier()
; #define PG8_SCHED __builtin_amdgcn_sched_barrier(0)
; template <int EK, int SK = -1>
; __device__ __forceinline__ void gemm_phase(LAS unsigned char* lds, const bf16_t* A, const bf16_t* Bt, int nM, int N, int K, const EpiArgs& E) {
;     ...
;             PG8_LDB(B0, 1, 0); PG8_LDB(B1, 1, 1); PG8_SCHED; PG8_LDA(At, 1, 0); PG8_STAGEA(PG8_SA(0, 1), a2 + hstep);
;             PG8_WAIT_V(8); PG8_WAIT_L(0); PG8_BAR; PG8_MMA(0, 0, At, B0); PG8_MMA(0, 1, At, B1); PG8_BAR; PG8_SCHED;
;             PG8_LDA(At, 1, 1); PG8_STAGEB(PG8_SB(1, 0), b3); PG8_STAGEB(PG8_SB(1, 1), b3 + hstep); PG8_STAGEA(PG8_SA(1, 0), a3);
;             PG8_WAIT_V(8); PG8_WAIT_L(0); PG8_BAR; PG8_MMA(1, 0, At, B0); PG8_MMA(1, 1, At, B1); PG8_BAR; PG8_SCHED;
;         }
	s_add_i32 s77, 0, 0x18000
	s_add_i32 s78, 0, 0x1c000
	v_add_u32_e32 v168, s77, v152
	v_add_u32_e32 v184, s78, v152
	ds_read_b128 v[156:159], v168
	ds_read_b128 v[160:163], v168 offset:1024
	ds_read_b128 v[164:167], v168 offset:2048
	ds_read_b128 v[168:171], v168 offset:3072
	ds_read_b128 v[172:175], v184
	ds_read_b128 v[176:179], v184 offset:1024
	ds_read_b128 v[180:183], v184 offset:2048
	ds_read_b128 v[184:187], v184 offset:3072
	s_add_u32 s50, s50, 0x40000
	s_addc_u32 s51, s51, 0
	s_mov_b32 m0, s55
	v_lshl_add_u64 v[226:227], s[50:51], 0, v[130:131]
	ds_read_b128 v[188:191], v154 offset:32768
	ds_read_b128 v[192:195], v154 offset:33792
	ds_read_b128 v[196:199], v154 offset:34816
	ds_read_b128 v[200:203], v154 offset:35840
	ds_read_b128 v[204:207], v154 offset:36864
	ds_read_b128 v[208:211], v154 offset:37888
	ds_read_b128 v[212:215], v154 offset:38912
	ds_read_b128 v[216:219], v154 offset:39936
	global_load_lds_dwordx4 v[226:227], off
	v_lshl_add_u64 v[226:227], s[50:51], 0, v[134:135]
	s_mov_b32 m0, s56
	s_nop 0
	global_load_lds_dwordx4 v[226:227], off
	s_waitcnt vmcnt(8)
	s_waitcnt lgkmcnt(0)
	s_barrier
	s_waitcnt lgkmcnt(0)
	v_mfma_f32_16x16x32_bf16 v[126:129], v[156:159], v[188:191], v[126:129]
	v_mfma_f32_16x16x32_bf16 v[122:125], v[164:167], v[188:191], v[122:125]
	v_mfma_f32_16x16x32_bf16 v[94:97], v[172:175], v[188:191], v[94:97]
	v_mfma_f32_16x16x32_bf16 v[90:93], v[180:183], v[188:191], v[90:93]
	v_mfma_f32_16x16x32_bf16 v[82:85], v[180:183], v[196:199], v[82:85]
	v_mfma_f32_16x16x32_bf16 v[86:89], v[172:175], v[196:199], v[86:89]
	v_mfma_f32_16x16x32_bf16 v[114:117], v[164:167], v[196:199], v[114:117]
	v_mfma_f32_16x16x32_bf16 v[118:121], v[156:159], v[196:199], v[118:121]
	v_mfma_f32_16x16x32_bf16 v[110:113], v[156:159], v[204:207], v[110:113]
	v_mfma_f32_16x16x32_bf16 v[106:109], v[164:167], v[204:207], v[106:109]
	v_mfma_f32_16x16x32_bf16 v[78:81], v[172:175], v[204:207], v[78:81]
	v_mfma_f32_16x16x32_bf16 v[74:77], v[180:183], v[204:207], v[74:77]
	v_mfma_f32_16x16x32_bf16 v[66:69], v[180:183], v[212:215], v[66:69]
	v_mfma_f32_16x16x32_bf16 v[70:73], v[172:175], v[212:215], v[70:73]
	v_mfma_f32_16x16x32_bf16 v[98:101], v[164:167], v[212:215], v[98:101]
	v_mfma_f32_16x16x32_bf16 v[102:105], v[156:159], v[212:215], v[102:105]
	v_mfma_f32_16x16x32_bf16 v[126:129], v[160:163], v[192:195], v[126:129]
	v_mfma_f32_16x16x32_bf16 v[122:125], v[168:171], v[192:195], v[122:125]
	v_mfma_f32_16x16x32_bf16 v[94:97], v[176:179], v[192:195], v[94:97]
	v_mfma_f32_16x16x32_bf16 v[90:93], v[184:187], v[192:195], v[90:93]
	v_mfma_f32_16x16x32_bf16 v[82:85], v[184:187], v[200:203], v[82:85]
	v_mfma_f32_16x16x32_bf16 v[86:89], v[176:179], v[200:203], v[86:89]
	v_mfma_f32_16x16x32_bf16 v[114:117], v[168:171], v[200:203], v[114:117]
	v_mfma_f32_16x16x32_bf16 v[118:121], v[160:163], v[200:203], v[118:121]
	v_mfma_f32_16x16x32_bf16 v[110:113], v[160:163], v[208:211], v[110:113]
	v_mfma_f32_16x16x32_bf16 v[106:109], v[168:171], v[208:211], v[106:109]
	v_mfma_f32_16x16x32_bf16 v[78:81], v[176:179], v[208:211], v[78:81]
	v_mfma_f32_16x16x32_bf16 v[74:77], v[184:187], v[208:211], v[74:77]
	v_mfma_f32_16x16x32_bf16 v[66:69], v[184:187], v[216:219], v[66:69]
	v_mfma_f32_16x16x32_bf16 v[70:73], v[176:179], v[216:219], v[70:73]
	v_mfma_f32_16x16x32_bf16 v[98:101], v[168:171], v[216:219], v[98:101]
	v_mfma_f32_16x16x32_bf16 v[102:105], v[160:163], v[216:219], v[102:105]
	s_barrier
	s_add_i32 s50, s77, s54
	v_lshl_add_u64 v[150:151], v[150:151], 0, s[26:27]
	s_mov_b32 m0, s50
	ds_read_b128 v[188:191], v154 offset:49152
	ds_read_b128 v[192:195], v154 offset:50176
	ds_read_b128 v[196:199], v154 offset:51200
	ds_read_b128 v[200:203], v154 offset:52224
	ds_read_b128 v[204:207], v154 offset:53248
	ds_read_b128 v[208:211], v154 offset:54272
	ds_read_b128 v[212:215], v154 offset:55296
	ds_read_b128 v[216:219], v154 offset:56320
	global_load_lds_dwordx4 v[150:151], off
	s_add_i32 m0, s50, 0x2000
	s_add_u32 s48, s48, 0x40080
	v_lshl_add_u64 v[150:151], v[220:221], 0, s[26:27]
	s_addc_u32 s49, s49, 0
	s_add_i32 s50, s78, s54
	global_load_lds_dwordx4 v[150:151], off
	v_lshl_add_u64 v[150:151], s[48:49], 0, v[132:133]
	s_mov_b32 m0, s50
	s_nop 0
	global_load_lds_dwordx4 v[150:151], off
	v_lshl_add_u64 v[150:151], s[48:49], 0, v[136:137]
	s_add_i32 m0, s50, 0x2000
	s_nop 0
	global_load_lds_dwordx4 v[150:151], off
	v_lshl_add_u64 v[150:151], v[222:223], 0, s[26:27]
	s_mov_b32 m0, s59
	s_nop 0
	global_load_lds_dwordx4 v[150:151], off
	v_lshl_add_u64 v[150:151], v[224:225], 0, s[26:27]
	s_mov_b32 m0, s68
	s_nop 0
	global_load_lds_dwordx4 v[150:151], off
	s_waitcnt vmcnt(8)
	s_waitcnt lgkmcnt(0)
	s_barrier
	s_waitcnt lgkmcnt(0)
	v_mfma_f32_16x16x32_bf16 v[62:65], v[156:159], v[188:191], v[62:65]
	v_mfma_f32_16x16x32_bf16 v[58:61], v[164:167], v[188:191], v[58:61]
	v_mfma_f32_16x16x32_bf16 v[30:33], v[172:175], v[188:191], v[30:33]
	v_mfma_f32_16x16x32_bf16 v[26:29], v[180:183], v[188:191], v[26:29]
	v_mfma_f32_16x16x32_bf16 v[18:21], v[180:183], v[196:199], v[18:21]
	v_mfma_f32_16x16x32_bf16 v[22:25], v[172:175], v[196:199], v[22:25]
	v_mfma_f32_16x16x32_bf16 v[50:53], v[164:167], v[196:199], v[50:53]
	v_mfma_f32_16x16x32_bf16 v[54:57], v[156:159], v[196:199], v[54:57]
	v_mfma_f32_16x16x32_bf16 v[46:49], v[156:159], v[204:207], v[46:49]
	v_mfma_f32_16x16x32_bf16 v[42:45], v[164:167], v[204:207], v[42:45]
	v_mfma_f32_16x16x32_bf16 v[14:17], v[172:175], v[204:207], v[14:17]
	v_mfma_f32_16x16x32_bf16 v[10:13], v[180:183], v[204:207], v[10:13]
	v_mfma_f32_16x16x32_bf16 v[2:5], v[180:183], v[212:215], v[2:5]
	v_mfma_f32_16x16x32_bf16 v[6:9], v[172:175], v[212:215], v[6:9]
	v_mfma_f32_16x16x32_bf16 v[34:37], v[164:167], v[212:215], v[34:37]
	v_mfma_f32_16x16x32_bf16 v[38:41], v[156:159], v[212:215], v[38:41]
	v_mfma_f32_16x16x32_bf16 v[62:65], v[160:163], v[192:195], v[62:65]
	v_mfma_f32_16x16x32_bf16 v[58:61], v[168:171], v[192:195], v[58:61]
	v_mfma_f32_16x16x32_bf16 v[30:33], v[176:179], v[192:195], v[30:33]
	v_mfma_f32_16x16x32_bf16 v[26:29], v[184:187], v[192:195], v[26:29]
	v_mfma_f32_16x16x32_bf16 v[18:21], v[184:187], v[200:203], v[18:21]
	v_mfma_f32_16x16x32_bf16 v[22:25], v[176:179], v[200:203], v[22:25]
	v_mfma_f32_16x16x32_bf16 v[50:53], v[168:171], v[200:203], v[50:53]
	v_mfma_f32_16x16x32_bf16 v[54:57], v[160:163], v[200:203], v[54:57]
	v_mfma_f32_16x16x32_bf16 v[46:49], v[160:163], v[208:211], v[46:49]
	v_mfma_f32_16x16x32_bf16 v[42:45], v[168:171], v[208:211], v[42:45]
	v_mfma_f32_16x16x32_bf16 v[14:17], v[176:179], v[208:211], v[14:17]
	v_mfma_f32_16x16x32_bf16 v[10:13], v[184:187], v[208:211], v[10:13]
	v_mfma_f32_16x16x32_bf16 v[2:5], v[184:187], v[216:219], v[2:5]
	v_mfma_f32_16x16x32_bf16 v[6:9], v[176:179], v[216:219], v[6:9]
	v_mfma_f32_16x16x32_bf16 v[34:37], v[168:171], v[216:219], v[34:37]
	v_mfma_f32_16x16x32_bf16 v[38:41], v[160:163], v[216:219], v[38:41]
	s_barrier
	s_add_i32 s76, s76, 2
	s_add_u32 s46, s46, 0x100
	s_addc_u32 s47, s47, 0
	s_cmp_gt_u32 s76, 13
	s_cbranch_scc0 .LBB0_1120

; #define PG8_STAGEA(bufoff, gbase) PG8_STAGE_(bufoff, gbase, voffA)
; #define PG8_STAGEB(bufoff, gbase) PG8_STAGE_(bufoff, gbase, voffB)
; #define PG8_LDA(dst, b, h) do { _Pragma("unroll") for (int m = 0; m < 4; ++m) _Pragma("unroll") for (int k = 0; k < 2; ++k) dst[m][k] = *(const LAS bf16x8*)(lds + PG8_SA(b, h) + aoff + m * 2048 + k * 1024); } while (0)
; #define PG8_LDB(dst, b, h) do { _Pragma("unroll") for (int n = 0; n < 2; ++n) _Pragma("unroll") for (int k = 0; k < 2; ++k) dst[n][k] = *(const LAS bf16x8*)(lds + PG8_SB(b, h) + boff + n * 2048 + k * 1024); } while (0)
; #define PG8_MMA(ai, bj, At, Bt_) do { __builtin_amdgcn_s_setprio(1); _Pragma("unroll") for (int m = 0; m < 4; ++m) _Pragma("unroll") for (int n = 0; n < 2; ++n) _Pragma("unroll") for (int k = 0; k < 2; ++k) \
;         acc[ai][bj][m][n] = __builtin_amdgcn_mfma_f32_16x16x32_bf16(Bt_[n][k], At[m][k], acc[ai][bj][m][n], 0, 0, 0); __builtin_amdgcn_s_setprio(0); } while (0)
; #define PG8_WAIT_V(n) asm volatile("s_waitcnt vmcnt(" #n ")" ::: "memory")
; #define PG8_WAIT_L(n) asm volatile("s_waitcnt lgkmcnt(" #n ")" ::: "memory")
; #define PG8_BAR __builtin_amdgcn_s_barrier()
; template <int EK, int SK = -1>
; __device__ __forceinline__ void gemm_phase(LAS unsigned char* lds, const bf16_t* A, const bf16_t* Bt, int nM, int N, int K, const EpiArgs& E) {
;     ...
;         const bool has_next = S.next(ui + 1, nxt);
;         const char* nA = has_next ? (const char*)A + (size_t)nxt.pm * tstep : cA; const char* nB = has_next ? (const char*)Bt + (size_t)nxt.pn * tstep : cB;
;         for (int t = 0; t < nt; t += 2) {
;             const bool last = (t == nt - 2);
;             const char* a1 = cA + (size_t)(t + 1) * kstep;
;             const char* a2 = last ? nA : cA + (size_t)(t + 2) * kstep; const char* b2 = last ? nB : cB + (size_t)(t + 2) * kstep;
;             const char* a3 = a2 + kstep; const char* b3 = b2 + kstep;
;             PG8_LDB(B0, 0, 0); PG8_LDB(B1, 0, 1); PG8_SCHED; PG8_LDA(At, 0, 0); PG8_STAGEA(PG8_SA(1, 1), a1 + hstep);
;             PG8_WAIT_V(8); PG8_WAIT_L(0); PG8_BAR; PG8_MMA(0, 0, At, B0); PG8_MMA(0, 1, At, B1); PG8_BAR; PG8_SCHED;
;             PG8_LDA(At, 0, 1); PG8_STAGEB(PG8_SB(0, 0), b2); PG8_STAGEB(PG8_SB(0, 1), b2 + hstep); PG8_STAGEA(PG8_SA(0, 0), a2);
;             PG8_WAIT_V(8); PG8_WAIT_L(0); PG8_BAR; PG8_MMA(1, 0, At, B0); PG8_MMA(1, 1, At, B1); PG8_BAR; PG8_SCHED;
.LBB0_1244:
	s_add_u32 s59, s40, 0x100
	s_addc_u32 s66, s41, 0
	s_ashr_i32 s27, s26, 31
	s_lshl_b64 s[36:37], s[26:27], 19
	s_add_u32 s38, s62, s36
	s_addc_u32 s39, s63, s37
	s_and_b64 s[36:37], s[6:7], exec
	s_cselect_b32 s27, s39, s21
	s_cselect_b32 s67, s38, s20
	s_ashr_i32 s23, s22, 31
	s_lshl_b64 s[36:37], s[22:23], 19
	s_add_u32 s36, s47, s36
	s_addc_u32 s37, s48, s37
	s_and_b64 s[42:43], s[6:7], exec
	s_cselect_b32 s23, s37, s41
	s_cselect_b32 s68, s36, s40
	v_lshl_add_u64 v[146:147], s[20:21], 0, v[138:139]
	v_lshl_add_u64 v[148:149], s[20:21], 0, v[140:141]
	s_mov_b32 s69, -2
	s_mov_b64 s[40:41], 0
	v_add_u32_e32 v154, s54, v156
	ds_read_b128 v[150:153], v154
	ds_read_b128 v[160:163], v154 offset:1024
	ds_read_b128 v[164:167], v154 offset:2048
	ds_read_b128 v[168:171], v154 offset:3072
	v_add_u32_e32 v154, s55, v156
	s_add_u32 s42, s20, s40
	ds_read_b128 v[172:175], v154
	ds_read_b128 v[176:179], v154 offset:1024
	ds_read_b128 v[180:183], v154 offset:2048
	ds_read_b128 v[184:187], v154 offset:3072
	s_addc_u32 s43, s21, s41
	s_add_u32 s42, s42, 0x100
	s_addc_u32 s43, s43, 0
	s_add_u32 s70, s59, s40
	s_addc_u32 s71, s66, s41
	s_cmpk_eq_i32 s40, 0x700
	s_cselect_b32 s45, s27, s43
	s_cselect_b32 s44, s67, s42
	s_cselect_b32 s43, s23, s71
	s_cselect_b32 s42, s68, s70
	v_lshl_add_u64 v[154:155], v[146:147], 0, s[40:41]
	s_add_i32 m0, s17, 0xc000
	ds_read_b128 v[188:191], v159
	ds_read_b128 v[192:195], v159 offset:1024
	ds_read_b128 v[196:199], v159 offset:2048
	ds_read_b128 v[200:203], v159 offset:3072
	ds_read_b128 v[204:207], v159 offset:4096
	ds_read_b128 v[208:211], v159 offset:5120
	ds_read_b128 v[212:215], v159 offset:6144
	ds_read_b128 v[216:219], v159 offset:7168
	global_load_lds_dwordx4 v[154:155], off
	v_lshl_add_u64 v[154:155], v[148:149], 0, s[40:41]
	s_add_i32 m0, s17, 0xe000
	s_nop 0
	global_load_lds_dwordx4 v[154:155], off
	s_waitcnt vmcnt(8)
	s_waitcnt lgkmcnt(0)
	s_barrier
	s_waitcnt lgkmcnt(0)
	v_mfma_f32_16x16x32_bf16 v[110:113], v[150:153], v[188:191], 0
	v_mfma_f32_16x16x32_bf16 v[106:109], v[164:167], v[188:191], 0
	v_mfma_f32_16x16x32_bf16 v[78:81], v[172:175], v[188:191], 0
	v_mfma_f32_16x16x32_bf16 v[74:77], v[180:183], v[188:191], 0
	v_mfma_f32_16x16x32_bf16 v[66:69], v[180:183], v[196:199], 0
	v_mfma_f32_16x16x32_bf16 v[70:73], v[172:175], v[196:199], 0
	v_mfma_f32_16x16x32_bf16 v[98:101], v[164:167], v[196:199], 0
	v_mfma_f32_16x16x32_bf16 v[102:105], v[150:153], v[196:199], 0
	v_mfma_f32_16x16x32_bf16 v[94:97], v[150:153], v[204:207], 0
	v_mfma_f32_16x16x32_bf16 v[90:93], v[164:167], v[204:207], 0
	v_mfma_f32_16x16x32_bf16 v[62:65], v[172:175], v[204:207], 0
	v_mfma_f32_16x16x32_bf16 v[58:61], v[180:183], v[204:207], 0
	v_mfma_f32_16x16x32_bf16 v[50:53], v[180:183], v[212:215], 0
	v_mfma_f32_16x16x32_bf16 v[54:57], v[172:175], v[212:215], 0
	v_mfma_f32_16x16x32_bf16 v[82:85], v[164:167], v[212:215], 0
	v_mfma_f32_16x16x32_bf16 v[86:89], v[150:153], v[212:215], 0
	v_mfma_f32_16x16x32_bf16 v[110:113], v[160:163], v[192:195], v[110:113]
	v_mfma_f32_16x16x32_bf16 v[106:109], v[168:171], v[192:195], v[106:109]
	v_mfma_f32_16x16x32_bf16 v[78:81], v[176:179], v[192:195], v[78:81]
	v_mfma_f32_16x16x32_bf16 v[74:77], v[184:187], v[192:195], v[74:77]
	v_mfma_f32_16x16x32_bf16 v[66:69], v[184:187], v[200:203], v[66:69]
	v_mfma_f32_16x16x32_bf16 v[70:73], v[176:179], v[200:203], v[70:73]
	v_mfma_f32_16x16x32_bf16 v[98:101], v[168:171], v[200:203], v[98:101]
	v_mfma_f32_16x16x32_bf16 v[102:105], v[160:163], v[200:203], v[102:105]
	v_mfma_f32_16x16x32_bf16 v[94:97], v[160:163], v[208:211], v[94:97]
	v_mfma_f32_16x16x32_bf16 v[90:93], v[168:171], v[208:211], v[90:93]
	v_mfma_f32_16x16x32_bf16 v[62:65], v[176:179], v[208:211], v[62:65]
	v_mfma_f32_16x16x32_bf16 v[58:61], v[184:187], v[208:211], v[58:61]
	v_mfma_f32_16x16x32_bf16 v[50:53], v[184:187], v[216:219], v[50:53]
	v_mfma_f32_16x16x32_bf16 v[54:57], v[176:179], v[216:219], v[54:57]
	v_mfma_f32_16x16x32_bf16 v[82:85], v[168:171], v[216:219], v[82:85]
	v_mfma_f32_16x16x32_bf16 v[86:89], v[160:163], v[216:219], v[86:89]
	s_barrier
	s_add_i32 s70, s54, s49
	v_lshl_add_u64 v[154:155], s[42:43], 0, v[132:133]
	s_mov_b32 m0, s70
	ds_read_b128 v[188:191], v159 offset:16384
	ds_read_b128 v[192:195], v159 offset:17408
	ds_read_b128 v[196:199], v159 offset:18432
	ds_read_b128 v[200:203], v159 offset:19456
	ds_read_b128 v[204:207], v159 offset:20480
	ds_read_b128 v[208:211], v159 offset:21504
	ds_read_b128 v[212:215], v159 offset:22528
	ds_read_b128 v[216:219], v159 offset:23552
	global_load_lds_dwordx4 v[154:155], off
	s_add_i32 m0, s70, 0x2000
	s_add_u32 s70, s42, 0x40000
	v_lshl_add_u64 v[220:221], s[42:43], 0, v[136:137]
	s_addc_u32 s71, s43, 0
	s_add_i32 s72, s55, s49
	global_load_lds_dwordx4 v[220:221], off
	v_lshl_add_u64 v[222:223], s[70:71], 0, v[132:133]
	s_mov_b32 m0, s72
	v_lshl_add_u64 v[224:225], s[44:45], 0, v[134:135]
	global_load_lds_dwordx4 v[222:223], off
	v_lshl_add_u64 v[222:223], s[70:71], 0, v[136:137]
	s_add_i32 m0, s72, 0x2000
	s_nop 0
	global_load_lds_dwordx4 v[222:223], off
	v_lshl_add_u64 v[222:223], s[44:45], 0, v[130:131]
	s_mov_b32 m0, s17
	s_nop 0
	global_load_lds_dwordx4 v[222:223], off
	s_mov_b32 m0, s19
	s_nop 0
	global_load_lds_dwordx4 v[224:225], off
	s_waitcnt vmcnt(8)
	s_waitcnt lgkmcnt(0)
	s_barrier
; #define PG8_STAGEA(bufoff, gbase) PG8_STAGE_(bufoff, gbase, voffA)
; #define PG8_STAGEB(bufoff, gbase) PG8_STAGE_(bufoff, gbase, voffB)
; #define PG8_LDA(dst, b, h) do { _Pragma("unroll") for (int m = 0; m < 4; ++m) _Pragma("unroll") for (int k = 0; k < 2; ++k) dst[m][k] = *(const LAS bf16x8*)(lds + PG8_SA(b, h) + aoff + m * 2048 + k * 1024); } while (0)
; #define PG8_LDB(dst, b, h) do { _Pragma("unroll") for (int n = 0; n < 2; ++n) _Pragma("unroll") for (int k = 0; k < 2; ++k) dst[n][k] = *(const LAS bf16x8*)(lds + PG8_SB(b, h) + boff + n * 2048 + k * 1024); } while (0)
; #define PG8_MMA(ai, bj, At, Bt_) do { __builtin_amdgcn_s_setprio(1); _Pragma("unroll") for (int m = 0; m < 4; ++m) _Pragma("unroll") for (int n = 0; n < 2; ++n) _Pragma("unroll") for (int k = 0; k < 2; ++k) \
;         acc[ai][bj][m][n] = __builtin_amdgcn_mfma_f32_16x16x32_bf16(Bt_[n][k], At[m][k], acc[ai][bj][m][n], 0, 0, 0); __builtin_amdgcn_s_setprio(0); } while (0)
; #define PG8_WAIT_V(n) asm volatile("s_waitcnt vmcnt(" #n ")" ::: "memory")
; #define PG8_WAIT_L(n) asm volatile("s_waitcnt lgkmcnt(" #n ")" ::: "memory")
; #define PG8_BAR __builtin_amdgcn_s_barrier()
; #define PG8_SCHED __builtin_amdgcn_sched_barrier(0)
; template <int EK, int SK = -1>
; __device__ __forceinline__ void gemm_phase(LAS unsigned char* lds, const bf16_t* A, const bf16_t* Bt, int nM, int N, int K, const EpiArgs& E) {
;     ...
;             PG8_LDA(At, 0, 1); PG8_STAGEB(PG8_SB(0, 0), b2); PG8_STAGEB(PG8_SB(0, 1), b2 + hstep); PG8_STAGEA(PG8_SA(0, 0), a2);
;             PG8_WAIT_V(8); PG8_WAIT_L(0); PG8_BAR; PG8_MMA(1, 0, At, B0); PG8_MMA(1, 1, At, B1); PG8_BAR; PG8_SCHED;
;             PG8_LDB(B0, 1, 0); PG8_LDB(B1, 1, 1); PG8_SCHED; PG8_LDA(At, 1, 0); PG8_STAGEA(PG8_SA(0, 1), a2 + hstep);
;             PG8_WAIT_V(8); PG8_WAIT_L(0); PG8_BAR; PG8_MMA(0, 0, At, B0); PG8_MMA(0, 1, At, B1); PG8_BAR; PG8_SCHED;
	s_waitcnt lgkmcnt(0)
	v_mfma_f32_16x16x32_bf16 v[46:49], v[150:153], v[188:191], 0
	v_mfma_f32_16x16x32_bf16 v[42:45], v[164:167], v[188:191], 0
	v_mfma_f32_16x16x32_bf16 v[14:17], v[172:175], v[188:191], 0
	v_mfma_f32_16x16x32_bf16 v[10:13], v[180:183], v[188:191], 0
	v_mfma_f32_16x16x32_bf16 v[2:5], v[180:183], v[196:199], 0
	v_mfma_f32_16x16x32_bf16 v[6:9], v[172:175], v[196:199], 0
	v_mfma_f32_16x16x32_bf16 v[34:37], v[164:167], v[196:199], 0
	v_mfma_f32_16x16x32_bf16 v[38:41], v[150:153], v[196:199], 0
	v_mfma_f32_16x16x32_bf16 v[30:33], v[150:153], v[204:207], 0
	v_mfma_f32_16x16x32_bf16 v[26:29], v[164:167], v[204:207], 0
	v_mfma_f32_16x16x32_bf16 v[114:117], v[172:175], v[204:207], 0
	v_mfma_f32_16x16x32_bf16 v[118:121], v[180:183], v[204:207], 0
	v_mfma_f32_16x16x32_bf16 v[126:129], v[180:183], v[212:215], 0
	v_mfma_f32_16x16x32_bf16 v[122:125], v[172:175], v[212:215], 0
	v_mfma_f32_16x16x32_bf16 v[18:21], v[164:167], v[212:215], 0
	v_mfma_f32_16x16x32_bf16 v[22:25], v[150:153], v[212:215], 0
	v_mfma_f32_16x16x32_bf16 v[46:49], v[160:163], v[192:195], v[46:49]
	v_mfma_f32_16x16x32_bf16 v[42:45], v[168:171], v[192:195], v[42:45]
	v_mfma_f32_16x16x32_bf16 v[14:17], v[176:179], v[192:195], v[14:17]
	v_mfma_f32_16x16x32_bf16 v[10:13], v[184:187], v[192:195], v[10:13]
	v_mfma_f32_16x16x32_bf16 v[2:5], v[184:187], v[200:203], v[2:5]
	v_mfma_f32_16x16x32_bf16 v[6:9], v[176:179], v[200:203], v[6:9]
	v_mfma_f32_16x16x32_bf16 v[34:37], v[168:171], v[200:203], v[34:37]
	v_mfma_f32_16x16x32_bf16 v[38:41], v[160:163], v[200:203], v[38:41]
	v_mfma_f32_16x16x32_bf16 v[30:33], v[160:163], v[208:211], v[30:33]
	v_mfma_f32_16x16x32_bf16 v[26:29], v[168:171], v[208:211], v[26:29]
	v_mfma_f32_16x16x32_bf16 v[114:117], v[176:179], v[208:211], v[114:117]
	v_mfma_f32_16x16x32_bf16 v[118:121], v[184:187], v[208:211], v[118:121]
	v_mfma_f32_16x16x32_bf16 v[126:129], v[184:187], v[216:219], v[126:129]
	v_mfma_f32_16x16x32_bf16 v[122:125], v[176:179], v[216:219], v[122:125]
	v_mfma_f32_16x16x32_bf16 v[18:21], v[168:171], v[216:219], v[18:21]
	v_mfma_f32_16x16x32_bf16 v[22:25], v[160:163], v[216:219], v[22:25]
	s_barrier
	s_add_i32 s70, 0, 0x18000
	s_add_i32 s71, 0, 0x1c000
	v_add_u32_e32 v168, s70, v156
	v_add_u32_e32 v184, s71, v156
	ds_read_b128 v[150:153], v168
	ds_read_b128 v[160:163], v168 offset:1024
	ds_read_b128 v[164:167], v168 offset:2048
	ds_read_b128 v[168:171], v168 offset:3072
	ds_read_b128 v[172:175], v184
	ds_read_b128 v[176:179], v184 offset:1024
	ds_read_b128 v[180:183], v184 offset:2048
	ds_read_b128 v[184:187], v184 offset:3072
	s_add_u32 s44, s44, 0x40000
	s_addc_u32 s45, s45, 0
	s_mov_b32 m0, s50
	v_lshl_add_u64 v[226:227], s[44:45], 0, v[130:131]
	ds_read_b128 v[188:191], v159 offset:32768
	ds_read_b128 v[192:195], v159 offset:33792
	ds_read_b128 v[196:199], v159 offset:34816
	ds_read_b128 v[200:203], v159 offset:35840
	ds_read_b128 v[204:207], v159 offset:36864
	ds_read_b128 v[208:211], v159 offset:37888
	ds_read_b128 v[212:215], v159 offset:38912
	ds_read_b128 v[216:219], v159 offset:39936
	global_load_lds_dwordx4 v[226:227], off
	v_lshl_add_u64 v[226:227], s[44:45], 0, v[134:135]
	s_mov_b32 m0, s51
	s_nop 0
	global_load_lds_dwordx4 v[226:227], off
	s_waitcnt vmcnt(8)
	s_waitcnt lgkmcnt(0)
	s_barrier
	s_waitcnt lgkmcnt(0)
	v_mfma_f32_16x16x32_bf16 v[110:113], v[150:153], v[188:191], v[110:113]
	v_mfma_f32_16x16x32_bf16 v[106:109], v[164:167], v[188:191], v[106:109]
	v_mfma_f32_16x16x32_bf16 v[78:81], v[172:175], v[188:191], v[78:81]
	v_mfma_f32_16x16x32_bf16 v[74:77], v[180:183], v[188:191], v[74:77]
	v_mfma_f32_16x16x32_bf16 v[66:69], v[180:183], v[196:199], v[66:69]
	v_mfma_f32_16x16x32_bf16 v[70:73], v[172:175], v[196:199], v[70:73]
	v_mfma_f32_16x16x32_bf16 v[98:101], v[164:167], v[196:199], v[98:101]
	v_mfma_f32_16x16x32_bf16 v[102:105], v[150:153], v[196:199], v[102:105]
	v_mfma_f32_16x16x32_bf16 v[94:97], v[150:153], v[204:207], v[94:97]
	v_mfma_f32_16x16x32_bf16 v[90:93], v[164:167], v[204:207], v[90:93]
	v_mfma_f32_16x16x32_bf16 v[62:65], v[172:175], v[204:207], v[62:65]
	v_mfma_f32_16x16x32_bf16 v[58:61], v[180:183], v[204:207], v[58:61]
	v_mfma_f32_16x16x32_bf16 v[50:53], v[180:183], v[212:215], v[50:53]
	v_mfma_f32_16x16x32_bf16 v[54:57], v[172:175], v[212:215], v[54:57]
	v_mfma_f32_16x16x32_bf16 v[82:85], v[164:167], v[212:215], v[82:85]
	v_mfma_f32_16x16x32_bf16 v[86:89], v[150:153], v[212:215], v[86:89]
	v_mfma_f32_16x16x32_bf16 v[110:113], v[160:163], v[192:195], v[110:113]
	v_mfma_f32_16x16x32_bf16 v[106:109], v[168:171], v[192:195], v[106:109]
	v_mfma_f32_16x16x32_bf16 v[78:81], v[176:179], v[192:195], v[78:81]
	v_mfma_f32_16x16x32_bf16 v[74:77], v[184:187], v[192:195], v[74:77]
	v_mfma_f32_16x16x32_bf16 v[66:69], v[184:187], v[200:203], v[66:69]
	v_mfma_f32_16x16x32_bf16 v[70:73], v[176:179], v[200:203], v[70:73]
	v_mfma_f32_16x16x32_bf16 v[98:101], v[168:171], v[200:203], v[98:101]
	v_mfma_f32_16x16x32_bf16 v[102:105], v[160:163], v[200:203], v[102:105]
	v_mfma_f32_16x16x32_bf16 v[94:97], v[160:163], v[208:211], v[94:97]
	v_mfma_f32_16x16x32_bf16 v[90:93], v[168:171], v[208:211], v[90:93]
	v_mfma_f32_16x16x32_bf16 v[62:65], v[176:179], v[208:211], v[62:65]
	v_mfma_f32_16x16x32_bf16 v[58:61], v[184:187], v[208:211], v[58:61]
	v_mfma_f32_16x16x32_bf16 v[50:53], v[184:187], v[216:219], v[50:53]
	v_mfma_f32_16x16x32_bf16 v[54:57], v[176:179], v[216:219], v[54:57]
	v_mfma_f32_16x16x32_bf16 v[82:85], v[168:171], v[216:219], v[82:85]
	v_mfma_f32_16x16x32_bf16 v[86:89], v[160:163], v[216:219], v[86:89]
	s_barrier
; #define PG8_STAGEA(bufoff, gbase) PG8_STAGE_(bufoff, gbase, voffA)
; #define PG8_STAGEB(bufoff, gbase) PG8_STAGE_(bufoff, gbase, voffB)
; #define PG8_LDA(dst, b, h) do { _Pragma("unroll") for (int m = 0; m < 4; ++m) _Pragma("unroll") for (int k = 0; k < 2; ++k) dst[m][k] = *(const LAS bf16x8*)(lds + PG8_SA(b, h) + aoff + m * 2048 + k * 1024); } while (0)
; #define PG8_LDB(dst, b, h) do { _Pragma("unroll") for (int n = 0; n < 2; ++n) _Pragma("unroll") for (int k = 0; k < 2; ++k) dst[n][k] = *(const LAS bf16x8*)(lds + PG8_SB(b, h) + boff + n * 2048 + k * 1024); } while (0)
; #define PG8_MMA(ai, bj, At, Bt_) do { __builtin_amdgcn_s_setprio(1); _Pragma("unroll") for (int m = 0; m < 4; ++m) _Pragma("unroll") for (int n = 0; n < 2; ++n) _Pragma("unroll") for (int k = 0; k < 2; ++k) \
;         acc[ai][bj][m][n] = __builtin_amdgcn_mfma_f32_16x16x32_bf16(Bt_[n][k], At[m][k], acc[ai][bj][m][n], 0, 0, 0); __builtin_amdgcn_s_setprio(0); } while (0)
; #define PG8_WAIT_V(n) asm volatile("s_waitcnt vmcnt(" #n ")" ::: "memory")
; #define PG8_WAIT_L(n) asm volatile("s_waitcnt lgkmcnt(" #n ")" ::: "memory")
; #define PG8_BAR __builtin_amdgcn_s_barrier()
; #define PG8_SCHED __builtin_amdgcn_sched_barrier(0)
; template <int EK, int SK = -1>
; __device__ __forceinline__ void gemm_phase(LAS unsigned char* lds, const bf16_t* A, const bf16_t* Bt, int nM, int N, int K, const EpiArgs& E) {
;     ...
;             PG8_LDB(B0, 0, 0); PG8_LDB(B1, 0, 1); PG8_SCHED; PG8_LDA(At, 0, 0); PG8_STAGEA(PG8_SA(1, 1), a1 + hstep);
;             PG8_WAIT_V(8); PG8_WAIT_L(0); PG8_BAR; PG8_MMA(0, 0, At, B0); PG8_MMA(0, 1, At, B1); PG8_BAR; PG8_SCHED;
;             PG8_LDA(At, 0, 1); PG8_STAGEB(PG8_SB(0, 0), b2); PG8_STAGEB(PG8_SB(0, 1), b2 + hstep); PG8_STAGEA(PG8_SA(0, 0), a2);
;             PG8_WAIT_V(8); PG8_WAIT_L(0); PG8_BAR; PG8_MMA(1, 0, At, B0); PG8_MMA(1, 1, At, B1); PG8_BAR; PG8_SCHED;
;             PG8_LDB(B0, 1, 0); PG8_LDB(B1, 1, 1); PG8_SCHED; PG8_LDA(At, 1, 0); PG8_STAGEA(PG8_SA(0, 1), a2 + hstep);
;             PG8_WAIT_V(8); PG8_WAIT_L(0); PG8_BAR; PG8_MMA(0, 0, At, B0); PG8_MMA(0, 1, At, B1); PG8_BAR; PG8_SCHED;
;             PG8_LDA(At, 1, 1); PG8_STAGEB(PG8_SB(1, 0), b3); PG8_STAGEB(PG8_SB(1, 1), b3 + hstep); PG8_STAGEA(PG8_SA(1, 0), a3);
;             PG8_WAIT_V(8); PG8_WAIT_L(0); PG8_BAR; PG8_MMA(1, 0, At, B0); PG8_MMA(1, 1, At, B1); PG8_BAR; PG8_SCHED;
;         }
	s_add_i32 s44, s70, s49
	v_lshl_add_u64 v[154:155], v[154:155], 0, s[10:11]
	s_mov_b32 m0, s44
	ds_read_b128 v[188:191], v159 offset:49152
	ds_read_b128 v[192:195], v159 offset:50176
	ds_read_b128 v[196:199], v159 offset:51200
	ds_read_b128 v[200:203], v159 offset:52224
	ds_read_b128 v[204:207], v159 offset:53248
	ds_read_b128 v[208:211], v159 offset:54272
	ds_read_b128 v[212:215], v159 offset:55296
	ds_read_b128 v[216:219], v159 offset:56320
	global_load_lds_dwordx4 v[154:155], off
	s_add_i32 m0, s44, 0x2000
	s_add_u32 s42, s42, 0x40080
	v_lshl_add_u64 v[154:155], v[220:221], 0, s[10:11]
	s_addc_u32 s43, s43, 0
	s_add_i32 s44, s71, s49
	global_load_lds_dwordx4 v[154:155], off
	v_lshl_add_u64 v[154:155], s[42:43], 0, v[132:133]
	s_mov_b32 m0, s44
	s_nop 0
	global_load_lds_dwordx4 v[154:155], off
	v_lshl_add_u64 v[154:155], s[42:43], 0, v[136:137]
	s_add_i32 m0, s44, 0x2000
	s_nop 0
	global_load_lds_dwordx4 v[154:155], off
	v_lshl_add_u64 v[154:155], v[222:223], 0, s[10:11]
	s_mov_b32 m0, s52
	s_nop 0
	global_load_lds_dwordx4 v[154:155], off
	v_lshl_add_u64 v[154:155], v[224:225], 0, s[10:11]
	s_mov_b32 m0, s53
	s_nop 0
	global_load_lds_dwordx4 v[154:155], off
	s_waitcnt vmcnt(8)
	s_waitcnt lgkmcnt(0)
	s_barrier
	s_waitcnt lgkmcnt(0)
	v_mfma_f32_16x16x32_bf16 v[46:49], v[150:153], v[188:191], v[46:49]
	v_mfma_f32_16x16x32_bf16 v[42:45], v[164:167], v[188:191], v[42:45]
	v_mfma_f32_16x16x32_bf16 v[14:17], v[172:175], v[188:191], v[14:17]
	v_mfma_f32_16x16x32_bf16 v[10:13], v[180:183], v[188:191], v[10:13]
	v_mfma_f32_16x16x32_bf16 v[2:5], v[180:183], v[196:199], v[2:5]
	v_mfma_f32_16x16x32_bf16 v[6:9], v[172:175], v[196:199], v[6:9]
	v_mfma_f32_16x16x32_bf16 v[34:37], v[164:167], v[196:199], v[34:37]
	v_mfma_f32_16x16x32_bf16 v[38:41], v[150:153], v[196:199], v[38:41]
	v_mfma_f32_16x16x32_bf16 v[30:33], v[150:153], v[204:207], v[30:33]
	v_mfma_f32_16x16x32_bf16 v[26:29], v[164:167], v[204:207], v[26:29]
	v_mfma_f32_16x16x32_bf16 v[114:117], v[172:175], v[204:207], v[114:117]
	v_mfma_f32_16x16x32_bf16 v[118:121], v[180:183], v[204:207], v[118:121]
	v_mfma_f32_16x16x32_bf16 v[126:129], v[180:183], v[212:215], v[126:129]
	v_mfma_f32_16x16x32_bf16 v[122:125], v[172:175], v[212:215], v[122:125]
	v_mfma_f32_16x16x32_bf16 v[18:21], v[164:167], v[212:215], v[18:21]
	v_mfma_f32_16x16x32_bf16 v[22:25], v[150:153], v[212:215], v[22:25]
	v_mfma_f32_16x16x32_bf16 v[46:49], v[160:163], v[192:195], v[46:49]
	v_mfma_f32_16x16x32_bf16 v[42:45], v[168:171], v[192:195], v[42:45]
	v_mfma_f32_16x16x32_bf16 v[14:17], v[176:179], v[192:195], v[14:17]
	v_mfma_f32_16x16x32_bf16 v[10:13], v[184:187], v[192:195], v[10:13]
	v_mfma_f32_16x16x32_bf16 v[2:5], v[184:187], v[200:203], v[2:5]
	v_mfma_f32_16x16x32_bf16 v[6:9], v[176:179], v[200:203], v[6:9]
	v_mfma_f32_16x16x32_bf16 v[34:37], v[168:171], v[200:203], v[34:37]
	v_mfma_f32_16x16x32_bf16 v[38:41], v[160:163], v[200:203], v[38:41]
	v_mfma_f32_16x16x32_bf16 v[30:33], v[160:163], v[208:211], v[30:33]
	v_mfma_f32_16x16x32_bf16 v[26:29], v[168:171], v[208:211], v[26:29]
	v_mfma_f32_16x16x32_bf16 v[114:117], v[176:179], v[208:211], v[114:117]
	v_mfma_f32_16x16x32_bf16 v[118:121], v[184:187], v[208:211], v[118:121]
	v_mfma_f32_16x16x32_bf16 v[126:129], v[184:187], v[216:219], v[126:129]
	v_mfma_f32_16x16x32_bf16 v[122:125], v[176:179], v[216:219], v[122:125]
	v_mfma_f32_16x16x32_bf16 v[18:21], v[168:171], v[216:219], v[18:21]
	v_mfma_f32_16x16x32_bf16 v[22:25], v[160:163], v[216:219], v[22:25]
	s_barrier
	s_add_i32 s69, s69, 2
	s_add_u32 s40, s40, 0x100
	s_addc_u32 s41, s41, 0
	s_cmp_gt_u32 s69, 13
	s_cbranch_scc0 .LBB0_1245
	s_branch .Lmy_kexit_6
.LBB0_1245:
	v_add_u32_e32 v154, s54, v156
	ds_read_b128 v[150:153], v154
	ds_read_b128 v[160:163], v154 offset:1024
	ds_read_b128 v[164:167], v154 offset:2048
	ds_read_b128 v[168:171], v154 offset:3072
	v_add_u32_e32 v154, s55, v156
	s_add_u32 s42, s20, s40
	ds_read_b128 v[172:175], v154
	ds_read_b128 v[176:179], v154 offset:1024
	ds_read_b128 v[180:183], v154 offset:2048
	ds_read_b128 v[184:187], v154 offset:3072
	s_addc_u32 s43, s21, s41
	s_add_u32 s42, s42, 0x100
	s_addc_u32 s43, s43, 0
	s_add_u32 s70, s59, s40
	s_addc_u32 s71, s66, s41
	s_cmpk_eq_i32 s40, 0x700
	s_cselect_b32 s45, s27, s43
	s_cselect_b32 s44, s67, s42
	s_cselect_b32 s43, s23, s71
	s_cselect_b32 s42, s68, s70
	v_lshl_add_u64 v[154:155], v[146:147], 0, s[40:41]
	s_add_i32 m0, s17, 0xc000
	ds_read_b128 v[188:191], v159
	ds_read_b128 v[192:195], v159 offset:1024
	ds_read_b128 v[196:199], v159 offset:2048
	ds_read_b128 v[200:203], v159 offset:3072
	ds_read_b128 v[204:207], v159 offset:4096
	ds_read_b128 v[208:211], v159 offset:5120
	ds_read_b128 v[212:215], v159 offset:6144
	ds_read_b128 v[216:219], v159 offset:7168
	global_load_lds_dwordx4 v[154:155], off
	v_lshl_add_u64 v[154:155], v[148:149], 0, s[40:41]
	s_add_i32 m0, s17, 0xe000
	s_nop 0
	global_load_lds_dwordx4 v[154:155], off
	s_waitcnt vmcnt(8)
	s_waitcnt lgkmcnt(0)
	s_barrier
; #define PG8_STAGEA(bufoff, gbase) PG8_STAGE_(bufoff, gbase, voffA)
; #define PG8_STAGEB(bufoff, gbase) PG8_STAGE_(bufoff, gbase, voffB)
; #define PG8_LDA(dst, b, h) do { _Pragma("unroll") for (int m = 0; m < 4; ++m) _Pragma("unroll") for (int k = 0; k < 2; ++k) dst[m][k] = *(const LAS bf16x8*)(lds + PG8_SA(b, h) + aoff + m * 2048 + k * 1024); } while (0)
; #define PG8_LDB(dst, b, h) do { _Pragma("unroll") for (int n = 0; n < 2; ++n) _Pragma("unroll") for (int k = 0; k < 2; ++k) dst[n][k] = *(const LAS bf16x8*)(lds + PG8_SB(b, h) + boff + n * 2048 + k * 1024); } while (0)
; #define PG8_MMA(ai, bj, At, Bt_) do { __builtin_amdgcn_s_setprio(1); _Pragma("unroll") for (int m = 0; m < 4; ++m) _Pragma("unroll") for (int n = 0; n < 2; ++n) _Pragma("unroll") for (int k = 0; k < 2; ++k) \
;         acc[ai][bj][m][n] = __builtin_amdgcn_mfma_f32_16x16x32_bf16(Bt_[n][k], At[m][k], acc[ai][bj][m][n], 0, 0, 0); __builtin_amdgcn_s_setprio(0); } while (0)
; #define PG8_WAIT_V(n) asm volatile("s_waitcnt vmcnt(" #n ")" ::: "memory")
; #define PG8_WAIT_L(n) asm volatile("s_waitcnt lgkmcnt(" #n ")" ::: "memory")
; #define PG8_BAR __builtin_amdgcn_s_barrier()
; #define PG8_SCHED __builtin_amdgcn_sched_barrier(0)
; template <int EK, int SK = -1>
; __device__ __forceinline__ void gemm_phase(LAS unsigned char* lds, const bf16_t* A, const bf16_t* Bt, int nM, int N, int K, const EpiArgs& E) {
;     ...
;             PG8_LDB(B0, 0, 0); PG8_LDB(B1, 0, 1); PG8_SCHED; PG8_LDA(At, 0, 0); PG8_STAGEA(PG8_SA(1, 1), a1 + hstep);
;             PG8_WAIT_V(8); PG8_WAIT_L(0); PG8_BAR; PG8_MMA(0, 0, At, B0); PG8_MMA(0, 1, At, B1); PG8_BAR; PG8_SCHED;
;             PG8_LDA(At, 0, 1); PG8_STAGEB(PG8_SB(0, 0), b2); PG8_STAGEB(PG8_SB(0, 1), b2 + hstep); PG8_STAGEA(PG8_SA(0, 0), a2);
;             PG8_WAIT_V(8); PG8_WAIT_L(0); PG8_BAR; PG8_MMA(1, 0, At, B0); PG8_MMA(1, 1, At, B1); PG8_BAR; PG8_SCHED;
	s_waitcnt lgkmcnt(0)
	v_mfma_f32_16x16x32_bf16 v[110:113], v[150:153], v[188:191], v[110:113]
	v_mfma_f32_16x16x32_bf16 v[106:109], v[164:167], v[188:191], v[106:109]
	v_mfma_f32_16x16x32_bf16 v[78:81], v[172:175], v[188:191], v[78:81]
	v_mfma_f32_16x16x32_bf16 v[74:77], v[180:183], v[188:191], v[74:77]
	v_mfma_f32_16x16x32_bf16 v[66:69], v[180:183], v[196:199], v[66:69]
	v_mfma_f32_16x16x32_bf16 v[70:73], v[172:175], v[196:199], v[70:73]
	v_mfma_f32_16x16x32_bf16 v[98:101], v[164:167], v[196:199], v[98:101]
	v_mfma_f32_16x16x32_bf16 v[102:105], v[150:153], v[196:199], v[102:105]
	v_mfma_f32_16x16x32_bf16 v[94:97], v[150:153], v[204:207], v[94:97]
	v_mfma_f32_16x16x32_bf16 v[90:93], v[164:167], v[204:207], v[90:93]
	v_mfma_f32_16x16x32_bf16 v[62:65], v[172:175], v[204:207], v[62:65]
	v_mfma_f32_16x16x32_bf16 v[58:61], v[180:183], v[204:207], v[58:61]
	v_mfma_f32_16x16x32_bf16 v[50:53], v[180:183], v[212:215], v[50:53]
	v_mfma_f32_16x16x32_bf16 v[54:57], v[172:175], v[212:215], v[54:57]
	v_mfma_f32_16x16x32_bf16 v[82:85], v[164:167], v[212:215], v[82:85]
	v_mfma_f32_16x16x32_bf16 v[86:89], v[150:153], v[212:215], v[86:89]
	v_mfma_f32_16x16x32_bf16 v[110:113], v[160:163], v[192:195], v[110:113]
	v_mfma_f32_16x16x32_bf16 v[106:109], v[168:171], v[192:195], v[106:109]
	v_mfma_f32_16x16x32_bf16 v[78:81], v[176:179], v[192:195], v[78:81]
	v_mfma_f32_16x16x32_bf16 v[74:77], v[184:187], v[192:195], v[74:77]
	v_mfma_f32_16x16x32_bf16 v[66:69], v[184:187], v[200:203], v[66:69]
	v_mfma_f32_16x16x32_bf16 v[70:73], v[176:179], v[200:203], v[70:73]
	v_mfma_f32_16x16x32_bf16 v[98:101], v[168:171], v[200:203], v[98:101]
	v_mfma_f32_16x16x32_bf16 v[102:105], v[160:163], v[200:203], v[102:105]
	v_mfma_f32_16x16x32_bf16 v[94:97], v[160:163], v[208:211], v[94:97]
	v_mfma_f32_16x16x32_bf16 v[90:93], v[168:171], v[208:211], v[90:93]
	v_mfma_f32_16x16x32_bf16 v[62:65], v[176:179], v[208:211], v[62:65]
	v_mfma_f32_16x16x32_bf16 v[58:61], v[184:187], v[208:211], v[58:61]
	v_mfma_f32_16x16x32_bf16 v[50:53], v[184:187], v[216:219], v[50:53]
	v_mfma_f32_16x16x32_bf16 v[54:57], v[176:179], v[216:219], v[54:57]
	v_mfma_f32_16x16x32_bf16 v[82:85], v[168:171], v[216:219], v[82:85]
	v_mfma_f32_16x16x32_bf16 v[86:89], v[160:163], v[216:219], v[86:89]
	s_barrier
	s_add_i32 s70, s54, s49
	v_lshl_add_u64 v[154:155], s[42:43], 0, v[132:133]
	s_mov_b32 m0, s70
	ds_read_b128 v[188:191], v159 offset:16384
	ds_read_b128 v[192:195], v159 offset:17408
	ds_read_b128 v[196:199], v159 offset:18432
	ds_read_b128 v[200:203], v159 offset:19456
	ds_read_b128 v[204:207], v159 offset:20480
	ds_read_b128 v[208:211], v159 offset:21504
	ds_read_b128 v[212:215], v159 offset:22528
	ds_read_b128 v[216:219], v159 offset:23552
	global_load_lds_dwordx4 v[154:155], off
	s_add_i32 m0, s70, 0x2000
	s_add_u32 s70, s42, 0x40000
	v_lshl_add_u64 v[220:221], s[42:43], 0, v[136:137]
	s_addc_u32 s71, s43, 0
	s_add_i32 s72, s55, s49
	global_load_lds_dwordx4 v[220:221], off
	v_lshl_add_u64 v[222:223], s[70:71], 0, v[132:133]
	s_mov_b32 m0, s72
	v_lshl_add_u64 v[224:225], s[44:45], 0, v[134:135]
	global_load_lds_dwordx4 v[222:223], off
	v_lshl_add_u64 v[222:223], s[70:71], 0, v[136:137]
	s_add_i32 m0, s72, 0x2000
	s_nop 0
	global_load_lds_dwordx4 v[222:223], off
	v_lshl_add_u64 v[222:223], s[44:45], 0, v[130:131]
	s_mov_b32 m0, s17
	s_nop 0
	global_load_lds_dwordx4 v[222:223], off
	s_mov_b32 m0, s19
	s_nop 0
	global_load_lds_dwordx4 v[224:225], off
	s_waitcnt vmcnt(8)
	s_waitcnt lgkmcnt(0)
	s_barrier
	s_waitcnt lgkmcnt(0)
	v_mfma_f32_16x16x32_bf16 v[46:49], v[150:153], v[188:191], v[46:49]
	v_mfma_f32_16x16x32_bf16 v[42:45], v[164:167], v[188:191], v[42:45]
	v_mfma_f32_16x16x32_bf16 v[14:17], v[172:175], v[188:191], v[14:17]
	v_mfma_f32_16x16x32_bf16 v[10:13], v[180:183], v[188:191], v[10:13]
	v_mfma_f32_16x16x32_bf16 v[2:5], v[180:183], v[196:199], v[2:5]
	v_mfma_f32_16x16x32_bf16 v[6:9], v[172:175], v[196:199], v[6:9]
	v_mfma_f32_16x16x32_bf16 v[34:37], v[164:167], v[196:199], v[34:37]
	v_mfma_f32_16x16x32_bf16 v[38:41], v[150:153], v[196:199], v[38:41]
	v_mfma_f32_16x16x32_bf16 v[30:33], v[150:153], v[204:207], v[30:33]
	v_mfma_f32_16x16x32_bf16 v[26:29], v[164:167], v[204:207], v[26:29]
	v_mfma_f32_16x16x32_bf16 v[114:117], v[172:175], v[204:207], v[114:117]
	v_mfma_f32_16x16x32_bf16 v[118:121], v[180:183], v[204:207], v[118:121]
	v_mfma_f32_16x16x32_bf16 v[126:129], v[180:183], v[212:215], v[126:129]
	v_mfma_f32_16x16x32_bf16 v[122:125], v[172:175], v[212:215], v[122:125]
	v_mfma_f32_16x16x32_bf16 v[18:21], v[164:167], v[212:215], v[18:21]
	v_mfma_f32_16x16x32_bf16 v[22:25], v[150:153], v[212:215], v[22:25]
	v_mfma_f32_16x16x32_bf16 v[46:49], v[160:163], v[192:195], v[46:49]
	v_mfma_f32_16x16x32_bf16 v[42:45], v[168:171], v[192:195], v[42:45]
	v_mfma_f32_16x16x32_bf16 v[14:17], v[176:179], v[192:195], v[14:17]
	v_mfma_f32_16x16x32_bf16 v[10:13], v[184:187], v[192:195], v[10:13]
	v_mfma_f32_16x16x32_bf16 v[2:5], v[184:187], v[200:203], v[2:5]
	v_mfma_f32_16x16x32_bf16 v[6:9], v[176:179], v[200:203], v[6:9]
	v_mfma_f32_16x16x32_bf16 v[34:37], v[168:171], v[200:203], v[34:37]
	v_mfma_f32_16x16x32_bf16 v[38:41], v[160:163], v[200:203], v[38:41]
	v_mfma_f32_16x16x32_bf16 v[30:33], v[160:163], v[208:211], v[30:33]
	v_mfma_f32_16x16x32_bf16 v[26:29], v[168:171], v[208:211], v[26:29]
	v_mfma_f32_16x16x32_bf16 v[114:117], v[176:179], v[208:211], v[114:117]
	v_mfma_f32_16x16x32_bf16 v[118:121], v[184:187], v[208:211], v[118:121]
	v_mfma_f32_16x16x32_bf16 v[126:129], v[184:187], v[216:219], v[126:129]
	v_mfma_f32_16x16x32_bf16 v[122:125], v[176:179], v[216:219], v[122:125]
	v_mfma_f32_16x16x32_bf16 v[18:21], v[168:171], v[216:219], v[18:21]
	v_mfma_f32_16x16x32_bf16 v[22:25], v[160:163], v[216:219], v[22:25]
	s_barrier
; #define PG8_STAGEA(bufoff, gbase) PG8_STAGE_(bufoff, gbase, voffA)
; #define PG8_STAGEB(bufoff, gbase) PG8_STAGE_(bufoff, gbase, voffB)
; #define PG8_LDA(dst, b, h) do { _Pragma("unroll") for (int m = 0; m < 4; ++m) _Pragma("unroll") for (int k = 0; k < 2; ++k) dst[m][k] = *(const LAS bf16x8*)(lds + PG8_SA(b, h) + aoff + m * 2048 + k * 1024); } while (0)
; #define PG8_LDB(dst, b, h) do { _Pragma("unroll") for (int n = 0; n < 2; ++n) _Pragma("unroll") for (int k = 0; k < 2; ++k) dst[n][k] = *(const LAS bf16x8*)(lds + PG8_SB(b, h) + boff + n * 2048 + k * 1024); } while (0)
; #define PG8_MMA(ai, bj, At, Bt_) do { __builtin_amdgcn_s_setprio(1); _Pragma("unroll") for (int m = 0; m < 4; ++m) _Pragma("unroll") for (int n = 0; n < 2; ++n) _Pragma("unroll") for (int k = 0; k < 2; ++k) \
;         acc[ai][bj][m][n] = __builtin_amdgcn_mfma_f32_16x16x32_bf16(Bt_[n][k], At[m][k], acc[ai][bj][m][n], 0, 0, 0); __builtin_amdgcn_s_setprio(0); } while (0)
; #define PG8_WAIT_V(n) asm volatile("s_waitcnt vmcnt(" #n ")" ::: "memory")
; #define PG8_WAIT_L(n) asm volatile("s_waitcnt lgkmcnt(" #n ")" ::: "memory")
; #define PG8_BAR __builtin_amdgcn_s_barrier()
; #define PG8_SCHED __builtin_amdgcn_sched_barrier(0)
; template <int EK, int SK = -1>
; __device__ __forceinline__ void gemm_phase(LAS unsigned char* lds, const bf16_t* A, const bf16_t* Bt, int nM, int N, int K, const EpiArgs& E) {
;     ...
;             PG8_LDB(B0, 1, 0); PG8_LDB(B1, 1, 1); PG8_SCHED; PG8_LDA(At, 1, 0); PG8_STAGEA(PG8_SA(0, 1), a2 + hstep);
;             PG8_WAIT_V(8); PG8_WAIT_L(0); PG8_BAR; PG8_MMA(0, 0, At, B0); PG8_MMA(0, 1, At, B1); PG8_BAR; PG8_SCHED;
;             PG8_LDA(At, 1, 1); PG8_STAGEB(PG8_SB(1, 0), b3); PG8_STAGEB(PG8_SB(1, 1), b3 + hstep); PG8_STAGEA(PG8_SA(1, 0), a3);
;             PG8_WAIT_V(8); PG8_WAIT_L(0); PG8_BAR; PG8_MMA(1, 0, At, B0); PG8_MMA(1, 1, At, B1); PG8_BAR; PG8_SCHED;
;         }
	s_add_i32 s70, 0, 0x18000
	s_add_i32 s71, 0, 0x1c000
	v_add_u32_e32 v168, s70, v156
	v_add_u32_e32 v184, s71, v156
	ds_read_b128 v[150:153], v168
	ds_read_b128 v[160:163], v168 offset:1024
	ds_read_b128 v[164:167], v168 offset:2048
	ds_read_b128 v[168:171], v168 offset:3072
	ds_read_b128 v[172:175], v184
	ds_read_b128 v[176:179], v184 offset:1024
	ds_read_b128 v[180:183], v184 offset:2048
	ds_read_b128 v[184:187], v184 offset:3072
	s_add_u32 s44, s44, 0x40000
	s_addc_u32 s45, s45, 0
	s_mov_b32 m0, s50
	v_lshl_add_u64 v[226:227], s[44:45], 0, v[130:131]
	ds_read_b128 v[188:191], v159 offset:32768
	ds_read_b128 v[192:195], v159 offset:33792
	ds_read_b128 v[196:199], v159 offset:34816
	ds_read_b128 v[200:203], v159 offset:35840
	ds_read_b128 v[204:207], v159 offset:36864
	ds_read_b128 v[208:211], v159 offset:37888
	ds_read_b128 v[212:215], v159 offset:38912
	ds_read_b128 v[216:219], v159 offset:39936
	global_load_lds_dwordx4 v[226:227], off
	v_lshl_add_u64 v[226:227], s[44:45], 0, v[134:135]
	s_mov_b32 m0, s51
	s_nop 0
	global_load_lds_dwordx4 v[226:227], off
	s_waitcnt vmcnt(8)
	s_waitcnt lgkmcnt(0)
	s_barrier
	s_waitcnt lgkmcnt(0)
	v_mfma_f32_16x16x32_bf16 v[110:113], v[150:153], v[188:191], v[110:113]
	v_mfma_f32_16x16x32_bf16 v[106:109], v[164:167], v[188:191], v[106:109]
	v_mfma_f32_16x16x32_bf16 v[78:81], v[172:175], v[188:191], v[78:81]
	v_mfma_f32_16x16x32_bf16 v[74:77], v[180:183], v[188:191], v[74:77]
	v_mfma_f32_16x16x32_bf16 v[66:69], v[180:183], v[196:199], v[66:69]
	v_mfma_f32_16x16x32_bf16 v[70:73], v[172:175], v[196:199], v[70:73]
	v_mfma_f32_16x16x32_bf16 v[98:101], v[164:167], v[196:199], v[98:101]
	v_mfma_f32_16x16x32_bf16 v[102:105], v[150:153], v[196:199], v[102:105]
	v_mfma_f32_16x16x32_bf16 v[94:97], v[150:153], v[204:207], v[94:97]
	v_mfma_f32_16x16x32_bf16 v[90:93], v[164:167], v[204:207], v[90:93]
	v_mfma_f32_16x16x32_bf16 v[62:65], v[172:175], v[204:207], v[62:65]
	v_mfma_f32_16x16x32_bf16 v[58:61], v[180:183], v[204:207], v[58:61]
	v_mfma_f32_16x16x32_bf16 v[50:53], v[180:183], v[212:215], v[50:53]
	v_mfma_f32_16x16x32_bf16 v[54:57], v[172:175], v[212:215], v[54:57]
	v_mfma_f32_16x16x32_bf16 v[82:85], v[164:167], v[212:215], v[82:85]
	v_mfma_f32_16x16x32_bf16 v[86:89], v[150:153], v[212:215], v[86:89]
	v_mfma_f32_16x16x32_bf16 v[110:113], v[160:163], v[192:195], v[110:113]
	v_mfma_f32_16x16x32_bf16 v[106:109], v[168:171], v[192:195], v[106:109]
	v_mfma_f32_16x16x32_bf16 v[78:81], v[176:179], v[192:195], v[78:81]
	v_mfma_f32_16x16x32_bf16 v[74:77], v[184:187], v[192:195], v[74:77]
	v_mfma_f32_16x16x32_bf16 v[66:69], v[184:187], v[200:203], v[66:69]
	v_mfma_f32_16x16x32_bf16 v[70:73], v[176:179], v[200:203], v[70:73]
	v_mfma_f32_16x16x32_bf16 v[98:101], v[168:171], v[200:203], v[98:101]
	v_mfma_f32_16x16x32_bf16 v[102:105], v[160:163], v[200:203], v[102:105]
	v_mfma_f32_16x16x32_bf16 v[94:97], v[160:163], v[208:211], v[94:97]
	v_mfma_f32_16x16x32_bf16 v[90:93], v[168:171], v[208:211], v[90:93]
	v_mfma_f32_16x16x32_bf16 v[62:65], v[176:179], v[208:211], v[62:65]
	v_mfma_f32_16x16x32_bf16 v[58:61], v[184:187], v[208:211], v[58:61]
	v_mfma_f32_16x16x32_bf16 v[50:53], v[184:187], v[216:219], v[50:53]
	v_mfma_f32_16x16x32_bf16 v[54:57], v[176:179], v[216:219], v[54:57]
	v_mfma_f32_16x16x32_bf16 v[82:85], v[168:171], v[216:219], v[82:85]
	v_mfma_f32_16x16x32_bf16 v[86:89], v[160:163], v[216:219], v[86:89]
	s_barrier
	s_add_i32 s44, s70, s49
	v_lshl_add_u64 v[154:155], v[154:155], 0, s[10:11]
	s_mov_b32 m0, s44
	ds_read_b128 v[188:191], v159 offset:49152
	ds_read_b128 v[192:195], v159 offset:50176
	ds_read_b128 v[196:199], v159 offset:51200
	ds_read_b128 v[200:203], v159 offset:52224
	ds_read_b128 v[204:207], v159 offset:53248
	ds_read_b128 v[208:211], v159 offset:54272
	ds_read_b128 v[212:215], v159 offset:55296
	ds_read_b128 v[216:219], v159 offset:56320
	global_load_lds_dwordx4 v[154:155], off
	s_add_i32 m0, s44, 0x2000
	s_add_u32 s42, s42, 0x40080
	v_lshl_add_u64 v[154:155], v[220:221], 0, s[10:11]
	s_addc_u32 s43, s43, 0
	s_add_i32 s44, s71, s49
	global_load_lds_dwordx4 v[154:155], off
	v_lshl_add_u64 v[154:155], s[42:43], 0, v[132:133]
	s_mov_b32 m0, s44
	s_nop 0
	global_load_lds_dwordx4 v[154:155], off
	v_lshl_add_u64 v[154:155], s[42:43], 0, v[136:137]
	s_add_i32 m0, s44, 0x2000
	s_nop 0
	global_load_lds_dwordx4 v[154:155], off
	v_lshl_add_u64 v[154:155], v[222:223], 0, s[10:11]
	s_mov_b32 m0, s52
	s_nop 0
	global_load_lds_dwordx4 v[154:155], off
	v_lshl_add_u64 v[154:155], v[224:225], 0, s[10:11]
	s_mov_b32 m0, s53
	s_nop 0
	global_load_lds_dwordx4 v[154:155], off
	s_waitcnt vmcnt(8)
	s_waitcnt lgkmcnt(0)
	s_barrier
	s_waitcnt lgkmcnt(0)
	v_mfma_f32_16x16x32_bf16 v[46:49], v[150:153], v[188:191], v[46:49]
	v_mfma_f32_16x16x32_bf16 v[42:45], v[164:167], v[188:191], v[42:45]
	v_mfma_f32_16x16x32_bf16 v[14:17], v[172:175], v[188:191], v[14:17]
	v_mfma_f32_16x16x32_bf16 v[10:13], v[180:183], v[188:191], v[10:13]
	v_mfma_f32_16x16x32_bf16 v[2:5], v[180:183], v[196:199], v[2:5]
	v_mfma_f32_16x16x32_bf16 v[6:9], v[172:175], v[196:199], v[6:9]
	v_mfma_f32_16x16x32_bf16 v[34:37], v[164:167], v[196:199], v[34:37]
	v_mfma_f32_16x16x32_bf16 v[38:41], v[150:153], v[196:199], v[38:41]
	v_mfma_f32_16x16x32_bf16 v[30:33], v[150:153], v[204:207], v[30:33]
	v_mfma_f32_16x16x32_bf16 v[26:29], v[164:167], v[204:207], v[26:29]
	v_mfma_f32_16x16x32_bf16 v[114:117], v[172:175], v[204:207], v[114:117]
	v_mfma_f32_16x16x32_bf16 v[118:121], v[180:183], v[204:207], v[118:121]
	v_mfma_f32_16x16x32_bf16 v[126:129], v[180:183], v[212:215], v[126:129]
	v_mfma_f32_16x16x32_bf16 v[122:125], v[172:175], v[212:215], v[122:125]
	v_mfma_f32_16x16x32_bf16 v[18:21], v[164:167], v[212:215], v[18:21]
	v_mfma_f32_16x16x32_bf16 v[22:25], v[150:153], v[212:215], v[22:25]
	v_mfma_f32_16x16x32_bf16 v[46:49], v[160:163], v[192:195], v[46:49]
	v_mfma_f32_16x16x32_bf16 v[42:45], v[168:171], v[192:195], v[42:45]
	v_mfma_f32_16x16x32_bf16 v[14:17], v[176:179], v[192:195], v[14:17]
	v_mfma_f32_16x16x32_bf16 v[10:13], v[184:187], v[192:195], v[10:13]
	v_mfma_f32_16x16x32_bf16 v[2:5], v[184:187], v[200:203], v[2:5]
	v_mfma_f32_16x16x32_bf16 v[6:9], v[176:179], v[200:203], v[6:9]
	v_mfma_f32_16x16x32_bf16 v[34:37], v[168:171], v[200:203], v[34:37]
	v_mfma_f32_16x16x32_bf16 v[38:41], v[160:163], v[200:203], v[38:41]
	v_mfma_f32_16x16x32_bf16 v[30:33], v[160:163], v[208:211], v[30:33]
	v_mfma_f32_16x16x32_bf16 v[26:29], v[168:171], v[208:211], v[26:29]
	v_mfma_f32_16x16x32_bf16 v[114:117], v[176:179], v[208:211], v[114:117]
	v_mfma_f32_16x16x32_bf16 v[118:121], v[184:187], v[208:211], v[118:121]
	v_mfma_f32_16x16x32_bf16 v[126:129], v[184:187], v[216:219], v[126:129]
	v_mfma_f32_16x16x32_bf16 v[122:125], v[176:179], v[216:219], v[122:125]
	v_mfma_f32_16x16x32_bf16 v[18:21], v[168:171], v[216:219], v[18:21]
	v_mfma_f32_16x16x32_bf16 v[22:25], v[160:163], v[216:219], v[22:25]
	s_barrier
	s_add_i32 s69, s69, 2
	s_add_u32 s40, s40, 0x100
	s_addc_u32 s41, s41, 0
	s_cmp_gt_u32 s69, 13
	s_cbranch_scc0 .LBB0_1245

; #define PG8_STAGEA(bufoff, gbase) PG8_STAGE_(bufoff, gbase, voffA)
; #define PG8_STAGEB(bufoff, gbase) PG8_STAGE_(bufoff, gbase, voffB)
; #define PG8_LDA(dst, b, h) do { _Pragma("unroll") for (int m = 0; m < 4; ++m) _Pragma("unroll") for (int k = 0; k < 2; ++k) dst[m][k] = *(const LAS bf16x8*)(lds + PG8_SA(b, h) + aoff + m * 2048 + k * 1024); } while (0)
; #define PG8_LDB(dst, b, h) do { _Pragma("unroll") for (int n = 0; n < 2; ++n) _Pragma("unroll") for (int k = 0; k < 2; ++k) dst[n][k] = *(const LAS bf16x8*)(lds + PG8_SB(b, h) + boff + n * 2048 + k * 1024); } while (0)
; #define PG8_MMA(ai, bj, At, Bt_) do { __builtin_amdgcn_s_setprio(1); _Pragma("unroll") for (int m = 0; m < 4; ++m) _Pragma("unroll") for (int n = 0; n < 2; ++n) _Pragma("unroll") for (int k = 0; k < 2; ++k) \
;         acc[ai][bj][m][n] = __builtin_amdgcn_mfma_f32_16x16x32_bf16(Bt_[n][k], At[m][k], acc[ai][bj][m][n], 0, 0, 0); __builtin_amdgcn_s_setprio(0); } while (0)
; #define PG8_WAIT_V(n) asm volatile("s_waitcnt vmcnt(" #n ")" ::: "memory")
; #define PG8_WAIT_L(n) asm volatile("s_waitcnt lgkmcnt(" #n ")" ::: "memory")
; #define PG8_BAR __builtin_amdgcn_s_barrier()
; template <int EK, int SK = -1>
; __device__ __forceinline__ void gemm_phase(LAS unsigned char* lds, const bf16_t* A, const bf16_t* Bt, int nM, int N, int K, const EpiArgs& E) {
;     ...
;         const bool has_next = S.next(ui + 1, nxt);
;         const char* nA = has_next ? (const char*)A + (size_t)nxt.pm * tstep : cA; const char* nB = has_next ? (const char*)Bt + (size_t)nxt.pn * tstep : cB;
;         for (int t = 0; t < nt; t += 2) {
;             const bool last = (t == nt - 2);
;             const char* a1 = cA + (size_t)(t + 1) * kstep;
;             const char* a2 = last ? nA : cA + (size_t)(t + 2) * kstep; const char* b2 = last ? nB : cB + (size_t)(t + 2) * kstep;
;             const char* a3 = a2 + kstep; const char* b3 = b2 + kstep;
;             PG8_LDB(B0, 0, 0); PG8_LDB(B1, 0, 1); PG8_SCHED; PG8_LDA(At, 0, 0); PG8_STAGEA(PG8_SA(1, 1), a1 + hstep);
;             PG8_WAIT_V(8); PG8_WAIT_L(0); PG8_BAR; PG8_MMA(0, 0, At, B0); PG8_MMA(0, 1, At, B1); PG8_BAR; PG8_SCHED;
;             PG8_LDA(At, 0, 1); PG8_STAGEB(PG8_SB(0, 0), b2); PG8_STAGEB(PG8_SB(0, 1), b2 + hstep); PG8_STAGEA(PG8_SA(0, 0), a2);
;             PG8_WAIT_V(8); PG8_WAIT_L(0); PG8_BAR; PG8_MMA(1, 0, At, B0); PG8_MMA(1, 1, At, B1); PG8_BAR; PG8_SCHED;
.LBB0_1337:
	s_add_u32 s73, s42, 0x100
	s_addc_u32 s74, s43, 0
	s_waitcnt lgkmcnt(0)
	v_lshl_add_u64 v[146:147], s[20:21], 0, v[138:139]
	v_lshl_add_u64 v[148:149], s[20:21], 0, v[140:141]
	s_mov_b32 s26, -2
	s_mov_b64 s[42:43], 0
	v_add_u32_e32 v150, s67, v152
	ds_read_b128 v[156:159], v150
	ds_read_b128 v[160:163], v150 offset:1024
	ds_read_b128 v[164:167], v150 offset:2048
	ds_read_b128 v[168:171], v150 offset:3072
	v_add_u32_e32 v150, s68, v152
	s_add_u32 s44, s20, s42
	ds_read_b128 v[172:175], v150
	ds_read_b128 v[176:179], v150 offset:1024
	ds_read_b128 v[180:183], v150 offset:2048
	ds_read_b128 v[184:187], v150 offset:3072
	s_addc_u32 s45, s21, s43
	s_add_u32 s44, s44, 0x100
	s_addc_u32 s45, s45, 0
	s_add_u32 s75, s73, s42
	s_addc_u32 s76, s74, s43
	s_cmpk_eq_i32 s42, 0x1500
	s_cselect_b32 s47, s41, s45
	s_cselect_b32 s46, s40, s44
	s_cselect_b32 s45, s9, s76
	s_cselect_b32 s44, s8, s75
	v_lshl_add_u64 v[150:151], v[146:147], 0, s[42:43]
	s_add_i32 m0, s53, 0xc000
	ds_read_b128 v[188:191], v154
	ds_read_b128 v[192:195], v154 offset:1024
	ds_read_b128 v[196:199], v154 offset:2048
	ds_read_b128 v[200:203], v154 offset:3072
	ds_read_b128 v[204:207], v154 offset:4096
	ds_read_b128 v[208:211], v154 offset:5120
	ds_read_b128 v[212:215], v154 offset:6144
	ds_read_b128 v[216:219], v154 offset:7168
	global_load_lds_dwordx4 v[150:151], off
	v_lshl_add_u64 v[150:151], v[148:149], 0, s[42:43]
	s_add_i32 m0, s53, 0xe000
	s_nop 0
	global_load_lds_dwordx4 v[150:151], off
	s_waitcnt vmcnt(8)
	s_waitcnt lgkmcnt(0)
	s_barrier
	s_waitcnt lgkmcnt(0)
	v_mfma_f32_16x16x32_bf16 v[126:129], v[156:159], v[188:191], 0
	v_mfma_f32_16x16x32_bf16 v[122:125], v[164:167], v[188:191], 0
	v_mfma_f32_16x16x32_bf16 v[94:97], v[172:175], v[188:191], 0
	v_mfma_f32_16x16x32_bf16 v[90:93], v[180:183], v[188:191], 0
	v_mfma_f32_16x16x32_bf16 v[82:85], v[180:183], v[196:199], 0
	v_mfma_f32_16x16x32_bf16 v[86:89], v[172:175], v[196:199], 0
	v_mfma_f32_16x16x32_bf16 v[114:117], v[164:167], v[196:199], 0
	v_mfma_f32_16x16x32_bf16 v[118:121], v[156:159], v[196:199], 0
	v_mfma_f32_16x16x32_bf16 v[110:113], v[156:159], v[204:207], 0
	v_mfma_f32_16x16x32_bf16 v[106:109], v[164:167], v[204:207], 0
	v_mfma_f32_16x16x32_bf16 v[78:81], v[172:175], v[204:207], 0
	v_mfma_f32_16x16x32_bf16 v[74:77], v[180:183], v[204:207], 0
	v_mfma_f32_16x16x32_bf16 v[66:69], v[180:183], v[212:215], 0
	v_mfma_f32_16x16x32_bf16 v[70:73], v[172:175], v[212:215], 0
	v_mfma_f32_16x16x32_bf16 v[98:101], v[164:167], v[212:215], 0
	v_mfma_f32_16x16x32_bf16 v[102:105], v[156:159], v[212:215], 0
	v_mfma_f32_16x16x32_bf16 v[126:129], v[160:163], v[192:195], v[126:129]
	v_mfma_f32_16x16x32_bf16 v[122:125], v[168:171], v[192:195], v[122:125]
	v_mfma_f32_16x16x32_bf16 v[94:97], v[176:179], v[192:195], v[94:97]
	v_mfma_f32_16x16x32_bf16 v[90:93], v[184:187], v[192:195], v[90:93]
	v_mfma_f32_16x16x32_bf16 v[82:85], v[184:187], v[200:203], v[82:85]
	v_mfma_f32_16x16x32_bf16 v[86:89], v[176:179], v[200:203], v[86:89]
	v_mfma_f32_16x16x32_bf16 v[114:117], v[168:171], v[200:203], v[114:117]
	v_mfma_f32_16x16x32_bf16 v[118:121], v[160:163], v[200:203], v[118:121]
	v_mfma_f32_16x16x32_bf16 v[110:113], v[160:163], v[208:211], v[110:113]
	v_mfma_f32_16x16x32_bf16 v[106:109], v[168:171], v[208:211], v[106:109]
	v_mfma_f32_16x16x32_bf16 v[78:81], v[176:179], v[208:211], v[78:81]
	v_mfma_f32_16x16x32_bf16 v[74:77], v[184:187], v[208:211], v[74:77]
	v_mfma_f32_16x16x32_bf16 v[66:69], v[184:187], v[216:219], v[66:69]
	v_mfma_f32_16x16x32_bf16 v[70:73], v[176:179], v[216:219], v[70:73]
	v_mfma_f32_16x16x32_bf16 v[98:101], v[168:171], v[216:219], v[98:101]
	v_mfma_f32_16x16x32_bf16 v[102:105], v[160:163], v[216:219], v[102:105]
	s_barrier
	s_add_i32 s75, s67, s52
	v_lshl_add_u64 v[150:151], s[44:45], 0, v[132:133]
	s_mov_b32 m0, s75
	ds_read_b128 v[188:191], v154 offset:16384
	ds_read_b128 v[192:195], v154 offset:17408
	ds_read_b128 v[196:199], v154 offset:18432
	ds_read_b128 v[200:203], v154 offset:19456
	ds_read_b128 v[204:207], v154 offset:20480
	ds_read_b128 v[208:211], v154 offset:21504
	ds_read_b128 v[212:215], v154 offset:22528
	ds_read_b128 v[216:219], v154 offset:23552
	global_load_lds_dwordx4 v[150:151], off
	s_add_i32 m0, s75, 0x2000
	s_add_u32 s76, s44, 0xb0000
	v_lshl_add_u64 v[220:221], s[44:45], 0, v[136:137]
	s_addc_u32 s77, s45, 0
	s_add_i32 s75, s68, s52
	global_load_lds_dwordx4 v[220:221], off
	v_lshl_add_u64 v[222:223], s[76:77], 0, v[132:133]
	s_mov_b32 m0, s75
	v_lshl_add_u64 v[224:225], s[46:47], 0, v[134:135]
	global_load_lds_dwordx4 v[222:223], off
	v_lshl_add_u64 v[222:223], s[76:77], 0, v[136:137]
	s_add_i32 m0, s75, 0x2000
	s_nop 0
	global_load_lds_dwordx4 v[222:223], off
	v_lshl_add_u64 v[222:223], s[46:47], 0, v[130:131]
	s_mov_b32 m0, s53
	s_nop 0
	global_load_lds_dwordx4 v[222:223], off
	s_mov_b32 m0, s54
	s_nop 0
	global_load_lds_dwordx4 v[224:225], off
	s_waitcnt vmcnt(8)
	s_waitcnt lgkmcnt(0)
	s_barrier
; #define PG8_STAGEA(bufoff, gbase) PG8_STAGE_(bufoff, gbase, voffA)
; #define PG8_STAGEB(bufoff, gbase) PG8_STAGE_(bufoff, gbase, voffB)
; #define PG8_LDA(dst, b, h) do { _Pragma("unroll") for (int m = 0; m < 4; ++m) _Pragma("unroll") for (int k = 0; k < 2; ++k) dst[m][k] = *(const LAS bf16x8*)(lds + PG8_SA(b, h) + aoff + m * 2048 + k * 1024); } while (0)
; #define PG8_LDB(dst, b, h) do { _Pragma("unroll") for (int n = 0; n < 2; ++n) _Pragma("unroll") for (int k = 0; k < 2; ++k) dst[n][k] = *(const LAS bf16x8*)(lds + PG8_SB(b, h) + boff + n * 2048 + k * 1024); } while (0)
; #define PG8_MMA(ai, bj, At, Bt_) do { __builtin_amdgcn_s_setprio(1); _Pragma("unroll") for (int m = 0; m < 4; ++m) _Pragma("unroll") for (int n = 0; n < 2; ++n) _Pragma("unroll") for (int k = 0; k < 2; ++k) \
;         acc[ai][bj][m][n] = __builtin_amdgcn_mfma_f32_16x16x32_bf16(Bt_[n][k], At[m][k], acc[ai][bj][m][n], 0, 0, 0); __builtin_amdgcn_s_setprio(0); } while (0)
; #define PG8_WAIT_V(n) asm volatile("s_waitcnt vmcnt(" #n ")" ::: "memory")
; #define PG8_WAIT_L(n) asm volatile("s_waitcnt lgkmcnt(" #n ")" ::: "memory")
; #define PG8_BAR __builtin_amdgcn_s_barrier()
; #define PG8_SCHED __builtin_amdgcn_sched_barrier(0)
; template <int EK, int SK = -1>
; __device__ __forceinline__ void gemm_phase(LAS unsigned char* lds, const bf16_t* A, const bf16_t* Bt, int nM, int N, int K, const EpiArgs& E) {
;     ...
;             PG8_LDA(At, 0, 1); PG8_STAGEB(PG8_SB(0, 0), b2); PG8_STAGEB(PG8_SB(0, 1), b2 + hstep); PG8_STAGEA(PG8_SA(0, 0), a2);
;             PG8_WAIT_V(8); PG8_WAIT_L(0); PG8_BAR; PG8_MMA(1, 0, At, B0); PG8_MMA(1, 1, At, B1); PG8_BAR; PG8_SCHED;
;             PG8_LDB(B0, 1, 0); PG8_LDB(B1, 1, 1); PG8_SCHED; PG8_LDA(At, 1, 0); PG8_STAGEA(PG8_SA(0, 1), a2 + hstep);
;             PG8_WAIT_V(8); PG8_WAIT_L(0); PG8_BAR; PG8_MMA(0, 0, At, B0); PG8_MMA(0, 1, At, B1); PG8_BAR; PG8_SCHED;
	s_waitcnt lgkmcnt(0)
	v_mfma_f32_16x16x32_bf16 v[62:65], v[156:159], v[188:191], 0
	v_mfma_f32_16x16x32_bf16 v[58:61], v[164:167], v[188:191], 0
	v_mfma_f32_16x16x32_bf16 v[30:33], v[172:175], v[188:191], 0
	v_mfma_f32_16x16x32_bf16 v[26:29], v[180:183], v[188:191], 0
	v_mfma_f32_16x16x32_bf16 v[18:21], v[180:183], v[196:199], 0
	v_mfma_f32_16x16x32_bf16 v[22:25], v[172:175], v[196:199], 0
	v_mfma_f32_16x16x32_bf16 v[50:53], v[164:167], v[196:199], 0
	v_mfma_f32_16x16x32_bf16 v[54:57], v[156:159], v[196:199], 0
	v_mfma_f32_16x16x32_bf16 v[46:49], v[156:159], v[204:207], 0
	v_mfma_f32_16x16x32_bf16 v[42:45], v[164:167], v[204:207], 0
	v_mfma_f32_16x16x32_bf16 v[14:17], v[172:175], v[204:207], 0
	v_mfma_f32_16x16x32_bf16 v[10:13], v[180:183], v[204:207], 0
	v_mfma_f32_16x16x32_bf16 v[2:5], v[180:183], v[212:215], 0
	v_mfma_f32_16x16x32_bf16 v[6:9], v[172:175], v[212:215], 0
	v_mfma_f32_16x16x32_bf16 v[34:37], v[164:167], v[212:215], 0
	v_mfma_f32_16x16x32_bf16 v[38:41], v[156:159], v[212:215], 0
	v_mfma_f32_16x16x32_bf16 v[62:65], v[160:163], v[192:195], v[62:65]
	v_mfma_f32_16x16x32_bf16 v[58:61], v[168:171], v[192:195], v[58:61]
	v_mfma_f32_16x16x32_bf16 v[30:33], v[176:179], v[192:195], v[30:33]
	v_mfma_f32_16x16x32_bf16 v[26:29], v[184:187], v[192:195], v[26:29]
	v_mfma_f32_16x16x32_bf16 v[18:21], v[184:187], v[200:203], v[18:21]
	v_mfma_f32_16x16x32_bf16 v[22:25], v[176:179], v[200:203], v[22:25]
	v_mfma_f32_16x16x32_bf16 v[50:53], v[168:171], v[200:203], v[50:53]
	v_mfma_f32_16x16x32_bf16 v[54:57], v[160:163], v[200:203], v[54:57]
	v_mfma_f32_16x16x32_bf16 v[46:49], v[160:163], v[208:211], v[46:49]
	v_mfma_f32_16x16x32_bf16 v[42:45], v[168:171], v[208:211], v[42:45]
	v_mfma_f32_16x16x32_bf16 v[14:17], v[176:179], v[208:211], v[14:17]
	v_mfma_f32_16x16x32_bf16 v[10:13], v[184:187], v[208:211], v[10:13]
	v_mfma_f32_16x16x32_bf16 v[2:5], v[184:187], v[216:219], v[2:5]
	v_mfma_f32_16x16x32_bf16 v[6:9], v[176:179], v[216:219], v[6:9]
	v_mfma_f32_16x16x32_bf16 v[34:37], v[168:171], v[216:219], v[34:37]
	v_mfma_f32_16x16x32_bf16 v[38:41], v[160:163], v[216:219], v[38:41]
	s_barrier
	s_add_i32 s75, 0, 0x18000
	s_add_i32 s76, 0, 0x1c000
	v_add_u32_e32 v168, s75, v152
	v_add_u32_e32 v184, s76, v152
	ds_read_b128 v[156:159], v168
	ds_read_b128 v[160:163], v168 offset:1024
	ds_read_b128 v[164:167], v168 offset:2048
	ds_read_b128 v[168:171], v168 offset:3072
	ds_read_b128 v[172:175], v184
	ds_read_b128 v[176:179], v184 offset:1024
	ds_read_b128 v[180:183], v184 offset:2048
	ds_read_b128 v[184:187], v184 offset:3072
	s_add_u32 s46, s46, 0xb0000
	s_addc_u32 s47, s47, 0
	s_mov_b32 m0, s55
	v_lshl_add_u64 v[226:227], s[46:47], 0, v[130:131]
	ds_read_b128 v[188:191], v154 offset:32768
	ds_read_b128 v[192:195], v154 offset:33792
	ds_read_b128 v[196:199], v154 offset:34816
	ds_read_b128 v[200:203], v154 offset:35840
	ds_read_b128 v[204:207], v154 offset:36864
	ds_read_b128 v[208:211], v154 offset:37888
	ds_read_b128 v[212:215], v154 offset:38912
	ds_read_b128 v[216:219], v154 offset:39936
	global_load_lds_dwordx4 v[226:227], off
	v_lshl_add_u64 v[226:227], s[46:47], 0, v[134:135]
	s_mov_b32 m0, s56
	s_nop 0
	global_load_lds_dwordx4 v[226:227], off
	s_waitcnt vmcnt(8)
	s_waitcnt lgkmcnt(0)
	s_barrier
	s_waitcnt lgkmcnt(0)
	v_mfma_f32_16x16x32_bf16 v[126:129], v[156:159], v[188:191], v[126:129]
	v_mfma_f32_16x16x32_bf16 v[122:125], v[164:167], v[188:191], v[122:125]
	v_mfma_f32_16x16x32_bf16 v[94:97], v[172:175], v[188:191], v[94:97]
	v_mfma_f32_16x16x32_bf16 v[90:93], v[180:183], v[188:191], v[90:93]
	v_mfma_f32_16x16x32_bf16 v[82:85], v[180:183], v[196:199], v[82:85]
	v_mfma_f32_16x16x32_bf16 v[86:89], v[172:175], v[196:199], v[86:89]
	v_mfma_f32_16x16x32_bf16 v[114:117], v[164:167], v[196:199], v[114:117]
	v_mfma_f32_16x16x32_bf16 v[118:121], v[156:159], v[196:199], v[118:121]
	v_mfma_f32_16x16x32_bf16 v[110:113], v[156:159], v[204:207], v[110:113]
	v_mfma_f32_16x16x32_bf16 v[106:109], v[164:167], v[204:207], v[106:109]
	v_mfma_f32_16x16x32_bf16 v[78:81], v[172:175], v[204:207], v[78:81]
	v_mfma_f32_16x16x32_bf16 v[74:77], v[180:183], v[204:207], v[74:77]
	v_mfma_f32_16x16x32_bf16 v[66:69], v[180:183], v[212:215], v[66:69]
	v_mfma_f32_16x16x32_bf16 v[70:73], v[172:175], v[212:215], v[70:73]
	v_mfma_f32_16x16x32_bf16 v[98:101], v[164:167], v[212:215], v[98:101]
	v_mfma_f32_16x16x32_bf16 v[102:105], v[156:159], v[212:215], v[102:105]
	v_mfma_f32_16x16x32_bf16 v[126:129], v[160:163], v[192:195], v[126:129]
	v_mfma_f32_16x16x32_bf16 v[122:125], v[168:171], v[192:195], v[122:125]
	v_mfma_f32_16x16x32_bf16 v[94:97], v[176:179], v[192:195], v[94:97]
	v_mfma_f32_16x16x32_bf16 v[90:93], v[184:187], v[192:195], v[90:93]
	v_mfma_f32_16x16x32_bf16 v[82:85], v[184:187], v[200:203], v[82:85]
	v_mfma_f32_16x16x32_bf16 v[86:89], v[176:179], v[200:203], v[86:89]
	v_mfma_f32_16x16x32_bf16 v[114:117], v[168:171], v[200:203], v[114:117]
	v_mfma_f32_16x16x32_bf16 v[118:121], v[160:163], v[200:203], v[118:121]
	v_mfma_f32_16x16x32_bf16 v[110:113], v[160:163], v[208:211], v[110:113]
	v_mfma_f32_16x16x32_bf16 v[106:109], v[168:171], v[208:211], v[106:109]
	v_mfma_f32_16x16x32_bf16 v[78:81], v[176:179], v[208:211], v[78:81]
	v_mfma_f32_16x16x32_bf16 v[74:77], v[184:187], v[208:211], v[74:77]
	v_mfma_f32_16x16x32_bf16 v[66:69], v[184:187], v[216:219], v[66:69]
	v_mfma_f32_16x16x32_bf16 v[70:73], v[176:179], v[216:219], v[70:73]
	v_mfma_f32_16x16x32_bf16 v[98:101], v[168:171], v[216:219], v[98:101]
	v_mfma_f32_16x16x32_bf16 v[102:105], v[160:163], v[216:219], v[102:105]
	s_barrier
; #define PG8_STAGEA(bufoff, gbase) PG8_STAGE_(bufoff, gbase, voffA)
; #define PG8_STAGEB(bufoff, gbase) PG8_STAGE_(bufoff, gbase, voffB)
; #define PG8_LDA(dst, b, h) do { _Pragma("unroll") for (int m = 0; m < 4; ++m) _Pragma("unroll") for (int k = 0; k < 2; ++k) dst[m][k] = *(const LAS bf16x8*)(lds + PG8_SA(b, h) + aoff + m * 2048 + k * 1024); } while (0)
; #define PG8_LDB(dst, b, h) do { _Pragma("unroll") for (int n = 0; n < 2; ++n) _Pragma("unroll") for (int k = 0; k < 2; ++k) dst[n][k] = *(const LAS bf16x8*)(lds + PG8_SB(b, h) + boff + n * 2048 + k * 1024); } while (0)
; #define PG8_MMA(ai, bj, At, Bt_) do { __builtin_amdgcn_s_setprio(1); _Pragma("unroll") for (int m = 0; m < 4; ++m) _Pragma("unroll") for (int n = 0; n < 2; ++n) _Pragma("unroll") for (int k = 0; k < 2; ++k) \
;         acc[ai][bj][m][n] = __builtin_amdgcn_mfma_f32_16x16x32_bf16(Bt_[n][k], At[m][k], acc[ai][bj][m][n], 0, 0, 0); __builtin_amdgcn_s_setprio(0); } while (0)
; #define PG8_WAIT_V(n) asm volatile("s_waitcnt vmcnt(" #n ")" ::: "memory")
; #define PG8_WAIT_L(n) asm volatile("s_waitcnt lgkmcnt(" #n ")" ::: "memory")
; #define PG8_BAR __builtin_amdgcn_s_barrier()
; #define PG8_SCHED __builtin_amdgcn_sched_barrier(0)
; template <int EK, int SK = -1>
; __device__ __forceinline__ void gemm_phase(LAS unsigned char* lds, const bf16_t* A, const bf16_t* Bt, int nM, int N, int K, const EpiArgs& E) {
;     ...
;             PG8_LDB(B0, 0, 0); PG8_LDB(B1, 0, 1); PG8_SCHED; PG8_LDA(At, 0, 0); PG8_STAGEA(PG8_SA(1, 1), a1 + hstep);
;             PG8_WAIT_V(8); PG8_WAIT_L(0); PG8_BAR; PG8_MMA(0, 0, At, B0); PG8_MMA(0, 1, At, B1); PG8_BAR; PG8_SCHED;
;             PG8_LDA(At, 0, 1); PG8_STAGEB(PG8_SB(0, 0), b2); PG8_STAGEB(PG8_SB(0, 1), b2 + hstep); PG8_STAGEA(PG8_SA(0, 0), a2);
;             PG8_WAIT_V(8); PG8_WAIT_L(0); PG8_BAR; PG8_MMA(1, 0, At, B0); PG8_MMA(1, 1, At, B1); PG8_BAR; PG8_SCHED;
;             PG8_LDB(B0, 1, 0); PG8_LDB(B1, 1, 1); PG8_SCHED; PG8_LDA(At, 1, 0); PG8_STAGEA(PG8_SA(0, 1), a2 + hstep);
;             PG8_WAIT_V(8); PG8_WAIT_L(0); PG8_BAR; PG8_MMA(0, 0, At, B0); PG8_MMA(0, 1, At, B1); PG8_BAR; PG8_SCHED;
;             PG8_LDA(At, 1, 1); PG8_STAGEB(PG8_SB(1, 0), b3); PG8_STAGEB(PG8_SB(1, 1), b3 + hstep); PG8_STAGEA(PG8_SA(1, 0), a3);
;             PG8_WAIT_V(8); PG8_WAIT_L(0); PG8_BAR; PG8_MMA(1, 0, At, B0); PG8_MMA(1, 1, At, B1); PG8_BAR; PG8_SCHED;
;         }
	s_add_i32 s46, s75, s52
	v_lshl_add_u64 v[150:151], v[150:151], 0, s[36:37]
	s_mov_b32 m0, s46
	ds_read_b128 v[188:191], v154 offset:49152
	ds_read_b128 v[192:195], v154 offset:50176
	ds_read_b128 v[196:199], v154 offset:51200
	ds_read_b128 v[200:203], v154 offset:52224
	ds_read_b128 v[204:207], v154 offset:53248
	ds_read_b128 v[208:211], v154 offset:54272
	ds_read_b128 v[212:215], v154 offset:55296
	ds_read_b128 v[216:219], v154 offset:56320
	global_load_lds_dwordx4 v[150:151], off
	s_add_i32 m0, s46, 0x2000
	s_add_u32 s44, s44, 0xb0080
	v_lshl_add_u64 v[150:151], v[220:221], 0, s[36:37]
	s_addc_u32 s45, s45, 0
	s_add_i32 s46, s76, s52
	global_load_lds_dwordx4 v[150:151], off
	v_lshl_add_u64 v[150:151], s[44:45], 0, v[132:133]
	s_mov_b32 m0, s46
	s_nop 0
	global_load_lds_dwordx4 v[150:151], off
	v_lshl_add_u64 v[150:151], s[44:45], 0, v[136:137]
	s_add_i32 m0, s46, 0x2000
	s_nop 0
	global_load_lds_dwordx4 v[150:151], off
	v_lshl_add_u64 v[150:151], v[222:223], 0, s[36:37]
	s_mov_b32 m0, s59
	s_nop 0
	global_load_lds_dwordx4 v[150:151], off
	v_lshl_add_u64 v[150:151], v[224:225], 0, s[36:37]
	s_mov_b32 m0, s66
	s_nop 0
	global_load_lds_dwordx4 v[150:151], off
	s_waitcnt vmcnt(8)
	s_waitcnt lgkmcnt(0)
	s_barrier
	s_waitcnt lgkmcnt(0)
	v_mfma_f32_16x16x32_bf16 v[62:65], v[156:159], v[188:191], v[62:65]
	v_mfma_f32_16x16x32_bf16 v[58:61], v[164:167], v[188:191], v[58:61]
	v_mfma_f32_16x16x32_bf16 v[30:33], v[172:175], v[188:191], v[30:33]
	v_mfma_f32_16x16x32_bf16 v[26:29], v[180:183], v[188:191], v[26:29]
	v_mfma_f32_16x16x32_bf16 v[18:21], v[180:183], v[196:199], v[18:21]
	v_mfma_f32_16x16x32_bf16 v[22:25], v[172:175], v[196:199], v[22:25]
	v_mfma_f32_16x16x32_bf16 v[50:53], v[164:167], v[196:199], v[50:53]
	v_mfma_f32_16x16x32_bf16 v[54:57], v[156:159], v[196:199], v[54:57]
	v_mfma_f32_16x16x32_bf16 v[46:49], v[156:159], v[204:207], v[46:49]
	v_mfma_f32_16x16x32_bf16 v[42:45], v[164:167], v[204:207], v[42:45]
	v_mfma_f32_16x16x32_bf16 v[14:17], v[172:175], v[204:207], v[14:17]
	v_mfma_f32_16x16x32_bf16 v[10:13], v[180:183], v[204:207], v[10:13]
	v_mfma_f32_16x16x32_bf16 v[2:5], v[180:183], v[212:215], v[2:5]
	v_mfma_f32_16x16x32_bf16 v[6:9], v[172:175], v[212:215], v[6:9]
	v_mfma_f32_16x16x32_bf16 v[34:37], v[164:167], v[212:215], v[34:37]
	v_mfma_f32_16x16x32_bf16 v[38:41], v[156:159], v[212:215], v[38:41]
	v_mfma_f32_16x16x32_bf16 v[62:65], v[160:163], v[192:195], v[62:65]
	v_mfma_f32_16x16x32_bf16 v[58:61], v[168:171], v[192:195], v[58:61]
	v_mfma_f32_16x16x32_bf16 v[30:33], v[176:179], v[192:195], v[30:33]
	v_mfma_f32_16x16x32_bf16 v[26:29], v[184:187], v[192:195], v[26:29]
	v_mfma_f32_16x16x32_bf16 v[18:21], v[184:187], v[200:203], v[18:21]
	v_mfma_f32_16x16x32_bf16 v[22:25], v[176:179], v[200:203], v[22:25]
	v_mfma_f32_16x16x32_bf16 v[50:53], v[168:171], v[200:203], v[50:53]
	v_mfma_f32_16x16x32_bf16 v[54:57], v[160:163], v[200:203], v[54:57]
	v_mfma_f32_16x16x32_bf16 v[46:49], v[160:163], v[208:211], v[46:49]
	v_mfma_f32_16x16x32_bf16 v[42:45], v[168:171], v[208:211], v[42:45]
	v_mfma_f32_16x16x32_bf16 v[14:17], v[176:179], v[208:211], v[14:17]
	v_mfma_f32_16x16x32_bf16 v[10:13], v[184:187], v[208:211], v[10:13]
	v_mfma_f32_16x16x32_bf16 v[2:5], v[184:187], v[216:219], v[2:5]
	v_mfma_f32_16x16x32_bf16 v[6:9], v[176:179], v[216:219], v[6:9]
	v_mfma_f32_16x16x32_bf16 v[34:37], v[168:171], v[216:219], v[34:37]
	v_mfma_f32_16x16x32_bf16 v[38:41], v[160:163], v[216:219], v[38:41]
	s_barrier
	s_add_i32 s26, s26, 2
	s_add_u32 s42, s42, 0x100
	s_addc_u32 s43, s43, 0
	s_cmp_gt_u32 s26, 41
	s_cbranch_scc0 .LBB0_1338
	s_branch .Lmy_kexit_7
.LBB0_1338:
	v_add_u32_e32 v150, s67, v152
	ds_read_b128 v[156:159], v150
	ds_read_b128 v[160:163], v150 offset:1024
	ds_read_b128 v[164:167], v150 offset:2048
	ds_read_b128 v[168:171], v150 offset:3072
	v_add_u32_e32 v150, s68, v152
	s_add_u32 s44, s20, s42
	ds_read_b128 v[172:175], v150
	ds_read_b128 v[176:179], v150 offset:1024
	ds_read_b128 v[180:183], v150 offset:2048
	ds_read_b128 v[184:187], v150 offset:3072
	s_addc_u32 s45, s21, s43
	s_add_u32 s44, s44, 0x100
	s_addc_u32 s45, s45, 0
	s_add_u32 s75, s73, s42
	s_addc_u32 s76, s74, s43
	s_cmpk_eq_i32 s42, 0x1500
	s_cselect_b32 s47, s41, s45
	s_cselect_b32 s46, s40, s44
	s_cselect_b32 s45, s9, s76
	s_cselect_b32 s44, s8, s75
	v_lshl_add_u64 v[150:151], v[146:147], 0, s[42:43]
	s_add_i32 m0, s53, 0xc000
	ds_read_b128 v[188:191], v154
	ds_read_b128 v[192:195], v154 offset:1024
	ds_read_b128 v[196:199], v154 offset:2048
	ds_read_b128 v[200:203], v154 offset:3072
	ds_read_b128 v[204:207], v154 offset:4096
	ds_read_b128 v[208:211], v154 offset:5120
	ds_read_b128 v[212:215], v154 offset:6144
	ds_read_b128 v[216:219], v154 offset:7168
	global_load_lds_dwordx4 v[150:151], off
	v_lshl_add_u64 v[150:151], v[148:149], 0, s[42:43]
	s_add_i32 m0, s53, 0xe000
	s_nop 0
	global_load_lds_dwordx4 v[150:151], off
	s_waitcnt vmcnt(8)
	s_waitcnt lgkmcnt(0)
	s_barrier
; #define PG8_STAGEA(bufoff, gbase) PG8_STAGE_(bufoff, gbase, voffA)
; #define PG8_STAGEB(bufoff, gbase) PG8_STAGE_(bufoff, gbase, voffB)
; #define PG8_LDA(dst, b, h) do { _Pragma("unroll") for (int m = 0; m < 4; ++m) _Pragma("unroll") for (int k = 0; k < 2; ++k) dst[m][k] = *(const LAS bf16x8*)(lds + PG8_SA(b, h) + aoff + m * 2048 + k * 1024); } while (0)
; #define PG8_MMA(ai, bj, At, Bt_) do { __builtin_amdgcn_s_setprio(1); _Pragma("unroll") for (int m = 0; m < 4; ++m) _Pragma("unroll") for (int n = 0; n < 2; ++n) _Pragma("unroll") for (int k = 0; k < 2; ++k) \
;         acc[ai][bj][m][n] = __builtin_amdgcn_mfma_f32_16x16x32_bf16(Bt_[n][k], At[m][k], acc[ai][bj][m][n], 0, 0, 0); __builtin_amdgcn_s_setprio(0); } while (0)
; #define PG8_WAIT_V(n) asm volatile("s_waitcnt vmcnt(" #n ")" ::: "memory")
; #define PG8_WAIT_L(n) asm volatile("s_waitcnt lgkmcnt(" #n ")" ::: "memory")
; #define PG8_BAR __builtin_amdgcn_s_barrier()
; #define PG8_SCHED __builtin_amdgcn_sched_barrier(0)
; template <int EK, int SK = -1>
; __device__ __forceinline__ void gemm_phase(LAS unsigned char* lds, const bf16_t* A, const bf16_t* Bt, int nM, int N, int K, const EpiArgs& E) {
;     ...
;             PG8_WAIT_V(8); PG8_WAIT_L(0); PG8_BAR; PG8_MMA(0, 0, At, B0); PG8_MMA(0, 1, At, B1); PG8_BAR; PG8_SCHED;
;             PG8_LDA(At, 0, 1); PG8_STAGEB(PG8_SB(0, 0), b2); PG8_STAGEB(PG8_SB(0, 1), b2 + hstep); PG8_STAGEA(PG8_SA(0, 0), a2);
;             PG8_WAIT_V(8); PG8_WAIT_L(0); PG8_BAR; PG8_MMA(1, 0, At, B0); PG8_MMA(1, 1, At, B1); PG8_BAR; PG8_SCHED;
	s_waitcnt lgkmcnt(0)
	v_mfma_f32_16x16x32_bf16 v[126:129], v[156:159], v[188:191], v[126:129]
	v_mfma_f32_16x16x32_bf16 v[122:125], v[164:167], v[188:191], v[122:125]
	v_mfma_f32_16x16x32_bf16 v[94:97], v[172:175], v[188:191], v[94:97]
	v_mfma_f32_16x16x32_bf16 v[90:93], v[180:183], v[188:191], v[90:93]
	v_mfma_f32_16x16x32_bf16 v[82:85], v[180:183], v[196:199], v[82:85]
	v_mfma_f32_16x16x32_bf16 v[86:89], v[172:175], v[196:199], v[86:89]
	v_mfma_f32_16x16x32_bf16 v[114:117], v[164:167], v[196:199], v[114:117]
	v_mfma_f32_16x16x32_bf16 v[118:121], v[156:159], v[196:199], v[118:121]
	v_mfma_f32_16x16x32_bf16 v[110:113], v[156:159], v[204:207], v[110:113]
	v_mfma_f32_16x16x32_bf16 v[106:109], v[164:167], v[204:207], v[106:109]
	v_mfma_f32_16x16x32_bf16 v[78:81], v[172:175], v[204:207], v[78:81]
	v_mfma_f32_16x16x32_bf16 v[74:77], v[180:183], v[204:207], v[74:77]
	v_mfma_f32_16x16x32_bf16 v[66:69], v[180:183], v[212:215], v[66:69]
	v_mfma_f32_16x16x32_bf16 v[70:73], v[172:175], v[212:215], v[70:73]
	v_mfma_f32_16x16x32_bf16 v[98:101], v[164:167], v[212:215], v[98:101]
	v_mfma_f32_16x16x32_bf16 v[102:105], v[156:159], v[212:215], v[102:105]
	v_mfma_f32_16x16x32_bf16 v[126:129], v[160:163], v[192:195], v[126:129]
	v_mfma_f32_16x16x32_bf16 v[122:125], v[168:171], v[192:195], v[122:125]
	v_mfma_f32_16x16x32_bf16 v[94:97], v[176:179], v[192:195], v[94:97]
	v_mfma_f32_16x16x32_bf16 v[90:93], v[184:187], v[192:195], v[90:93]
	v_mfma_f32_16x16x32_bf16 v[82:85], v[184:187], v[200:203], v[82:85]
	v_mfma_f32_16x16x32_bf16 v[86:89], v[176:179], v[200:203], v[86:89]
	v_mfma_f32_16x16x32_bf16 v[114:117], v[168:171], v[200:203], v[114:117]
	v_mfma_f32_16x16x32_bf16 v[118:121], v[160:163], v[200:203], v[118:121]
	v_mfma_f32_16x16x32_bf16 v[110:113], v[160:163], v[208:211], v[110:113]
	v_mfma_f32_16x16x32_bf16 v[106:109], v[168:171], v[208:211], v[106:109]
	v_mfma_f32_16x16x32_bf16 v[78:81], v[176:179], v[208:211], v[78:81]
	v_mfma_f32_16x16x32_bf16 v[74:77], v[184:187], v[208:211], v[74:77]
	v_mfma_f32_16x16x32_bf16 v[66:69], v[184:187], v[216:219], v[66:69]
	v_mfma_f32_16x16x32_bf16 v[70:73], v[176:179], v[216:219], v[70:73]
	v_mfma_f32_16x16x32_bf16 v[98:101], v[168:171], v[216:219], v[98:101]
	v_mfma_f32_16x16x32_bf16 v[102:105], v[160:163], v[216:219], v[102:105]
	s_barrier
	s_add_i32 s75, s67, s52
	v_lshl_add_u64 v[150:151], s[44:45], 0, v[132:133]
	s_mov_b32 m0, s75
	ds_read_b128 v[188:191], v154 offset:16384
	ds_read_b128 v[192:195], v154 offset:17408
	ds_read_b128 v[196:199], v154 offset:18432
	ds_read_b128 v[200:203], v154 offset:19456
	ds_read_b128 v[204:207], v154 offset:20480
	ds_read_b128 v[208:211], v154 offset:21504
	ds_read_b128 v[212:215], v154 offset:22528
	ds_read_b128 v[216:219], v154 offset:23552
	global_load_lds_dwordx4 v[150:151], off
	s_add_i32 m0, s75, 0x2000
	s_add_u32 s76, s44, 0xb0000
	v_lshl_add_u64 v[220:221], s[44:45], 0, v[136:137]
	s_addc_u32 s77, s45, 0
	s_add_i32 s75, s68, s52
	global_load_lds_dwordx4 v[220:221], off
	v_lshl_add_u64 v[222:223], s[76:77], 0, v[132:133]
	s_mov_b32 m0, s75
	v_lshl_add_u64 v[224:225], s[46:47], 0, v[134:135]
	global_load_lds_dwordx4 v[222:223], off
	v_lshl_add_u64 v[222:223], s[76:77], 0, v[136:137]
	s_add_i32 m0, s75, 0x2000
	s_nop 0
	global_load_lds_dwordx4 v[222:223], off
	v_lshl_add_u64 v[222:223], s[46:47], 0, v[130:131]
	s_mov_b32 m0, s53
	s_nop 0
	global_load_lds_dwordx4 v[222:223], off
	s_mov_b32 m0, s54
	s_nop 0
	global_load_lds_dwordx4 v[224:225], off
	s_waitcnt vmcnt(8)
	s_waitcnt lgkmcnt(0)
	s_barrier
	s_waitcnt lgkmcnt(0)
	v_mfma_f32_16x16x32_bf16 v[62:65], v[156:159], v[188:191], v[62:65]
	v_mfma_f32_16x16x32_bf16 v[58:61], v[164:167], v[188:191], v[58:61]
	v_mfma_f32_16x16x32_bf16 v[30:33], v[172:175], v[188:191], v[30:33]
	v_mfma_f32_16x16x32_bf16 v[26:29], v[180:183], v[188:191], v[26:29]
	v_mfma_f32_16x16x32_bf16 v[18:21], v[180:183], v[196:199], v[18:21]
	v_mfma_f32_16x16x32_bf16 v[22:25], v[172:175], v[196:199], v[22:25]
	v_mfma_f32_16x16x32_bf16 v[50:53], v[164:167], v[196:199], v[50:53]
	v_mfma_f32_16x16x32_bf16 v[54:57], v[156:159], v[196:199], v[54:57]
	v_mfma_f32_16x16x32_bf16 v[46:49], v[156:159], v[204:207], v[46:49]
	v_mfma_f32_16x16x32_bf16 v[42:45], v[164:167], v[204:207], v[42:45]
	v_mfma_f32_16x16x32_bf16 v[14:17], v[172:175], v[204:207], v[14:17]
	v_mfma_f32_16x16x32_bf16 v[10:13], v[180:183], v[204:207], v[10:13]
	v_mfma_f32_16x16x32_bf16 v[2:5], v[180:183], v[212:215], v[2:5]
	v_mfma_f32_16x16x32_bf16 v[6:9], v[172:175], v[212:215], v[6:9]
	v_mfma_f32_16x16x32_bf16 v[34:37], v[164:167], v[212:215], v[34:37]
	v_mfma_f32_16x16x32_bf16 v[38:41], v[156:159], v[212:215], v[38:41]
	v_mfma_f32_16x16x32_bf16 v[62:65], v[160:163], v[192:195], v[62:65]
	v_mfma_f32_16x16x32_bf16 v[58:61], v[168:171], v[192:195], v[58:61]
	v_mfma_f32_16x16x32_bf16 v[30:33], v[176:179], v[192:195], v[30:33]
	v_mfma_f32_16x16x32_bf16 v[26:29], v[184:187], v[192:195], v[26:29]
	v_mfma_f32_16x16x32_bf16 v[18:21], v[184:187], v[200:203], v[18:21]
	v_mfma_f32_16x16x32_bf16 v[22:25], v[176:179], v[200:203], v[22:25]
	v_mfma_f32_16x16x32_bf16 v[50:53], v[168:171], v[200:203], v[50:53]
	v_mfma_f32_16x16x32_bf16 v[54:57], v[160:163], v[200:203], v[54:57]
	v_mfma_f32_16x16x32_bf16 v[46:49], v[160:163], v[208:211], v[46:49]
	v_mfma_f32_16x16x32_bf16 v[42:45], v[168:171], v[208:211], v[42:45]
	v_mfma_f32_16x16x32_bf16 v[14:17], v[176:179], v[208:211], v[14:17]
	v_mfma_f32_16x16x32_bf16 v[10:13], v[184:187], v[208:211], v[10:13]
	v_mfma_f32_16x16x32_bf16 v[2:5], v[184:187], v[216:219], v[2:5]
	v_mfma_f32_16x16x32_bf16 v[6:9], v[176:179], v[216:219], v[6:9]
	v_mfma_f32_16x16x32_bf16 v[34:37], v[168:171], v[216:219], v[34:37]
	v_mfma_f32_16x16x32_bf16 v[38:41], v[160:163], v[216:219], v[38:41]
	s_barrier
; #define PG8_STAGEA(bufoff, gbase) PG8_STAGE_(bufoff, gbase, voffA)
; #define PG8_STAGEB(bufoff, gbase) PG8_STAGE_(bufoff, gbase, voffB)
; #define PG8_LDA(dst, b, h) do { _Pragma("unroll") for (int m = 0; m < 4; ++m) _Pragma("unroll") for (int k = 0; k < 2; ++k) dst[m][k] = *(const LAS bf16x8*)(lds + PG8_SA(b, h) + aoff + m * 2048 + k * 1024); } while (0)
; #define PG8_LDB(dst, b, h) do { _Pragma("unroll") for (int n = 0; n < 2; ++n) _Pragma("unroll") for (int k = 0; k < 2; ++k) dst[n][k] = *(const LAS bf16x8*)(lds + PG8_SB(b, h) + boff + n * 2048 + k * 1024); } while (0)
; #define PG8_MMA(ai, bj, At, Bt_) do { __builtin_amdgcn_s_setprio(1); _Pragma("unroll") for (int m = 0; m < 4; ++m) _Pragma("unroll") for (int n = 0; n < 2; ++n) _Pragma("unroll") for (int k = 0; k < 2; ++k) \
;         acc[ai][bj][m][n] = __builtin_amdgcn_mfma_f32_16x16x32_bf16(Bt_[n][k], At[m][k], acc[ai][bj][m][n], 0, 0, 0); __builtin_amdgcn_s_setprio(0); } while (0)
; #define PG8_WAIT_V(n) asm volatile("s_waitcnt vmcnt(" #n ")" ::: "memory")
; #define PG8_WAIT_L(n) asm volatile("s_waitcnt lgkmcnt(" #n ")" ::: "memory")
; #define PG8_BAR __builtin_amdgcn_s_barrier()
; #define PG8_SCHED __builtin_amdgcn_sched_barrier(0)
; template <int EK, int SK = -1>
; __device__ __forceinline__ void gemm_phase(LAS unsigned char* lds, const bf16_t* A, const bf16_t* Bt, int nM, int N, int K, const EpiArgs& E) {
;     ...
;             PG8_LDB(B0, 1, 0); PG8_LDB(B1, 1, 1); PG8_SCHED; PG8_LDA(At, 1, 0); PG8_STAGEA(PG8_SA(0, 1), a2 + hstep);
;             PG8_WAIT_V(8); PG8_WAIT_L(0); PG8_BAR; PG8_MMA(0, 0, At, B0); PG8_MMA(0, 1, At, B1); PG8_BAR; PG8_SCHED;
;             PG8_LDA(At, 1, 1); PG8_STAGEB(PG8_SB(1, 0), b3); PG8_STAGEB(PG8_SB(1, 1), b3 + hstep); PG8_STAGEA(PG8_SA(1, 0), a3);
;             PG8_WAIT_V(8); PG8_WAIT_L(0); PG8_BAR; PG8_MMA(1, 0, At, B0); PG8_MMA(1, 1, At, B1); PG8_BAR; PG8_SCHED;
	s_add_i32 s75, 0, 0x18000
	s_add_i32 s76, 0, 0x1c000
	v_add_u32_e32 v168, s75, v152
	v_add_u32_e32 v184, s76, v152
	ds_read_b128 v[156:159], v168
	ds_read_b128 v[160:163], v168 offset:1024
	ds_read_b128 v[164:167], v168 offset:2048
	ds_read_b128 v[168:171], v168 offset:3072
	ds_read_b128 v[172:175], v184
	ds_read_b128 v[176:179], v184 offset:1024
	ds_read_b128 v[180:183], v184 offset:2048
	ds_read_b128 v[184:187], v184 offset:3072
	s_add_u32 s46, s46, 0xb0000
	s_addc_u32 s47, s47, 0
	s_mov_b32 m0, s55
	v_lshl_add_u64 v[226:227], s[46:47], 0, v[130:131]
	ds_read_b128 v[188:191], v154 offset:32768
	ds_read_b128 v[192:195], v154 offset:33792
	ds_read_b128 v[196:199], v154 offset:34816
	ds_read_b128 v[200:203], v154 offset:35840
	ds_read_b128 v[204:207], v154 offset:36864
	ds_read_b128 v[208:211], v154 offset:37888
	ds_read_b128 v[212:215], v154 offset:38912
	ds_read_b128 v[216:219], v154 offset:39936
	global_load_lds_dwordx4 v[226:227], off
	v_lshl_add_u64 v[226:227], s[46:47], 0, v[134:135]
	s_mov_b32 m0, s56
	s_nop 0
	global_load_lds_dwordx4 v[226:227], off
	s_waitcnt vmcnt(8)
	s_waitcnt lgkmcnt(0)
	s_barrier
	s_waitcnt lgkmcnt(0)
	v_mfma_f32_16x16x32_bf16 v[126:129], v[156:159], v[188:191], v[126:129]
	v_mfma_f32_16x16x32_bf16 v[122:125], v[164:167], v[188:191], v[122:125]
	v_mfma_f32_16x16x32_bf16 v[94:97], v[172:175], v[188:191], v[94:97]
	v_mfma_f32_16x16x32_bf16 v[90:93], v[180:183], v[188:191], v[90:93]
	v_mfma_f32_16x16x32_bf16 v[82:85], v[180:183], v[196:199], v[82:85]
	v_mfma_f32_16x16x32_bf16 v[86:89], v[172:175], v[196:199], v[86:89]
	v_mfma_f32_16x16x32_bf16 v[114:117], v[164:167], v[196:199], v[114:117]
	v_mfma_f32_16x16x32_bf16 v[118:121], v[156:159], v[196:199], v[118:121]
	v_mfma_f32_16x16x32_bf16 v[110:113], v[156:159], v[204:207], v[110:113]
	v_mfma_f32_16x16x32_bf16 v[106:109], v[164:167], v[204:207], v[106:109]
	v_mfma_f32_16x16x32_bf16 v[78:81], v[172:175], v[204:207], v[78:81]
	v_mfma_f32_16x16x32_bf16 v[74:77], v[180:183], v[204:207], v[74:77]
	v_mfma_f32_16x16x32_bf16 v[66:69], v[180:183], v[212:215], v[66:69]
	v_mfma_f32_16x16x32_bf16 v[70:73], v[172:175], v[212:215], v[70:73]
	v_mfma_f32_16x16x32_bf16 v[98:101], v[164:167], v[212:215], v[98:101]
	v_mfma_f32_16x16x32_bf16 v[102:105], v[156:159], v[212:215], v[102:105]
	v_mfma_f32_16x16x32_bf16 v[126:129], v[160:163], v[192:195], v[126:129]
	v_mfma_f32_16x16x32_bf16 v[122:125], v[168:171], v[192:195], v[122:125]
	v_mfma_f32_16x16x32_bf16 v[94:97], v[176:179], v[192:195], v[94:97]
	v_mfma_f32_16x16x32_bf16 v[90:93], v[184:187], v[192:195], v[90:93]
	v_mfma_f32_16x16x32_bf16 v[82:85], v[184:187], v[200:203], v[82:85]
	v_mfma_f32_16x16x32_bf16 v[86:89], v[176:179], v[200:203], v[86:89]
	v_mfma_f32_16x16x32_bf16 v[114:117], v[168:171], v[200:203], v[114:117]
	v_mfma_f32_16x16x32_bf16 v[118:121], v[160:163], v[200:203], v[118:121]
	v_mfma_f32_16x16x32_bf16 v[110:113], v[160:163], v[208:211], v[110:113]
	v_mfma_f32_16x16x32_bf16 v[106:109], v[168:171], v[208:211], v[106:109]
	v_mfma_f32_16x16x32_bf16 v[78:81], v[176:179], v[208:211], v[78:81]
	v_mfma_f32_16x16x32_bf16 v[74:77], v[184:187], v[208:211], v[74:77]
	v_mfma_f32_16x16x32_bf16 v[66:69], v[184:187], v[216:219], v[66:69]
	v_mfma_f32_16x16x32_bf16 v[70:73], v[176:179], v[216:219], v[70:73]
	v_mfma_f32_16x16x32_bf16 v[98:101], v[168:171], v[216:219], v[98:101]
	v_mfma_f32_16x16x32_bf16 v[102:105], v[160:163], v[216:219], v[102:105]
	s_barrier
	s_add_i32 s46, s75, s52
	v_lshl_add_u64 v[150:151], v[150:151], 0, s[36:37]
	s_mov_b32 m0, s46
	ds_read_b128 v[188:191], v154 offset:49152
	ds_read_b128 v[192:195], v154 offset:50176
	ds_read_b128 v[196:199], v154 offset:51200
	ds_read_b128 v[200:203], v154 offset:52224
	ds_read_b128 v[204:207], v154 offset:53248
	ds_read_b128 v[208:211], v154 offset:54272
	ds_read_b128 v[212:215], v154 offset:55296
	ds_read_b128 v[216:219], v154 offset:56320
	global_load_lds_dwordx4 v[150:151], off
	s_add_i32 m0, s46, 0x2000
	s_add_u32 s44, s44, 0xb0080
	v_lshl_add_u64 v[150:151], v[220:221], 0, s[36:37]
	s_addc_u32 s45, s45, 0
	s_add_i32 s46, s76, s52
	global_load_lds_dwordx4 v[150:151], off
	v_lshl_add_u64 v[150:151], s[44:45], 0, v[132:133]
	s_mov_b32 m0, s46
	s_nop 0
	global_load_lds_dwordx4 v[150:151], off
	v_lshl_add_u64 v[150:151], s[44:45], 0, v[136:137]
	s_add_i32 m0, s46, 0x2000
	s_nop 0
	global_load_lds_dwordx4 v[150:151], off
	v_lshl_add_u64 v[150:151], v[222:223], 0, s[36:37]
	s_mov_b32 m0, s59
	s_nop 0
	global_load_lds_dwordx4 v[150:151], off
	v_lshl_add_u64 v[150:151], v[224:225], 0, s[36:37]
	s_mov_b32 m0, s66
	s_nop 0
	global_load_lds_dwordx4 v[150:151], off
	s_waitcnt vmcnt(8)
	s_waitcnt lgkmcnt(0)
	s_barrier
	s_waitcnt lgkmcnt(0)
	v_mfma_f32_16x16x32_bf16 v[62:65], v[156:159], v[188:191], v[62:65]
	v_mfma_f32_16x16x32_bf16 v[58:61], v[164:167], v[188:191], v[58:61]
	v_mfma_f32_16x16x32_bf16 v[30:33], v[172:175], v[188:191], v[30:33]
	v_mfma_f32_16x16x32_bf16 v[26:29], v[180:183], v[188:191], v[26:29]
	v_mfma_f32_16x16x32_bf16 v[18:21], v[180:183], v[196:199], v[18:21]
	v_mfma_f32_16x16x32_bf16 v[22:25], v[172:175], v[196:199], v[22:25]
	v_mfma_f32_16x16x32_bf16 v[50:53], v[164:167], v[196:199], v[50:53]
	v_mfma_f32_16x16x32_bf16 v[54:57], v[156:159], v[196:199], v[54:57]
	v_mfma_f32_16x16x32_bf16 v[46:49], v[156:159], v[204:207], v[46:49]
	v_mfma_f32_16x16x32_bf16 v[42:45], v[164:167], v[204:207], v[42:45]
	v_mfma_f32_16x16x32_bf16 v[14:17], v[172:175], v[204:207], v[14:17]
	v_mfma_f32_16x16x32_bf16 v[10:13], v[180:183], v[204:207], v[10:13]
	v_mfma_f32_16x16x32_bf16 v[2:5], v[180:183], v[212:215], v[2:5]
	v_mfma_f32_16x16x32_bf16 v[6:9], v[172:175], v[212:215], v[6:9]
	v_mfma_f32_16x16x32_bf16 v[34:37], v[164:167], v[212:215], v[34:37]
	v_mfma_f32_16x16x32_bf16 v[38:41], v[156:159], v[212:215], v[38:41]
	v_mfma_f32_16x16x32_bf16 v[62:65], v[160:163], v[192:195], v[62:65]
	v_mfma_f32_16x16x32_bf16 v[58:61], v[168:171], v[192:195], v[58:61]
	v_mfma_f32_16x16x32_bf16 v[30:33], v[176:179], v[192:195], v[30:33]
	v_mfma_f32_16x16x32_bf16 v[26:29], v[184:187], v[192:195], v[26:29]
	v_mfma_f32_16x16x32_bf16 v[18:21], v[184:187], v[200:203], v[18:21]
	v_mfma_f32_16x16x32_bf16 v[22:25], v[176:179], v[200:203], v[22:25]
	v_mfma_f32_16x16x32_bf16 v[50:53], v[168:171], v[200:203], v[50:53]
	v_mfma_f32_16x16x32_bf16 v[54:57], v[160:163], v[200:203], v[54:57]
	v_mfma_f32_16x16x32_bf16 v[46:49], v[160:163], v[208:211], v[46:49]
	v_mfma_f32_16x16x32_bf16 v[42:45], v[168:171], v[208:211], v[42:45]
	v_mfma_f32_16x16x32_bf16 v[14:17], v[176:179], v[208:211], v[14:17]
	v_mfma_f32_16x16x32_bf16 v[10:13], v[184:187], v[208:211], v[10:13]
	v_mfma_f32_16x16x32_bf16 v[2:5], v[184:187], v[216:219], v[2:5]
	v_mfma_f32_16x16x32_bf16 v[6:9], v[176:179], v[216:219], v[6:9]
	v_mfma_f32_16x16x32_bf16 v[34:37], v[168:171], v[216:219], v[34:37]
	v_mfma_f32_16x16x32_bf16 v[38:41], v[160:163], v[216:219], v[38:41]
	s_barrier
	s_add_i32 s26, s26, 2
	s_add_u32 s42, s42, 0x100
	s_addc_u32 s43, s43, 0
	s_cmp_gt_u32 s26, 41
	s_cbranch_scc0 .LBB0_1338

; #define PG8_STAGEA(bufoff, gbase) PG8_STAGE_(bufoff, gbase, voffA)
; #define PG8_STAGEB(bufoff, gbase) PG8_STAGE_(bufoff, gbase, voffB)
; #define PG8_LDA(dst, b, h) do { _Pragma("unroll") for (int m = 0; m < 4; ++m) _Pragma("unroll") for (int k = 0; k < 2; ++k) dst[m][k] = *(const LAS bf16x8*)(lds + PG8_SA(b, h) + aoff + m * 2048 + k * 1024); } while (0)
; #define PG8_LDB(dst, b, h) do { _Pragma("unroll") for (int n = 0; n < 2; ++n) _Pragma("unroll") for (int k = 0; k < 2; ++k) dst[n][k] = *(const LAS bf16x8*)(lds + PG8_SB(b, h) + boff + n * 2048 + k * 1024); } while (0)
; #define PG8_MMA(ai, bj, At, Bt_) do { __builtin_amdgcn_s_setprio(1); _Pragma("unroll") for (int m = 0; m < 4; ++m) _Pragma("unroll") for (int n = 0; n < 2; ++n) _Pragma("unroll") for (int k = 0; k < 2; ++k) \
;         acc[ai][bj][m][n] = __builtin_amdgcn_mfma_f32_16x16x32_bf16(Bt_[n][k], At[m][k], acc[ai][bj][m][n], 0, 0, 0); __builtin_amdgcn_s_setprio(0); } while (0)
; #define PG8_WAIT_V(n) asm volatile("s_waitcnt vmcnt(" #n ")" ::: "memory")
; #define PG8_WAIT_L(n) asm volatile("s_waitcnt lgkmcnt(" #n ")" ::: "memory")
; #define PG8_BAR __builtin_amdgcn_s_barrier()
; #define PG8_SCHED __builtin_amdgcn_sched_barrier(0)
; template <int EK, int SK = -1>
; __device__ __forceinline__ void gemm_phase(LAS unsigned char* lds, const bf16_t* A, const bf16_t* Bt, int nM, int N, int K, const EpiArgs& E) {
;     ...
;             const bool last = (t == nt - 2);
;             const char* a1 = cA + (size_t)(t + 1) * kstep;
;             const char* a2 = last ? nA : cA + (size_t)(t + 2) * kstep; const char* b2 = last ? nB : cB + (size_t)(t + 2) * kstep;
;             const char* a3 = a2 + kstep; const char* b3 = b2 + kstep;
;             PG8_LDB(B0, 0, 0); PG8_LDB(B1, 0, 1); PG8_SCHED; PG8_LDA(At, 0, 0); PG8_STAGEA(PG8_SA(1, 1), a1 + hstep);
;             PG8_WAIT_V(8); PG8_WAIT_L(0); PG8_BAR; PG8_MMA(0, 0, At, B0); PG8_MMA(0, 1, At, B1); PG8_BAR; PG8_SCHED;
;             PG8_LDA(At, 0, 1); PG8_STAGEB(PG8_SB(0, 0), b2); PG8_STAGEB(PG8_SB(0, 1), b2 + hstep); PG8_STAGEA(PG8_SA(0, 0), a2);
;             PG8_WAIT_V(8); PG8_WAIT_L(0); PG8_BAR; PG8_MMA(1, 0, At, B0); PG8_MMA(1, 1, At, B1); PG8_BAR; PG8_SCHED;
.LBB0_1401:
	v_add_u32_e32 v168, s66, v154
	v_add_u32_e32 v184, s67, v154
	s_add_u32 s42, s20, s40
	ds_read_b128 v[156:159], v168
	ds_read_b128 v[160:163], v168 offset:1024
	ds_read_b128 v[164:167], v168 offset:2048
	ds_read_b128 v[168:171], v168 offset:3072
	ds_read_b128 v[172:175], v184
	ds_read_b128 v[176:179], v184 offset:1024
	ds_read_b128 v[180:183], v184 offset:2048
	ds_read_b128 v[184:187], v184 offset:3072
	s_addc_u32 s43, s21, s41
	s_add_u32 s42, s42, 0x100
	s_addc_u32 s43, s43, 0
	s_add_u32 s73, s37, s40
	s_addc_u32 s74, s71, s41
	s_cmpk_eq_i32 s40, 0x1500
	s_cselect_b32 s45, s7, s43
	s_cselect_b32 s44, s6, s42
	s_cselect_b32 s43, s39, s74
	s_cselect_b32 s42, s38, s73
	v_lshl_add_u64 v[220:221], v[146:147], 0, s[40:41]
	s_add_i32 m0, s53, 0xc000
	ds_read_b128 v[188:191], v155
	ds_read_b128 v[192:195], v155 offset:1024
	ds_read_b128 v[196:199], v155 offset:2048
	ds_read_b128 v[200:203], v155 offset:3072
	ds_read_b128 v[204:207], v155 offset:4096
	ds_read_b128 v[208:211], v155 offset:5120
	ds_read_b128 v[212:215], v155 offset:6144
	ds_read_b128 v[216:219], v155 offset:7168
	global_load_lds_dwordx4 v[220:221], off
	v_lshl_add_u64 v[220:221], v[148:149], 0, s[40:41]
	s_add_i32 m0, s53, 0xe000
	s_nop 0
	global_load_lds_dwordx4 v[220:221], off
	s_waitcnt vmcnt(8)
	s_waitcnt lgkmcnt(0)
	s_barrier
	s_waitcnt lgkmcnt(0)
	v_mfma_f32_16x16x32_bf16 v[126:129], v[156:159], v[188:191], v[126:129]
	v_mfma_f32_16x16x32_bf16 v[122:125], v[164:167], v[188:191], v[122:125]
	v_mfma_f32_16x16x32_bf16 v[118:121], v[172:175], v[188:191], v[118:121]
	v_mfma_f32_16x16x32_bf16 v[114:117], v[180:183], v[188:191], v[114:117]
	v_mfma_f32_16x16x32_bf16 v[98:101], v[180:183], v[196:199], v[98:101]
	v_mfma_f32_16x16x32_bf16 v[102:105], v[172:175], v[196:199], v[102:105]
	v_mfma_f32_16x16x32_bf16 v[106:109], v[164:167], v[196:199], v[106:109]
	v_mfma_f32_16x16x32_bf16 v[110:113], v[156:159], v[196:199], v[110:113]
	v_mfma_f32_16x16x32_bf16 v[94:97], v[156:159], v[204:207], v[94:97]
	v_mfma_f32_16x16x32_bf16 v[90:93], v[164:167], v[204:207], v[90:93]
	v_mfma_f32_16x16x32_bf16 v[86:89], v[172:175], v[204:207], v[86:89]
	v_mfma_f32_16x16x32_bf16 v[82:85], v[180:183], v[204:207], v[82:85]
	v_mfma_f32_16x16x32_bf16 v[66:69], v[180:183], v[212:215], v[66:69]
	v_mfma_f32_16x16x32_bf16 v[70:73], v[172:175], v[212:215], v[70:73]
	v_mfma_f32_16x16x32_bf16 v[74:77], v[164:167], v[212:215], v[74:77]
	v_mfma_f32_16x16x32_bf16 v[78:81], v[156:159], v[212:215], v[78:81]
	v_mfma_f32_16x16x32_bf16 v[126:129], v[160:163], v[192:195], v[126:129]
	v_mfma_f32_16x16x32_bf16 v[122:125], v[168:171], v[192:195], v[122:125]
	v_mfma_f32_16x16x32_bf16 v[118:121], v[176:179], v[192:195], v[118:121]
	v_mfma_f32_16x16x32_bf16 v[114:117], v[184:187], v[192:195], v[114:117]
	v_mfma_f32_16x16x32_bf16 v[98:101], v[184:187], v[200:203], v[98:101]
	v_mfma_f32_16x16x32_bf16 v[102:105], v[176:179], v[200:203], v[102:105]
	v_mfma_f32_16x16x32_bf16 v[106:109], v[168:171], v[200:203], v[106:109]
	v_mfma_f32_16x16x32_bf16 v[110:113], v[160:163], v[200:203], v[110:113]
	v_mfma_f32_16x16x32_bf16 v[94:97], v[160:163], v[208:211], v[94:97]
	v_mfma_f32_16x16x32_bf16 v[90:93], v[168:171], v[208:211], v[90:93]
	v_mfma_f32_16x16x32_bf16 v[86:89], v[176:179], v[208:211], v[86:89]
	v_mfma_f32_16x16x32_bf16 v[82:85], v[184:187], v[208:211], v[82:85]
	v_mfma_f32_16x16x32_bf16 v[66:69], v[184:187], v[216:219], v[66:69]
	v_mfma_f32_16x16x32_bf16 v[70:73], v[176:179], v[216:219], v[70:73]
	v_mfma_f32_16x16x32_bf16 v[74:77], v[168:171], v[216:219], v[74:77]
	v_mfma_f32_16x16x32_bf16 v[78:81], v[160:163], v[216:219], v[78:81]
	s_barrier
	s_add_i32 s73, s66, s52
	v_lshl_add_u64 v[220:221], s[42:43], 0, v[132:133]
	s_mov_b32 m0, s73
	ds_read_b128 v[188:191], v155 offset:16384
	ds_read_b128 v[192:195], v155 offset:17408
	ds_read_b128 v[196:199], v155 offset:18432
	ds_read_b128 v[200:203], v155 offset:19456
	ds_read_b128 v[204:207], v155 offset:20480
	ds_read_b128 v[208:211], v155 offset:21504
	ds_read_b128 v[212:215], v155 offset:22528
	ds_read_b128 v[216:219], v155 offset:23552
	global_load_lds_dwordx4 v[220:221], off
	s_add_i32 m0, s73, 0x2000
	s_add_u32 s74, s42, 0xb0000
	v_lshl_add_u64 v[222:223], s[42:43], 0, v[136:137]
	s_addc_u32 s75, s43, 0
	s_add_i32 s73, s67, s52
	global_load_lds_dwordx4 v[222:223], off
	v_lshl_add_u64 v[224:225], s[74:75], 0, v[132:133]
	s_mov_b32 m0, s73
	v_lshl_add_u64 v[226:227], s[44:45], 0, v[134:135]
	global_load_lds_dwordx4 v[224:225], off
	v_lshl_add_u64 v[224:225], s[74:75], 0, v[136:137]
	s_add_i32 m0, s73, 0x2000
	s_nop 0
	global_load_lds_dwordx4 v[224:225], off
	v_lshl_add_u64 v[224:225], s[44:45], 0, v[130:131]
	s_mov_b32 m0, s53
	s_nop 0
	global_load_lds_dwordx4 v[224:225], off
	s_mov_b32 m0, s54
	s_nop 0
	global_load_lds_dwordx4 v[226:227], off
	s_waitcnt vmcnt(8)
	s_waitcnt lgkmcnt(0)
	s_barrier
; #define PG8_STAGEA(bufoff, gbase) PG8_STAGE_(bufoff, gbase, voffA)
; #define PG8_LDA(dst, b, h) do { _Pragma("unroll") for (int m = 0; m < 4; ++m) _Pragma("unroll") for (int k = 0; k < 2; ++k) dst[m][k] = *(const LAS bf16x8*)(lds + PG8_SA(b, h) + aoff + m * 2048 + k * 1024); } while (0)
; #define PG8_LDB(dst, b, h) do { _Pragma("unroll") for (int n = 0; n < 2; ++n) _Pragma("unroll") for (int k = 0; k < 2; ++k) dst[n][k] = *(const LAS bf16x8*)(lds + PG8_SB(b, h) + boff + n * 2048 + k * 1024); } while (0)
; #define PG8_MMA(ai, bj, At, Bt_) do { __builtin_amdgcn_s_setprio(1); _Pragma("unroll") for (int m = 0; m < 4; ++m) _Pragma("unroll") for (int n = 0; n < 2; ++n) _Pragma("unroll") for (int k = 0; k < 2; ++k) \
;         acc[ai][bj][m][n] = __builtin_amdgcn_mfma_f32_16x16x32_bf16(Bt_[n][k], At[m][k], acc[ai][bj][m][n], 0, 0, 0); __builtin_amdgcn_s_setprio(0); } while (0)
; #define PG8_WAIT_V(n) asm volatile("s_waitcnt vmcnt(" #n ")" ::: "memory")
; #define PG8_WAIT_L(n) asm volatile("s_waitcnt lgkmcnt(" #n ")" ::: "memory")
; #define PG8_BAR __builtin_amdgcn_s_barrier()
; #define PG8_SCHED __builtin_amdgcn_sched_barrier(0)
; template <int EK, int SK = -1>
; __device__ __forceinline__ void gemm_phase(LAS unsigned char* lds, const bf16_t* A, const bf16_t* Bt, int nM, int N, int K, const EpiArgs& E) {
;     ...
;             PG8_WAIT_V(8); PG8_WAIT_L(0); PG8_BAR; PG8_MMA(1, 0, At, B0); PG8_MMA(1, 1, At, B1); PG8_BAR; PG8_SCHED;
;             PG8_LDB(B0, 1, 0); PG8_LDB(B1, 1, 1); PG8_SCHED; PG8_LDA(At, 1, 0); PG8_STAGEA(PG8_SA(0, 1), a2 + hstep);
;             PG8_WAIT_V(8); PG8_WAIT_L(0); PG8_BAR; PG8_MMA(0, 0, At, B0); PG8_MMA(0, 1, At, B1); PG8_BAR; PG8_SCHED;
	s_waitcnt lgkmcnt(0)
	v_mfma_f32_16x16x32_bf16 v[62:65], v[156:159], v[188:191], v[62:65]
	v_mfma_f32_16x16x32_bf16 v[58:61], v[164:167], v[188:191], v[58:61]
	v_mfma_f32_16x16x32_bf16 v[54:57], v[172:175], v[188:191], v[54:57]
	v_mfma_f32_16x16x32_bf16 v[50:53], v[180:183], v[188:191], v[50:53]
	v_mfma_f32_16x16x32_bf16 v[34:37], v[180:183], v[196:199], v[34:37]
	v_mfma_f32_16x16x32_bf16 v[38:41], v[172:175], v[196:199], v[38:41]
	v_mfma_f32_16x16x32_bf16 v[42:45], v[164:167], v[196:199], v[42:45]
	v_mfma_f32_16x16x32_bf16 v[46:49], v[156:159], v[196:199], v[46:49]
	v_mfma_f32_16x16x32_bf16 v[30:33], v[156:159], v[204:207], v[30:33]
	v_mfma_f32_16x16x32_bf16 v[26:29], v[164:167], v[204:207], v[26:29]
	v_mfma_f32_16x16x32_bf16 v[22:25], v[172:175], v[204:207], v[22:25]
	v_mfma_f32_16x16x32_bf16 v[18:21], v[180:183], v[204:207], v[18:21]
	v_mfma_f32_16x16x32_bf16 v[2:5], v[180:183], v[212:215], v[2:5]
	v_mfma_f32_16x16x32_bf16 v[6:9], v[172:175], v[212:215], v[6:9]
	v_mfma_f32_16x16x32_bf16 v[10:13], v[164:167], v[212:215], v[10:13]
	v_mfma_f32_16x16x32_bf16 v[14:17], v[156:159], v[212:215], v[14:17]
	v_mfma_f32_16x16x32_bf16 v[62:65], v[160:163], v[192:195], v[62:65]
	v_mfma_f32_16x16x32_bf16 v[58:61], v[168:171], v[192:195], v[58:61]
	v_mfma_f32_16x16x32_bf16 v[54:57], v[176:179], v[192:195], v[54:57]
	v_mfma_f32_16x16x32_bf16 v[50:53], v[184:187], v[192:195], v[50:53]
	v_mfma_f32_16x16x32_bf16 v[34:37], v[184:187], v[200:203], v[34:37]
	v_mfma_f32_16x16x32_bf16 v[38:41], v[176:179], v[200:203], v[38:41]
	v_mfma_f32_16x16x32_bf16 v[42:45], v[168:171], v[200:203], v[42:45]
	v_mfma_f32_16x16x32_bf16 v[46:49], v[160:163], v[200:203], v[46:49]
	v_mfma_f32_16x16x32_bf16 v[30:33], v[160:163], v[208:211], v[30:33]
	v_mfma_f32_16x16x32_bf16 v[26:29], v[168:171], v[208:211], v[26:29]
	v_mfma_f32_16x16x32_bf16 v[22:25], v[176:179], v[208:211], v[22:25]
	v_mfma_f32_16x16x32_bf16 v[18:21], v[184:187], v[208:211], v[18:21]
	v_mfma_f32_16x16x32_bf16 v[2:5], v[184:187], v[216:219], v[2:5]
	v_mfma_f32_16x16x32_bf16 v[6:9], v[176:179], v[216:219], v[6:9]
	v_mfma_f32_16x16x32_bf16 v[10:13], v[168:171], v[216:219], v[10:13]
	v_mfma_f32_16x16x32_bf16 v[14:17], v[160:163], v[216:219], v[14:17]
	s_barrier
	s_add_i32 s73, 0, 0x18000
	s_add_i32 s74, 0, 0x1c000
	v_add_u32_e32 v168, s73, v154
	v_add_u32_e32 v184, s74, v154
	ds_read_b128 v[156:159], v168
	ds_read_b128 v[160:163], v168 offset:1024
	ds_read_b128 v[164:167], v168 offset:2048
	ds_read_b128 v[168:171], v168 offset:3072
	ds_read_b128 v[172:175], v184
	ds_read_b128 v[176:179], v184 offset:1024
	ds_read_b128 v[180:183], v184 offset:2048
	ds_read_b128 v[184:187], v184 offset:3072
	s_add_u32 s44, s44, 0xb0000
	s_addc_u32 s45, s45, 0
	s_mov_b32 m0, s55
	v_lshl_add_u64 v[228:229], s[44:45], 0, v[130:131]
	ds_read_b128 v[188:191], v155 offset:32768
	ds_read_b128 v[192:195], v155 offset:33792
	ds_read_b128 v[196:199], v155 offset:34816
	ds_read_b128 v[200:203], v155 offset:35840
	ds_read_b128 v[204:207], v155 offset:36864
	ds_read_b128 v[208:211], v155 offset:37888
	ds_read_b128 v[212:215], v155 offset:38912
	ds_read_b128 v[216:219], v155 offset:39936
	global_load_lds_dwordx4 v[228:229], off
	v_lshl_add_u64 v[228:229], s[44:45], 0, v[134:135]
	s_mov_b32 m0, s56
	s_nop 0
	global_load_lds_dwordx4 v[228:229], off
	s_waitcnt vmcnt(8)
	s_waitcnt lgkmcnt(0)
	s_barrier
	s_waitcnt lgkmcnt(0)
	v_mfma_f32_16x16x32_bf16 v[126:129], v[156:159], v[188:191], v[126:129]
	v_mfma_f32_16x16x32_bf16 v[122:125], v[164:167], v[188:191], v[122:125]
	v_mfma_f32_16x16x32_bf16 v[118:121], v[172:175], v[188:191], v[118:121]
	v_mfma_f32_16x16x32_bf16 v[114:117], v[180:183], v[188:191], v[114:117]
	v_mfma_f32_16x16x32_bf16 v[98:101], v[180:183], v[196:199], v[98:101]
	v_mfma_f32_16x16x32_bf16 v[102:105], v[172:175], v[196:199], v[102:105]
	v_mfma_f32_16x16x32_bf16 v[106:109], v[164:167], v[196:199], v[106:109]
	v_mfma_f32_16x16x32_bf16 v[110:113], v[156:159], v[196:199], v[110:113]
	v_mfma_f32_16x16x32_bf16 v[94:97], v[156:159], v[204:207], v[94:97]
	v_mfma_f32_16x16x32_bf16 v[90:93], v[164:167], v[204:207], v[90:93]
	v_mfma_f32_16x16x32_bf16 v[86:89], v[172:175], v[204:207], v[86:89]
	v_mfma_f32_16x16x32_bf16 v[82:85], v[180:183], v[204:207], v[82:85]
	v_mfma_f32_16x16x32_bf16 v[66:69], v[180:183], v[212:215], v[66:69]
	v_mfma_f32_16x16x32_bf16 v[70:73], v[172:175], v[212:215], v[70:73]
	v_mfma_f32_16x16x32_bf16 v[74:77], v[164:167], v[212:215], v[74:77]
	v_mfma_f32_16x16x32_bf16 v[78:81], v[156:159], v[212:215], v[78:81]
	v_mfma_f32_16x16x32_bf16 v[126:129], v[160:163], v[192:195], v[126:129]
	v_mfma_f32_16x16x32_bf16 v[122:125], v[168:171], v[192:195], v[122:125]
	v_mfma_f32_16x16x32_bf16 v[118:121], v[176:179], v[192:195], v[118:121]
	v_mfma_f32_16x16x32_bf16 v[114:117], v[184:187], v[192:195], v[114:117]
	v_mfma_f32_16x16x32_bf16 v[98:101], v[184:187], v[200:203], v[98:101]
	v_mfma_f32_16x16x32_bf16 v[102:105], v[176:179], v[200:203], v[102:105]
	v_mfma_f32_16x16x32_bf16 v[106:109], v[168:171], v[200:203], v[106:109]
	v_mfma_f32_16x16x32_bf16 v[110:113], v[160:163], v[200:203], v[110:113]
	v_mfma_f32_16x16x32_bf16 v[94:97], v[160:163], v[208:211], v[94:97]
	v_mfma_f32_16x16x32_bf16 v[90:93], v[168:171], v[208:211], v[90:93]
	v_mfma_f32_16x16x32_bf16 v[86:89], v[176:179], v[208:211], v[86:89]
	v_mfma_f32_16x16x32_bf16 v[82:85], v[184:187], v[208:211], v[82:85]
	v_mfma_f32_16x16x32_bf16 v[66:69], v[184:187], v[216:219], v[66:69]
	v_mfma_f32_16x16x32_bf16 v[70:73], v[176:179], v[216:219], v[70:73]
	v_mfma_f32_16x16x32_bf16 v[74:77], v[168:171], v[216:219], v[74:77]
	v_mfma_f32_16x16x32_bf16 v[78:81], v[160:163], v[216:219], v[78:81]
	s_barrier
; #define PG8_STAGEA(bufoff, gbase) PG8_STAGE_(bufoff, gbase, voffA)
; #define PG8_STAGEB(bufoff, gbase) PG8_STAGE_(bufoff, gbase, voffB)
; #define PG8_LDA(dst, b, h) do { _Pragma("unroll") for (int m = 0; m < 4; ++m) _Pragma("unroll") for (int k = 0; k < 2; ++k) dst[m][k] = *(const LAS bf16x8*)(lds + PG8_SA(b, h) + aoff + m * 2048 + k * 1024); } while (0)
; #define PG8_MMA(ai, bj, At, Bt_) do { __builtin_amdgcn_s_setprio(1); _Pragma("unroll") for (int m = 0; m < 4; ++m) _Pragma("unroll") for (int n = 0; n < 2; ++n) _Pragma("unroll") for (int k = 0; k < 2; ++k) \
;         acc[ai][bj][m][n] = __builtin_amdgcn_mfma_f32_16x16x32_bf16(Bt_[n][k], At[m][k], acc[ai][bj][m][n], 0, 0, 0); __builtin_amdgcn_s_setprio(0); } while (0)
; #define PG8_WAIT_V(n) asm volatile("s_waitcnt vmcnt(" #n ")" ::: "memory")
; #define PG8_WAIT_L(n) asm volatile("s_waitcnt lgkmcnt(" #n ")" ::: "memory")
; #define PG8_BAR __builtin_amdgcn_s_barrier()
; #define PG8_SCHED __builtin_amdgcn_sched_barrier(0)
; template <int EK, int SK = -1>
; __device__ __forceinline__ void gemm_phase(LAS unsigned char* lds, const bf16_t* A, const bf16_t* Bt, int nM, int N, int K, const EpiArgs& E) {
;     ...
;             PG8_LDA(At, 1, 1); PG8_STAGEB(PG8_SB(1, 0), b3); PG8_STAGEB(PG8_SB(1, 1), b3 + hstep); PG8_STAGEA(PG8_SA(1, 0), a3);
;             PG8_WAIT_V(8); PG8_WAIT_L(0); PG8_BAR; PG8_MMA(1, 0, At, B0); PG8_MMA(1, 1, At, B1); PG8_BAR; PG8_SCHED;
;         }
;         if (wr == 0) PG8_BAR;
	s_add_i32 s44, s73, s52
	v_lshl_add_u64 v[220:221], v[220:221], 0, s[22:23]
	s_mov_b32 m0, s44
	ds_read_b128 v[188:191], v155 offset:49152
	ds_read_b128 v[192:195], v155 offset:50176
	ds_read_b128 v[196:199], v155 offset:51200
	ds_read_b128 v[200:203], v155 offset:52224
	ds_read_b128 v[204:207], v155 offset:53248
	ds_read_b128 v[208:211], v155 offset:54272
	ds_read_b128 v[212:215], v155 offset:55296
	ds_read_b128 v[216:219], v155 offset:56320
	global_load_lds_dwordx4 v[220:221], off
	s_add_i32 m0, s44, 0x2000
	s_add_u32 s42, s42, 0xb0080
	v_lshl_add_u64 v[220:221], v[222:223], 0, s[22:23]
	s_addc_u32 s43, s43, 0
	s_add_i32 s44, s74, s52
	global_load_lds_dwordx4 v[220:221], off
	v_lshl_add_u64 v[220:221], s[42:43], 0, v[132:133]
	s_mov_b32 m0, s44
	s_nop 0
	global_load_lds_dwordx4 v[220:221], off
	v_lshl_add_u64 v[220:221], s[42:43], 0, v[136:137]
	s_add_i32 m0, s44, 0x2000
	s_nop 0
	global_load_lds_dwordx4 v[220:221], off
	v_lshl_add_u64 v[220:221], v[224:225], 0, s[22:23]
	s_mov_b32 m0, s58
	s_nop 0
	global_load_lds_dwordx4 v[220:221], off
	v_lshl_add_u64 v[220:221], v[226:227], 0, s[22:23]
	s_mov_b32 m0, s59
	s_nop 0
	global_load_lds_dwordx4 v[220:221], off
	s_waitcnt vmcnt(8)
	s_waitcnt lgkmcnt(0)
	s_barrier
	s_waitcnt lgkmcnt(0)
	v_mfma_f32_16x16x32_bf16 v[62:65], v[156:159], v[188:191], v[62:65]
	v_mfma_f32_16x16x32_bf16 v[58:61], v[164:167], v[188:191], v[58:61]
	v_mfma_f32_16x16x32_bf16 v[54:57], v[172:175], v[188:191], v[54:57]
	v_mfma_f32_16x16x32_bf16 v[50:53], v[180:183], v[188:191], v[50:53]
	v_mfma_f32_16x16x32_bf16 v[34:37], v[180:183], v[196:199], v[34:37]
	v_mfma_f32_16x16x32_bf16 v[38:41], v[172:175], v[196:199], v[38:41]
	v_mfma_f32_16x16x32_bf16 v[42:45], v[164:167], v[196:199], v[42:45]
	v_mfma_f32_16x16x32_bf16 v[46:49], v[156:159], v[196:199], v[46:49]
	v_mfma_f32_16x16x32_bf16 v[30:33], v[156:159], v[204:207], v[30:33]
	v_mfma_f32_16x16x32_bf16 v[26:29], v[164:167], v[204:207], v[26:29]
	v_mfma_f32_16x16x32_bf16 v[22:25], v[172:175], v[204:207], v[22:25]
	v_mfma_f32_16x16x32_bf16 v[18:21], v[180:183], v[204:207], v[18:21]
	v_mfma_f32_16x16x32_bf16 v[2:5], v[180:183], v[212:215], v[2:5]
	v_mfma_f32_16x16x32_bf16 v[6:9], v[172:175], v[212:215], v[6:9]
	v_mfma_f32_16x16x32_bf16 v[10:13], v[164:167], v[212:215], v[10:13]
	v_mfma_f32_16x16x32_bf16 v[14:17], v[156:159], v[212:215], v[14:17]
	v_mfma_f32_16x16x32_bf16 v[62:65], v[160:163], v[192:195], v[62:65]
	v_mfma_f32_16x16x32_bf16 v[58:61], v[168:171], v[192:195], v[58:61]
	v_mfma_f32_16x16x32_bf16 v[54:57], v[176:179], v[192:195], v[54:57]
	v_mfma_f32_16x16x32_bf16 v[50:53], v[184:187], v[192:195], v[50:53]
	v_mfma_f32_16x16x32_bf16 v[34:37], v[184:187], v[200:203], v[34:37]
	v_mfma_f32_16x16x32_bf16 v[38:41], v[176:179], v[200:203], v[38:41]
	v_mfma_f32_16x16x32_bf16 v[42:45], v[168:171], v[200:203], v[42:45]
	v_mfma_f32_16x16x32_bf16 v[46:49], v[160:163], v[200:203], v[46:49]
	v_mfma_f32_16x16x32_bf16 v[30:33], v[160:163], v[208:211], v[30:33]
	v_mfma_f32_16x16x32_bf16 v[26:29], v[168:171], v[208:211], v[26:29]
	v_mfma_f32_16x16x32_bf16 v[22:25], v[176:179], v[208:211], v[22:25]
	v_mfma_f32_16x16x32_bf16 v[18:21], v[184:187], v[208:211], v[18:21]
	v_mfma_f32_16x16x32_bf16 v[2:5], v[184:187], v[216:219], v[2:5]
	v_mfma_f32_16x16x32_bf16 v[6:9], v[176:179], v[216:219], v[6:9]
	v_mfma_f32_16x16x32_bf16 v[10:13], v[168:171], v[216:219], v[10:13]
	v_mfma_f32_16x16x32_bf16 v[14:17], v[160:163], v[216:219], v[14:17]
	s_barrier
	s_add_i32 s72, s72, 2
	s_add_u32 s40, s40, 0x100
	s_addc_u32 s41, s41, 0
	s_cmp_gt_u32 s72, 41
	s_cbranch_scc0 .LBB0_1401
	s_and_b64 vcc, exec, s[26:27]
	s_cbranch_vccz .LBB0_1404
	s_barrier
